# phase11 PEER u-dots rewritten by hand (2 tokens interleaved, rolling 16-row prefetch, permlane/DPP butterfly); compiler paths kept for non power-of-two grids
# speedup vs baseline: 1.1085x; 1.0340x over previous
; DEVI int launder(int x) { asm volatile("" : "+v"(x)); return x; }
; template <int PART>
; DEVI void phase_peer_gather(const Params& p, unsigned char* smem) {
;     ...
;   for (int tok = blockIdx.x * 4 + w0_; tok < NTOK; tok += gridDim.x * 4) {
;     if (NTOK % (gridDim.x * 4) == 0) __syncthreads();
;     const int tid = launder(threadIdx.x), lane = tid & 63;
;     const uint4* hp4 = (const uint4*)(p.hn + (size_t)tok * LDA + lane * 16);
;     float hv[16], xn[16], y[16];
;     {
;       const uint4 a0 = hp4[0], a1 = hp4[1];
;       const unsigned hu[8] = {a0.x, a0.y, a0.z, a0.w, a1.x, a1.y, a1.z, a1.w};
; #pragma unroll
;       for (int i = 0; i < 8; ++i) { hv[2 * i] = __uint_as_float(hu[i] << 16); hv[2 * i + 1] = __uint_as_float(hu[i] & 0xffff0000u); }
;     }
;     float ss = 0.f;
; #pragma unroll
;     for (int i = 0; i < 16; ++i) ss += hv[i] * hv[i];
;     ss = wave_sum(ss);
;     const float rstd = rsqrtf(ss * (1.f / D) + 1e-6f);
;     {
;       const float4* g4 = (const float4*)p.peer_g + lane * 4;
;       const float4 a0 = g4[0], a1 = g4[1], a2 = g4[2], a3 = g4[3];
;       const float gg[16] = {a0.x, a0.y, a0.z, a0.w, a1.x, a1.y, a1.z, a1.w, a2.x, a2.y, a2.z, a2.w, a3.x, a3.y, a3.z, a3.w};
; #pragma unroll
;       for (int i = 0; i < 16; ++i) { xn[i] = hv[i] * rstd * gg[i]; y[i] = 0.f; }
.LBB0_1344:
	s_cmp_gt_i32 s88, 11
	s_cselect_b64 s[0:1], -1, 0
	s_cmp_lt_i32 s89, 11
	s_cselect_b64 s[2:3], -1, 0
	s_or_b64 s[0:1], s[0:1], s[2:3]
	s_and_b64 vcc, exec, s[0:1]
	v_lshrrev_b32_e32 v94, 6, v210
	s_cbranch_vccnz .LBB0_1447
	s_load_dword s2, s[68:69], 0x200
	s_waitcnt lgkmcnt(0)
	s_lshl_b32 s2, s2, 2
	s_add_i32 s3, s2, -1
	s_and_b32 s3, s3, s2
	s_cmp_lg_u32 s3, 0
	s_cbranch_scc1 .Lp11_compiler_path
	s_cmp_gt_u32 s2, 0x2000
	s_cbranch_scc1 .Lp11_compiler_path
	v_and_b32_e32 v226, 63, v210
	v_lshlrev_b32_e32 v208, 4, v226
	v_lshlrev_b32_e32 v209, 2, v226
	v_lshlrev_b32_e32 v211, 5, v226
	v_xor_b32_e32 v212, 16, v226
	v_lshlrev_b32_e32 v212, 2, v212
	v_xor_b32_e32 v213, 4, v226
	v_lshlrev_b32_e32 v213, 2, v213
	v_and_b32_e32 v214, 7, v226
	v_lshlrev_b32_e32 v214, 5, v214
	v_lshrrev_b32_e32 v215, 6, v210
	v_lshlrev_b32_e32 v215, 10, v215
	s_load_dwordx2 s[18:19], s[68:69], 0xa8
	s_load_dwordx2 s[6:7], s[68:69], 0xe0
	s_load_dwordx2 s[8:9], s[68:69], 0x1b0
	s_load_dwordx2 s[10:11], s[68:69], 0x1b8
	s_load_dwordx2 s[12:13], s[68:69], 0x1c0
	s_load_dwordx2 s[14:15], s[68:69], 0x1d0
	s_load_dwordx2 s[16:17], s[68:69], 0x1d8
	s_load_dword s2, s[68:69], 0x200
	v_lshrrev_b32_e32 v227, 6, v210
	s_nop 0
	v_readfirstlane_b32 s3, v227
	s_mov_b32 s26, 0xffff0000
	s_mov_b32 s27, 0xffff0000
	s_mov_b32 s28, 0xff00ff00
	s_mov_b32 s29, 0xff00ff00
	s_waitcnt lgkmcnt(0)
	s_lshl_b32 s2, s2, 2
	s_lshl_b32 s20, s90, 2
	s_add_u32 s3, s3, s20
	s_add_i32 s20, s2, -1
	s_and_b32 s21, s20, s2
	s_and_b32 s20, s20, 0x8000
	s_or_b32 s39, s20, s21
	s_mov_b32 s41, 0
	s_mov_b32 s43, 0
	s_cmp_ge_u32 s3, 0x8000
	s_cbranch_scc1 .Lp11_done
	v_lshlrev_b32_e32 v229, 2, v208
	global_load_dwordx4 v[96:99], v229, s[18:19]
	global_load_dwordx4 v[100:103], v229, s[18:19] offset:16
	global_load_dwordx4 v[104:107], v229, s[18:19] offset:32
	global_load_dwordx4 v[108:111], v229, s[18:19] offset:48
	s_mov_b32 s48, s43
	s_mov_b32 s40, s3
	s_cmp_lt_u32 s40, 0x8000
	s_cselect_b32 s40, s40, s3
	s_nop 0
	s_lshl_b32 s20, s40, 9
	v_add_u32_e32 v224, s20, v209
	s_mul_i32 s21, s40, 0x880
	v_add_u32_e32 v225, s21, v211
	global_load_dword v112, v224, s[8:9]
	global_load_dword v113, v224, s[8:9] offset:256
	global_load_dword v114, v224, s[10:11]
	global_load_dword v115, v224, s[10:11] offset:256
	global_load_dwordx4 v[144:147], v225, s[6:7]
	global_load_dwordx4 v[148:151], v225, s[6:7] offset:16
	s_mov_b32 s48, s43
	s_mov_b32 s40, s3
	s_add_u32 s40, s40, s2
	s_add_u32 s40, s40, s2
	s_cmp_lt_u32 s40, 0x8000
	s_cselect_b32 s40, s40, s3
	s_nop 0
	s_lshl_b32 s20, s40, 9
	v_add_u32_e32 v224, s20, v209
	s_mul_i32 s21, s40, 0x880
	v_add_u32_e32 v225, s21, v211
	global_load_dword v120, v224, s[8:9]
	global_load_dword v121, v224, s[8:9] offset:256
	global_load_dword v122, v224, s[10:11]
	global_load_dword v123, v224, s[10:11] offset:256
	global_load_dwordx4 v[152:155], v225, s[6:7]
	global_load_dwordx4 v[156:159], v225, s[6:7] offset:16
	s_waitcnt vmcnt(0)
	v_lshlrev_b32_e32 v64, 16, v144
	v_and_b32_e32 v65, 0xffff0000, v144
	v_lshlrev_b32_e32 v66, 16, v145
	v_and_b32_e32 v67, 0xffff0000, v145
	v_lshlrev_b32_e32 v68, 16, v146
	v_and_b32_e32 v69, 0xffff0000, v146
	v_lshlrev_b32_e32 v70, 16, v147
	v_and_b32_e32 v71, 0xffff0000, v147
	v_lshlrev_b32_e32 v72, 16, v148
	v_and_b32_e32 v73, 0xffff0000, v148
	v_lshlrev_b32_e32 v74, 16, v149
	v_and_b32_e32 v75, 0xffff0000, v149
	v_lshlrev_b32_e32 v76, 16, v150
	v_and_b32_e32 v77, 0xffff0000, v150
	v_lshlrev_b32_e32 v78, 16, v151
	v_and_b32_e32 v79, 0xffff0000, v151
	v_mul_f32_e32 v226, v64, v64
	v_fmac_f32_e32 v226, v65, v65
	v_fmac_f32_e32 v226, v66, v66
	v_fmac_f32_e32 v226, v67, v67
	v_fmac_f32_e32 v226, v68, v68
	v_fmac_f32_e32 v226, v69, v69
	v_fmac_f32_e32 v226, v70, v70
	v_fmac_f32_e32 v226, v71, v71
	v_fmac_f32_e32 v226, v72, v72
	v_fmac_f32_e32 v226, v73, v73
	v_fmac_f32_e32 v226, v74, v74
	v_fmac_f32_e32 v226, v75, v75
	v_fmac_f32_e32 v226, v76, v76
	v_fmac_f32_e32 v226, v77, v77
	v_fmac_f32_e32 v226, v78, v78
	v_fmac_f32_e32 v226, v79, v79
	s_nop 1
	v_add_f32_dpp v227, v226, v226 quad_perm:[1,0,3,2] row_mask:0xf bank_mask:0xf
	v_mov_b32_e32 v226, v227
	s_nop 1
	v_add_f32_dpp v227, v226, v226 quad_perm:[2,3,0,1] row_mask:0xf bank_mask:0xf
	v_mov_b32_e32 v226, v227
	s_nop 1
	v_add_f32_dpp v227, v226, v226 row_half_mirror row_mask:0xf bank_mask:0xf
	v_mov_b32_e32 v226, v227
	s_nop 1
	v_add_f32_dpp v227, v226, v226 row_mirror row_mask:0xf bank_mask:0xf
	v_mov_b32_e32 v226, v227
	s_nop 0
	v_readlane_b32 s44, v226, 0
	v_readlane_b32 s45, v226, 16
	v_readlane_b32 s46, v226, 32
	v_readlane_b32 s47, v226, 48
	s_nop 1
	v_mov_b32_e32 v226, s44
	v_add_f32_e32 v226, s45, v226
	v_add_f32_e32 v226, s46, v226
	v_add_f32_e32 v226, s47, v226
	v_mov_b32_e32 v228, 0x358637bd
	v_fmamk_f32 v226, v226, 0x3a800000, v228
	v_rsq_f32_e32 v226, v226
	s_nop 0
	v_mul_f32_e32 v64, v226, v64
	v_mul_f32_e32 v64, v96, v64
	v_mul_f32_e32 v65, v226, v65
	v_mul_f32_e32 v65, v97, v65
	v_mul_f32_e32 v66, v226, v66
	v_mul_f32_e32 v66, v98, v66
	v_mul_f32_e32 v67, v226, v67
	v_mul_f32_e32 v67, v99, v67
	v_mul_f32_e32 v68, v226, v68
	v_mul_f32_e32 v68, v100, v68
	v_mul_f32_e32 v69, v226, v69
	v_mul_f32_e32 v69, v101, v69
	v_mul_f32_e32 v70, v226, v70
	v_mul_f32_e32 v70, v102, v70
	v_mul_f32_e32 v71, v226, v71
	v_mul_f32_e32 v71, v103, v71
	v_mul_f32_e32 v72, v226, v72
	v_mul_f32_e32 v72, v104, v72
	v_mul_f32_e32 v73, v226, v73
	v_mul_f32_e32 v73, v105, v73
	v_mul_f32_e32 v74, v226, v74
	v_mul_f32_e32 v74, v106, v74
	v_mul_f32_e32 v75, v226, v75
	v_mul_f32_e32 v75, v107, v75
	v_mul_f32_e32 v76, v226, v76
	v_mul_f32_e32 v76, v108, v76
	v_mul_f32_e32 v77, v226, v77
	v_mul_f32_e32 v77, v109, v77
; template <int PART>
; DEVI void phase_peer_gather(const Params& p, unsigned char* smem) {
;     ...
;     const float rstd = rsqrtf(ss * (1.f / D) + 1e-6f);
;     {
;       const float4* g4 = (const float4*)p.peer_g + lane * 4;
;       const float4 a0 = g4[0], a1 = g4[1], a2 = g4[2], a3 = g4[3];
;       const float gg[16] = {a0.x, a0.y, a0.z, a0.w, a1.x, a1.y, a1.z, a1.w, a2.x, a2.y, a2.z, a2.w, a3.x, a3.y, a3.z, a3.w};
; #pragma unroll
;       for (int i = 0; i < 16; ++i) { xn[i] = hv[i] * rstd * gg[i]; y[i] = 0.f; }
;     }
;     int e0 = p.experts[(size_t)tok * 128 + lane], e1 = p.experts[(size_t)tok * 128 + 64 + lane];
;     float g0 = p.gates[(size_t)tok * 128 + lane], g1 = p.gates[(size_t)tok * 128 + 64 + lane];
;     if (PART == 0) {
;       int* sE = (int*)(smem + (tid >> 6) * 1024);
;       float* sG = (float*)(sE + 128);
;       int pos0 = 0, pos1 = 0, base = 0;
;       const int flip_ = (((tok - (blockIdx.x * 4 + w0_)) / (int)(gridDim.x * 4)) & 1) ? 15 : 0;
;       const int q0_ = (e0 >> 10) ^ flip_, q1_ = (e1 >> 10) ^ flip_;
; #pragma unroll
;       for (int q = 0; q < 16; ++q) {
;         const unsigned long long m0 = __ballot(q0_ == q), m1 = __ballot(q1_ == q);
;         const int c0 = __popcll(m0);
;         const int i0 = __builtin_amdgcn_mbcnt_hi((unsigned)(m0 >> 32), __builtin_amdgcn_mbcnt_lo((unsigned)m0, 0u));
;         const int i1 = __builtin_amdgcn_mbcnt_hi((unsigned)(m1 >> 32), __builtin_amdgcn_mbcnt_lo((unsigned)m1, 0u));
;         if (q0_ == q) pos0 = base + i0;
;         if (q1_ == q) pos1 = base + c0 + i1;
;         base += c0 + __popcll(m1);
;       }
	v_mul_f32_e32 v78, v226, v78
	v_mul_f32_e32 v78, v110, v78
	v_mul_f32_e32 v79, v226, v79
	v_mul_f32_e32 v79, v111, v79
	v_lshlrev_b32_e32 v80, 16, v152
	v_and_b32_e32 v81, 0xffff0000, v152
	v_lshlrev_b32_e32 v82, 16, v153
	v_and_b32_e32 v83, 0xffff0000, v153
	v_lshlrev_b32_e32 v84, 16, v154
	v_and_b32_e32 v85, 0xffff0000, v154
	v_lshlrev_b32_e32 v86, 16, v155
	v_and_b32_e32 v87, 0xffff0000, v155
	v_lshlrev_b32_e32 v88, 16, v156
	v_and_b32_e32 v89, 0xffff0000, v156
	v_lshlrev_b32_e32 v90, 16, v157
	v_and_b32_e32 v91, 0xffff0000, v157
	v_lshlrev_b32_e32 v92, 16, v158
	v_and_b32_e32 v93, 0xffff0000, v158
	v_lshlrev_b32_e32 v94, 16, v159
	v_and_b32_e32 v95, 0xffff0000, v159
	v_mul_f32_e32 v226, v80, v80
	v_fmac_f32_e32 v226, v81, v81
	v_fmac_f32_e32 v226, v82, v82
	v_fmac_f32_e32 v226, v83, v83
	v_fmac_f32_e32 v226, v84, v84
	v_fmac_f32_e32 v226, v85, v85
	v_fmac_f32_e32 v226, v86, v86
	v_fmac_f32_e32 v226, v87, v87
	v_fmac_f32_e32 v226, v88, v88
	v_fmac_f32_e32 v226, v89, v89
	v_fmac_f32_e32 v226, v90, v90
	v_fmac_f32_e32 v226, v91, v91
	v_fmac_f32_e32 v226, v92, v92
	v_fmac_f32_e32 v226, v93, v93
	v_fmac_f32_e32 v226, v94, v94
	v_fmac_f32_e32 v226, v95, v95
	s_nop 1
	v_add_f32_dpp v227, v226, v226 quad_perm:[1,0,3,2] row_mask:0xf bank_mask:0xf
	v_mov_b32_e32 v226, v227
	s_nop 1
	v_add_f32_dpp v227, v226, v226 quad_perm:[2,3,0,1] row_mask:0xf bank_mask:0xf
	v_mov_b32_e32 v226, v227
	s_nop 1
	v_add_f32_dpp v227, v226, v226 row_half_mirror row_mask:0xf bank_mask:0xf
	v_mov_b32_e32 v226, v227
	s_nop 1
	v_add_f32_dpp v227, v226, v226 row_mirror row_mask:0xf bank_mask:0xf
	v_mov_b32_e32 v226, v227
	s_nop 0
	v_readlane_b32 s44, v226, 0
	v_readlane_b32 s45, v226, 16
	v_readlane_b32 s46, v226, 32
	v_readlane_b32 s47, v226, 48
	s_nop 1
	v_mov_b32_e32 v226, s44
	v_add_f32_e32 v226, s45, v226
	v_add_f32_e32 v226, s46, v226
	v_add_f32_e32 v226, s47, v226
	v_mov_b32_e32 v228, 0x358637bd
	v_fmamk_f32 v226, v226, 0x3a800000, v228
	v_rsq_f32_e32 v226, v226
	s_nop 0
	v_mul_f32_e32 v80, v226, v80
	v_mul_f32_e32 v80, v96, v80
	v_mul_f32_e32 v81, v226, v81
	v_mul_f32_e32 v81, v97, v81
	v_mul_f32_e32 v82, v226, v82
	v_mul_f32_e32 v82, v98, v82
	v_mul_f32_e32 v83, v226, v83
	v_mul_f32_e32 v83, v99, v83
	v_mul_f32_e32 v84, v226, v84
	v_mul_f32_e32 v84, v100, v84
	v_mul_f32_e32 v85, v226, v85
	v_mul_f32_e32 v85, v101, v85
	v_mul_f32_e32 v86, v226, v86
	v_mul_f32_e32 v86, v102, v86
	v_mul_f32_e32 v87, v226, v87
	v_mul_f32_e32 v87, v103, v87
	v_mul_f32_e32 v88, v226, v88
	v_mul_f32_e32 v88, v104, v88
	v_mul_f32_e32 v89, v226, v89
	v_mul_f32_e32 v89, v105, v89
	v_mul_f32_e32 v90, v226, v90
	v_mul_f32_e32 v90, v106, v90
	v_mul_f32_e32 v91, v226, v91
	v_mul_f32_e32 v91, v107, v91
	v_mul_f32_e32 v92, v226, v92
	v_mul_f32_e32 v92, v108, v92
	v_mul_f32_e32 v93, v226, v93
	v_mul_f32_e32 v93, v109, v93
	v_mul_f32_e32 v94, v226, v94
	v_mul_f32_e32 v94, v110, v94
	v_mul_f32_e32 v95, v226, v95
	v_mul_f32_e32 v95, v111, v95
	s_mov_b32 s48, s43
	s_mov_b32 s40, s3
	s_cmp_lt_u32 s40, 0x8000
	s_cselect_b32 s40, s40, s3
	s_nop 0
	v_lshrrev_b32_e32 v226, 10, v112
	v_lshrrev_b32_e32 v227, 10, v113
	v_xor_b32_e32 v226, s48, v226
	v_xor_b32_e32 v227, s48, v227
	s_mov_b32 s38, 0
	v_cmp_eq_u32_e64 s[32:33], 0, v226
	v_cmp_eq_u32_e64 s[34:35], 0, v227
	s_bcnt1_i32_b64 s36, s[32:33]
	s_bcnt1_i32_b64 s37, s[34:35]
	s_add_u32 s36, s36, s38
	v_mbcnt_lo_u32_b32 v228, s32, 0
	v_mbcnt_hi_u32_b32 v228, s33, v228
	v_mbcnt_lo_u32_b32 v229, s34, 0
	v_mbcnt_hi_u32_b32 v229, s35, v229
	v_add_u32_e32 v228, s38, v228
	v_add_u32_e32 v229, s36, v229
	v_cndmask_b32_e64 v232, v232, v228, s[32:33]
	v_cndmask_b32_e64 v233, v233, v229, s[34:35]
	s_add_u32 s38, s36, s37
	v_cmp_eq_u32_e64 s[32:33], 1, v226
	v_cmp_eq_u32_e64 s[34:35], 1, v227
	s_bcnt1_i32_b64 s36, s[32:33]
	s_bcnt1_i32_b64 s37, s[34:35]
	s_add_u32 s36, s36, s38
	v_mbcnt_lo_u32_b32 v228, s32, 0
	v_mbcnt_hi_u32_b32 v228, s33, v228
	v_mbcnt_lo_u32_b32 v229, s34, 0
	v_mbcnt_hi_u32_b32 v229, s35, v229
	v_add_u32_e32 v228, s38, v228
	v_add_u32_e32 v229, s36, v229
	v_cndmask_b32_e64 v232, v232, v228, s[32:33]
	v_cndmask_b32_e64 v233, v233, v229, s[34:35]
	s_add_u32 s38, s36, s37
	v_cmp_eq_u32_e64 s[32:33], 2, v226
	v_cmp_eq_u32_e64 s[34:35], 2, v227
	s_bcnt1_i32_b64 s36, s[32:33]
	s_bcnt1_i32_b64 s37, s[34:35]
	s_add_u32 s36, s36, s38
	v_mbcnt_lo_u32_b32 v228, s32, 0
	v_mbcnt_hi_u32_b32 v228, s33, v228
	v_mbcnt_lo_u32_b32 v229, s34, 0
	v_mbcnt_hi_u32_b32 v229, s35, v229
	v_add_u32_e32 v228, s38, v228
	v_add_u32_e32 v229, s36, v229
	v_cndmask_b32_e64 v232, v232, v228, s[32:33]
	v_cndmask_b32_e64 v233, v233, v229, s[34:35]
	s_add_u32 s38, s36, s37
	v_cmp_eq_u32_e64 s[32:33], 3, v226
	v_cmp_eq_u32_e64 s[34:35], 3, v227
	s_bcnt1_i32_b64 s36, s[32:33]
	s_bcnt1_i32_b64 s37, s[34:35]
	s_add_u32 s36, s36, s38
	v_mbcnt_lo_u32_b32 v228, s32, 0
	v_mbcnt_hi_u32_b32 v228, s33, v228
	v_mbcnt_lo_u32_b32 v229, s34, 0
	v_mbcnt_hi_u32_b32 v229, s35, v229
	v_add_u32_e32 v228, s38, v228
	v_add_u32_e32 v229, s36, v229
	v_cndmask_b32_e64 v232, v232, v228, s[32:33]
	v_cndmask_b32_e64 v233, v233, v229, s[34:35]
	s_add_u32 s38, s36, s37
	v_cmp_eq_u32_e64 s[32:33], 4, v226
	v_cmp_eq_u32_e64 s[34:35], 4, v227
	s_bcnt1_i32_b64 s36, s[32:33]
	s_bcnt1_i32_b64 s37, s[34:35]
	s_add_u32 s36, s36, s38
	v_mbcnt_lo_u32_b32 v228, s32, 0
	v_mbcnt_hi_u32_b32 v228, s33, v228
	v_mbcnt_lo_u32_b32 v229, s34, 0
	v_mbcnt_hi_u32_b32 v229, s35, v229
	v_add_u32_e32 v228, s38, v228
	v_add_u32_e32 v229, s36, v229
	v_cndmask_b32_e64 v232, v232, v228, s[32:33]
	v_cndmask_b32_e64 v233, v233, v229, s[34:35]
	s_add_u32 s38, s36, s37
	v_cmp_eq_u32_e64 s[32:33], 5, v226
	v_cmp_eq_u32_e64 s[34:35], 5, v227
; template <int PART>
; DEVI void phase_peer_gather(const Params& p, unsigned char* smem) {
;     ...
; #pragma unroll
;       for (int q = 0; q < 16; ++q) {
;         const unsigned long long m0 = __ballot(q0_ == q), m1 = __ballot(q1_ == q);
;         const int c0 = __popcll(m0);
;         const int i0 = __builtin_amdgcn_mbcnt_hi((unsigned)(m0 >> 32), __builtin_amdgcn_mbcnt_lo((unsigned)m0, 0u));
;         const int i1 = __builtin_amdgcn_mbcnt_hi((unsigned)(m1 >> 32), __builtin_amdgcn_mbcnt_lo((unsigned)m1, 0u));
;         if (q0_ == q) pos0 = base + i0;
;         if (q1_ == q) pos1 = base + c0 + i1;
;         base += c0 + __popcll(m1);
;       }
;       __builtin_amdgcn_fence(__ATOMIC_RELEASE, "wavefront");
;       __builtin_amdgcn_wave_barrier();
;       sE[pos0] = e0; sG[pos0] = g0;
;       sE[pos1] = e1; sG[pos1] = g1;
;       __builtin_amdgcn_fence(__ATOMIC_RELEASE, "wavefront");
;       __builtin_amdgcn_wave_barrier();
;       __builtin_amdgcn_fence(__ATOMIC_ACQUIRE, "wavefront");
;       e0 = sE[lane]; e1 = sE[64 + lane];
;       g0 = sG[lane]; g1 = sG[64 + lane];
	s_bcnt1_i32_b64 s36, s[32:33]
	s_bcnt1_i32_b64 s37, s[34:35]
	s_add_u32 s36, s36, s38
	v_mbcnt_lo_u32_b32 v228, s32, 0
	v_mbcnt_hi_u32_b32 v228, s33, v228
	v_mbcnt_lo_u32_b32 v229, s34, 0
	v_mbcnt_hi_u32_b32 v229, s35, v229
	v_add_u32_e32 v228, s38, v228
	v_add_u32_e32 v229, s36, v229
	v_cndmask_b32_e64 v232, v232, v228, s[32:33]
	v_cndmask_b32_e64 v233, v233, v229, s[34:35]
	s_add_u32 s38, s36, s37
	v_cmp_eq_u32_e64 s[32:33], 6, v226
	v_cmp_eq_u32_e64 s[34:35], 6, v227
	s_bcnt1_i32_b64 s36, s[32:33]
	s_bcnt1_i32_b64 s37, s[34:35]
	s_add_u32 s36, s36, s38
	v_mbcnt_lo_u32_b32 v228, s32, 0
	v_mbcnt_hi_u32_b32 v228, s33, v228
	v_mbcnt_lo_u32_b32 v229, s34, 0
	v_mbcnt_hi_u32_b32 v229, s35, v229
	v_add_u32_e32 v228, s38, v228
	v_add_u32_e32 v229, s36, v229
	v_cndmask_b32_e64 v232, v232, v228, s[32:33]
	v_cndmask_b32_e64 v233, v233, v229, s[34:35]
	s_add_u32 s38, s36, s37
	v_cmp_eq_u32_e64 s[32:33], 7, v226
	v_cmp_eq_u32_e64 s[34:35], 7, v227
	s_bcnt1_i32_b64 s36, s[32:33]
	s_bcnt1_i32_b64 s37, s[34:35]
	s_add_u32 s36, s36, s38
	v_mbcnt_lo_u32_b32 v228, s32, 0
	v_mbcnt_hi_u32_b32 v228, s33, v228
	v_mbcnt_lo_u32_b32 v229, s34, 0
	v_mbcnt_hi_u32_b32 v229, s35, v229
	v_add_u32_e32 v228, s38, v228
	v_add_u32_e32 v229, s36, v229
	v_cndmask_b32_e64 v232, v232, v228, s[32:33]
	v_cndmask_b32_e64 v233, v233, v229, s[34:35]
	s_add_u32 s38, s36, s37
	v_cmp_eq_u32_e64 s[32:33], 8, v226
	v_cmp_eq_u32_e64 s[34:35], 8, v227
	s_bcnt1_i32_b64 s36, s[32:33]
	s_bcnt1_i32_b64 s37, s[34:35]
	s_add_u32 s36, s36, s38
	v_mbcnt_lo_u32_b32 v228, s32, 0
	v_mbcnt_hi_u32_b32 v228, s33, v228
	v_mbcnt_lo_u32_b32 v229, s34, 0
	v_mbcnt_hi_u32_b32 v229, s35, v229
	v_add_u32_e32 v228, s38, v228
	v_add_u32_e32 v229, s36, v229
	v_cndmask_b32_e64 v232, v232, v228, s[32:33]
	v_cndmask_b32_e64 v233, v233, v229, s[34:35]
	s_add_u32 s38, s36, s37
	v_cmp_eq_u32_e64 s[32:33], 9, v226
	v_cmp_eq_u32_e64 s[34:35], 9, v227
	s_bcnt1_i32_b64 s36, s[32:33]
	s_bcnt1_i32_b64 s37, s[34:35]
	s_add_u32 s36, s36, s38
	v_mbcnt_lo_u32_b32 v228, s32, 0
	v_mbcnt_hi_u32_b32 v228, s33, v228
	v_mbcnt_lo_u32_b32 v229, s34, 0
	v_mbcnt_hi_u32_b32 v229, s35, v229
	v_add_u32_e32 v228, s38, v228
	v_add_u32_e32 v229, s36, v229
	v_cndmask_b32_e64 v232, v232, v228, s[32:33]
	v_cndmask_b32_e64 v233, v233, v229, s[34:35]
	s_add_u32 s38, s36, s37
	v_cmp_eq_u32_e64 s[32:33], 10, v226
	v_cmp_eq_u32_e64 s[34:35], 10, v227
	s_bcnt1_i32_b64 s36, s[32:33]
	s_bcnt1_i32_b64 s37, s[34:35]
	s_add_u32 s36, s36, s38
	v_mbcnt_lo_u32_b32 v228, s32, 0
	v_mbcnt_hi_u32_b32 v228, s33, v228
	v_mbcnt_lo_u32_b32 v229, s34, 0
	v_mbcnt_hi_u32_b32 v229, s35, v229
	v_add_u32_e32 v228, s38, v228
	v_add_u32_e32 v229, s36, v229
	v_cndmask_b32_e64 v232, v232, v228, s[32:33]
	v_cndmask_b32_e64 v233, v233, v229, s[34:35]
	s_add_u32 s38, s36, s37
	v_cmp_eq_u32_e64 s[32:33], 11, v226
	v_cmp_eq_u32_e64 s[34:35], 11, v227
	s_bcnt1_i32_b64 s36, s[32:33]
	s_bcnt1_i32_b64 s37, s[34:35]
	s_add_u32 s36, s36, s38
	v_mbcnt_lo_u32_b32 v228, s32, 0
	v_mbcnt_hi_u32_b32 v228, s33, v228
	v_mbcnt_lo_u32_b32 v229, s34, 0
	v_mbcnt_hi_u32_b32 v229, s35, v229
	v_add_u32_e32 v228, s38, v228
	v_add_u32_e32 v229, s36, v229
	v_cndmask_b32_e64 v232, v232, v228, s[32:33]
	v_cndmask_b32_e64 v233, v233, v229, s[34:35]
	s_add_u32 s38, s36, s37
	v_cmp_eq_u32_e64 s[32:33], 12, v226
	v_cmp_eq_u32_e64 s[34:35], 12, v227
	s_bcnt1_i32_b64 s36, s[32:33]
	s_bcnt1_i32_b64 s37, s[34:35]
	s_add_u32 s36, s36, s38
	v_mbcnt_lo_u32_b32 v228, s32, 0
	v_mbcnt_hi_u32_b32 v228, s33, v228
	v_mbcnt_lo_u32_b32 v229, s34, 0
	v_mbcnt_hi_u32_b32 v229, s35, v229
	v_add_u32_e32 v228, s38, v228
	v_add_u32_e32 v229, s36, v229
	v_cndmask_b32_e64 v232, v232, v228, s[32:33]
	v_cndmask_b32_e64 v233, v233, v229, s[34:35]
	s_add_u32 s38, s36, s37
	v_cmp_eq_u32_e64 s[32:33], 13, v226
	v_cmp_eq_u32_e64 s[34:35], 13, v227
	s_bcnt1_i32_b64 s36, s[32:33]
	s_bcnt1_i32_b64 s37, s[34:35]
	s_add_u32 s36, s36, s38
	v_mbcnt_lo_u32_b32 v228, s32, 0
	v_mbcnt_hi_u32_b32 v228, s33, v228
	v_mbcnt_lo_u32_b32 v229, s34, 0
	v_mbcnt_hi_u32_b32 v229, s35, v229
	v_add_u32_e32 v228, s38, v228
	v_add_u32_e32 v229, s36, v229
	v_cndmask_b32_e64 v232, v232, v228, s[32:33]
	v_cndmask_b32_e64 v233, v233, v229, s[34:35]
	s_add_u32 s38, s36, s37
	v_cmp_eq_u32_e64 s[32:33], 14, v226
	v_cmp_eq_u32_e64 s[34:35], 14, v227
	s_bcnt1_i32_b64 s36, s[32:33]
	s_bcnt1_i32_b64 s37, s[34:35]
	s_add_u32 s36, s36, s38
	v_mbcnt_lo_u32_b32 v228, s32, 0
	v_mbcnt_hi_u32_b32 v228, s33, v228
	v_mbcnt_lo_u32_b32 v229, s34, 0
	v_mbcnt_hi_u32_b32 v229, s35, v229
	v_add_u32_e32 v228, s38, v228
	v_add_u32_e32 v229, s36, v229
	v_cndmask_b32_e64 v232, v232, v228, s[32:33]
	v_cndmask_b32_e64 v233, v233, v229, s[34:35]
	s_add_u32 s38, s36, s37
	v_cmp_eq_u32_e64 s[32:33], 15, v226
	v_cmp_eq_u32_e64 s[34:35], 15, v227
	s_bcnt1_i32_b64 s36, s[32:33]
	s_bcnt1_i32_b64 s37, s[34:35]
	s_add_u32 s36, s36, s38
	v_mbcnt_lo_u32_b32 v228, s32, 0
	v_mbcnt_hi_u32_b32 v228, s33, v228
	v_mbcnt_lo_u32_b32 v229, s34, 0
	v_mbcnt_hi_u32_b32 v229, s35, v229
	v_add_u32_e32 v228, s38, v228
	v_add_u32_e32 v229, s36, v229
	v_cndmask_b32_e64 v232, v232, v228, s[32:33]
	v_cndmask_b32_e64 v233, v233, v229, s[34:35]
	s_add_u32 s38, s36, s37
	v_lshl_add_u32 v232, v232, 2, v215
	v_lshl_add_u32 v233, v233, 2, v215
	ds_write_b32 v232, v112
	ds_write_b32 v232, v114 offset:512
	ds_write_b32 v233, v113
	ds_write_b32 v233, v115 offset:512
	v_add_u32_e32 v228, v209, v215
	s_waitcnt lgkmcnt(0)
	ds_read_b32 v112, v228
	ds_read_b32 v113, v228 offset:256
	ds_read_b32 v114, v228 offset:512
	ds_read_b32 v115, v228 offset:768
	s_waitcnt lgkmcnt(0)
; template <int PART>
; DEVI void phase_peer_gather(const Params& p, unsigned char* smem) {
;     ...
;       int pos0 = 0, pos1 = 0, base = 0;
;       const int flip_ = (((tok - (blockIdx.x * 4 + w0_)) / (int)(gridDim.x * 4)) & 1) ? 15 : 0;
;       const int q0_ = (e0 >> 10) ^ flip_, q1_ = (e1 >> 10) ^ flip_;
; #pragma unroll
;       for (int q = 0; q < 16; ++q) {
;         const unsigned long long m0 = __ballot(q0_ == q), m1 = __ballot(q1_ == q);
;         const int c0 = __popcll(m0);
;         const int i0 = __builtin_amdgcn_mbcnt_hi((unsigned)(m0 >> 32), __builtin_amdgcn_mbcnt_lo((unsigned)m0, 0u));
;         const int i1 = __builtin_amdgcn_mbcnt_hi((unsigned)(m1 >> 32), __builtin_amdgcn_mbcnt_lo((unsigned)m1, 0u));
;         if (q0_ == q) pos0 = base + i0;
;         if (q1_ == q) pos1 = base + c0 + i1;
;         base += c0 + __popcll(m1);
;       }
;     ...
;       p.experts[(size_t)tok * 128 + lane] = e0;
;       p.experts[(size_t)tok * 128 + 64 + lane] = e1;
;     }
;     const float su0 = p.uscale[e0], su1 = p.uscale[e1];
;     const float sv0 = p.vscale[e0], sv1 = p.vscale[e1];
	s_lshl_b32 s20, s40, 9
	v_add_u32_e32 v224, s20, v209
	global_store_dword v224, v112, s[8:9]
	global_store_dword v224, v113, s[8:9] offset:256
	v_lshlrev_b32_e32 v228, 2, v112
	v_lshlrev_b32_e32 v229, 2, v113
	global_load_dword v116, v228, s[14:15]
	global_load_dword v117, v229, s[14:15]
	global_load_dword v118, v228, s[16:17]
	global_load_dword v119, v229, s[16:17]
	s_mov_b32 s48, s43
	s_mov_b32 s40, s3
	s_add_u32 s40, s40, s2
	s_add_u32 s40, s40, s2
	s_cmp_lt_u32 s40, 0x8000
	s_cselect_b32 s40, s40, s3
	s_nop 0
	v_lshrrev_b32_e32 v226, 10, v120
	v_lshrrev_b32_e32 v227, 10, v121
	v_xor_b32_e32 v226, s48, v226
	v_xor_b32_e32 v227, s48, v227
	s_mov_b32 s38, 0
	v_cmp_eq_u32_e64 s[32:33], 0, v226
	v_cmp_eq_u32_e64 s[34:35], 0, v227
	s_bcnt1_i32_b64 s36, s[32:33]
	s_bcnt1_i32_b64 s37, s[34:35]
	s_add_u32 s36, s36, s38
	v_mbcnt_lo_u32_b32 v228, s32, 0
	v_mbcnt_hi_u32_b32 v228, s33, v228
	v_mbcnt_lo_u32_b32 v229, s34, 0
	v_mbcnt_hi_u32_b32 v229, s35, v229
	v_add_u32_e32 v228, s38, v228
	v_add_u32_e32 v229, s36, v229
	v_cndmask_b32_e64 v232, v232, v228, s[32:33]
	v_cndmask_b32_e64 v233, v233, v229, s[34:35]
	s_add_u32 s38, s36, s37
	v_cmp_eq_u32_e64 s[32:33], 1, v226
	v_cmp_eq_u32_e64 s[34:35], 1, v227
	s_bcnt1_i32_b64 s36, s[32:33]
	s_bcnt1_i32_b64 s37, s[34:35]
	s_add_u32 s36, s36, s38
	v_mbcnt_lo_u32_b32 v228, s32, 0
	v_mbcnt_hi_u32_b32 v228, s33, v228
	v_mbcnt_lo_u32_b32 v229, s34, 0
	v_mbcnt_hi_u32_b32 v229, s35, v229
	v_add_u32_e32 v228, s38, v228
	v_add_u32_e32 v229, s36, v229
	v_cndmask_b32_e64 v232, v232, v228, s[32:33]
	v_cndmask_b32_e64 v233, v233, v229, s[34:35]
	s_add_u32 s38, s36, s37
	v_cmp_eq_u32_e64 s[32:33], 2, v226
	v_cmp_eq_u32_e64 s[34:35], 2, v227
	s_bcnt1_i32_b64 s36, s[32:33]
	s_bcnt1_i32_b64 s37, s[34:35]
	s_add_u32 s36, s36, s38
	v_mbcnt_lo_u32_b32 v228, s32, 0
	v_mbcnt_hi_u32_b32 v228, s33, v228
	v_mbcnt_lo_u32_b32 v229, s34, 0
	v_mbcnt_hi_u32_b32 v229, s35, v229
	v_add_u32_e32 v228, s38, v228
	v_add_u32_e32 v229, s36, v229
	v_cndmask_b32_e64 v232, v232, v228, s[32:33]
	v_cndmask_b32_e64 v233, v233, v229, s[34:35]
	s_add_u32 s38, s36, s37
	v_cmp_eq_u32_e64 s[32:33], 3, v226
	v_cmp_eq_u32_e64 s[34:35], 3, v227
	s_bcnt1_i32_b64 s36, s[32:33]
	s_bcnt1_i32_b64 s37, s[34:35]
	s_add_u32 s36, s36, s38
	v_mbcnt_lo_u32_b32 v228, s32, 0
	v_mbcnt_hi_u32_b32 v228, s33, v228
	v_mbcnt_lo_u32_b32 v229, s34, 0
	v_mbcnt_hi_u32_b32 v229, s35, v229
	v_add_u32_e32 v228, s38, v228
	v_add_u32_e32 v229, s36, v229
	v_cndmask_b32_e64 v232, v232, v228, s[32:33]
	v_cndmask_b32_e64 v233, v233, v229, s[34:35]
	s_add_u32 s38, s36, s37
	v_cmp_eq_u32_e64 s[32:33], 4, v226
	v_cmp_eq_u32_e64 s[34:35], 4, v227
	s_bcnt1_i32_b64 s36, s[32:33]
	s_bcnt1_i32_b64 s37, s[34:35]
	s_add_u32 s36, s36, s38
	v_mbcnt_lo_u32_b32 v228, s32, 0
	v_mbcnt_hi_u32_b32 v228, s33, v228
	v_mbcnt_lo_u32_b32 v229, s34, 0
	v_mbcnt_hi_u32_b32 v229, s35, v229
	v_add_u32_e32 v228, s38, v228
	v_add_u32_e32 v229, s36, v229
	v_cndmask_b32_e64 v232, v232, v228, s[32:33]
	v_cndmask_b32_e64 v233, v233, v229, s[34:35]
	s_add_u32 s38, s36, s37
	v_cmp_eq_u32_e64 s[32:33], 5, v226
	v_cmp_eq_u32_e64 s[34:35], 5, v227
	s_bcnt1_i32_b64 s36, s[32:33]
	s_bcnt1_i32_b64 s37, s[34:35]
	s_add_u32 s36, s36, s38
	v_mbcnt_lo_u32_b32 v228, s32, 0
	v_mbcnt_hi_u32_b32 v228, s33, v228
	v_mbcnt_lo_u32_b32 v229, s34, 0
	v_mbcnt_hi_u32_b32 v229, s35, v229
	v_add_u32_e32 v228, s38, v228
	v_add_u32_e32 v229, s36, v229
	v_cndmask_b32_e64 v232, v232, v228, s[32:33]
	v_cndmask_b32_e64 v233, v233, v229, s[34:35]
	s_add_u32 s38, s36, s37
	v_cmp_eq_u32_e64 s[32:33], 6, v226
	v_cmp_eq_u32_e64 s[34:35], 6, v227
	s_bcnt1_i32_b64 s36, s[32:33]
	s_bcnt1_i32_b64 s37, s[34:35]
	s_add_u32 s36, s36, s38
	v_mbcnt_lo_u32_b32 v228, s32, 0
	v_mbcnt_hi_u32_b32 v228, s33, v228
	v_mbcnt_lo_u32_b32 v229, s34, 0
	v_mbcnt_hi_u32_b32 v229, s35, v229
	v_add_u32_e32 v228, s38, v228
	v_add_u32_e32 v229, s36, v229
	v_cndmask_b32_e64 v232, v232, v228, s[32:33]
	v_cndmask_b32_e64 v233, v233, v229, s[34:35]
	s_add_u32 s38, s36, s37
	v_cmp_eq_u32_e64 s[32:33], 7, v226
	v_cmp_eq_u32_e64 s[34:35], 7, v227
	s_bcnt1_i32_b64 s36, s[32:33]
	s_bcnt1_i32_b64 s37, s[34:35]
	s_add_u32 s36, s36, s38
	v_mbcnt_lo_u32_b32 v228, s32, 0
	v_mbcnt_hi_u32_b32 v228, s33, v228
	v_mbcnt_lo_u32_b32 v229, s34, 0
	v_mbcnt_hi_u32_b32 v229, s35, v229
	v_add_u32_e32 v228, s38, v228
	v_add_u32_e32 v229, s36, v229
	v_cndmask_b32_e64 v232, v232, v228, s[32:33]
	v_cndmask_b32_e64 v233, v233, v229, s[34:35]
	s_add_u32 s38, s36, s37
	v_cmp_eq_u32_e64 s[32:33], 8, v226
	v_cmp_eq_u32_e64 s[34:35], 8, v227
	s_bcnt1_i32_b64 s36, s[32:33]
	s_bcnt1_i32_b64 s37, s[34:35]
	s_add_u32 s36, s36, s38
	v_mbcnt_lo_u32_b32 v228, s32, 0
	v_mbcnt_hi_u32_b32 v228, s33, v228
	v_mbcnt_lo_u32_b32 v229, s34, 0
	v_mbcnt_hi_u32_b32 v229, s35, v229
	v_add_u32_e32 v228, s38, v228
	v_add_u32_e32 v229, s36, v229
	v_cndmask_b32_e64 v232, v232, v228, s[32:33]
	v_cndmask_b32_e64 v233, v233, v229, s[34:35]
	s_add_u32 s38, s36, s37
	v_cmp_eq_u32_e64 s[32:33], 9, v226
	v_cmp_eq_u32_e64 s[34:35], 9, v227
	s_bcnt1_i32_b64 s36, s[32:33]
	s_bcnt1_i32_b64 s37, s[34:35]
	s_add_u32 s36, s36, s38
	v_mbcnt_lo_u32_b32 v228, s32, 0
	v_mbcnt_hi_u32_b32 v228, s33, v228
	v_mbcnt_lo_u32_b32 v229, s34, 0
	v_mbcnt_hi_u32_b32 v229, s35, v229
	v_add_u32_e32 v228, s38, v228
	v_add_u32_e32 v229, s36, v229
	v_cndmask_b32_e64 v232, v232, v228, s[32:33]
	v_cndmask_b32_e64 v233, v233, v229, s[34:35]
	s_add_u32 s38, s36, s37
	v_cmp_eq_u32_e64 s[32:33], 10, v226
	v_cmp_eq_u32_e64 s[34:35], 10, v227
	s_bcnt1_i32_b64 s36, s[32:33]
	s_bcnt1_i32_b64 s37, s[34:35]
	s_add_u32 s36, s36, s38
	v_mbcnt_lo_u32_b32 v228, s32, 0
; template <int PART>
; DEVI void phase_peer_gather(const Params& p, unsigned char* smem) {
;     ...
; #pragma unroll
;       for (int q = 0; q < 16; ++q) {
;         const unsigned long long m0 = __ballot(q0_ == q), m1 = __ballot(q1_ == q);
;         const int c0 = __popcll(m0);
;         const int i0 = __builtin_amdgcn_mbcnt_hi((unsigned)(m0 >> 32), __builtin_amdgcn_mbcnt_lo((unsigned)m0, 0u));
;         const int i1 = __builtin_amdgcn_mbcnt_hi((unsigned)(m1 >> 32), __builtin_amdgcn_mbcnt_lo((unsigned)m1, 0u));
;         if (q0_ == q) pos0 = base + i0;
;         if (q1_ == q) pos1 = base + c0 + i1;
;         base += c0 + __popcll(m1);
;       }
;       __builtin_amdgcn_fence(__ATOMIC_RELEASE, "wavefront");
;       __builtin_amdgcn_wave_barrier();
;       sE[pos0] = e0; sG[pos0] = g0;
;       sE[pos1] = e1; sG[pos1] = g1;
;       __builtin_amdgcn_fence(__ATOMIC_RELEASE, "wavefront");
;       __builtin_amdgcn_wave_barrier();
;       __builtin_amdgcn_fence(__ATOMIC_ACQUIRE, "wavefront");
;       e0 = sE[lane]; e1 = sE[64 + lane];
;       g0 = sG[lane]; g1 = sG[64 + lane];
;       p.experts[(size_t)tok * 128 + lane] = e0;
;       p.experts[(size_t)tok * 128 + 64 + lane] = e1;
;     }
;     const float su0 = p.uscale[e0], su1 = p.uscale[e1];
;     const float sv0 = p.vscale[e0], sv1 = p.vscale[e1];
	v_mbcnt_hi_u32_b32 v228, s33, v228
	v_mbcnt_lo_u32_b32 v229, s34, 0
	v_mbcnt_hi_u32_b32 v229, s35, v229
	v_add_u32_e32 v228, s38, v228
	v_add_u32_e32 v229, s36, v229
	v_cndmask_b32_e64 v232, v232, v228, s[32:33]
	v_cndmask_b32_e64 v233, v233, v229, s[34:35]
	s_add_u32 s38, s36, s37
	v_cmp_eq_u32_e64 s[32:33], 11, v226
	v_cmp_eq_u32_e64 s[34:35], 11, v227
	s_bcnt1_i32_b64 s36, s[32:33]
	s_bcnt1_i32_b64 s37, s[34:35]
	s_add_u32 s36, s36, s38
	v_mbcnt_lo_u32_b32 v228, s32, 0
	v_mbcnt_hi_u32_b32 v228, s33, v228
	v_mbcnt_lo_u32_b32 v229, s34, 0
	v_mbcnt_hi_u32_b32 v229, s35, v229
	v_add_u32_e32 v228, s38, v228
	v_add_u32_e32 v229, s36, v229
	v_cndmask_b32_e64 v232, v232, v228, s[32:33]
	v_cndmask_b32_e64 v233, v233, v229, s[34:35]
	s_add_u32 s38, s36, s37
	v_cmp_eq_u32_e64 s[32:33], 12, v226
	v_cmp_eq_u32_e64 s[34:35], 12, v227
	s_bcnt1_i32_b64 s36, s[32:33]
	s_bcnt1_i32_b64 s37, s[34:35]
	s_add_u32 s36, s36, s38
	v_mbcnt_lo_u32_b32 v228, s32, 0
	v_mbcnt_hi_u32_b32 v228, s33, v228
	v_mbcnt_lo_u32_b32 v229, s34, 0
	v_mbcnt_hi_u32_b32 v229, s35, v229
	v_add_u32_e32 v228, s38, v228
	v_add_u32_e32 v229, s36, v229
	v_cndmask_b32_e64 v232, v232, v228, s[32:33]
	v_cndmask_b32_e64 v233, v233, v229, s[34:35]
	s_add_u32 s38, s36, s37
	v_cmp_eq_u32_e64 s[32:33], 13, v226
	v_cmp_eq_u32_e64 s[34:35], 13, v227
	s_bcnt1_i32_b64 s36, s[32:33]
	s_bcnt1_i32_b64 s37, s[34:35]
	s_add_u32 s36, s36, s38
	v_mbcnt_lo_u32_b32 v228, s32, 0
	v_mbcnt_hi_u32_b32 v228, s33, v228
	v_mbcnt_lo_u32_b32 v229, s34, 0
	v_mbcnt_hi_u32_b32 v229, s35, v229
	v_add_u32_e32 v228, s38, v228
	v_add_u32_e32 v229, s36, v229
	v_cndmask_b32_e64 v232, v232, v228, s[32:33]
	v_cndmask_b32_e64 v233, v233, v229, s[34:35]
	s_add_u32 s38, s36, s37
	v_cmp_eq_u32_e64 s[32:33], 14, v226
	v_cmp_eq_u32_e64 s[34:35], 14, v227
	s_bcnt1_i32_b64 s36, s[32:33]
	s_bcnt1_i32_b64 s37, s[34:35]
	s_add_u32 s36, s36, s38
	v_mbcnt_lo_u32_b32 v228, s32, 0
	v_mbcnt_hi_u32_b32 v228, s33, v228
	v_mbcnt_lo_u32_b32 v229, s34, 0
	v_mbcnt_hi_u32_b32 v229, s35, v229
	v_add_u32_e32 v228, s38, v228
	v_add_u32_e32 v229, s36, v229
	v_cndmask_b32_e64 v232, v232, v228, s[32:33]
	v_cndmask_b32_e64 v233, v233, v229, s[34:35]
	s_add_u32 s38, s36, s37
	v_cmp_eq_u32_e64 s[32:33], 15, v226
	v_cmp_eq_u32_e64 s[34:35], 15, v227
	s_bcnt1_i32_b64 s36, s[32:33]
	s_bcnt1_i32_b64 s37, s[34:35]
	s_add_u32 s36, s36, s38
	v_mbcnt_lo_u32_b32 v228, s32, 0
	v_mbcnt_hi_u32_b32 v228, s33, v228
	v_mbcnt_lo_u32_b32 v229, s34, 0
	v_mbcnt_hi_u32_b32 v229, s35, v229
	v_add_u32_e32 v228, s38, v228
	v_add_u32_e32 v229, s36, v229
	v_cndmask_b32_e64 v232, v232, v228, s[32:33]
	v_cndmask_b32_e64 v233, v233, v229, s[34:35]
	s_add_u32 s38, s36, s37
	v_lshl_add_u32 v232, v232, 2, v215
	v_lshl_add_u32 v233, v233, 2, v215
	ds_write_b32 v232, v120
	ds_write_b32 v232, v122 offset:512
	ds_write_b32 v233, v121
	ds_write_b32 v233, v123 offset:512
	v_add_u32_e32 v228, v209, v215
	s_waitcnt lgkmcnt(0)
	ds_read_b32 v120, v228
	ds_read_b32 v121, v228 offset:256
	ds_read_b32 v122, v228 offset:512
	ds_read_b32 v123, v228 offset:768
	s_waitcnt lgkmcnt(0)
	s_lshl_b32 s20, s40, 9
	v_add_u32_e32 v224, s20, v209
	global_store_dword v224, v120, s[8:9]
	global_store_dword v224, v121, s[8:9] offset:256
	v_lshlrev_b32_e32 v228, 2, v120
	v_lshlrev_b32_e32 v229, 2, v121
	global_load_dword v124, v228, s[14:15]
	global_load_dword v125, v229, s[14:15]
	global_load_dword v126, v228, s[16:17]
	global_load_dword v127, v229, s[16:17]
	s_waitcnt vmcnt(0)
	v_readlane_b32 s22, v112, 0
	s_lshl_b32 s22, s22, 10
	v_add_u32_e32 v204, s22, v208
	global_load_dwordx4 v[0:3], v204, s[12:13]
	v_readlane_b32 s23, v120, 0
	s_lshl_b32 s23, s23, 10
	v_add_u32_e32 v205, s23, v208
	global_load_dwordx4 v[4:7], v205, s[12:13]
	v_readlane_b32 s24, v112, 1
	s_lshl_b32 s24, s24, 10
	v_add_u32_e32 v206, s24, v208
	global_load_dwordx4 v[8:11], v206, s[12:13]
	v_readlane_b32 s25, v120, 1
	s_lshl_b32 s25, s25, 10
	v_add_u32_e32 v207, s25, v208
	global_load_dwordx4 v[12:15], v207, s[12:13]
	v_readlane_b32 s22, v112, 2
	s_lshl_b32 s22, s22, 10
	v_add_u32_e32 v204, s22, v208
	global_load_dwordx4 v[16:19], v204, s[12:13]
	v_readlane_b32 s23, v120, 2
	s_lshl_b32 s23, s23, 10
	v_add_u32_e32 v205, s23, v208
	global_load_dwordx4 v[20:23], v205, s[12:13]
	v_readlane_b32 s24, v112, 3
	s_lshl_b32 s24, s24, 10
	v_add_u32_e32 v206, s24, v208
	global_load_dwordx4 v[24:27], v206, s[12:13]
	v_readlane_b32 s25, v120, 3
	s_lshl_b32 s25, s25, 10
	v_add_u32_e32 v207, s25, v208
	global_load_dwordx4 v[28:31], v207, s[12:13]
	v_readlane_b32 s22, v112, 4
	s_lshl_b32 s22, s22, 10
	v_add_u32_e32 v204, s22, v208
	global_load_dwordx4 v[32:35], v204, s[12:13]
	v_readlane_b32 s23, v120, 4
	s_lshl_b32 s23, s23, 10
	v_add_u32_e32 v205, s23, v208
	global_load_dwordx4 v[36:39], v205, s[12:13]
	v_readlane_b32 s24, v112, 5
	s_lshl_b32 s24, s24, 10
	v_add_u32_e32 v206, s24, v208
	global_load_dwordx4 v[40:43], v206, s[12:13]
	v_readlane_b32 s25, v120, 5
	s_lshl_b32 s25, s25, 10
	v_add_u32_e32 v207, s25, v208
	global_load_dwordx4 v[44:47], v207, s[12:13]
	v_readlane_b32 s22, v112, 6
	s_lshl_b32 s22, s22, 10
	v_add_u32_e32 v204, s22, v208
	global_load_dwordx4 v[48:51], v204, s[12:13]
	v_readlane_b32 s23, v120, 6
	s_lshl_b32 s23, s23, 10
	v_add_u32_e32 v205, s23, v208
	global_load_dwordx4 v[52:55], v205, s[12:13]
	v_readlane_b32 s24, v112, 7
	s_lshl_b32 s24, s24, 10
	v_add_u32_e32 v206, s24, v208
	global_load_dwordx4 v[56:59], v206, s[12:13]
	v_readlane_b32 s25, v120, 7
	s_lshl_b32 s25, s25, 10
	v_add_u32_e32 v207, s25, v208
	global_load_dwordx4 v[60:63], v207, s[12:13]
.Lp11_group:
	s_cmp_lg_u32 s39, 0
	s_cbranch_scc1 .Lp11_nobar
	s_barrier
; template <int PART>
; DEVI void phase_peer_gather(const Params& p, unsigned char* smem) {
;     ...
;     const uint4* hp4 = (const uint4*)(p.hn + (size_t)tok * LDA + lane * 16);
;     float hv[16], xn[16], y[16];
;     {
;       const uint4 a0 = hp4[0], a1 = hp4[1];
;       const unsigned hu[8] = {a0.x, a0.y, a0.z, a0.w, a1.x, a1.y, a1.z, a1.w};
; #pragma unroll
;       for (int i = 0; i < 8; ++i) { hv[2 * i] = __uint_as_float(hu[i] << 16); hv[2 * i + 1] = __uint_as_float(hu[i] & 0xffff0000u); }
;     }
;     float ss = 0.f;
; #pragma unroll
;     for (int i = 0; i < 16; ++i) ss += hv[i] * hv[i];
;     ss = wave_sum(ss);
;     const float rstd = rsqrtf(ss * (1.f / D) + 1e-6f);
;     {
;       const float4* g4 = (const float4*)p.peer_g + lane * 4;
;       const float4 a0 = g4[0], a1 = g4[1], a2 = g4[2], a3 = g4[3];
;       const float gg[16] = {a0.x, a0.y, a0.z, a0.w, a1.x, a1.y, a1.z, a1.w, a2.x, a2.y, a2.z, a2.w, a3.x, a3.y, a3.z, a3.w};
; #pragma unroll
;       for (int i = 0; i < 16; ++i) { xn[i] = hv[i] * rstd * gg[i]; y[i] = 0.f; }
;     }
;     int e0 = p.experts[(size_t)tok * 128 + lane], e1 = p.experts[(size_t)tok * 128 + 64 + lane];
;     float g0 = p.gates[(size_t)tok * 128 + lane], g1 = p.gates[(size_t)tok * 128 + 64 + lane];
.Lp11_nobar:
	s_mul_i32 s42, s2, 3
	s_bitcmp1_b32 s41, 0
	s_cselect_b32 s42, s42, s2
	s_xor_b32 s48, s43, 15
	s_add_u32 s40, s3, s42
	s_cmp_lt_u32 s40, 0x8000
	s_cselect_b32 s40, s40, s3
	s_cselect_b32 s48, s43, s48
	s_lshl_b32 s20, s40, 9
	v_add_u32_e32 v224, s20, v209
	s_mul_i32 s21, s40, 0x880
	v_add_u32_e32 v225, s21, v211
	global_load_dword v128, v224, s[8:9]
	global_load_dword v129, v224, s[8:9] offset:256
	global_load_dword v130, v224, s[10:11]
	global_load_dword v131, v224, s[10:11] offset:256
	global_load_dwordx4 v[144:147], v225, s[6:7]
	global_load_dwordx4 v[148:151], v225, s[6:7] offset:16
	s_xor_b32 s48, s43, 15
	s_add_u32 s40, s3, s42
	s_add_u32 s40, s40, s2
	s_add_u32 s40, s40, s2
	s_cmp_lt_u32 s40, 0x8000
	s_cselect_b32 s40, s40, s3
	s_cselect_b32 s48, s43, s48
	s_lshl_b32 s20, s40, 9
	v_add_u32_e32 v224, s20, v209
	s_mul_i32 s21, s40, 0x880
	v_add_u32_e32 v225, s21, v211
	global_load_dword v136, v224, s[8:9]
	global_load_dword v137, v224, s[8:9] offset:256
	global_load_dword v138, v224, s[10:11]
	global_load_dword v139, v224, s[10:11] offset:256
	global_load_dwordx4 v[152:155], v225, s[6:7]
	global_load_dwordx4 v[156:159], v225, s[6:7] offset:16
	v_mov_b32_e32 v176, 0
	v_mov_b32_e32 v177, 0
	v_mov_b32_e32 v178, 0
	v_mov_b32_e32 v179, 0
	v_mov_b32_e32 v180, 0
	v_mov_b32_e32 v181, 0
	s_waitcnt vmcnt(27)
	v_cvt_pk_f32_fp8_e32 v[184:185], v0
	v_cvt_pk_f32_fp8_sdwa v[186:187], v0 src0_sel:WORD_1
	v_cvt_pk_f32_fp8_e32 v[188:189], v1
	v_cvt_pk_f32_fp8_sdwa v[190:191], v1 src0_sel:WORD_1
	v_pk_mul_f32 v[200:201], v[64:65], v[184:185]
	v_cvt_pk_f32_fp8_e32 v[192:193], v2
	v_pk_mul_f32 v[202:203], v[66:67], v[186:187]
	v_cvt_pk_f32_fp8_sdwa v[194:195], v2 src0_sel:WORD_1
	v_pk_fma_f32 v[200:201], v[68:69], v[188:189], v[200:201]
	v_cvt_pk_f32_fp8_e32 v[196:197], v3
	v_pk_fma_f32 v[202:203], v[70:71], v[190:191], v[202:203]
	v_cvt_pk_f32_fp8_sdwa v[198:199], v3 src0_sel:WORD_1
	v_pk_fma_f32 v[200:201], v[72:73], v[192:193], v[200:201]
	v_pk_fma_f32 v[202:203], v[74:75], v[194:195], v[202:203]
	v_pk_fma_f32 v[200:201], v[76:77], v[196:197], v[200:201]
	v_pk_fma_f32 v[202:203], v[78:79], v[198:199], v[202:203]
	v_pk_add_f32 v[200:201], v[200:201], v[202:203]
	v_add_f32_e32 v160, v200, v201
	v_readlane_b32 s22, v112, 8
	s_lshl_b32 s22, s22, 10
	v_add_u32_e32 v204, s22, v208
	global_load_dwordx4 v[0:3], v204, s[12:13]
	s_waitcnt vmcnt(27)
	v_cvt_pk_f32_fp8_e32 v[184:185], v4
	v_cvt_pk_f32_fp8_sdwa v[186:187], v4 src0_sel:WORD_1
	v_cvt_pk_f32_fp8_e32 v[188:189], v5
	v_cvt_pk_f32_fp8_sdwa v[190:191], v5 src0_sel:WORD_1
	v_pk_mul_f32 v[200:201], v[80:81], v[184:185]
	v_cvt_pk_f32_fp8_e32 v[192:193], v6
	v_pk_mul_f32 v[202:203], v[82:83], v[186:187]
	v_cvt_pk_f32_fp8_sdwa v[194:195], v6 src0_sel:WORD_1
	v_pk_fma_f32 v[200:201], v[84:85], v[188:189], v[200:201]
	v_cvt_pk_f32_fp8_e32 v[196:197], v7
	v_pk_fma_f32 v[202:203], v[86:87], v[190:191], v[202:203]
	v_cvt_pk_f32_fp8_sdwa v[198:199], v7 src0_sel:WORD_1
	v_pk_fma_f32 v[200:201], v[88:89], v[192:193], v[200:201]
	v_pk_fma_f32 v[202:203], v[90:91], v[194:195], v[202:203]
	v_pk_fma_f32 v[200:201], v[92:93], v[196:197], v[200:201]
	v_pk_fma_f32 v[202:203], v[94:95], v[198:199], v[202:203]
	v_pk_add_f32 v[200:201], v[200:201], v[202:203]
	v_add_f32_e32 v168, v200, v201
	v_readlane_b32 s23, v120, 8
	s_lshl_b32 s23, s23, 10
	v_add_u32_e32 v205, s23, v208
	global_load_dwordx4 v[4:7], v205, s[12:13]
	s_waitcnt vmcnt(27)
	v_cvt_pk_f32_fp8_e32 v[184:185], v8
	v_cvt_pk_f32_fp8_sdwa v[186:187], v8 src0_sel:WORD_1
	v_cvt_pk_f32_fp8_e32 v[188:189], v9
	v_cvt_pk_f32_fp8_sdwa v[190:191], v9 src0_sel:WORD_1
	v_pk_mul_f32 v[200:201], v[64:65], v[184:185]
	v_cvt_pk_f32_fp8_e32 v[192:193], v10
	v_pk_mul_f32 v[202:203], v[66:67], v[186:187]
	v_cvt_pk_f32_fp8_sdwa v[194:195], v10 src0_sel:WORD_1
	v_pk_fma_f32 v[200:201], v[68:69], v[188:189], v[200:201]
	v_cvt_pk_f32_fp8_e32 v[196:197], v11
	v_pk_fma_f32 v[202:203], v[70:71], v[190:191], v[202:203]
	v_cvt_pk_f32_fp8_sdwa v[198:199], v11 src0_sel:WORD_1
	v_pk_fma_f32 v[200:201], v[72:73], v[192:193], v[200:201]
	v_pk_fma_f32 v[202:203], v[74:75], v[194:195], v[202:203]
	v_pk_fma_f32 v[200:201], v[76:77], v[196:197], v[200:201]
	v_pk_fma_f32 v[202:203], v[78:79], v[198:199], v[202:203]
	v_pk_add_f32 v[200:201], v[200:201], v[202:203]
	v_add_f32_e32 v161, v200, v201
	v_readlane_b32 s24, v112, 9
	s_lshl_b32 s24, s24, 10
	v_add_u32_e32 v206, s24, v208
	global_load_dwordx4 v[8:11], v206, s[12:13]
	s_waitcnt vmcnt(27)
	v_cvt_pk_f32_fp8_e32 v[184:185], v12
	v_cvt_pk_f32_fp8_sdwa v[186:187], v12 src0_sel:WORD_1
	v_cvt_pk_f32_fp8_e32 v[188:189], v13
	v_cvt_pk_f32_fp8_sdwa v[190:191], v13 src0_sel:WORD_1
	v_pk_mul_f32 v[200:201], v[80:81], v[184:185]
	v_cvt_pk_f32_fp8_e32 v[192:193], v14
	v_pk_mul_f32 v[202:203], v[82:83], v[186:187]
	v_cvt_pk_f32_fp8_sdwa v[194:195], v14 src0_sel:WORD_1
	v_pk_fma_f32 v[200:201], v[84:85], v[188:189], v[200:201]
	v_cvt_pk_f32_fp8_e32 v[196:197], v15
	v_pk_fma_f32 v[202:203], v[86:87], v[190:191], v[202:203]
	v_cvt_pk_f32_fp8_sdwa v[198:199], v15 src0_sel:WORD_1
	v_pk_fma_f32 v[200:201], v[88:89], v[192:193], v[200:201]
	v_pk_fma_f32 v[202:203], v[90:91], v[194:195], v[202:203]
	v_pk_fma_f32 v[200:201], v[92:93], v[196:197], v[200:201]
	v_pk_fma_f32 v[202:203], v[94:95], v[198:199], v[202:203]
	v_pk_add_f32 v[200:201], v[200:201], v[202:203]
	v_add_f32_e32 v169, v200, v201
	v_readlane_b32 s25, v120, 9
	s_lshl_b32 s25, s25, 10
	v_add_u32_e32 v207, s25, v208
	global_load_dwordx4 v[12:15], v207, s[12:13]
	s_waitcnt vmcnt(27)
	v_cvt_pk_f32_fp8_e32 v[184:185], v16
	v_cvt_pk_f32_fp8_sdwa v[186:187], v16 src0_sel:WORD_1
	v_cvt_pk_f32_fp8_e32 v[188:189], v17
	v_cvt_pk_f32_fp8_sdwa v[190:191], v17 src0_sel:WORD_1
	v_pk_mul_f32 v[200:201], v[64:65], v[184:185]
	v_cvt_pk_f32_fp8_e32 v[192:193], v18
	v_pk_mul_f32 v[202:203], v[66:67], v[186:187]
	v_cvt_pk_f32_fp8_sdwa v[194:195], v18 src0_sel:WORD_1
	v_pk_fma_f32 v[200:201], v[68:69], v[188:189], v[200:201]
	v_cvt_pk_f32_fp8_e32 v[196:197], v19
	v_pk_fma_f32 v[202:203], v[70:71], v[190:191], v[202:203]
	v_cvt_pk_f32_fp8_sdwa v[198:199], v19 src0_sel:WORD_1
	v_pk_fma_f32 v[200:201], v[72:73], v[192:193], v[200:201]
	v_pk_fma_f32 v[202:203], v[74:75], v[194:195], v[202:203]
	v_pk_fma_f32 v[200:201], v[76:77], v[196:197], v[200:201]
	v_pk_fma_f32 v[202:203], v[78:79], v[198:199], v[202:203]
	v_pk_add_f32 v[200:201], v[200:201], v[202:203]
	v_add_f32_e32 v162, v200, v201
	v_readlane_b32 s22, v112, 10
	s_lshl_b32 s22, s22, 10
	v_add_u32_e32 v204, s22, v208
	global_load_dwordx4 v[16:19], v204, s[12:13]
	s_waitcnt vmcnt(27)
	v_cvt_pk_f32_fp8_e32 v[184:185], v20
	v_cvt_pk_f32_fp8_sdwa v[186:187], v20 src0_sel:WORD_1
	v_cvt_pk_f32_fp8_e32 v[188:189], v21
	v_cvt_pk_f32_fp8_sdwa v[190:191], v21 src0_sel:WORD_1
	v_pk_mul_f32 v[200:201], v[80:81], v[184:185]
	v_cvt_pk_f32_fp8_e32 v[192:193], v22
	v_pk_mul_f32 v[202:203], v[82:83], v[186:187]
	v_cvt_pk_f32_fp8_sdwa v[194:195], v22 src0_sel:WORD_1
	v_pk_fma_f32 v[200:201], v[84:85], v[188:189], v[200:201]
	v_cvt_pk_f32_fp8_e32 v[196:197], v23
	v_pk_fma_f32 v[202:203], v[86:87], v[190:191], v[202:203]
	v_cvt_pk_f32_fp8_sdwa v[198:199], v23 src0_sel:WORD_1
	v_pk_fma_f32 v[200:201], v[88:89], v[192:193], v[200:201]
	v_pk_fma_f32 v[202:203], v[90:91], v[194:195], v[202:203]
	v_pk_fma_f32 v[200:201], v[92:93], v[196:197], v[200:201]
	v_pk_fma_f32 v[202:203], v[94:95], v[198:199], v[202:203]
	v_pk_add_f32 v[200:201], v[200:201], v[202:203]
	v_add_f32_e32 v170, v200, v201
	v_readlane_b32 s23, v120, 10
	s_lshl_b32 s23, s23, 10
	v_add_u32_e32 v205, s23, v208
	global_load_dwordx4 v[20:23], v205, s[12:13]
	s_waitcnt vmcnt(27)
	v_cvt_pk_f32_fp8_e32 v[184:185], v24
	v_cvt_pk_f32_fp8_sdwa v[186:187], v24 src0_sel:WORD_1
	v_cvt_pk_f32_fp8_e32 v[188:189], v25
	v_cvt_pk_f32_fp8_sdwa v[190:191], v25 src0_sel:WORD_1
	v_pk_mul_f32 v[200:201], v[64:65], v[184:185]
	v_cvt_pk_f32_fp8_e32 v[192:193], v26
	v_pk_mul_f32 v[202:203], v[66:67], v[186:187]
	v_cvt_pk_f32_fp8_sdwa v[194:195], v26 src0_sel:WORD_1
	v_pk_fma_f32 v[200:201], v[68:69], v[188:189], v[200:201]
	v_cvt_pk_f32_fp8_e32 v[196:197], v27
	v_pk_fma_f32 v[202:203], v[70:71], v[190:191], v[202:203]
	v_cvt_pk_f32_fp8_sdwa v[198:199], v27 src0_sel:WORD_1
	v_pk_fma_f32 v[200:201], v[72:73], v[192:193], v[200:201]
	v_pk_fma_f32 v[202:203], v[74:75], v[194:195], v[202:203]
	v_pk_fma_f32 v[200:201], v[76:77], v[196:197], v[200:201]
	v_pk_fma_f32 v[202:203], v[78:79], v[198:199], v[202:203]
	v_pk_add_f32 v[200:201], v[200:201], v[202:203]
	v_add_f32_e32 v163, v200, v201
	v_readlane_b32 s24, v112, 11
	s_lshl_b32 s24, s24, 10
	v_add_u32_e32 v206, s24, v208
	global_load_dwordx4 v[24:27], v206, s[12:13]
	s_waitcnt vmcnt(27)
	v_cvt_pk_f32_fp8_e32 v[184:185], v28
	v_cvt_pk_f32_fp8_sdwa v[186:187], v28 src0_sel:WORD_1
	v_cvt_pk_f32_fp8_e32 v[188:189], v29
	v_cvt_pk_f32_fp8_sdwa v[190:191], v29 src0_sel:WORD_1
	v_pk_mul_f32 v[200:201], v[80:81], v[184:185]
	v_cvt_pk_f32_fp8_e32 v[192:193], v30
	v_pk_mul_f32 v[202:203], v[82:83], v[186:187]
	v_cvt_pk_f32_fp8_sdwa v[194:195], v30 src0_sel:WORD_1
	v_pk_fma_f32 v[200:201], v[84:85], v[188:189], v[200:201]
	v_cvt_pk_f32_fp8_e32 v[196:197], v31
	v_pk_fma_f32 v[202:203], v[86:87], v[190:191], v[202:203]
	v_cvt_pk_f32_fp8_sdwa v[198:199], v31 src0_sel:WORD_1
	v_pk_fma_f32 v[200:201], v[88:89], v[192:193], v[200:201]
	v_pk_fma_f32 v[202:203], v[90:91], v[194:195], v[202:203]
	v_pk_fma_f32 v[200:201], v[92:93], v[196:197], v[200:201]
	v_pk_fma_f32 v[202:203], v[94:95], v[198:199], v[202:203]
	v_pk_add_f32 v[200:201], v[200:201], v[202:203]
	v_add_f32_e32 v171, v200, v201
	v_readlane_b32 s25, v120, 11
	s_lshl_b32 s25, s25, 10
	v_add_u32_e32 v207, s25, v208
	global_load_dwordx4 v[28:31], v207, s[12:13]
	s_waitcnt vmcnt(27)
	v_cvt_pk_f32_fp8_e32 v[184:185], v32
	v_cvt_pk_f32_fp8_sdwa v[186:187], v32 src0_sel:WORD_1
	v_cvt_pk_f32_fp8_e32 v[188:189], v33
	v_cvt_pk_f32_fp8_sdwa v[190:191], v33 src0_sel:WORD_1
	v_pk_mul_f32 v[200:201], v[64:65], v[184:185]
	v_cvt_pk_f32_fp8_e32 v[192:193], v34
	v_pk_mul_f32 v[202:203], v[66:67], v[186:187]
	v_cvt_pk_f32_fp8_sdwa v[194:195], v34 src0_sel:WORD_1
	v_pk_fma_f32 v[200:201], v[68:69], v[188:189], v[200:201]
	v_cvt_pk_f32_fp8_e32 v[196:197], v35
	v_pk_fma_f32 v[202:203], v[70:71], v[190:191], v[202:203]
	v_cvt_pk_f32_fp8_sdwa v[198:199], v35 src0_sel:WORD_1
	v_pk_fma_f32 v[200:201], v[72:73], v[192:193], v[200:201]
	v_pk_fma_f32 v[202:203], v[74:75], v[194:195], v[202:203]
	v_pk_fma_f32 v[200:201], v[76:77], v[196:197], v[200:201]
	v_pk_fma_f32 v[202:203], v[78:79], v[198:199], v[202:203]
	v_pk_add_f32 v[200:201], v[200:201], v[202:203]
	v_add_f32_e32 v164, v200, v201
	v_readlane_b32 s22, v112, 12
	s_lshl_b32 s22, s22, 10
	v_add_u32_e32 v204, s22, v208
	global_load_dwordx4 v[32:35], v204, s[12:13]
	s_waitcnt vmcnt(27)
	v_cvt_pk_f32_fp8_e32 v[184:185], v36
	v_cvt_pk_f32_fp8_sdwa v[186:187], v36 src0_sel:WORD_1
	v_cvt_pk_f32_fp8_e32 v[188:189], v37
	v_cvt_pk_f32_fp8_sdwa v[190:191], v37 src0_sel:WORD_1
	v_pk_mul_f32 v[200:201], v[80:81], v[184:185]
	v_cvt_pk_f32_fp8_e32 v[192:193], v38
	v_pk_mul_f32 v[202:203], v[82:83], v[186:187]
	v_cvt_pk_f32_fp8_sdwa v[194:195], v38 src0_sel:WORD_1
	v_pk_fma_f32 v[200:201], v[84:85], v[188:189], v[200:201]
	v_cvt_pk_f32_fp8_e32 v[196:197], v39
	v_pk_fma_f32 v[202:203], v[86:87], v[190:191], v[202:203]
	v_cvt_pk_f32_fp8_sdwa v[198:199], v39 src0_sel:WORD_1
	v_pk_fma_f32 v[200:201], v[88:89], v[192:193], v[200:201]
	v_pk_fma_f32 v[202:203], v[90:91], v[194:195], v[202:203]
	v_pk_fma_f32 v[200:201], v[92:93], v[196:197], v[200:201]
	v_pk_fma_f32 v[202:203], v[94:95], v[198:199], v[202:203]
	v_pk_add_f32 v[200:201], v[200:201], v[202:203]
	v_add_f32_e32 v172, v200, v201
	v_readlane_b32 s23, v120, 12
	s_lshl_b32 s23, s23, 10
	v_add_u32_e32 v205, s23, v208
	global_load_dwordx4 v[36:39], v205, s[12:13]
	s_waitcnt vmcnt(27)
	v_cvt_pk_f32_fp8_e32 v[184:185], v40
	v_cvt_pk_f32_fp8_sdwa v[186:187], v40 src0_sel:WORD_1
	v_cvt_pk_f32_fp8_e32 v[188:189], v41
	v_cvt_pk_f32_fp8_sdwa v[190:191], v41 src0_sel:WORD_1
	v_pk_mul_f32 v[200:201], v[64:65], v[184:185]
	v_cvt_pk_f32_fp8_e32 v[192:193], v42
	v_pk_mul_f32 v[202:203], v[66:67], v[186:187]
	v_cvt_pk_f32_fp8_sdwa v[194:195], v42 src0_sel:WORD_1
	v_pk_fma_f32 v[200:201], v[68:69], v[188:189], v[200:201]
	v_cvt_pk_f32_fp8_e32 v[196:197], v43
	v_pk_fma_f32 v[202:203], v[70:71], v[190:191], v[202:203]
	v_cvt_pk_f32_fp8_sdwa v[198:199], v43 src0_sel:WORD_1
	v_pk_fma_f32 v[200:201], v[72:73], v[192:193], v[200:201]
	v_pk_fma_f32 v[202:203], v[74:75], v[194:195], v[202:203]
	v_pk_fma_f32 v[200:201], v[76:77], v[196:197], v[200:201]
	v_pk_fma_f32 v[202:203], v[78:79], v[198:199], v[202:203]
	v_pk_add_f32 v[200:201], v[200:201], v[202:203]
	v_add_f32_e32 v165, v200, v201
	v_readlane_b32 s24, v112, 13
	s_lshl_b32 s24, s24, 10
	v_add_u32_e32 v206, s24, v208
	global_load_dwordx4 v[40:43], v206, s[12:13]
	s_waitcnt vmcnt(27)
	v_cvt_pk_f32_fp8_e32 v[184:185], v44
	v_cvt_pk_f32_fp8_sdwa v[186:187], v44 src0_sel:WORD_1
	v_cvt_pk_f32_fp8_e32 v[188:189], v45
	v_cvt_pk_f32_fp8_sdwa v[190:191], v45 src0_sel:WORD_1
	v_pk_mul_f32 v[200:201], v[80:81], v[184:185]
	v_cvt_pk_f32_fp8_e32 v[192:193], v46
	v_pk_mul_f32 v[202:203], v[82:83], v[186:187]
	v_cvt_pk_f32_fp8_sdwa v[194:195], v46 src0_sel:WORD_1
	v_pk_fma_f32 v[200:201], v[84:85], v[188:189], v[200:201]
	v_cvt_pk_f32_fp8_e32 v[196:197], v47
	v_pk_fma_f32 v[202:203], v[86:87], v[190:191], v[202:203]
	v_cvt_pk_f32_fp8_sdwa v[198:199], v47 src0_sel:WORD_1
	v_pk_fma_f32 v[200:201], v[88:89], v[192:193], v[200:201]
	v_pk_fma_f32 v[202:203], v[90:91], v[194:195], v[202:203]
	v_pk_fma_f32 v[200:201], v[92:93], v[196:197], v[200:201]
	v_pk_fma_f32 v[202:203], v[94:95], v[198:199], v[202:203]
	v_pk_add_f32 v[200:201], v[200:201], v[202:203]
	v_add_f32_e32 v173, v200, v201
	v_readlane_b32 s25, v120, 13
	s_lshl_b32 s25, s25, 10
	v_add_u32_e32 v207, s25, v208
	global_load_dwordx4 v[44:47], v207, s[12:13]
	s_waitcnt vmcnt(27)
	v_cvt_pk_f32_fp8_e32 v[184:185], v48
	v_cvt_pk_f32_fp8_sdwa v[186:187], v48 src0_sel:WORD_1
	v_cvt_pk_f32_fp8_e32 v[188:189], v49
	v_cvt_pk_f32_fp8_sdwa v[190:191], v49 src0_sel:WORD_1
	v_pk_mul_f32 v[200:201], v[64:65], v[184:185]
	v_cvt_pk_f32_fp8_e32 v[192:193], v50
	v_pk_mul_f32 v[202:203], v[66:67], v[186:187]
	v_cvt_pk_f32_fp8_sdwa v[194:195], v50 src0_sel:WORD_1
	v_pk_fma_f32 v[200:201], v[68:69], v[188:189], v[200:201]
	v_cvt_pk_f32_fp8_e32 v[196:197], v51
	v_pk_fma_f32 v[202:203], v[70:71], v[190:191], v[202:203]
	v_cvt_pk_f32_fp8_sdwa v[198:199], v51 src0_sel:WORD_1
	v_pk_fma_f32 v[200:201], v[72:73], v[192:193], v[200:201]
	v_pk_fma_f32 v[202:203], v[74:75], v[194:195], v[202:203]
	v_pk_fma_f32 v[200:201], v[76:77], v[196:197], v[200:201]
	v_pk_fma_f32 v[202:203], v[78:79], v[198:199], v[202:203]
	v_pk_add_f32 v[200:201], v[200:201], v[202:203]
	v_add_f32_e32 v166, v200, v201
	v_readlane_b32 s22, v112, 14
	s_lshl_b32 s22, s22, 10
	v_add_u32_e32 v204, s22, v208
	global_load_dwordx4 v[48:51], v204, s[12:13]
	s_waitcnt vmcnt(27)
	v_cvt_pk_f32_fp8_e32 v[184:185], v52
	v_cvt_pk_f32_fp8_sdwa v[186:187], v52 src0_sel:WORD_1
	v_cvt_pk_f32_fp8_e32 v[188:189], v53
	v_cvt_pk_f32_fp8_sdwa v[190:191], v53 src0_sel:WORD_1
	v_pk_mul_f32 v[200:201], v[80:81], v[184:185]
	v_cvt_pk_f32_fp8_e32 v[192:193], v54
	v_pk_mul_f32 v[202:203], v[82:83], v[186:187]
	v_cvt_pk_f32_fp8_sdwa v[194:195], v54 src0_sel:WORD_1
	v_pk_fma_f32 v[200:201], v[84:85], v[188:189], v[200:201]
	v_cvt_pk_f32_fp8_e32 v[196:197], v55
	v_pk_fma_f32 v[202:203], v[86:87], v[190:191], v[202:203]
	v_cvt_pk_f32_fp8_sdwa v[198:199], v55 src0_sel:WORD_1
	v_pk_fma_f32 v[200:201], v[88:89], v[192:193], v[200:201]
	v_pk_fma_f32 v[202:203], v[90:91], v[194:195], v[202:203]
	v_pk_fma_f32 v[200:201], v[92:93], v[196:197], v[200:201]
	v_pk_fma_f32 v[202:203], v[94:95], v[198:199], v[202:203]
	v_pk_add_f32 v[200:201], v[200:201], v[202:203]
	v_add_f32_e32 v174, v200, v201
	v_readlane_b32 s23, v120, 14
	s_lshl_b32 s23, s23, 10
	v_add_u32_e32 v205, s23, v208
	global_load_dwordx4 v[52:55], v205, s[12:13]
	s_waitcnt vmcnt(27)
	v_cvt_pk_f32_fp8_e32 v[184:185], v56
	v_cvt_pk_f32_fp8_sdwa v[186:187], v56 src0_sel:WORD_1
	v_cvt_pk_f32_fp8_e32 v[188:189], v57
	v_cvt_pk_f32_fp8_sdwa v[190:191], v57 src0_sel:WORD_1
	v_pk_mul_f32 v[200:201], v[64:65], v[184:185]
	v_cvt_pk_f32_fp8_e32 v[192:193], v58
	v_pk_mul_f32 v[202:203], v[66:67], v[186:187]
	v_cvt_pk_f32_fp8_sdwa v[194:195], v58 src0_sel:WORD_1
	v_pk_fma_f32 v[200:201], v[68:69], v[188:189], v[200:201]
	v_cvt_pk_f32_fp8_e32 v[196:197], v59
	v_pk_fma_f32 v[202:203], v[70:71], v[190:191], v[202:203]
	v_cvt_pk_f32_fp8_sdwa v[198:199], v59 src0_sel:WORD_1
	v_pk_fma_f32 v[200:201], v[72:73], v[192:193], v[200:201]
	v_pk_fma_f32 v[202:203], v[74:75], v[194:195], v[202:203]
	v_pk_fma_f32 v[200:201], v[76:77], v[196:197], v[200:201]
	v_pk_fma_f32 v[202:203], v[78:79], v[198:199], v[202:203]
	v_pk_add_f32 v[200:201], v[200:201], v[202:203]
	v_add_f32_e32 v167, v200, v201
	v_readlane_b32 s24, v112, 15
	s_lshl_b32 s24, s24, 10
	v_add_u32_e32 v206, s24, v208
	global_load_dwordx4 v[56:59], v206, s[12:13]
	s_nop 1
	v_permlane32_swap_b32_e32 v160, v164
	v_permlane32_swap_b32_e32 v161, v165
	v_permlane32_swap_b32_e32 v162, v166
	v_permlane32_swap_b32_e32 v163, v167
	v_add_f32_e32 v160, v160, v164
	v_add_f32_e32 v161, v161, v165
	v_add_f32_e32 v162, v162, v166
	v_add_f32_e32 v163, v163, v167
	v_cndmask_b32_e64 v216, v162, v160, s[26:27]
	v_cndmask_b32_e64 v218, v160, v162, s[26:27]
	v_cndmask_b32_e64 v217, v163, v161, s[26:27]
	v_cndmask_b32_e64 v219, v161, v163, s[26:27]
	ds_bpermute_b32 v220, v212, v216
	ds_bpermute_b32 v221, v212, v217
	s_waitcnt lgkmcnt(0)
	v_add_f32_e32 v218, v220, v218
	v_add_f32_e32 v219, v221, v219
	v_cndmask_b32_e64 v216, v219, v218, s[28:29]
	v_cndmask_b32_e64 v217, v218, v219, s[28:29]
	s_nop 1
	v_add_f32_dpp v222, v216, v217 row_ror:8 row_mask:0xf bank_mask:0xf
	ds_bpermute_b32 v220, v213, v222
	s_waitcnt lgkmcnt(0)
	v_add_f32_e32 v222, v220, v222
	s_nop 1
	v_add_f32_dpp v223, v222, v222 quad_perm:[2,3,0,1] row_mask:0xf bank_mask:0xf
	s_nop 1
	v_add_f32_dpp v222, v223, v223 quad_perm:[1,0,3,2] row_mask:0xf bank_mask:0xf
	ds_bpermute_b32 v220, v214, v222
	s_mov_b32 s30, 0xff
	s_mov_b32 s31, 0x0
	s_waitcnt lgkmcnt(0)
	v_cndmask_b32_e64 v176, v176, v220, s[30:31]
	s_waitcnt vmcnt(27)
	v_cvt_pk_f32_fp8_e32 v[184:185], v60
	v_cvt_pk_f32_fp8_sdwa v[186:187], v60 src0_sel:WORD_1
	v_cvt_pk_f32_fp8_e32 v[188:189], v61
	v_cvt_pk_f32_fp8_sdwa v[190:191], v61 src0_sel:WORD_1
	v_pk_mul_f32 v[200:201], v[80:81], v[184:185]
	v_cvt_pk_f32_fp8_e32 v[192:193], v62
	v_pk_mul_f32 v[202:203], v[82:83], v[186:187]
	v_cvt_pk_f32_fp8_sdwa v[194:195], v62 src0_sel:WORD_1
	v_pk_fma_f32 v[200:201], v[84:85], v[188:189], v[200:201]
	v_cvt_pk_f32_fp8_e32 v[196:197], v63
	v_pk_fma_f32 v[202:203], v[86:87], v[190:191], v[202:203]
	v_cvt_pk_f32_fp8_sdwa v[198:199], v63 src0_sel:WORD_1
	v_pk_fma_f32 v[200:201], v[88:89], v[192:193], v[200:201]
	v_pk_fma_f32 v[202:203], v[90:91], v[194:195], v[202:203]
	v_pk_fma_f32 v[200:201], v[92:93], v[196:197], v[200:201]
	v_pk_fma_f32 v[202:203], v[94:95], v[198:199], v[202:203]
	v_pk_add_f32 v[200:201], v[200:201], v[202:203]
	v_add_f32_e32 v175, v200, v201
	v_readlane_b32 s25, v120, 15
	s_lshl_b32 s25, s25, 10
	v_add_u32_e32 v207, s25, v208
	global_load_dwordx4 v[60:63], v207, s[12:13]
	s_nop 1
	v_permlane32_swap_b32_e32 v168, v172
	v_permlane32_swap_b32_e32 v169, v173
	v_permlane32_swap_b32_e32 v170, v174
	v_permlane32_swap_b32_e32 v171, v175
	v_add_f32_e32 v168, v168, v172
	v_add_f32_e32 v169, v169, v173
	v_add_f32_e32 v170, v170, v174
	v_add_f32_e32 v171, v171, v175
	v_cndmask_b32_e64 v216, v170, v168, s[26:27]
	v_cndmask_b32_e64 v218, v168, v170, s[26:27]
	v_cndmask_b32_e64 v217, v171, v169, s[26:27]
	v_cndmask_b32_e64 v219, v169, v171, s[26:27]
	ds_bpermute_b32 v220, v212, v216
	ds_bpermute_b32 v221, v212, v217
	s_waitcnt lgkmcnt(0)
	v_add_f32_e32 v218, v220, v218
	v_add_f32_e32 v219, v221, v219
	v_cndmask_b32_e64 v216, v219, v218, s[28:29]
	v_cndmask_b32_e64 v217, v218, v219, s[28:29]
	s_nop 1
	v_add_f32_dpp v222, v216, v217 row_ror:8 row_mask:0xf bank_mask:0xf
	ds_bpermute_b32 v220, v213, v222
	s_waitcnt lgkmcnt(0)
	v_add_f32_e32 v222, v220, v222
	s_nop 1
	v_add_f32_dpp v223, v222, v222 quad_perm:[2,3,0,1] row_mask:0xf bank_mask:0xf
	s_nop 1
	v_add_f32_dpp v222, v223, v223 quad_perm:[1,0,3,2] row_mask:0xf bank_mask:0xf
	ds_bpermute_b32 v220, v214, v222
	s_mov_b32 s30, 0xff
	s_mov_b32 s31, 0x0
	s_waitcnt lgkmcnt(0)
	v_cndmask_b32_e64 v179, v179, v220, s[30:31]
	s_waitcnt vmcnt(15)
	v_cvt_pk_f32_fp8_e32 v[184:185], v0
	v_cvt_pk_f32_fp8_sdwa v[186:187], v0 src0_sel:WORD_1
	v_cvt_pk_f32_fp8_e32 v[188:189], v1
	v_cvt_pk_f32_fp8_sdwa v[190:191], v1 src0_sel:WORD_1
	v_pk_mul_f32 v[200:201], v[64:65], v[184:185]
	v_cvt_pk_f32_fp8_e32 v[192:193], v2
	v_pk_mul_f32 v[202:203], v[66:67], v[186:187]
	v_cvt_pk_f32_fp8_sdwa v[194:195], v2 src0_sel:WORD_1
	v_pk_fma_f32 v[200:201], v[68:69], v[188:189], v[200:201]
	v_cvt_pk_f32_fp8_e32 v[196:197], v3
	v_pk_fma_f32 v[202:203], v[70:71], v[190:191], v[202:203]
	v_cvt_pk_f32_fp8_sdwa v[198:199], v3 src0_sel:WORD_1
	v_pk_fma_f32 v[200:201], v[72:73], v[192:193], v[200:201]
	v_pk_fma_f32 v[202:203], v[74:75], v[194:195], v[202:203]
	v_pk_fma_f32 v[200:201], v[76:77], v[196:197], v[200:201]
	v_pk_fma_f32 v[202:203], v[78:79], v[198:199], v[202:203]
	v_pk_add_f32 v[200:201], v[200:201], v[202:203]
	v_add_f32_e32 v160, v200, v201
	v_readlane_b32 s22, v112, 16
	s_lshl_b32 s22, s22, 10
	v_add_u32_e32 v204, s22, v208
	global_load_dwordx4 v[0:3], v204, s[12:13]
	s_waitcnt vmcnt(15)
	v_cvt_pk_f32_fp8_e32 v[184:185], v4
	v_cvt_pk_f32_fp8_sdwa v[186:187], v4 src0_sel:WORD_1
	v_cvt_pk_f32_fp8_e32 v[188:189], v5
	v_cvt_pk_f32_fp8_sdwa v[190:191], v5 src0_sel:WORD_1
	v_pk_mul_f32 v[200:201], v[80:81], v[184:185]
	v_cvt_pk_f32_fp8_e32 v[192:193], v6
	v_pk_mul_f32 v[202:203], v[82:83], v[186:187]
	v_cvt_pk_f32_fp8_sdwa v[194:195], v6 src0_sel:WORD_1
	v_pk_fma_f32 v[200:201], v[84:85], v[188:189], v[200:201]
	v_cvt_pk_f32_fp8_e32 v[196:197], v7
	v_pk_fma_f32 v[202:203], v[86:87], v[190:191], v[202:203]
	v_cvt_pk_f32_fp8_sdwa v[198:199], v7 src0_sel:WORD_1
	v_pk_fma_f32 v[200:201], v[88:89], v[192:193], v[200:201]
	v_pk_fma_f32 v[202:203], v[90:91], v[194:195], v[202:203]
	v_pk_fma_f32 v[200:201], v[92:93], v[196:197], v[200:201]
	v_pk_fma_f32 v[202:203], v[94:95], v[198:199], v[202:203]
	v_pk_add_f32 v[200:201], v[200:201], v[202:203]
	v_add_f32_e32 v168, v200, v201
	v_readlane_b32 s23, v120, 16
	s_lshl_b32 s23, s23, 10
	v_add_u32_e32 v205, s23, v208
	global_load_dwordx4 v[4:7], v205, s[12:13]
	s_waitcnt vmcnt(15)
	v_cvt_pk_f32_fp8_e32 v[184:185], v8
	v_cvt_pk_f32_fp8_sdwa v[186:187], v8 src0_sel:WORD_1
	v_cvt_pk_f32_fp8_e32 v[188:189], v9
	v_cvt_pk_f32_fp8_sdwa v[190:191], v9 src0_sel:WORD_1
	v_pk_mul_f32 v[200:201], v[64:65], v[184:185]
	v_cvt_pk_f32_fp8_e32 v[192:193], v10
	v_pk_mul_f32 v[202:203], v[66:67], v[186:187]
	v_cvt_pk_f32_fp8_sdwa v[194:195], v10 src0_sel:WORD_1
	v_pk_fma_f32 v[200:201], v[68:69], v[188:189], v[200:201]
	v_cvt_pk_f32_fp8_e32 v[196:197], v11
	v_pk_fma_f32 v[202:203], v[70:71], v[190:191], v[202:203]
	v_cvt_pk_f32_fp8_sdwa v[198:199], v11 src0_sel:WORD_1
	v_pk_fma_f32 v[200:201], v[72:73], v[192:193], v[200:201]
	v_pk_fma_f32 v[202:203], v[74:75], v[194:195], v[202:203]
	v_pk_fma_f32 v[200:201], v[76:77], v[196:197], v[200:201]
	v_pk_fma_f32 v[202:203], v[78:79], v[198:199], v[202:203]
	v_pk_add_f32 v[200:201], v[200:201], v[202:203]
	v_add_f32_e32 v161, v200, v201
	v_readlane_b32 s24, v112, 17
	s_lshl_b32 s24, s24, 10
	v_add_u32_e32 v206, s24, v208
	global_load_dwordx4 v[8:11], v206, s[12:13]
	s_waitcnt vmcnt(15)
	v_cvt_pk_f32_fp8_e32 v[184:185], v12
	v_cvt_pk_f32_fp8_sdwa v[186:187], v12 src0_sel:WORD_1
	v_cvt_pk_f32_fp8_e32 v[188:189], v13
	v_cvt_pk_f32_fp8_sdwa v[190:191], v13 src0_sel:WORD_1
	v_pk_mul_f32 v[200:201], v[80:81], v[184:185]
	v_cvt_pk_f32_fp8_e32 v[192:193], v14
	v_pk_mul_f32 v[202:203], v[82:83], v[186:187]
	v_cvt_pk_f32_fp8_sdwa v[194:195], v14 src0_sel:WORD_1
	v_pk_fma_f32 v[200:201], v[84:85], v[188:189], v[200:201]
	v_cvt_pk_f32_fp8_e32 v[196:197], v15
	v_pk_fma_f32 v[202:203], v[86:87], v[190:191], v[202:203]
	v_cvt_pk_f32_fp8_sdwa v[198:199], v15 src0_sel:WORD_1
	v_pk_fma_f32 v[200:201], v[88:89], v[192:193], v[200:201]
	v_pk_fma_f32 v[202:203], v[90:91], v[194:195], v[202:203]
	v_pk_fma_f32 v[200:201], v[92:93], v[196:197], v[200:201]
	v_pk_fma_f32 v[202:203], v[94:95], v[198:199], v[202:203]
	v_pk_add_f32 v[200:201], v[200:201], v[202:203]
	v_add_f32_e32 v169, v200, v201
	v_readlane_b32 s25, v120, 17
	s_lshl_b32 s25, s25, 10
	v_add_u32_e32 v207, s25, v208
	global_load_dwordx4 v[12:15], v207, s[12:13]
	s_waitcnt vmcnt(15)
	v_cvt_pk_f32_fp8_e32 v[184:185], v16
	v_cvt_pk_f32_fp8_sdwa v[186:187], v16 src0_sel:WORD_1
	v_cvt_pk_f32_fp8_e32 v[188:189], v17
	v_cvt_pk_f32_fp8_sdwa v[190:191], v17 src0_sel:WORD_1
	v_pk_mul_f32 v[200:201], v[64:65], v[184:185]
	v_cvt_pk_f32_fp8_e32 v[192:193], v18
	v_pk_mul_f32 v[202:203], v[66:67], v[186:187]
	v_cvt_pk_f32_fp8_sdwa v[194:195], v18 src0_sel:WORD_1
	v_pk_fma_f32 v[200:201], v[68:69], v[188:189], v[200:201]
	v_cvt_pk_f32_fp8_e32 v[196:197], v19
	v_pk_fma_f32 v[202:203], v[70:71], v[190:191], v[202:203]
	v_cvt_pk_f32_fp8_sdwa v[198:199], v19 src0_sel:WORD_1
	v_pk_fma_f32 v[200:201], v[72:73], v[192:193], v[200:201]
	v_pk_fma_f32 v[202:203], v[74:75], v[194:195], v[202:203]
	v_pk_fma_f32 v[200:201], v[76:77], v[196:197], v[200:201]
	v_pk_fma_f32 v[202:203], v[78:79], v[198:199], v[202:203]
	v_pk_add_f32 v[200:201], v[200:201], v[202:203]
	v_add_f32_e32 v162, v200, v201
	v_readlane_b32 s22, v112, 18
	s_lshl_b32 s22, s22, 10
	v_add_u32_e32 v204, s22, v208
	global_load_dwordx4 v[16:19], v204, s[12:13]
	s_waitcnt vmcnt(15)
	v_cvt_pk_f32_fp8_e32 v[184:185], v20
	v_cvt_pk_f32_fp8_sdwa v[186:187], v20 src0_sel:WORD_1
	v_cvt_pk_f32_fp8_e32 v[188:189], v21
	v_cvt_pk_f32_fp8_sdwa v[190:191], v21 src0_sel:WORD_1
	v_pk_mul_f32 v[200:201], v[80:81], v[184:185]
	v_cvt_pk_f32_fp8_e32 v[192:193], v22
	v_pk_mul_f32 v[202:203], v[82:83], v[186:187]
	v_cvt_pk_f32_fp8_sdwa v[194:195], v22 src0_sel:WORD_1
	v_pk_fma_f32 v[200:201], v[84:85], v[188:189], v[200:201]
	v_cvt_pk_f32_fp8_e32 v[196:197], v23
	v_pk_fma_f32 v[202:203], v[86:87], v[190:191], v[202:203]
	v_cvt_pk_f32_fp8_sdwa v[198:199], v23 src0_sel:WORD_1
	v_pk_fma_f32 v[200:201], v[88:89], v[192:193], v[200:201]
	v_pk_fma_f32 v[202:203], v[90:91], v[194:195], v[202:203]
	v_pk_fma_f32 v[200:201], v[92:93], v[196:197], v[200:201]
	v_pk_fma_f32 v[202:203], v[94:95], v[198:199], v[202:203]
	v_pk_add_f32 v[200:201], v[200:201], v[202:203]
	v_add_f32_e32 v170, v200, v201
	v_readlane_b32 s23, v120, 18
	s_lshl_b32 s23, s23, 10
	v_add_u32_e32 v205, s23, v208
	global_load_dwordx4 v[20:23], v205, s[12:13]
	s_waitcnt vmcnt(15)
	v_cvt_pk_f32_fp8_e32 v[184:185], v24
	v_cvt_pk_f32_fp8_sdwa v[186:187], v24 src0_sel:WORD_1
	v_cvt_pk_f32_fp8_e32 v[188:189], v25
	v_cvt_pk_f32_fp8_sdwa v[190:191], v25 src0_sel:WORD_1
	v_pk_mul_f32 v[200:201], v[64:65], v[184:185]
	v_cvt_pk_f32_fp8_e32 v[192:193], v26
	v_pk_mul_f32 v[202:203], v[66:67], v[186:187]
	v_cvt_pk_f32_fp8_sdwa v[194:195], v26 src0_sel:WORD_1
	v_pk_fma_f32 v[200:201], v[68:69], v[188:189], v[200:201]
	v_cvt_pk_f32_fp8_e32 v[196:197], v27
	v_pk_fma_f32 v[202:203], v[70:71], v[190:191], v[202:203]
	v_cvt_pk_f32_fp8_sdwa v[198:199], v27 src0_sel:WORD_1
	v_pk_fma_f32 v[200:201], v[72:73], v[192:193], v[200:201]
	v_pk_fma_f32 v[202:203], v[74:75], v[194:195], v[202:203]
	v_pk_fma_f32 v[200:201], v[76:77], v[196:197], v[200:201]
	v_pk_fma_f32 v[202:203], v[78:79], v[198:199], v[202:203]
	v_pk_add_f32 v[200:201], v[200:201], v[202:203]
	v_add_f32_e32 v163, v200, v201
	v_readlane_b32 s24, v112, 19
	s_lshl_b32 s24, s24, 10
	v_add_u32_e32 v206, s24, v208
	global_load_dwordx4 v[24:27], v206, s[12:13]
	s_waitcnt vmcnt(15)
	v_cvt_pk_f32_fp8_e32 v[184:185], v28
	v_cvt_pk_f32_fp8_sdwa v[186:187], v28 src0_sel:WORD_1
	v_cvt_pk_f32_fp8_e32 v[188:189], v29
	v_cvt_pk_f32_fp8_sdwa v[190:191], v29 src0_sel:WORD_1
	v_pk_mul_f32 v[200:201], v[80:81], v[184:185]
	v_cvt_pk_f32_fp8_e32 v[192:193], v30
	v_pk_mul_f32 v[202:203], v[82:83], v[186:187]
	v_cvt_pk_f32_fp8_sdwa v[194:195], v30 src0_sel:WORD_1
	v_pk_fma_f32 v[200:201], v[84:85], v[188:189], v[200:201]
	v_cvt_pk_f32_fp8_e32 v[196:197], v31
	v_pk_fma_f32 v[202:203], v[86:87], v[190:191], v[202:203]
	v_cvt_pk_f32_fp8_sdwa v[198:199], v31 src0_sel:WORD_1
	v_pk_fma_f32 v[200:201], v[88:89], v[192:193], v[200:201]
	v_pk_fma_f32 v[202:203], v[90:91], v[194:195], v[202:203]
	v_pk_fma_f32 v[200:201], v[92:93], v[196:197], v[200:201]
	v_pk_fma_f32 v[202:203], v[94:95], v[198:199], v[202:203]
	v_pk_add_f32 v[200:201], v[200:201], v[202:203]
	v_add_f32_e32 v171, v200, v201
	v_readlane_b32 s25, v120, 19
	s_lshl_b32 s25, s25, 10
	v_add_u32_e32 v207, s25, v208
	global_load_dwordx4 v[28:31], v207, s[12:13]
	s_waitcnt vmcnt(15)
	v_cvt_pk_f32_fp8_e32 v[184:185], v32
	v_cvt_pk_f32_fp8_sdwa v[186:187], v32 src0_sel:WORD_1
	v_cvt_pk_f32_fp8_e32 v[188:189], v33
	v_cvt_pk_f32_fp8_sdwa v[190:191], v33 src0_sel:WORD_1
	v_pk_mul_f32 v[200:201], v[64:65], v[184:185]
	v_cvt_pk_f32_fp8_e32 v[192:193], v34
	v_pk_mul_f32 v[202:203], v[66:67], v[186:187]
	v_cvt_pk_f32_fp8_sdwa v[194:195], v34 src0_sel:WORD_1
	v_pk_fma_f32 v[200:201], v[68:69], v[188:189], v[200:201]
	v_cvt_pk_f32_fp8_e32 v[196:197], v35
	v_pk_fma_f32 v[202:203], v[70:71], v[190:191], v[202:203]
	v_cvt_pk_f32_fp8_sdwa v[198:199], v35 src0_sel:WORD_1
	v_pk_fma_f32 v[200:201], v[72:73], v[192:193], v[200:201]
	v_pk_fma_f32 v[202:203], v[74:75], v[194:195], v[202:203]
	v_pk_fma_f32 v[200:201], v[76:77], v[196:197], v[200:201]
	v_pk_fma_f32 v[202:203], v[78:79], v[198:199], v[202:203]
	v_pk_add_f32 v[200:201], v[200:201], v[202:203]
	v_add_f32_e32 v164, v200, v201
	v_readlane_b32 s22, v112, 20
	s_lshl_b32 s22, s22, 10
	v_add_u32_e32 v204, s22, v208
	global_load_dwordx4 v[32:35], v204, s[12:13]
	s_waitcnt vmcnt(15)
	v_cvt_pk_f32_fp8_e32 v[184:185], v36
	v_cvt_pk_f32_fp8_sdwa v[186:187], v36 src0_sel:WORD_1
	v_cvt_pk_f32_fp8_e32 v[188:189], v37
	v_cvt_pk_f32_fp8_sdwa v[190:191], v37 src0_sel:WORD_1
	v_pk_mul_f32 v[200:201], v[80:81], v[184:185]
	v_cvt_pk_f32_fp8_e32 v[192:193], v38
	v_pk_mul_f32 v[202:203], v[82:83], v[186:187]
	v_cvt_pk_f32_fp8_sdwa v[194:195], v38 src0_sel:WORD_1
	v_pk_fma_f32 v[200:201], v[84:85], v[188:189], v[200:201]
	v_cvt_pk_f32_fp8_e32 v[196:197], v39
	v_pk_fma_f32 v[202:203], v[86:87], v[190:191], v[202:203]
	v_cvt_pk_f32_fp8_sdwa v[198:199], v39 src0_sel:WORD_1
	v_pk_fma_f32 v[200:201], v[88:89], v[192:193], v[200:201]
	v_pk_fma_f32 v[202:203], v[90:91], v[194:195], v[202:203]
	v_pk_fma_f32 v[200:201], v[92:93], v[196:197], v[200:201]
	v_pk_fma_f32 v[202:203], v[94:95], v[198:199], v[202:203]
	v_pk_add_f32 v[200:201], v[200:201], v[202:203]
	v_add_f32_e32 v172, v200, v201
	v_readlane_b32 s23, v120, 20
	s_lshl_b32 s23, s23, 10
	v_add_u32_e32 v205, s23, v208
	global_load_dwordx4 v[36:39], v205, s[12:13]
	s_waitcnt vmcnt(15)
	v_cvt_pk_f32_fp8_e32 v[184:185], v40
	v_cvt_pk_f32_fp8_sdwa v[186:187], v40 src0_sel:WORD_1
	v_cvt_pk_f32_fp8_e32 v[188:189], v41
	v_cvt_pk_f32_fp8_sdwa v[190:191], v41 src0_sel:WORD_1
	v_pk_mul_f32 v[200:201], v[64:65], v[184:185]
	v_cvt_pk_f32_fp8_e32 v[192:193], v42
	v_pk_mul_f32 v[202:203], v[66:67], v[186:187]
	v_cvt_pk_f32_fp8_sdwa v[194:195], v42 src0_sel:WORD_1
	v_pk_fma_f32 v[200:201], v[68:69], v[188:189], v[200:201]
	v_cvt_pk_f32_fp8_e32 v[196:197], v43
	v_pk_fma_f32 v[202:203], v[70:71], v[190:191], v[202:203]
	v_cvt_pk_f32_fp8_sdwa v[198:199], v43 src0_sel:WORD_1
	v_pk_fma_f32 v[200:201], v[72:73], v[192:193], v[200:201]
	v_pk_fma_f32 v[202:203], v[74:75], v[194:195], v[202:203]
	v_pk_fma_f32 v[200:201], v[76:77], v[196:197], v[200:201]
	v_pk_fma_f32 v[202:203], v[78:79], v[198:199], v[202:203]
	v_pk_add_f32 v[200:201], v[200:201], v[202:203]
	v_add_f32_e32 v165, v200, v201
	v_readlane_b32 s24, v112, 21
	s_lshl_b32 s24, s24, 10
	v_add_u32_e32 v206, s24, v208
	global_load_dwordx4 v[40:43], v206, s[12:13]
	s_waitcnt vmcnt(15)
	v_cvt_pk_f32_fp8_e32 v[184:185], v44
	v_cvt_pk_f32_fp8_sdwa v[186:187], v44 src0_sel:WORD_1
	v_cvt_pk_f32_fp8_e32 v[188:189], v45
	v_cvt_pk_f32_fp8_sdwa v[190:191], v45 src0_sel:WORD_1
	v_pk_mul_f32 v[200:201], v[80:81], v[184:185]
	v_cvt_pk_f32_fp8_e32 v[192:193], v46
	v_pk_mul_f32 v[202:203], v[82:83], v[186:187]
	v_cvt_pk_f32_fp8_sdwa v[194:195], v46 src0_sel:WORD_1
	v_pk_fma_f32 v[200:201], v[84:85], v[188:189], v[200:201]
	v_cvt_pk_f32_fp8_e32 v[196:197], v47
	v_pk_fma_f32 v[202:203], v[86:87], v[190:191], v[202:203]
	v_cvt_pk_f32_fp8_sdwa v[198:199], v47 src0_sel:WORD_1
	v_pk_fma_f32 v[200:201], v[88:89], v[192:193], v[200:201]
	v_pk_fma_f32 v[202:203], v[90:91], v[194:195], v[202:203]
	v_pk_fma_f32 v[200:201], v[92:93], v[196:197], v[200:201]
	v_pk_fma_f32 v[202:203], v[94:95], v[198:199], v[202:203]
	v_pk_add_f32 v[200:201], v[200:201], v[202:203]
	v_add_f32_e32 v173, v200, v201
	v_readlane_b32 s25, v120, 21
	s_lshl_b32 s25, s25, 10
	v_add_u32_e32 v207, s25, v208
	global_load_dwordx4 v[44:47], v207, s[12:13]
	s_waitcnt vmcnt(15)
	v_cvt_pk_f32_fp8_e32 v[184:185], v48
	v_cvt_pk_f32_fp8_sdwa v[186:187], v48 src0_sel:WORD_1
	v_cvt_pk_f32_fp8_e32 v[188:189], v49
	v_cvt_pk_f32_fp8_sdwa v[190:191], v49 src0_sel:WORD_1
	v_pk_mul_f32 v[200:201], v[64:65], v[184:185]
	v_cvt_pk_f32_fp8_e32 v[192:193], v50
	v_pk_mul_f32 v[202:203], v[66:67], v[186:187]
	v_cvt_pk_f32_fp8_sdwa v[194:195], v50 src0_sel:WORD_1
	v_pk_fma_f32 v[200:201], v[68:69], v[188:189], v[200:201]
	v_cvt_pk_f32_fp8_e32 v[196:197], v51
	v_pk_fma_f32 v[202:203], v[70:71], v[190:191], v[202:203]
	v_cvt_pk_f32_fp8_sdwa v[198:199], v51 src0_sel:WORD_1
	v_pk_fma_f32 v[200:201], v[72:73], v[192:193], v[200:201]
	v_pk_fma_f32 v[202:203], v[74:75], v[194:195], v[202:203]
	v_pk_fma_f32 v[200:201], v[76:77], v[196:197], v[200:201]
	v_pk_fma_f32 v[202:203], v[78:79], v[198:199], v[202:203]
	v_pk_add_f32 v[200:201], v[200:201], v[202:203]
	v_add_f32_e32 v166, v200, v201
	v_readlane_b32 s22, v112, 22
	s_lshl_b32 s22, s22, 10
	v_add_u32_e32 v204, s22, v208
	global_load_dwordx4 v[48:51], v204, s[12:13]
	s_waitcnt vmcnt(15)
	v_cvt_pk_f32_fp8_e32 v[184:185], v52
	v_cvt_pk_f32_fp8_sdwa v[186:187], v52 src0_sel:WORD_1
	v_cvt_pk_f32_fp8_e32 v[188:189], v53
	v_cvt_pk_f32_fp8_sdwa v[190:191], v53 src0_sel:WORD_1
	v_pk_mul_f32 v[200:201], v[80:81], v[184:185]
	v_cvt_pk_f32_fp8_e32 v[192:193], v54
	v_pk_mul_f32 v[202:203], v[82:83], v[186:187]
	v_cvt_pk_f32_fp8_sdwa v[194:195], v54 src0_sel:WORD_1
	v_pk_fma_f32 v[200:201], v[84:85], v[188:189], v[200:201]
	v_cvt_pk_f32_fp8_e32 v[196:197], v55
	v_pk_fma_f32 v[202:203], v[86:87], v[190:191], v[202:203]
	v_cvt_pk_f32_fp8_sdwa v[198:199], v55 src0_sel:WORD_1
	v_pk_fma_f32 v[200:201], v[88:89], v[192:193], v[200:201]
	v_pk_fma_f32 v[202:203], v[90:91], v[194:195], v[202:203]
	v_pk_fma_f32 v[200:201], v[92:93], v[196:197], v[200:201]
	v_pk_fma_f32 v[202:203], v[94:95], v[198:199], v[202:203]
	v_pk_add_f32 v[200:201], v[200:201], v[202:203]
	v_add_f32_e32 v174, v200, v201
	v_readlane_b32 s23, v120, 22
	s_lshl_b32 s23, s23, 10
	v_add_u32_e32 v205, s23, v208
	global_load_dwordx4 v[52:55], v205, s[12:13]
	s_waitcnt vmcnt(15)
	v_cvt_pk_f32_fp8_e32 v[184:185], v56
	v_cvt_pk_f32_fp8_sdwa v[186:187], v56 src0_sel:WORD_1
	v_cvt_pk_f32_fp8_e32 v[188:189], v57
	v_cvt_pk_f32_fp8_sdwa v[190:191], v57 src0_sel:WORD_1
	v_pk_mul_f32 v[200:201], v[64:65], v[184:185]
	v_cvt_pk_f32_fp8_e32 v[192:193], v58
	v_pk_mul_f32 v[202:203], v[66:67], v[186:187]
	v_cvt_pk_f32_fp8_sdwa v[194:195], v58 src0_sel:WORD_1
	v_pk_fma_f32 v[200:201], v[68:69], v[188:189], v[200:201]
	v_cvt_pk_f32_fp8_e32 v[196:197], v59
	v_pk_fma_f32 v[202:203], v[70:71], v[190:191], v[202:203]
	v_cvt_pk_f32_fp8_sdwa v[198:199], v59 src0_sel:WORD_1
	v_pk_fma_f32 v[200:201], v[72:73], v[192:193], v[200:201]
	v_pk_fma_f32 v[202:203], v[74:75], v[194:195], v[202:203]
	v_pk_fma_f32 v[200:201], v[76:77], v[196:197], v[200:201]
	v_pk_fma_f32 v[202:203], v[78:79], v[198:199], v[202:203]
	v_pk_add_f32 v[200:201], v[200:201], v[202:203]
	v_add_f32_e32 v167, v200, v201
	v_readlane_b32 s24, v112, 23
	s_lshl_b32 s24, s24, 10
	v_add_u32_e32 v206, s24, v208
	global_load_dwordx4 v[56:59], v206, s[12:13]
	s_nop 1
	v_permlane32_swap_b32_e32 v160, v164
	v_permlane32_swap_b32_e32 v161, v165
	v_permlane32_swap_b32_e32 v162, v166
	v_permlane32_swap_b32_e32 v163, v167
	v_add_f32_e32 v160, v160, v164
	v_add_f32_e32 v161, v161, v165
	v_add_f32_e32 v162, v162, v166
	v_add_f32_e32 v163, v163, v167
	v_cndmask_b32_e64 v216, v162, v160, s[26:27]
	v_cndmask_b32_e64 v218, v160, v162, s[26:27]
	v_cndmask_b32_e64 v217, v163, v161, s[26:27]
	v_cndmask_b32_e64 v219, v161, v163, s[26:27]
	ds_bpermute_b32 v220, v212, v216
	ds_bpermute_b32 v221, v212, v217
	s_waitcnt lgkmcnt(0)
	v_add_f32_e32 v218, v220, v218
	v_add_f32_e32 v219, v221, v219
	v_cndmask_b32_e64 v216, v219, v218, s[28:29]
	v_cndmask_b32_e64 v217, v218, v219, s[28:29]
	s_nop 1
	v_add_f32_dpp v222, v216, v217 row_ror:8 row_mask:0xf bank_mask:0xf
	ds_bpermute_b32 v220, v213, v222
	s_waitcnt lgkmcnt(0)
	v_add_f32_e32 v222, v220, v222
	s_nop 1
	v_add_f32_dpp v223, v222, v222 quad_perm:[2,3,0,1] row_mask:0xf bank_mask:0xf
	s_nop 1
	v_add_f32_dpp v222, v223, v223 quad_perm:[1,0,3,2] row_mask:0xf bank_mask:0xf
	ds_bpermute_b32 v220, v214, v222
	s_mov_b32 s30, 0xff00
	s_mov_b32 s31, 0x0
	s_waitcnt lgkmcnt(0)
	v_cndmask_b32_e64 v176, v176, v220, s[30:31]
	s_waitcnt vmcnt(15)
	v_cvt_pk_f32_fp8_e32 v[184:185], v60
	v_cvt_pk_f32_fp8_sdwa v[186:187], v60 src0_sel:WORD_1
	v_cvt_pk_f32_fp8_e32 v[188:189], v61
	v_cvt_pk_f32_fp8_sdwa v[190:191], v61 src0_sel:WORD_1
	v_pk_mul_f32 v[200:201], v[80:81], v[184:185]
	v_cvt_pk_f32_fp8_e32 v[192:193], v62
	v_pk_mul_f32 v[202:203], v[82:83], v[186:187]
	v_cvt_pk_f32_fp8_sdwa v[194:195], v62 src0_sel:WORD_1
	v_pk_fma_f32 v[200:201], v[84:85], v[188:189], v[200:201]
	v_cvt_pk_f32_fp8_e32 v[196:197], v63
	v_pk_fma_f32 v[202:203], v[86:87], v[190:191], v[202:203]
	v_cvt_pk_f32_fp8_sdwa v[198:199], v63 src0_sel:WORD_1
	v_pk_fma_f32 v[200:201], v[88:89], v[192:193], v[200:201]
	v_pk_fma_f32 v[202:203], v[90:91], v[194:195], v[202:203]
	v_pk_fma_f32 v[200:201], v[92:93], v[196:197], v[200:201]
	v_pk_fma_f32 v[202:203], v[94:95], v[198:199], v[202:203]
	v_pk_add_f32 v[200:201], v[200:201], v[202:203]
	v_add_f32_e32 v175, v200, v201
	v_readlane_b32 s25, v120, 23
	s_lshl_b32 s25, s25, 10
	v_add_u32_e32 v207, s25, v208
	global_load_dwordx4 v[60:63], v207, s[12:13]
	s_nop 1
	v_permlane32_swap_b32_e32 v168, v172
	v_permlane32_swap_b32_e32 v169, v173
	v_permlane32_swap_b32_e32 v170, v174
	v_permlane32_swap_b32_e32 v171, v175
	v_add_f32_e32 v168, v168, v172
	v_add_f32_e32 v169, v169, v173
	v_add_f32_e32 v170, v170, v174
	v_add_f32_e32 v171, v171, v175
	v_cndmask_b32_e64 v216, v170, v168, s[26:27]
	v_cndmask_b32_e64 v218, v168, v170, s[26:27]
	v_cndmask_b32_e64 v217, v171, v169, s[26:27]
	v_cndmask_b32_e64 v219, v169, v171, s[26:27]
	ds_bpermute_b32 v220, v212, v216
	ds_bpermute_b32 v221, v212, v217
	s_waitcnt lgkmcnt(0)
	v_add_f32_e32 v218, v220, v218
	v_add_f32_e32 v219, v221, v219
	v_cndmask_b32_e64 v216, v219, v218, s[28:29]
	v_cndmask_b32_e64 v217, v218, v219, s[28:29]
	s_nop 1
	v_add_f32_dpp v222, v216, v217 row_ror:8 row_mask:0xf bank_mask:0xf
	ds_bpermute_b32 v220, v213, v222
	s_waitcnt lgkmcnt(0)
	v_add_f32_e32 v222, v220, v222
	s_nop 1
	v_add_f32_dpp v223, v222, v222 quad_perm:[2,3,0,1] row_mask:0xf bank_mask:0xf
	s_nop 1
	v_add_f32_dpp v222, v223, v223 quad_perm:[1,0,3,2] row_mask:0xf bank_mask:0xf
	ds_bpermute_b32 v220, v214, v222
	s_mov_b32 s30, 0xff00
	s_mov_b32 s31, 0x0
	s_waitcnt lgkmcnt(0)
	v_cndmask_b32_e64 v179, v179, v220, s[30:31]
	s_waitcnt vmcnt(15)
	v_cvt_pk_f32_fp8_e32 v[184:185], v0
	v_cvt_pk_f32_fp8_sdwa v[186:187], v0 src0_sel:WORD_1
	v_cvt_pk_f32_fp8_e32 v[188:189], v1
	v_cvt_pk_f32_fp8_sdwa v[190:191], v1 src0_sel:WORD_1
	v_pk_mul_f32 v[200:201], v[64:65], v[184:185]
	v_cvt_pk_f32_fp8_e32 v[192:193], v2
	v_pk_mul_f32 v[202:203], v[66:67], v[186:187]
	v_cvt_pk_f32_fp8_sdwa v[194:195], v2 src0_sel:WORD_1
	v_pk_fma_f32 v[200:201], v[68:69], v[188:189], v[200:201]
	v_cvt_pk_f32_fp8_e32 v[196:197], v3
	v_pk_fma_f32 v[202:203], v[70:71], v[190:191], v[202:203]
	v_cvt_pk_f32_fp8_sdwa v[198:199], v3 src0_sel:WORD_1
	v_pk_fma_f32 v[200:201], v[72:73], v[192:193], v[200:201]
	v_pk_fma_f32 v[202:203], v[74:75], v[194:195], v[202:203]
	v_pk_fma_f32 v[200:201], v[76:77], v[196:197], v[200:201]
	v_pk_fma_f32 v[202:203], v[78:79], v[198:199], v[202:203]
	v_pk_add_f32 v[200:201], v[200:201], v[202:203]
	v_add_f32_e32 v160, v200, v201
	v_readlane_b32 s22, v112, 24
	s_lshl_b32 s22, s22, 10
	v_add_u32_e32 v204, s22, v208
	global_load_dwordx4 v[0:3], v204, s[12:13]
	s_waitcnt vmcnt(15)
	v_cvt_pk_f32_fp8_e32 v[184:185], v4
	v_cvt_pk_f32_fp8_sdwa v[186:187], v4 src0_sel:WORD_1
	v_cvt_pk_f32_fp8_e32 v[188:189], v5
	v_cvt_pk_f32_fp8_sdwa v[190:191], v5 src0_sel:WORD_1
	v_pk_mul_f32 v[200:201], v[80:81], v[184:185]
	v_cvt_pk_f32_fp8_e32 v[192:193], v6
	v_pk_mul_f32 v[202:203], v[82:83], v[186:187]
	v_cvt_pk_f32_fp8_sdwa v[194:195], v6 src0_sel:WORD_1
	v_pk_fma_f32 v[200:201], v[84:85], v[188:189], v[200:201]
	v_cvt_pk_f32_fp8_e32 v[196:197], v7
	v_pk_fma_f32 v[202:203], v[86:87], v[190:191], v[202:203]
	v_cvt_pk_f32_fp8_sdwa v[198:199], v7 src0_sel:WORD_1
	v_pk_fma_f32 v[200:201], v[88:89], v[192:193], v[200:201]
	v_pk_fma_f32 v[202:203], v[90:91], v[194:195], v[202:203]
	v_pk_fma_f32 v[200:201], v[92:93], v[196:197], v[200:201]
	v_pk_fma_f32 v[202:203], v[94:95], v[198:199], v[202:203]
	v_pk_add_f32 v[200:201], v[200:201], v[202:203]
	v_add_f32_e32 v168, v200, v201
	v_readlane_b32 s23, v120, 24
	s_lshl_b32 s23, s23, 10
	v_add_u32_e32 v205, s23, v208
	global_load_dwordx4 v[4:7], v205, s[12:13]
	s_waitcnt vmcnt(15)
	v_cvt_pk_f32_fp8_e32 v[184:185], v8
	v_cvt_pk_f32_fp8_sdwa v[186:187], v8 src0_sel:WORD_1
	v_cvt_pk_f32_fp8_e32 v[188:189], v9
	v_cvt_pk_f32_fp8_sdwa v[190:191], v9 src0_sel:WORD_1
	v_pk_mul_f32 v[200:201], v[64:65], v[184:185]
	v_cvt_pk_f32_fp8_e32 v[192:193], v10
	v_pk_mul_f32 v[202:203], v[66:67], v[186:187]
	v_cvt_pk_f32_fp8_sdwa v[194:195], v10 src0_sel:WORD_1
	v_pk_fma_f32 v[200:201], v[68:69], v[188:189], v[200:201]
	v_cvt_pk_f32_fp8_e32 v[196:197], v11
	v_pk_fma_f32 v[202:203], v[70:71], v[190:191], v[202:203]
	v_cvt_pk_f32_fp8_sdwa v[198:199], v11 src0_sel:WORD_1
	v_pk_fma_f32 v[200:201], v[72:73], v[192:193], v[200:201]
	v_pk_fma_f32 v[202:203], v[74:75], v[194:195], v[202:203]
	v_pk_fma_f32 v[200:201], v[76:77], v[196:197], v[200:201]
	v_pk_fma_f32 v[202:203], v[78:79], v[198:199], v[202:203]
	v_pk_add_f32 v[200:201], v[200:201], v[202:203]
	v_add_f32_e32 v161, v200, v201
	v_readlane_b32 s24, v112, 25
	s_lshl_b32 s24, s24, 10
	v_add_u32_e32 v206, s24, v208
	global_load_dwordx4 v[8:11], v206, s[12:13]
	s_waitcnt vmcnt(15)
	v_cvt_pk_f32_fp8_e32 v[184:185], v12
	v_cvt_pk_f32_fp8_sdwa v[186:187], v12 src0_sel:WORD_1
	v_cvt_pk_f32_fp8_e32 v[188:189], v13
	v_cvt_pk_f32_fp8_sdwa v[190:191], v13 src0_sel:WORD_1
	v_pk_mul_f32 v[200:201], v[80:81], v[184:185]
	v_cvt_pk_f32_fp8_e32 v[192:193], v14
	v_pk_mul_f32 v[202:203], v[82:83], v[186:187]
	v_cvt_pk_f32_fp8_sdwa v[194:195], v14 src0_sel:WORD_1
	v_pk_fma_f32 v[200:201], v[84:85], v[188:189], v[200:201]
	v_cvt_pk_f32_fp8_e32 v[196:197], v15
	v_pk_fma_f32 v[202:203], v[86:87], v[190:191], v[202:203]
	v_cvt_pk_f32_fp8_sdwa v[198:199], v15 src0_sel:WORD_1
	v_pk_fma_f32 v[200:201], v[88:89], v[192:193], v[200:201]
	v_pk_fma_f32 v[202:203], v[90:91], v[194:195], v[202:203]
	v_pk_fma_f32 v[200:201], v[92:93], v[196:197], v[200:201]
	v_pk_fma_f32 v[202:203], v[94:95], v[198:199], v[202:203]
	v_pk_add_f32 v[200:201], v[200:201], v[202:203]
	v_add_f32_e32 v169, v200, v201
	v_readlane_b32 s25, v120, 25
	s_lshl_b32 s25, s25, 10
	v_add_u32_e32 v207, s25, v208
	global_load_dwordx4 v[12:15], v207, s[12:13]
	s_waitcnt vmcnt(15)
	v_cvt_pk_f32_fp8_e32 v[184:185], v16
	v_cvt_pk_f32_fp8_sdwa v[186:187], v16 src0_sel:WORD_1
	v_cvt_pk_f32_fp8_e32 v[188:189], v17
	v_cvt_pk_f32_fp8_sdwa v[190:191], v17 src0_sel:WORD_1
	v_pk_mul_f32 v[200:201], v[64:65], v[184:185]
	v_cvt_pk_f32_fp8_e32 v[192:193], v18
	v_pk_mul_f32 v[202:203], v[66:67], v[186:187]
	v_cvt_pk_f32_fp8_sdwa v[194:195], v18 src0_sel:WORD_1
	v_pk_fma_f32 v[200:201], v[68:69], v[188:189], v[200:201]
	v_cvt_pk_f32_fp8_e32 v[196:197], v19
	v_pk_fma_f32 v[202:203], v[70:71], v[190:191], v[202:203]
	v_cvt_pk_f32_fp8_sdwa v[198:199], v19 src0_sel:WORD_1
	v_pk_fma_f32 v[200:201], v[72:73], v[192:193], v[200:201]
	v_pk_fma_f32 v[202:203], v[74:75], v[194:195], v[202:203]
	v_pk_fma_f32 v[200:201], v[76:77], v[196:197], v[200:201]
	v_pk_fma_f32 v[202:203], v[78:79], v[198:199], v[202:203]
	v_pk_add_f32 v[200:201], v[200:201], v[202:203]
	v_add_f32_e32 v162, v200, v201
	v_readlane_b32 s22, v112, 26
	s_lshl_b32 s22, s22, 10
	v_add_u32_e32 v204, s22, v208
	global_load_dwordx4 v[16:19], v204, s[12:13]
	s_waitcnt vmcnt(15)
	v_cvt_pk_f32_fp8_e32 v[184:185], v20
	v_cvt_pk_f32_fp8_sdwa v[186:187], v20 src0_sel:WORD_1
	v_cvt_pk_f32_fp8_e32 v[188:189], v21
	v_cvt_pk_f32_fp8_sdwa v[190:191], v21 src0_sel:WORD_1
	v_pk_mul_f32 v[200:201], v[80:81], v[184:185]
	v_cvt_pk_f32_fp8_e32 v[192:193], v22
	v_pk_mul_f32 v[202:203], v[82:83], v[186:187]
	v_cvt_pk_f32_fp8_sdwa v[194:195], v22 src0_sel:WORD_1
	v_pk_fma_f32 v[200:201], v[84:85], v[188:189], v[200:201]
	v_cvt_pk_f32_fp8_e32 v[196:197], v23
	v_pk_fma_f32 v[202:203], v[86:87], v[190:191], v[202:203]
	v_cvt_pk_f32_fp8_sdwa v[198:199], v23 src0_sel:WORD_1
	v_pk_fma_f32 v[200:201], v[88:89], v[192:193], v[200:201]
	v_pk_fma_f32 v[202:203], v[90:91], v[194:195], v[202:203]
	v_pk_fma_f32 v[200:201], v[92:93], v[196:197], v[200:201]
	v_pk_fma_f32 v[202:203], v[94:95], v[198:199], v[202:203]
	v_pk_add_f32 v[200:201], v[200:201], v[202:203]
	v_add_f32_e32 v170, v200, v201
	v_readlane_b32 s23, v120, 26
	s_lshl_b32 s23, s23, 10
	v_add_u32_e32 v205, s23, v208
	global_load_dwordx4 v[20:23], v205, s[12:13]
	s_waitcnt vmcnt(15)
	v_cvt_pk_f32_fp8_e32 v[184:185], v24
	v_cvt_pk_f32_fp8_sdwa v[186:187], v24 src0_sel:WORD_1
	v_cvt_pk_f32_fp8_e32 v[188:189], v25
	v_cvt_pk_f32_fp8_sdwa v[190:191], v25 src0_sel:WORD_1
	v_pk_mul_f32 v[200:201], v[64:65], v[184:185]
	v_cvt_pk_f32_fp8_e32 v[192:193], v26
	v_pk_mul_f32 v[202:203], v[66:67], v[186:187]
	v_cvt_pk_f32_fp8_sdwa v[194:195], v26 src0_sel:WORD_1
	v_pk_fma_f32 v[200:201], v[68:69], v[188:189], v[200:201]
	v_cvt_pk_f32_fp8_e32 v[196:197], v27
	v_pk_fma_f32 v[202:203], v[70:71], v[190:191], v[202:203]
	v_cvt_pk_f32_fp8_sdwa v[198:199], v27 src0_sel:WORD_1
	v_pk_fma_f32 v[200:201], v[72:73], v[192:193], v[200:201]
	v_pk_fma_f32 v[202:203], v[74:75], v[194:195], v[202:203]
	v_pk_fma_f32 v[200:201], v[76:77], v[196:197], v[200:201]
	v_pk_fma_f32 v[202:203], v[78:79], v[198:199], v[202:203]
	v_pk_add_f32 v[200:201], v[200:201], v[202:203]
	v_add_f32_e32 v163, v200, v201
	v_readlane_b32 s24, v112, 27
	s_lshl_b32 s24, s24, 10
	v_add_u32_e32 v206, s24, v208
	global_load_dwordx4 v[24:27], v206, s[12:13]
	s_waitcnt vmcnt(15)
	v_cvt_pk_f32_fp8_e32 v[184:185], v28
	v_cvt_pk_f32_fp8_sdwa v[186:187], v28 src0_sel:WORD_1
	v_cvt_pk_f32_fp8_e32 v[188:189], v29
	v_cvt_pk_f32_fp8_sdwa v[190:191], v29 src0_sel:WORD_1
	v_pk_mul_f32 v[200:201], v[80:81], v[184:185]
	v_cvt_pk_f32_fp8_e32 v[192:193], v30
	v_pk_mul_f32 v[202:203], v[82:83], v[186:187]
	v_cvt_pk_f32_fp8_sdwa v[194:195], v30 src0_sel:WORD_1
	v_pk_fma_f32 v[200:201], v[84:85], v[188:189], v[200:201]
	v_cvt_pk_f32_fp8_e32 v[196:197], v31
	v_pk_fma_f32 v[202:203], v[86:87], v[190:191], v[202:203]
	v_cvt_pk_f32_fp8_sdwa v[198:199], v31 src0_sel:WORD_1
	v_pk_fma_f32 v[200:201], v[88:89], v[192:193], v[200:201]
	v_pk_fma_f32 v[202:203], v[90:91], v[194:195], v[202:203]
	v_pk_fma_f32 v[200:201], v[92:93], v[196:197], v[200:201]
	v_pk_fma_f32 v[202:203], v[94:95], v[198:199], v[202:203]
	v_pk_add_f32 v[200:201], v[200:201], v[202:203]
	v_add_f32_e32 v171, v200, v201
	v_readlane_b32 s25, v120, 27
	s_lshl_b32 s25, s25, 10
	v_add_u32_e32 v207, s25, v208
	global_load_dwordx4 v[28:31], v207, s[12:13]
	s_waitcnt vmcnt(15)
	v_cvt_pk_f32_fp8_e32 v[184:185], v32
	v_cvt_pk_f32_fp8_sdwa v[186:187], v32 src0_sel:WORD_1
	v_cvt_pk_f32_fp8_e32 v[188:189], v33
	v_cvt_pk_f32_fp8_sdwa v[190:191], v33 src0_sel:WORD_1
	v_pk_mul_f32 v[200:201], v[64:65], v[184:185]
	v_cvt_pk_f32_fp8_e32 v[192:193], v34
	v_pk_mul_f32 v[202:203], v[66:67], v[186:187]
	v_cvt_pk_f32_fp8_sdwa v[194:195], v34 src0_sel:WORD_1
	v_pk_fma_f32 v[200:201], v[68:69], v[188:189], v[200:201]
	v_cvt_pk_f32_fp8_e32 v[196:197], v35
	v_pk_fma_f32 v[202:203], v[70:71], v[190:191], v[202:203]
	v_cvt_pk_f32_fp8_sdwa v[198:199], v35 src0_sel:WORD_1
	v_pk_fma_f32 v[200:201], v[72:73], v[192:193], v[200:201]
	v_pk_fma_f32 v[202:203], v[74:75], v[194:195], v[202:203]
	v_pk_fma_f32 v[200:201], v[76:77], v[196:197], v[200:201]
	v_pk_fma_f32 v[202:203], v[78:79], v[198:199], v[202:203]
	v_pk_add_f32 v[200:201], v[200:201], v[202:203]
	v_add_f32_e32 v164, v200, v201
	v_readlane_b32 s22, v112, 28
	s_lshl_b32 s22, s22, 10
	v_add_u32_e32 v204, s22, v208
	global_load_dwordx4 v[32:35], v204, s[12:13]
	s_waitcnt vmcnt(15)
	v_cvt_pk_f32_fp8_e32 v[184:185], v36
	v_cvt_pk_f32_fp8_sdwa v[186:187], v36 src0_sel:WORD_1
	v_cvt_pk_f32_fp8_e32 v[188:189], v37
	v_cvt_pk_f32_fp8_sdwa v[190:191], v37 src0_sel:WORD_1
	v_pk_mul_f32 v[200:201], v[80:81], v[184:185]
	v_cvt_pk_f32_fp8_e32 v[192:193], v38
	v_pk_mul_f32 v[202:203], v[82:83], v[186:187]
	v_cvt_pk_f32_fp8_sdwa v[194:195], v38 src0_sel:WORD_1
	v_pk_fma_f32 v[200:201], v[84:85], v[188:189], v[200:201]
	v_cvt_pk_f32_fp8_e32 v[196:197], v39
	v_pk_fma_f32 v[202:203], v[86:87], v[190:191], v[202:203]
	v_cvt_pk_f32_fp8_sdwa v[198:199], v39 src0_sel:WORD_1
	v_pk_fma_f32 v[200:201], v[88:89], v[192:193], v[200:201]
	v_pk_fma_f32 v[202:203], v[90:91], v[194:195], v[202:203]
	v_pk_fma_f32 v[200:201], v[92:93], v[196:197], v[200:201]
	v_pk_fma_f32 v[202:203], v[94:95], v[198:199], v[202:203]
	v_pk_add_f32 v[200:201], v[200:201], v[202:203]
	v_add_f32_e32 v172, v200, v201
	v_readlane_b32 s23, v120, 28
	s_lshl_b32 s23, s23, 10
	v_add_u32_e32 v205, s23, v208
	global_load_dwordx4 v[36:39], v205, s[12:13]
	s_waitcnt vmcnt(15)
	v_cvt_pk_f32_fp8_e32 v[184:185], v40
	v_cvt_pk_f32_fp8_sdwa v[186:187], v40 src0_sel:WORD_1
	v_cvt_pk_f32_fp8_e32 v[188:189], v41
	v_cvt_pk_f32_fp8_sdwa v[190:191], v41 src0_sel:WORD_1
	v_pk_mul_f32 v[200:201], v[64:65], v[184:185]
	v_cvt_pk_f32_fp8_e32 v[192:193], v42
	v_pk_mul_f32 v[202:203], v[66:67], v[186:187]
	v_cvt_pk_f32_fp8_sdwa v[194:195], v42 src0_sel:WORD_1
	v_pk_fma_f32 v[200:201], v[68:69], v[188:189], v[200:201]
	v_cvt_pk_f32_fp8_e32 v[196:197], v43
	v_pk_fma_f32 v[202:203], v[70:71], v[190:191], v[202:203]
	v_cvt_pk_f32_fp8_sdwa v[198:199], v43 src0_sel:WORD_1
	v_pk_fma_f32 v[200:201], v[72:73], v[192:193], v[200:201]
	v_pk_fma_f32 v[202:203], v[74:75], v[194:195], v[202:203]
	v_pk_fma_f32 v[200:201], v[76:77], v[196:197], v[200:201]
	v_pk_fma_f32 v[202:203], v[78:79], v[198:199], v[202:203]
	v_pk_add_f32 v[200:201], v[200:201], v[202:203]
	v_add_f32_e32 v165, v200, v201
	v_readlane_b32 s24, v112, 29
	s_lshl_b32 s24, s24, 10
	v_add_u32_e32 v206, s24, v208
	global_load_dwordx4 v[40:43], v206, s[12:13]
	s_waitcnt vmcnt(15)
	v_cvt_pk_f32_fp8_e32 v[184:185], v44
	v_cvt_pk_f32_fp8_sdwa v[186:187], v44 src0_sel:WORD_1
	v_cvt_pk_f32_fp8_e32 v[188:189], v45
	v_cvt_pk_f32_fp8_sdwa v[190:191], v45 src0_sel:WORD_1
	v_pk_mul_f32 v[200:201], v[80:81], v[184:185]
	v_cvt_pk_f32_fp8_e32 v[192:193], v46
	v_pk_mul_f32 v[202:203], v[82:83], v[186:187]
	v_cvt_pk_f32_fp8_sdwa v[194:195], v46 src0_sel:WORD_1
	v_pk_fma_f32 v[200:201], v[84:85], v[188:189], v[200:201]
	v_cvt_pk_f32_fp8_e32 v[196:197], v47
	v_pk_fma_f32 v[202:203], v[86:87], v[190:191], v[202:203]
	v_cvt_pk_f32_fp8_sdwa v[198:199], v47 src0_sel:WORD_1
	v_pk_fma_f32 v[200:201], v[88:89], v[192:193], v[200:201]
	v_pk_fma_f32 v[202:203], v[90:91], v[194:195], v[202:203]
	v_pk_fma_f32 v[200:201], v[92:93], v[196:197], v[200:201]
	v_pk_fma_f32 v[202:203], v[94:95], v[198:199], v[202:203]
	v_pk_add_f32 v[200:201], v[200:201], v[202:203]
	v_add_f32_e32 v173, v200, v201
	v_readlane_b32 s25, v120, 29
	s_lshl_b32 s25, s25, 10
	v_add_u32_e32 v207, s25, v208
	global_load_dwordx4 v[44:47], v207, s[12:13]
	s_waitcnt vmcnt(15)
	v_cvt_pk_f32_fp8_e32 v[184:185], v48
	v_cvt_pk_f32_fp8_sdwa v[186:187], v48 src0_sel:WORD_1
	v_cvt_pk_f32_fp8_e32 v[188:189], v49
	v_cvt_pk_f32_fp8_sdwa v[190:191], v49 src0_sel:WORD_1
	v_pk_mul_f32 v[200:201], v[64:65], v[184:185]
	v_cvt_pk_f32_fp8_e32 v[192:193], v50
	v_pk_mul_f32 v[202:203], v[66:67], v[186:187]
	v_cvt_pk_f32_fp8_sdwa v[194:195], v50 src0_sel:WORD_1
	v_pk_fma_f32 v[200:201], v[68:69], v[188:189], v[200:201]
	v_cvt_pk_f32_fp8_e32 v[196:197], v51
	v_pk_fma_f32 v[202:203], v[70:71], v[190:191], v[202:203]
	v_cvt_pk_f32_fp8_sdwa v[198:199], v51 src0_sel:WORD_1
	v_pk_fma_f32 v[200:201], v[72:73], v[192:193], v[200:201]
	v_pk_fma_f32 v[202:203], v[74:75], v[194:195], v[202:203]
	v_pk_fma_f32 v[200:201], v[76:77], v[196:197], v[200:201]
	v_pk_fma_f32 v[202:203], v[78:79], v[198:199], v[202:203]
	v_pk_add_f32 v[200:201], v[200:201], v[202:203]
	v_add_f32_e32 v166, v200, v201
	v_readlane_b32 s22, v112, 30
	s_lshl_b32 s22, s22, 10
	v_add_u32_e32 v204, s22, v208
	global_load_dwordx4 v[48:51], v204, s[12:13]
	s_waitcnt vmcnt(15)
	v_cvt_pk_f32_fp8_e32 v[184:185], v52
	v_cvt_pk_f32_fp8_sdwa v[186:187], v52 src0_sel:WORD_1
	v_cvt_pk_f32_fp8_e32 v[188:189], v53
	v_cvt_pk_f32_fp8_sdwa v[190:191], v53 src0_sel:WORD_1
	v_pk_mul_f32 v[200:201], v[80:81], v[184:185]
	v_cvt_pk_f32_fp8_e32 v[192:193], v54
	v_pk_mul_f32 v[202:203], v[82:83], v[186:187]
	v_cvt_pk_f32_fp8_sdwa v[194:195], v54 src0_sel:WORD_1
	v_pk_fma_f32 v[200:201], v[84:85], v[188:189], v[200:201]
	v_cvt_pk_f32_fp8_e32 v[196:197], v55
	v_pk_fma_f32 v[202:203], v[86:87], v[190:191], v[202:203]
	v_cvt_pk_f32_fp8_sdwa v[198:199], v55 src0_sel:WORD_1
	v_pk_fma_f32 v[200:201], v[88:89], v[192:193], v[200:201]
	v_pk_fma_f32 v[202:203], v[90:91], v[194:195], v[202:203]
	v_pk_fma_f32 v[200:201], v[92:93], v[196:197], v[200:201]
	v_pk_fma_f32 v[202:203], v[94:95], v[198:199], v[202:203]
	v_pk_add_f32 v[200:201], v[200:201], v[202:203]
	v_add_f32_e32 v174, v200, v201
	v_readlane_b32 s23, v120, 30
	s_lshl_b32 s23, s23, 10
	v_add_u32_e32 v205, s23, v208
	global_load_dwordx4 v[52:55], v205, s[12:13]
	s_waitcnt vmcnt(15)
	v_cvt_pk_f32_fp8_e32 v[184:185], v56
	v_cvt_pk_f32_fp8_sdwa v[186:187], v56 src0_sel:WORD_1
	v_cvt_pk_f32_fp8_e32 v[188:189], v57
	v_cvt_pk_f32_fp8_sdwa v[190:191], v57 src0_sel:WORD_1
	v_pk_mul_f32 v[200:201], v[64:65], v[184:185]
	v_cvt_pk_f32_fp8_e32 v[192:193], v58
	v_pk_mul_f32 v[202:203], v[66:67], v[186:187]
	v_cvt_pk_f32_fp8_sdwa v[194:195], v58 src0_sel:WORD_1
	v_pk_fma_f32 v[200:201], v[68:69], v[188:189], v[200:201]
	v_cvt_pk_f32_fp8_e32 v[196:197], v59
	v_pk_fma_f32 v[202:203], v[70:71], v[190:191], v[202:203]
	v_cvt_pk_f32_fp8_sdwa v[198:199], v59 src0_sel:WORD_1
	v_pk_fma_f32 v[200:201], v[72:73], v[192:193], v[200:201]
	v_pk_fma_f32 v[202:203], v[74:75], v[194:195], v[202:203]
	v_pk_fma_f32 v[200:201], v[76:77], v[196:197], v[200:201]
	v_pk_fma_f32 v[202:203], v[78:79], v[198:199], v[202:203]
	v_pk_add_f32 v[200:201], v[200:201], v[202:203]
	v_add_f32_e32 v167, v200, v201
	v_readlane_b32 s24, v112, 31
	s_lshl_b32 s24, s24, 10
	v_add_u32_e32 v206, s24, v208
	global_load_dwordx4 v[56:59], v206, s[12:13]
	s_nop 1
	v_permlane32_swap_b32_e32 v160, v164
	v_permlane32_swap_b32_e32 v161, v165
	v_permlane32_swap_b32_e32 v162, v166
	v_permlane32_swap_b32_e32 v163, v167
	v_add_f32_e32 v160, v160, v164
	v_add_f32_e32 v161, v161, v165
	v_add_f32_e32 v162, v162, v166
	v_add_f32_e32 v163, v163, v167
	v_cndmask_b32_e64 v216, v162, v160, s[26:27]
	v_cndmask_b32_e64 v218, v160, v162, s[26:27]
	v_cndmask_b32_e64 v217, v163, v161, s[26:27]
	v_cndmask_b32_e64 v219, v161, v163, s[26:27]
	ds_bpermute_b32 v220, v212, v216
	ds_bpermute_b32 v221, v212, v217
	s_waitcnt lgkmcnt(0)
	v_add_f32_e32 v218, v220, v218
	v_add_f32_e32 v219, v221, v219
	v_cndmask_b32_e64 v216, v219, v218, s[28:29]
	v_cndmask_b32_e64 v217, v218, v219, s[28:29]
	s_nop 1
	v_add_f32_dpp v222, v216, v217 row_ror:8 row_mask:0xf bank_mask:0xf
	ds_bpermute_b32 v220, v213, v222
	s_waitcnt lgkmcnt(0)
	v_add_f32_e32 v222, v220, v222
	s_nop 1
	v_add_f32_dpp v223, v222, v222 quad_perm:[2,3,0,1] row_mask:0xf bank_mask:0xf
	s_nop 1
	v_add_f32_dpp v222, v223, v223 quad_perm:[1,0,3,2] row_mask:0xf bank_mask:0xf
	ds_bpermute_b32 v220, v214, v222
	s_mov_b32 s30, 0xff0000
	s_mov_b32 s31, 0x0
	s_waitcnt lgkmcnt(0)
	v_cndmask_b32_e64 v176, v176, v220, s[30:31]
	s_waitcnt vmcnt(15)
	v_cvt_pk_f32_fp8_e32 v[184:185], v60
	v_cvt_pk_f32_fp8_sdwa v[186:187], v60 src0_sel:WORD_1
	v_cvt_pk_f32_fp8_e32 v[188:189], v61
	v_cvt_pk_f32_fp8_sdwa v[190:191], v61 src0_sel:WORD_1
	v_pk_mul_f32 v[200:201], v[80:81], v[184:185]
	v_cvt_pk_f32_fp8_e32 v[192:193], v62
	v_pk_mul_f32 v[202:203], v[82:83], v[186:187]
	v_cvt_pk_f32_fp8_sdwa v[194:195], v62 src0_sel:WORD_1
	v_pk_fma_f32 v[200:201], v[84:85], v[188:189], v[200:201]
	v_cvt_pk_f32_fp8_e32 v[196:197], v63
	v_pk_fma_f32 v[202:203], v[86:87], v[190:191], v[202:203]
	v_cvt_pk_f32_fp8_sdwa v[198:199], v63 src0_sel:WORD_1
	v_pk_fma_f32 v[200:201], v[88:89], v[192:193], v[200:201]
	v_pk_fma_f32 v[202:203], v[90:91], v[194:195], v[202:203]
	v_pk_fma_f32 v[200:201], v[92:93], v[196:197], v[200:201]
	v_pk_fma_f32 v[202:203], v[94:95], v[198:199], v[202:203]
	v_pk_add_f32 v[200:201], v[200:201], v[202:203]
	v_add_f32_e32 v175, v200, v201
	v_readlane_b32 s25, v120, 31
	s_lshl_b32 s25, s25, 10
	v_add_u32_e32 v207, s25, v208
	global_load_dwordx4 v[60:63], v207, s[12:13]
	s_nop 1
	v_permlane32_swap_b32_e32 v168, v172
	v_permlane32_swap_b32_e32 v169, v173
	v_permlane32_swap_b32_e32 v170, v174
	v_permlane32_swap_b32_e32 v171, v175
	v_add_f32_e32 v168, v168, v172
	v_add_f32_e32 v169, v169, v173
	v_add_f32_e32 v170, v170, v174
	v_add_f32_e32 v171, v171, v175
	v_cndmask_b32_e64 v216, v170, v168, s[26:27]
	v_cndmask_b32_e64 v218, v168, v170, s[26:27]
	v_cndmask_b32_e64 v217, v171, v169, s[26:27]
	v_cndmask_b32_e64 v219, v169, v171, s[26:27]
	ds_bpermute_b32 v220, v212, v216
	ds_bpermute_b32 v221, v212, v217
	s_waitcnt lgkmcnt(0)
	v_add_f32_e32 v218, v220, v218
	v_add_f32_e32 v219, v221, v219
	v_cndmask_b32_e64 v216, v219, v218, s[28:29]
	v_cndmask_b32_e64 v217, v218, v219, s[28:29]
	s_nop 1
	v_add_f32_dpp v222, v216, v217 row_ror:8 row_mask:0xf bank_mask:0xf
	ds_bpermute_b32 v220, v213, v222
	s_waitcnt lgkmcnt(0)
	v_add_f32_e32 v222, v220, v222
	s_nop 1
	v_add_f32_dpp v223, v222, v222 quad_perm:[2,3,0,1] row_mask:0xf bank_mask:0xf
	s_nop 1
	v_add_f32_dpp v222, v223, v223 quad_perm:[1,0,3,2] row_mask:0xf bank_mask:0xf
	ds_bpermute_b32 v220, v214, v222
	s_mov_b32 s30, 0xff0000
	s_mov_b32 s31, 0x0
	s_waitcnt lgkmcnt(0)
	v_cndmask_b32_e64 v179, v179, v220, s[30:31]
	s_waitcnt vmcnt(15)
	v_cvt_pk_f32_fp8_e32 v[184:185], v0
	v_cvt_pk_f32_fp8_sdwa v[186:187], v0 src0_sel:WORD_1
	v_cvt_pk_f32_fp8_e32 v[188:189], v1
	v_cvt_pk_f32_fp8_sdwa v[190:191], v1 src0_sel:WORD_1
	v_pk_mul_f32 v[200:201], v[64:65], v[184:185]
	v_cvt_pk_f32_fp8_e32 v[192:193], v2
	v_pk_mul_f32 v[202:203], v[66:67], v[186:187]
	v_cvt_pk_f32_fp8_sdwa v[194:195], v2 src0_sel:WORD_1
	v_pk_fma_f32 v[200:201], v[68:69], v[188:189], v[200:201]
	v_cvt_pk_f32_fp8_e32 v[196:197], v3
	v_pk_fma_f32 v[202:203], v[70:71], v[190:191], v[202:203]
	v_cvt_pk_f32_fp8_sdwa v[198:199], v3 src0_sel:WORD_1
	v_pk_fma_f32 v[200:201], v[72:73], v[192:193], v[200:201]
	v_pk_fma_f32 v[202:203], v[74:75], v[194:195], v[202:203]
	v_pk_fma_f32 v[200:201], v[76:77], v[196:197], v[200:201]
	v_pk_fma_f32 v[202:203], v[78:79], v[198:199], v[202:203]
	v_pk_add_f32 v[200:201], v[200:201], v[202:203]
	v_add_f32_e32 v160, v200, v201
	v_readlane_b32 s22, v112, 32
	s_lshl_b32 s22, s22, 10
	v_add_u32_e32 v204, s22, v208
	global_load_dwordx4 v[0:3], v204, s[12:13]
	s_waitcnt vmcnt(15)
	v_cvt_pk_f32_fp8_e32 v[184:185], v4
	v_cvt_pk_f32_fp8_sdwa v[186:187], v4 src0_sel:WORD_1
	v_cvt_pk_f32_fp8_e32 v[188:189], v5
	v_cvt_pk_f32_fp8_sdwa v[190:191], v5 src0_sel:WORD_1
	v_pk_mul_f32 v[200:201], v[80:81], v[184:185]
	v_cvt_pk_f32_fp8_e32 v[192:193], v6
	v_pk_mul_f32 v[202:203], v[82:83], v[186:187]
	v_cvt_pk_f32_fp8_sdwa v[194:195], v6 src0_sel:WORD_1
	v_pk_fma_f32 v[200:201], v[84:85], v[188:189], v[200:201]
	v_cvt_pk_f32_fp8_e32 v[196:197], v7
	v_pk_fma_f32 v[202:203], v[86:87], v[190:191], v[202:203]
	v_cvt_pk_f32_fp8_sdwa v[198:199], v7 src0_sel:WORD_1
	v_pk_fma_f32 v[200:201], v[88:89], v[192:193], v[200:201]
	v_pk_fma_f32 v[202:203], v[90:91], v[194:195], v[202:203]
	v_pk_fma_f32 v[200:201], v[92:93], v[196:197], v[200:201]
	v_pk_fma_f32 v[202:203], v[94:95], v[198:199], v[202:203]
	v_pk_add_f32 v[200:201], v[200:201], v[202:203]
	v_add_f32_e32 v168, v200, v201
	v_readlane_b32 s23, v120, 32
	s_lshl_b32 s23, s23, 10
	v_add_u32_e32 v205, s23, v208
	global_load_dwordx4 v[4:7], v205, s[12:13]
	s_waitcnt vmcnt(15)
	v_cvt_pk_f32_fp8_e32 v[184:185], v8
	v_cvt_pk_f32_fp8_sdwa v[186:187], v8 src0_sel:WORD_1
	v_cvt_pk_f32_fp8_e32 v[188:189], v9
	v_cvt_pk_f32_fp8_sdwa v[190:191], v9 src0_sel:WORD_1
	v_pk_mul_f32 v[200:201], v[64:65], v[184:185]
	v_cvt_pk_f32_fp8_e32 v[192:193], v10
	v_pk_mul_f32 v[202:203], v[66:67], v[186:187]
	v_cvt_pk_f32_fp8_sdwa v[194:195], v10 src0_sel:WORD_1
	v_pk_fma_f32 v[200:201], v[68:69], v[188:189], v[200:201]
	v_cvt_pk_f32_fp8_e32 v[196:197], v11
	v_pk_fma_f32 v[202:203], v[70:71], v[190:191], v[202:203]
	v_cvt_pk_f32_fp8_sdwa v[198:199], v11 src0_sel:WORD_1
	v_pk_fma_f32 v[200:201], v[72:73], v[192:193], v[200:201]
	v_pk_fma_f32 v[202:203], v[74:75], v[194:195], v[202:203]
	v_pk_fma_f32 v[200:201], v[76:77], v[196:197], v[200:201]
	v_pk_fma_f32 v[202:203], v[78:79], v[198:199], v[202:203]
	v_pk_add_f32 v[200:201], v[200:201], v[202:203]
	v_add_f32_e32 v161, v200, v201
	v_readlane_b32 s24, v112, 33
	s_lshl_b32 s24, s24, 10
	v_add_u32_e32 v206, s24, v208
	global_load_dwordx4 v[8:11], v206, s[12:13]
	s_waitcnt vmcnt(15)
	v_cvt_pk_f32_fp8_e32 v[184:185], v12
	v_cvt_pk_f32_fp8_sdwa v[186:187], v12 src0_sel:WORD_1
	v_cvt_pk_f32_fp8_e32 v[188:189], v13
	v_cvt_pk_f32_fp8_sdwa v[190:191], v13 src0_sel:WORD_1
	v_pk_mul_f32 v[200:201], v[80:81], v[184:185]
	v_cvt_pk_f32_fp8_e32 v[192:193], v14
	v_pk_mul_f32 v[202:203], v[82:83], v[186:187]
	v_cvt_pk_f32_fp8_sdwa v[194:195], v14 src0_sel:WORD_1
	v_pk_fma_f32 v[200:201], v[84:85], v[188:189], v[200:201]
	v_cvt_pk_f32_fp8_e32 v[196:197], v15
	v_pk_fma_f32 v[202:203], v[86:87], v[190:191], v[202:203]
	v_cvt_pk_f32_fp8_sdwa v[198:199], v15 src0_sel:WORD_1
	v_pk_fma_f32 v[200:201], v[88:89], v[192:193], v[200:201]
	v_pk_fma_f32 v[202:203], v[90:91], v[194:195], v[202:203]
	v_pk_fma_f32 v[200:201], v[92:93], v[196:197], v[200:201]
	v_pk_fma_f32 v[202:203], v[94:95], v[198:199], v[202:203]
	v_pk_add_f32 v[200:201], v[200:201], v[202:203]
	v_add_f32_e32 v169, v200, v201
	v_readlane_b32 s25, v120, 33
	s_lshl_b32 s25, s25, 10
	v_add_u32_e32 v207, s25, v208
	global_load_dwordx4 v[12:15], v207, s[12:13]
	s_waitcnt vmcnt(15)
	v_cvt_pk_f32_fp8_e32 v[184:185], v16
	v_cvt_pk_f32_fp8_sdwa v[186:187], v16 src0_sel:WORD_1
	v_cvt_pk_f32_fp8_e32 v[188:189], v17
	v_cvt_pk_f32_fp8_sdwa v[190:191], v17 src0_sel:WORD_1
	v_pk_mul_f32 v[200:201], v[64:65], v[184:185]
	v_cvt_pk_f32_fp8_e32 v[192:193], v18
	v_pk_mul_f32 v[202:203], v[66:67], v[186:187]
	v_cvt_pk_f32_fp8_sdwa v[194:195], v18 src0_sel:WORD_1
	v_pk_fma_f32 v[200:201], v[68:69], v[188:189], v[200:201]
	v_cvt_pk_f32_fp8_e32 v[196:197], v19
	v_pk_fma_f32 v[202:203], v[70:71], v[190:191], v[202:203]
	v_cvt_pk_f32_fp8_sdwa v[198:199], v19 src0_sel:WORD_1
	v_pk_fma_f32 v[200:201], v[72:73], v[192:193], v[200:201]
	v_pk_fma_f32 v[202:203], v[74:75], v[194:195], v[202:203]
	v_pk_fma_f32 v[200:201], v[76:77], v[196:197], v[200:201]
	v_pk_fma_f32 v[202:203], v[78:79], v[198:199], v[202:203]
	v_pk_add_f32 v[200:201], v[200:201], v[202:203]
	v_add_f32_e32 v162, v200, v201
	v_readlane_b32 s22, v112, 34
	s_lshl_b32 s22, s22, 10
	v_add_u32_e32 v204, s22, v208
	global_load_dwordx4 v[16:19], v204, s[12:13]
	s_waitcnt vmcnt(15)
	v_cvt_pk_f32_fp8_e32 v[184:185], v20
	v_cvt_pk_f32_fp8_sdwa v[186:187], v20 src0_sel:WORD_1
	v_cvt_pk_f32_fp8_e32 v[188:189], v21
	v_cvt_pk_f32_fp8_sdwa v[190:191], v21 src0_sel:WORD_1
	v_pk_mul_f32 v[200:201], v[80:81], v[184:185]
	v_cvt_pk_f32_fp8_e32 v[192:193], v22
	v_pk_mul_f32 v[202:203], v[82:83], v[186:187]
	v_cvt_pk_f32_fp8_sdwa v[194:195], v22 src0_sel:WORD_1
	v_pk_fma_f32 v[200:201], v[84:85], v[188:189], v[200:201]
	v_cvt_pk_f32_fp8_e32 v[196:197], v23
	v_pk_fma_f32 v[202:203], v[86:87], v[190:191], v[202:203]
	v_cvt_pk_f32_fp8_sdwa v[198:199], v23 src0_sel:WORD_1
	v_pk_fma_f32 v[200:201], v[88:89], v[192:193], v[200:201]
	v_pk_fma_f32 v[202:203], v[90:91], v[194:195], v[202:203]
	v_pk_fma_f32 v[200:201], v[92:93], v[196:197], v[200:201]
	v_pk_fma_f32 v[202:203], v[94:95], v[198:199], v[202:203]
	v_pk_add_f32 v[200:201], v[200:201], v[202:203]
	v_add_f32_e32 v170, v200, v201
	v_readlane_b32 s23, v120, 34
	s_lshl_b32 s23, s23, 10
	v_add_u32_e32 v205, s23, v208
	global_load_dwordx4 v[20:23], v205, s[12:13]
	s_waitcnt vmcnt(15)
	v_cvt_pk_f32_fp8_e32 v[184:185], v24
	v_cvt_pk_f32_fp8_sdwa v[186:187], v24 src0_sel:WORD_1
	v_cvt_pk_f32_fp8_e32 v[188:189], v25
	v_cvt_pk_f32_fp8_sdwa v[190:191], v25 src0_sel:WORD_1
	v_pk_mul_f32 v[200:201], v[64:65], v[184:185]
	v_cvt_pk_f32_fp8_e32 v[192:193], v26
	v_pk_mul_f32 v[202:203], v[66:67], v[186:187]
	v_cvt_pk_f32_fp8_sdwa v[194:195], v26 src0_sel:WORD_1
	v_pk_fma_f32 v[200:201], v[68:69], v[188:189], v[200:201]
	v_cvt_pk_f32_fp8_e32 v[196:197], v27
	v_pk_fma_f32 v[202:203], v[70:71], v[190:191], v[202:203]
	v_cvt_pk_f32_fp8_sdwa v[198:199], v27 src0_sel:WORD_1
	v_pk_fma_f32 v[200:201], v[72:73], v[192:193], v[200:201]
	v_pk_fma_f32 v[202:203], v[74:75], v[194:195], v[202:203]
	v_pk_fma_f32 v[200:201], v[76:77], v[196:197], v[200:201]
	v_pk_fma_f32 v[202:203], v[78:79], v[198:199], v[202:203]
	v_pk_add_f32 v[200:201], v[200:201], v[202:203]
	v_add_f32_e32 v163, v200, v201
	v_readlane_b32 s24, v112, 35
	s_lshl_b32 s24, s24, 10
	v_add_u32_e32 v206, s24, v208
	global_load_dwordx4 v[24:27], v206, s[12:13]
	s_waitcnt vmcnt(15)
	v_cvt_pk_f32_fp8_e32 v[184:185], v28
	v_cvt_pk_f32_fp8_sdwa v[186:187], v28 src0_sel:WORD_1
	v_cvt_pk_f32_fp8_e32 v[188:189], v29
	v_cvt_pk_f32_fp8_sdwa v[190:191], v29 src0_sel:WORD_1
	v_pk_mul_f32 v[200:201], v[80:81], v[184:185]
	v_cvt_pk_f32_fp8_e32 v[192:193], v30
	v_pk_mul_f32 v[202:203], v[82:83], v[186:187]
	v_cvt_pk_f32_fp8_sdwa v[194:195], v30 src0_sel:WORD_1
	v_pk_fma_f32 v[200:201], v[84:85], v[188:189], v[200:201]
	v_cvt_pk_f32_fp8_e32 v[196:197], v31
	v_pk_fma_f32 v[202:203], v[86:87], v[190:191], v[202:203]
	v_cvt_pk_f32_fp8_sdwa v[198:199], v31 src0_sel:WORD_1
	v_pk_fma_f32 v[200:201], v[88:89], v[192:193], v[200:201]
	v_pk_fma_f32 v[202:203], v[90:91], v[194:195], v[202:203]
	v_pk_fma_f32 v[200:201], v[92:93], v[196:197], v[200:201]
	v_pk_fma_f32 v[202:203], v[94:95], v[198:199], v[202:203]
	v_pk_add_f32 v[200:201], v[200:201], v[202:203]
	v_add_f32_e32 v171, v200, v201
	v_readlane_b32 s25, v120, 35
	s_lshl_b32 s25, s25, 10
	v_add_u32_e32 v207, s25, v208
	global_load_dwordx4 v[28:31], v207, s[12:13]
	s_waitcnt vmcnt(15)
	v_cvt_pk_f32_fp8_e32 v[184:185], v32
	v_cvt_pk_f32_fp8_sdwa v[186:187], v32 src0_sel:WORD_1
	v_cvt_pk_f32_fp8_e32 v[188:189], v33
	v_cvt_pk_f32_fp8_sdwa v[190:191], v33 src0_sel:WORD_1
	v_pk_mul_f32 v[200:201], v[64:65], v[184:185]
	v_cvt_pk_f32_fp8_e32 v[192:193], v34
	v_pk_mul_f32 v[202:203], v[66:67], v[186:187]
	v_cvt_pk_f32_fp8_sdwa v[194:195], v34 src0_sel:WORD_1
	v_pk_fma_f32 v[200:201], v[68:69], v[188:189], v[200:201]
	v_cvt_pk_f32_fp8_e32 v[196:197], v35
	v_pk_fma_f32 v[202:203], v[70:71], v[190:191], v[202:203]
	v_cvt_pk_f32_fp8_sdwa v[198:199], v35 src0_sel:WORD_1
	v_pk_fma_f32 v[200:201], v[72:73], v[192:193], v[200:201]
	v_pk_fma_f32 v[202:203], v[74:75], v[194:195], v[202:203]
	v_pk_fma_f32 v[200:201], v[76:77], v[196:197], v[200:201]
	v_pk_fma_f32 v[202:203], v[78:79], v[198:199], v[202:203]
	v_pk_add_f32 v[200:201], v[200:201], v[202:203]
	v_add_f32_e32 v164, v200, v201
	v_readlane_b32 s22, v112, 36
	s_lshl_b32 s22, s22, 10
	v_add_u32_e32 v204, s22, v208
	global_load_dwordx4 v[32:35], v204, s[12:13]
	s_waitcnt vmcnt(15)
	v_cvt_pk_f32_fp8_e32 v[184:185], v36
	v_cvt_pk_f32_fp8_sdwa v[186:187], v36 src0_sel:WORD_1
	v_cvt_pk_f32_fp8_e32 v[188:189], v37
	v_cvt_pk_f32_fp8_sdwa v[190:191], v37 src0_sel:WORD_1
	v_pk_mul_f32 v[200:201], v[80:81], v[184:185]
	v_cvt_pk_f32_fp8_e32 v[192:193], v38
	v_pk_mul_f32 v[202:203], v[82:83], v[186:187]
	v_cvt_pk_f32_fp8_sdwa v[194:195], v38 src0_sel:WORD_1
	v_pk_fma_f32 v[200:201], v[84:85], v[188:189], v[200:201]
	v_cvt_pk_f32_fp8_e32 v[196:197], v39
	v_pk_fma_f32 v[202:203], v[86:87], v[190:191], v[202:203]
	v_cvt_pk_f32_fp8_sdwa v[198:199], v39 src0_sel:WORD_1
	v_pk_fma_f32 v[200:201], v[88:89], v[192:193], v[200:201]
	v_pk_fma_f32 v[202:203], v[90:91], v[194:195], v[202:203]
	v_pk_fma_f32 v[200:201], v[92:93], v[196:197], v[200:201]
	v_pk_fma_f32 v[202:203], v[94:95], v[198:199], v[202:203]
	v_pk_add_f32 v[200:201], v[200:201], v[202:203]
	v_add_f32_e32 v172, v200, v201
	v_readlane_b32 s23, v120, 36
	s_lshl_b32 s23, s23, 10
	v_add_u32_e32 v205, s23, v208
	global_load_dwordx4 v[36:39], v205, s[12:13]
	s_waitcnt vmcnt(15)
	v_cvt_pk_f32_fp8_e32 v[184:185], v40
	v_cvt_pk_f32_fp8_sdwa v[186:187], v40 src0_sel:WORD_1
	v_cvt_pk_f32_fp8_e32 v[188:189], v41
	v_cvt_pk_f32_fp8_sdwa v[190:191], v41 src0_sel:WORD_1
	v_pk_mul_f32 v[200:201], v[64:65], v[184:185]
	v_cvt_pk_f32_fp8_e32 v[192:193], v42
	v_pk_mul_f32 v[202:203], v[66:67], v[186:187]
	v_cvt_pk_f32_fp8_sdwa v[194:195], v42 src0_sel:WORD_1
	v_pk_fma_f32 v[200:201], v[68:69], v[188:189], v[200:201]
	v_cvt_pk_f32_fp8_e32 v[196:197], v43
	v_pk_fma_f32 v[202:203], v[70:71], v[190:191], v[202:203]
	v_cvt_pk_f32_fp8_sdwa v[198:199], v43 src0_sel:WORD_1
	v_pk_fma_f32 v[200:201], v[72:73], v[192:193], v[200:201]
	v_pk_fma_f32 v[202:203], v[74:75], v[194:195], v[202:203]
	v_pk_fma_f32 v[200:201], v[76:77], v[196:197], v[200:201]
	v_pk_fma_f32 v[202:203], v[78:79], v[198:199], v[202:203]
	v_pk_add_f32 v[200:201], v[200:201], v[202:203]
	v_add_f32_e32 v165, v200, v201
	v_readlane_b32 s24, v112, 37
	s_lshl_b32 s24, s24, 10
	v_add_u32_e32 v206, s24, v208
	global_load_dwordx4 v[40:43], v206, s[12:13]
	s_waitcnt vmcnt(15)
	v_cvt_pk_f32_fp8_e32 v[184:185], v44
	v_cvt_pk_f32_fp8_sdwa v[186:187], v44 src0_sel:WORD_1
	v_cvt_pk_f32_fp8_e32 v[188:189], v45
	v_cvt_pk_f32_fp8_sdwa v[190:191], v45 src0_sel:WORD_1
	v_pk_mul_f32 v[200:201], v[80:81], v[184:185]
	v_cvt_pk_f32_fp8_e32 v[192:193], v46
	v_pk_mul_f32 v[202:203], v[82:83], v[186:187]
	v_cvt_pk_f32_fp8_sdwa v[194:195], v46 src0_sel:WORD_1
	v_pk_fma_f32 v[200:201], v[84:85], v[188:189], v[200:201]
	v_cvt_pk_f32_fp8_e32 v[196:197], v47
	v_pk_fma_f32 v[202:203], v[86:87], v[190:191], v[202:203]
	v_cvt_pk_f32_fp8_sdwa v[198:199], v47 src0_sel:WORD_1
	v_pk_fma_f32 v[200:201], v[88:89], v[192:193], v[200:201]
	v_pk_fma_f32 v[202:203], v[90:91], v[194:195], v[202:203]
	v_pk_fma_f32 v[200:201], v[92:93], v[196:197], v[200:201]
	v_pk_fma_f32 v[202:203], v[94:95], v[198:199], v[202:203]
	v_pk_add_f32 v[200:201], v[200:201], v[202:203]
	v_add_f32_e32 v173, v200, v201
	v_readlane_b32 s25, v120, 37
	s_lshl_b32 s25, s25, 10
	v_add_u32_e32 v207, s25, v208
	global_load_dwordx4 v[44:47], v207, s[12:13]
	s_waitcnt vmcnt(15)
	v_cvt_pk_f32_fp8_e32 v[184:185], v48
	v_cvt_pk_f32_fp8_sdwa v[186:187], v48 src0_sel:WORD_1
	v_cvt_pk_f32_fp8_e32 v[188:189], v49
	v_cvt_pk_f32_fp8_sdwa v[190:191], v49 src0_sel:WORD_1
	v_pk_mul_f32 v[200:201], v[64:65], v[184:185]
	v_cvt_pk_f32_fp8_e32 v[192:193], v50
	v_pk_mul_f32 v[202:203], v[66:67], v[186:187]
	v_cvt_pk_f32_fp8_sdwa v[194:195], v50 src0_sel:WORD_1
	v_pk_fma_f32 v[200:201], v[68:69], v[188:189], v[200:201]
	v_cvt_pk_f32_fp8_e32 v[196:197], v51
	v_pk_fma_f32 v[202:203], v[70:71], v[190:191], v[202:203]
	v_cvt_pk_f32_fp8_sdwa v[198:199], v51 src0_sel:WORD_1
	v_pk_fma_f32 v[200:201], v[72:73], v[192:193], v[200:201]
	v_pk_fma_f32 v[202:203], v[74:75], v[194:195], v[202:203]
	v_pk_fma_f32 v[200:201], v[76:77], v[196:197], v[200:201]
	v_pk_fma_f32 v[202:203], v[78:79], v[198:199], v[202:203]
	v_pk_add_f32 v[200:201], v[200:201], v[202:203]
	v_add_f32_e32 v166, v200, v201
	v_readlane_b32 s22, v112, 38
	s_lshl_b32 s22, s22, 10
	v_add_u32_e32 v204, s22, v208
	global_load_dwordx4 v[48:51], v204, s[12:13]
	s_waitcnt vmcnt(15)
	v_cvt_pk_f32_fp8_e32 v[184:185], v52
	v_cvt_pk_f32_fp8_sdwa v[186:187], v52 src0_sel:WORD_1
	v_cvt_pk_f32_fp8_e32 v[188:189], v53
	v_cvt_pk_f32_fp8_sdwa v[190:191], v53 src0_sel:WORD_1
	v_pk_mul_f32 v[200:201], v[80:81], v[184:185]
	v_cvt_pk_f32_fp8_e32 v[192:193], v54
	v_pk_mul_f32 v[202:203], v[82:83], v[186:187]
	v_cvt_pk_f32_fp8_sdwa v[194:195], v54 src0_sel:WORD_1
	v_pk_fma_f32 v[200:201], v[84:85], v[188:189], v[200:201]
	v_cvt_pk_f32_fp8_e32 v[196:197], v55
	v_pk_fma_f32 v[202:203], v[86:87], v[190:191], v[202:203]
	v_cvt_pk_f32_fp8_sdwa v[198:199], v55 src0_sel:WORD_1
	v_pk_fma_f32 v[200:201], v[88:89], v[192:193], v[200:201]
	v_pk_fma_f32 v[202:203], v[90:91], v[194:195], v[202:203]
	v_pk_fma_f32 v[200:201], v[92:93], v[196:197], v[200:201]
	v_pk_fma_f32 v[202:203], v[94:95], v[198:199], v[202:203]
	v_pk_add_f32 v[200:201], v[200:201], v[202:203]
	v_add_f32_e32 v174, v200, v201
	v_readlane_b32 s23, v120, 38
	s_lshl_b32 s23, s23, 10
	v_add_u32_e32 v205, s23, v208
	global_load_dwordx4 v[52:55], v205, s[12:13]
	s_waitcnt vmcnt(15)
	v_cvt_pk_f32_fp8_e32 v[184:185], v56
	v_cvt_pk_f32_fp8_sdwa v[186:187], v56 src0_sel:WORD_1
	v_cvt_pk_f32_fp8_e32 v[188:189], v57
	v_cvt_pk_f32_fp8_sdwa v[190:191], v57 src0_sel:WORD_1
	v_pk_mul_f32 v[200:201], v[64:65], v[184:185]
	v_cvt_pk_f32_fp8_e32 v[192:193], v58
	v_pk_mul_f32 v[202:203], v[66:67], v[186:187]
	v_cvt_pk_f32_fp8_sdwa v[194:195], v58 src0_sel:WORD_1
	v_pk_fma_f32 v[200:201], v[68:69], v[188:189], v[200:201]
	v_cvt_pk_f32_fp8_e32 v[196:197], v59
	v_pk_fma_f32 v[202:203], v[70:71], v[190:191], v[202:203]
	v_cvt_pk_f32_fp8_sdwa v[198:199], v59 src0_sel:WORD_1
	v_pk_fma_f32 v[200:201], v[72:73], v[192:193], v[200:201]
	v_pk_fma_f32 v[202:203], v[74:75], v[194:195], v[202:203]
	v_pk_fma_f32 v[200:201], v[76:77], v[196:197], v[200:201]
	v_pk_fma_f32 v[202:203], v[78:79], v[198:199], v[202:203]
	v_pk_add_f32 v[200:201], v[200:201], v[202:203]
	v_add_f32_e32 v167, v200, v201
	v_readlane_b32 s24, v112, 39
	s_lshl_b32 s24, s24, 10
	v_add_u32_e32 v206, s24, v208
	global_load_dwordx4 v[56:59], v206, s[12:13]
	s_nop 1
	v_permlane32_swap_b32_e32 v160, v164
	v_permlane32_swap_b32_e32 v161, v165
	v_permlane32_swap_b32_e32 v162, v166
	v_permlane32_swap_b32_e32 v163, v167
	v_add_f32_e32 v160, v160, v164
	v_add_f32_e32 v161, v161, v165
	v_add_f32_e32 v162, v162, v166
	v_add_f32_e32 v163, v163, v167
	v_cndmask_b32_e64 v216, v162, v160, s[26:27]
	v_cndmask_b32_e64 v218, v160, v162, s[26:27]
	v_cndmask_b32_e64 v217, v163, v161, s[26:27]
	v_cndmask_b32_e64 v219, v161, v163, s[26:27]
	ds_bpermute_b32 v220, v212, v216
	ds_bpermute_b32 v221, v212, v217
	s_waitcnt lgkmcnt(0)
	v_add_f32_e32 v218, v220, v218
	v_add_f32_e32 v219, v221, v219
	v_cndmask_b32_e64 v216, v219, v218, s[28:29]
	v_cndmask_b32_e64 v217, v218, v219, s[28:29]
	s_nop 1
	v_add_f32_dpp v222, v216, v217 row_ror:8 row_mask:0xf bank_mask:0xf
	ds_bpermute_b32 v220, v213, v222
	s_waitcnt lgkmcnt(0)
	v_add_f32_e32 v222, v220, v222
	s_nop 1
	v_add_f32_dpp v223, v222, v222 quad_perm:[2,3,0,1] row_mask:0xf bank_mask:0xf
	s_nop 1
	v_add_f32_dpp v222, v223, v223 quad_perm:[1,0,3,2] row_mask:0xf bank_mask:0xf
	ds_bpermute_b32 v220, v214, v222
	s_mov_b32 s30, 0xff000000
	s_mov_b32 s31, 0x0
	s_waitcnt lgkmcnt(0)
	v_cndmask_b32_e64 v176, v176, v220, s[30:31]
	s_waitcnt vmcnt(15)
	v_cvt_pk_f32_fp8_e32 v[184:185], v60
	v_cvt_pk_f32_fp8_sdwa v[186:187], v60 src0_sel:WORD_1
	v_cvt_pk_f32_fp8_e32 v[188:189], v61
	v_cvt_pk_f32_fp8_sdwa v[190:191], v61 src0_sel:WORD_1
	v_pk_mul_f32 v[200:201], v[80:81], v[184:185]
	v_cvt_pk_f32_fp8_e32 v[192:193], v62
	v_pk_mul_f32 v[202:203], v[82:83], v[186:187]
	v_cvt_pk_f32_fp8_sdwa v[194:195], v62 src0_sel:WORD_1
	v_pk_fma_f32 v[200:201], v[84:85], v[188:189], v[200:201]
	v_cvt_pk_f32_fp8_e32 v[196:197], v63
	v_pk_fma_f32 v[202:203], v[86:87], v[190:191], v[202:203]
	v_cvt_pk_f32_fp8_sdwa v[198:199], v63 src0_sel:WORD_1
	v_pk_fma_f32 v[200:201], v[88:89], v[192:193], v[200:201]
	v_pk_fma_f32 v[202:203], v[90:91], v[194:195], v[202:203]
	v_pk_fma_f32 v[200:201], v[92:93], v[196:197], v[200:201]
	v_pk_fma_f32 v[202:203], v[94:95], v[198:199], v[202:203]
	v_pk_add_f32 v[200:201], v[200:201], v[202:203]
	v_add_f32_e32 v175, v200, v201
	v_readlane_b32 s25, v120, 39
	s_lshl_b32 s25, s25, 10
	v_add_u32_e32 v207, s25, v208
	global_load_dwordx4 v[60:63], v207, s[12:13]
	s_nop 1
	v_permlane32_swap_b32_e32 v168, v172
	v_permlane32_swap_b32_e32 v169, v173
	v_permlane32_swap_b32_e32 v170, v174
	v_permlane32_swap_b32_e32 v171, v175
	v_add_f32_e32 v168, v168, v172
	v_add_f32_e32 v169, v169, v173
	v_add_f32_e32 v170, v170, v174
	v_add_f32_e32 v171, v171, v175
	v_cndmask_b32_e64 v216, v170, v168, s[26:27]
	v_cndmask_b32_e64 v218, v168, v170, s[26:27]
	v_cndmask_b32_e64 v217, v171, v169, s[26:27]
	v_cndmask_b32_e64 v219, v169, v171, s[26:27]
	ds_bpermute_b32 v220, v212, v216
	ds_bpermute_b32 v221, v212, v217
	s_waitcnt lgkmcnt(0)
	v_add_f32_e32 v218, v220, v218
	v_add_f32_e32 v219, v221, v219
	v_cndmask_b32_e64 v216, v219, v218, s[28:29]
	v_cndmask_b32_e64 v217, v218, v219, s[28:29]
	s_nop 1
	v_add_f32_dpp v222, v216, v217 row_ror:8 row_mask:0xf bank_mask:0xf
	ds_bpermute_b32 v220, v213, v222
	s_waitcnt lgkmcnt(0)
	v_add_f32_e32 v222, v220, v222
	s_nop 1
	v_add_f32_dpp v223, v222, v222 quad_perm:[2,3,0,1] row_mask:0xf bank_mask:0xf
	s_nop 1
	v_add_f32_dpp v222, v223, v223 quad_perm:[1,0,3,2] row_mask:0xf bank_mask:0xf
	ds_bpermute_b32 v220, v214, v222
	s_mov_b32 s30, 0xff000000
	s_mov_b32 s31, 0x0
	s_waitcnt lgkmcnt(0)
	v_cndmask_b32_e64 v179, v179, v220, s[30:31]
	s_waitcnt vmcnt(15)
	v_cvt_pk_f32_fp8_e32 v[184:185], v0
	v_cvt_pk_f32_fp8_sdwa v[186:187], v0 src0_sel:WORD_1
	v_cvt_pk_f32_fp8_e32 v[188:189], v1
	v_cvt_pk_f32_fp8_sdwa v[190:191], v1 src0_sel:WORD_1
	v_pk_mul_f32 v[200:201], v[64:65], v[184:185]
	v_cvt_pk_f32_fp8_e32 v[192:193], v2
	v_pk_mul_f32 v[202:203], v[66:67], v[186:187]
	v_cvt_pk_f32_fp8_sdwa v[194:195], v2 src0_sel:WORD_1
	v_pk_fma_f32 v[200:201], v[68:69], v[188:189], v[200:201]
	v_cvt_pk_f32_fp8_e32 v[196:197], v3
	v_pk_fma_f32 v[202:203], v[70:71], v[190:191], v[202:203]
	v_cvt_pk_f32_fp8_sdwa v[198:199], v3 src0_sel:WORD_1
	v_pk_fma_f32 v[200:201], v[72:73], v[192:193], v[200:201]
	v_pk_fma_f32 v[202:203], v[74:75], v[194:195], v[202:203]
	v_pk_fma_f32 v[200:201], v[76:77], v[196:197], v[200:201]
	v_pk_fma_f32 v[202:203], v[78:79], v[198:199], v[202:203]
	v_pk_add_f32 v[200:201], v[200:201], v[202:203]
	v_add_f32_e32 v160, v200, v201
	v_readlane_b32 s22, v112, 40
	s_lshl_b32 s22, s22, 10
	v_add_u32_e32 v204, s22, v208
	global_load_dwordx4 v[0:3], v204, s[12:13]
	s_waitcnt vmcnt(15)
	v_cvt_pk_f32_fp8_e32 v[184:185], v4
	v_cvt_pk_f32_fp8_sdwa v[186:187], v4 src0_sel:WORD_1
	v_cvt_pk_f32_fp8_e32 v[188:189], v5
	v_cvt_pk_f32_fp8_sdwa v[190:191], v5 src0_sel:WORD_1
	v_pk_mul_f32 v[200:201], v[80:81], v[184:185]
	v_cvt_pk_f32_fp8_e32 v[192:193], v6
	v_pk_mul_f32 v[202:203], v[82:83], v[186:187]
	v_cvt_pk_f32_fp8_sdwa v[194:195], v6 src0_sel:WORD_1
	v_pk_fma_f32 v[200:201], v[84:85], v[188:189], v[200:201]
	v_cvt_pk_f32_fp8_e32 v[196:197], v7
	v_pk_fma_f32 v[202:203], v[86:87], v[190:191], v[202:203]
	v_cvt_pk_f32_fp8_sdwa v[198:199], v7 src0_sel:WORD_1
	v_pk_fma_f32 v[200:201], v[88:89], v[192:193], v[200:201]
	v_pk_fma_f32 v[202:203], v[90:91], v[194:195], v[202:203]
	v_pk_fma_f32 v[200:201], v[92:93], v[196:197], v[200:201]
	v_pk_fma_f32 v[202:203], v[94:95], v[198:199], v[202:203]
	v_pk_add_f32 v[200:201], v[200:201], v[202:203]
	v_add_f32_e32 v168, v200, v201
	v_readlane_b32 s23, v120, 40
	s_lshl_b32 s23, s23, 10
	v_add_u32_e32 v205, s23, v208
	global_load_dwordx4 v[4:7], v205, s[12:13]
	s_waitcnt vmcnt(15)
	v_cvt_pk_f32_fp8_e32 v[184:185], v8
	v_cvt_pk_f32_fp8_sdwa v[186:187], v8 src0_sel:WORD_1
	v_cvt_pk_f32_fp8_e32 v[188:189], v9
	v_cvt_pk_f32_fp8_sdwa v[190:191], v9 src0_sel:WORD_1
	v_pk_mul_f32 v[200:201], v[64:65], v[184:185]
	v_cvt_pk_f32_fp8_e32 v[192:193], v10
	v_pk_mul_f32 v[202:203], v[66:67], v[186:187]
	v_cvt_pk_f32_fp8_sdwa v[194:195], v10 src0_sel:WORD_1
	v_pk_fma_f32 v[200:201], v[68:69], v[188:189], v[200:201]
	v_cvt_pk_f32_fp8_e32 v[196:197], v11
	v_pk_fma_f32 v[202:203], v[70:71], v[190:191], v[202:203]
	v_cvt_pk_f32_fp8_sdwa v[198:199], v11 src0_sel:WORD_1
	v_pk_fma_f32 v[200:201], v[72:73], v[192:193], v[200:201]
	v_pk_fma_f32 v[202:203], v[74:75], v[194:195], v[202:203]
	v_pk_fma_f32 v[200:201], v[76:77], v[196:197], v[200:201]
	v_pk_fma_f32 v[202:203], v[78:79], v[198:199], v[202:203]
	v_pk_add_f32 v[200:201], v[200:201], v[202:203]
	v_add_f32_e32 v161, v200, v201
	v_readlane_b32 s24, v112, 41
	s_lshl_b32 s24, s24, 10
	v_add_u32_e32 v206, s24, v208
	global_load_dwordx4 v[8:11], v206, s[12:13]
	s_waitcnt vmcnt(15)
	v_cvt_pk_f32_fp8_e32 v[184:185], v12
	v_cvt_pk_f32_fp8_sdwa v[186:187], v12 src0_sel:WORD_1
	v_cvt_pk_f32_fp8_e32 v[188:189], v13
	v_cvt_pk_f32_fp8_sdwa v[190:191], v13 src0_sel:WORD_1
	v_pk_mul_f32 v[200:201], v[80:81], v[184:185]
	v_cvt_pk_f32_fp8_e32 v[192:193], v14
	v_pk_mul_f32 v[202:203], v[82:83], v[186:187]
	v_cvt_pk_f32_fp8_sdwa v[194:195], v14 src0_sel:WORD_1
	v_pk_fma_f32 v[200:201], v[84:85], v[188:189], v[200:201]
	v_cvt_pk_f32_fp8_e32 v[196:197], v15
	v_pk_fma_f32 v[202:203], v[86:87], v[190:191], v[202:203]
	v_cvt_pk_f32_fp8_sdwa v[198:199], v15 src0_sel:WORD_1
	v_pk_fma_f32 v[200:201], v[88:89], v[192:193], v[200:201]
	v_pk_fma_f32 v[202:203], v[90:91], v[194:195], v[202:203]
	v_pk_fma_f32 v[200:201], v[92:93], v[196:197], v[200:201]
	v_pk_fma_f32 v[202:203], v[94:95], v[198:199], v[202:203]
	v_pk_add_f32 v[200:201], v[200:201], v[202:203]
	v_add_f32_e32 v169, v200, v201
	v_readlane_b32 s25, v120, 41
	s_lshl_b32 s25, s25, 10
	v_add_u32_e32 v207, s25, v208
	global_load_dwordx4 v[12:15], v207, s[12:13]
	s_waitcnt vmcnt(15)
	v_cvt_pk_f32_fp8_e32 v[184:185], v16
	v_cvt_pk_f32_fp8_sdwa v[186:187], v16 src0_sel:WORD_1
	v_cvt_pk_f32_fp8_e32 v[188:189], v17
	v_cvt_pk_f32_fp8_sdwa v[190:191], v17 src0_sel:WORD_1
	v_pk_mul_f32 v[200:201], v[64:65], v[184:185]
	v_cvt_pk_f32_fp8_e32 v[192:193], v18
	v_pk_mul_f32 v[202:203], v[66:67], v[186:187]
	v_cvt_pk_f32_fp8_sdwa v[194:195], v18 src0_sel:WORD_1
	v_pk_fma_f32 v[200:201], v[68:69], v[188:189], v[200:201]
	v_cvt_pk_f32_fp8_e32 v[196:197], v19
	v_pk_fma_f32 v[202:203], v[70:71], v[190:191], v[202:203]
	v_cvt_pk_f32_fp8_sdwa v[198:199], v19 src0_sel:WORD_1
	v_pk_fma_f32 v[200:201], v[72:73], v[192:193], v[200:201]
	v_pk_fma_f32 v[202:203], v[74:75], v[194:195], v[202:203]
	v_pk_fma_f32 v[200:201], v[76:77], v[196:197], v[200:201]
	v_pk_fma_f32 v[202:203], v[78:79], v[198:199], v[202:203]
	v_pk_add_f32 v[200:201], v[200:201], v[202:203]
	v_add_f32_e32 v162, v200, v201
	v_readlane_b32 s22, v112, 42
	s_lshl_b32 s22, s22, 10
	v_add_u32_e32 v204, s22, v208
	global_load_dwordx4 v[16:19], v204, s[12:13]
	s_waitcnt vmcnt(15)
	v_cvt_pk_f32_fp8_e32 v[184:185], v20
	v_cvt_pk_f32_fp8_sdwa v[186:187], v20 src0_sel:WORD_1
	v_cvt_pk_f32_fp8_e32 v[188:189], v21
	v_cvt_pk_f32_fp8_sdwa v[190:191], v21 src0_sel:WORD_1
	v_pk_mul_f32 v[200:201], v[80:81], v[184:185]
	v_cvt_pk_f32_fp8_e32 v[192:193], v22
	v_pk_mul_f32 v[202:203], v[82:83], v[186:187]
	v_cvt_pk_f32_fp8_sdwa v[194:195], v22 src0_sel:WORD_1
	v_pk_fma_f32 v[200:201], v[84:85], v[188:189], v[200:201]
	v_cvt_pk_f32_fp8_e32 v[196:197], v23
	v_pk_fma_f32 v[202:203], v[86:87], v[190:191], v[202:203]
	v_cvt_pk_f32_fp8_sdwa v[198:199], v23 src0_sel:WORD_1
	v_pk_fma_f32 v[200:201], v[88:89], v[192:193], v[200:201]
	v_pk_fma_f32 v[202:203], v[90:91], v[194:195], v[202:203]
	v_pk_fma_f32 v[200:201], v[92:93], v[196:197], v[200:201]
	v_pk_fma_f32 v[202:203], v[94:95], v[198:199], v[202:203]
	v_pk_add_f32 v[200:201], v[200:201], v[202:203]
	v_add_f32_e32 v170, v200, v201
	v_readlane_b32 s23, v120, 42
	s_lshl_b32 s23, s23, 10
	v_add_u32_e32 v205, s23, v208
	global_load_dwordx4 v[20:23], v205, s[12:13]
	s_waitcnt vmcnt(15)
	v_cvt_pk_f32_fp8_e32 v[184:185], v24
	v_cvt_pk_f32_fp8_sdwa v[186:187], v24 src0_sel:WORD_1
	v_cvt_pk_f32_fp8_e32 v[188:189], v25
	v_cvt_pk_f32_fp8_sdwa v[190:191], v25 src0_sel:WORD_1
	v_pk_mul_f32 v[200:201], v[64:65], v[184:185]
	v_cvt_pk_f32_fp8_e32 v[192:193], v26
	v_pk_mul_f32 v[202:203], v[66:67], v[186:187]
	v_cvt_pk_f32_fp8_sdwa v[194:195], v26 src0_sel:WORD_1
	v_pk_fma_f32 v[200:201], v[68:69], v[188:189], v[200:201]
	v_cvt_pk_f32_fp8_e32 v[196:197], v27
	v_pk_fma_f32 v[202:203], v[70:71], v[190:191], v[202:203]
	v_cvt_pk_f32_fp8_sdwa v[198:199], v27 src0_sel:WORD_1
	v_pk_fma_f32 v[200:201], v[72:73], v[192:193], v[200:201]
	v_pk_fma_f32 v[202:203], v[74:75], v[194:195], v[202:203]
	v_pk_fma_f32 v[200:201], v[76:77], v[196:197], v[200:201]
	v_pk_fma_f32 v[202:203], v[78:79], v[198:199], v[202:203]
	v_pk_add_f32 v[200:201], v[200:201], v[202:203]
	v_add_f32_e32 v163, v200, v201
	v_readlane_b32 s24, v112, 43
	s_lshl_b32 s24, s24, 10
	v_add_u32_e32 v206, s24, v208
	global_load_dwordx4 v[24:27], v206, s[12:13]
	s_waitcnt vmcnt(15)
	v_cvt_pk_f32_fp8_e32 v[184:185], v28
	v_cvt_pk_f32_fp8_sdwa v[186:187], v28 src0_sel:WORD_1
	v_cvt_pk_f32_fp8_e32 v[188:189], v29
	v_cvt_pk_f32_fp8_sdwa v[190:191], v29 src0_sel:WORD_1
	v_pk_mul_f32 v[200:201], v[80:81], v[184:185]
	v_cvt_pk_f32_fp8_e32 v[192:193], v30
	v_pk_mul_f32 v[202:203], v[82:83], v[186:187]
	v_cvt_pk_f32_fp8_sdwa v[194:195], v30 src0_sel:WORD_1
	v_pk_fma_f32 v[200:201], v[84:85], v[188:189], v[200:201]
	v_cvt_pk_f32_fp8_e32 v[196:197], v31
	v_pk_fma_f32 v[202:203], v[86:87], v[190:191], v[202:203]
	v_cvt_pk_f32_fp8_sdwa v[198:199], v31 src0_sel:WORD_1
	v_pk_fma_f32 v[200:201], v[88:89], v[192:193], v[200:201]
	v_pk_fma_f32 v[202:203], v[90:91], v[194:195], v[202:203]
	v_pk_fma_f32 v[200:201], v[92:93], v[196:197], v[200:201]
	v_pk_fma_f32 v[202:203], v[94:95], v[198:199], v[202:203]
	v_pk_add_f32 v[200:201], v[200:201], v[202:203]
	v_add_f32_e32 v171, v200, v201
	v_readlane_b32 s25, v120, 43
	s_lshl_b32 s25, s25, 10
	v_add_u32_e32 v207, s25, v208
	global_load_dwordx4 v[28:31], v207, s[12:13]
	s_waitcnt vmcnt(15)
	v_cvt_pk_f32_fp8_e32 v[184:185], v32
	v_cvt_pk_f32_fp8_sdwa v[186:187], v32 src0_sel:WORD_1
	v_cvt_pk_f32_fp8_e32 v[188:189], v33
	v_cvt_pk_f32_fp8_sdwa v[190:191], v33 src0_sel:WORD_1
	v_pk_mul_f32 v[200:201], v[64:65], v[184:185]
	v_cvt_pk_f32_fp8_e32 v[192:193], v34
	v_pk_mul_f32 v[202:203], v[66:67], v[186:187]
	v_cvt_pk_f32_fp8_sdwa v[194:195], v34 src0_sel:WORD_1
	v_pk_fma_f32 v[200:201], v[68:69], v[188:189], v[200:201]
	v_cvt_pk_f32_fp8_e32 v[196:197], v35
	v_pk_fma_f32 v[202:203], v[70:71], v[190:191], v[202:203]
	v_cvt_pk_f32_fp8_sdwa v[198:199], v35 src0_sel:WORD_1
	v_pk_fma_f32 v[200:201], v[72:73], v[192:193], v[200:201]
	v_pk_fma_f32 v[202:203], v[74:75], v[194:195], v[202:203]
	v_pk_fma_f32 v[200:201], v[76:77], v[196:197], v[200:201]
	v_pk_fma_f32 v[202:203], v[78:79], v[198:199], v[202:203]
	v_pk_add_f32 v[200:201], v[200:201], v[202:203]
	v_add_f32_e32 v164, v200, v201
	v_readlane_b32 s22, v112, 44
	s_lshl_b32 s22, s22, 10
	v_add_u32_e32 v204, s22, v208
	global_load_dwordx4 v[32:35], v204, s[12:13]
	s_waitcnt vmcnt(15)
	v_cvt_pk_f32_fp8_e32 v[184:185], v36
	v_cvt_pk_f32_fp8_sdwa v[186:187], v36 src0_sel:WORD_1
	v_cvt_pk_f32_fp8_e32 v[188:189], v37
	v_cvt_pk_f32_fp8_sdwa v[190:191], v37 src0_sel:WORD_1
	v_pk_mul_f32 v[200:201], v[80:81], v[184:185]
	v_cvt_pk_f32_fp8_e32 v[192:193], v38
	v_pk_mul_f32 v[202:203], v[82:83], v[186:187]
	v_cvt_pk_f32_fp8_sdwa v[194:195], v38 src0_sel:WORD_1
	v_pk_fma_f32 v[200:201], v[84:85], v[188:189], v[200:201]
	v_cvt_pk_f32_fp8_e32 v[196:197], v39
	v_pk_fma_f32 v[202:203], v[86:87], v[190:191], v[202:203]
	v_cvt_pk_f32_fp8_sdwa v[198:199], v39 src0_sel:WORD_1
	v_pk_fma_f32 v[200:201], v[88:89], v[192:193], v[200:201]
	v_pk_fma_f32 v[202:203], v[90:91], v[194:195], v[202:203]
	v_pk_fma_f32 v[200:201], v[92:93], v[196:197], v[200:201]
	v_pk_fma_f32 v[202:203], v[94:95], v[198:199], v[202:203]
	v_pk_add_f32 v[200:201], v[200:201], v[202:203]
	v_add_f32_e32 v172, v200, v201
	v_readlane_b32 s23, v120, 44
	s_lshl_b32 s23, s23, 10
	v_add_u32_e32 v205, s23, v208
	global_load_dwordx4 v[36:39], v205, s[12:13]
	s_waitcnt vmcnt(15)
	v_cvt_pk_f32_fp8_e32 v[184:185], v40
	v_cvt_pk_f32_fp8_sdwa v[186:187], v40 src0_sel:WORD_1
	v_cvt_pk_f32_fp8_e32 v[188:189], v41
	v_cvt_pk_f32_fp8_sdwa v[190:191], v41 src0_sel:WORD_1
	v_pk_mul_f32 v[200:201], v[64:65], v[184:185]
	v_cvt_pk_f32_fp8_e32 v[192:193], v42
	v_pk_mul_f32 v[202:203], v[66:67], v[186:187]
	v_cvt_pk_f32_fp8_sdwa v[194:195], v42 src0_sel:WORD_1
	v_pk_fma_f32 v[200:201], v[68:69], v[188:189], v[200:201]
	v_cvt_pk_f32_fp8_e32 v[196:197], v43
	v_pk_fma_f32 v[202:203], v[70:71], v[190:191], v[202:203]
	v_cvt_pk_f32_fp8_sdwa v[198:199], v43 src0_sel:WORD_1
	v_pk_fma_f32 v[200:201], v[72:73], v[192:193], v[200:201]
	v_pk_fma_f32 v[202:203], v[74:75], v[194:195], v[202:203]
	v_pk_fma_f32 v[200:201], v[76:77], v[196:197], v[200:201]
	v_pk_fma_f32 v[202:203], v[78:79], v[198:199], v[202:203]
	v_pk_add_f32 v[200:201], v[200:201], v[202:203]
	v_add_f32_e32 v165, v200, v201
	v_readlane_b32 s24, v112, 45
	s_lshl_b32 s24, s24, 10
	v_add_u32_e32 v206, s24, v208
	global_load_dwordx4 v[40:43], v206, s[12:13]
	s_waitcnt vmcnt(15)
	v_cvt_pk_f32_fp8_e32 v[184:185], v44
	v_cvt_pk_f32_fp8_sdwa v[186:187], v44 src0_sel:WORD_1
	v_cvt_pk_f32_fp8_e32 v[188:189], v45
	v_cvt_pk_f32_fp8_sdwa v[190:191], v45 src0_sel:WORD_1
	v_pk_mul_f32 v[200:201], v[80:81], v[184:185]
	v_cvt_pk_f32_fp8_e32 v[192:193], v46
	v_pk_mul_f32 v[202:203], v[82:83], v[186:187]
	v_cvt_pk_f32_fp8_sdwa v[194:195], v46 src0_sel:WORD_1
	v_pk_fma_f32 v[200:201], v[84:85], v[188:189], v[200:201]
	v_cvt_pk_f32_fp8_e32 v[196:197], v47
	v_pk_fma_f32 v[202:203], v[86:87], v[190:191], v[202:203]
	v_cvt_pk_f32_fp8_sdwa v[198:199], v47 src0_sel:WORD_1
	v_pk_fma_f32 v[200:201], v[88:89], v[192:193], v[200:201]
	v_pk_fma_f32 v[202:203], v[90:91], v[194:195], v[202:203]
	v_pk_fma_f32 v[200:201], v[92:93], v[196:197], v[200:201]
	v_pk_fma_f32 v[202:203], v[94:95], v[198:199], v[202:203]
	v_pk_add_f32 v[200:201], v[200:201], v[202:203]
	v_add_f32_e32 v173, v200, v201
	v_readlane_b32 s25, v120, 45
	s_lshl_b32 s25, s25, 10
	v_add_u32_e32 v207, s25, v208
	global_load_dwordx4 v[44:47], v207, s[12:13]
	s_waitcnt vmcnt(15)
	v_cvt_pk_f32_fp8_e32 v[184:185], v48
	v_cvt_pk_f32_fp8_sdwa v[186:187], v48 src0_sel:WORD_1
	v_cvt_pk_f32_fp8_e32 v[188:189], v49
	v_cvt_pk_f32_fp8_sdwa v[190:191], v49 src0_sel:WORD_1
	v_pk_mul_f32 v[200:201], v[64:65], v[184:185]
	v_cvt_pk_f32_fp8_e32 v[192:193], v50
	v_pk_mul_f32 v[202:203], v[66:67], v[186:187]
	v_cvt_pk_f32_fp8_sdwa v[194:195], v50 src0_sel:WORD_1
	v_pk_fma_f32 v[200:201], v[68:69], v[188:189], v[200:201]
	v_cvt_pk_f32_fp8_e32 v[196:197], v51
	v_pk_fma_f32 v[202:203], v[70:71], v[190:191], v[202:203]
	v_cvt_pk_f32_fp8_sdwa v[198:199], v51 src0_sel:WORD_1
	v_pk_fma_f32 v[200:201], v[72:73], v[192:193], v[200:201]
	v_pk_fma_f32 v[202:203], v[74:75], v[194:195], v[202:203]
	v_pk_fma_f32 v[200:201], v[76:77], v[196:197], v[200:201]
	v_pk_fma_f32 v[202:203], v[78:79], v[198:199], v[202:203]
	v_pk_add_f32 v[200:201], v[200:201], v[202:203]
	v_add_f32_e32 v166, v200, v201
	v_readlane_b32 s22, v112, 46
	s_lshl_b32 s22, s22, 10
	v_add_u32_e32 v204, s22, v208
	global_load_dwordx4 v[48:51], v204, s[12:13]
	s_waitcnt vmcnt(15)
	v_cvt_pk_f32_fp8_e32 v[184:185], v52
	v_cvt_pk_f32_fp8_sdwa v[186:187], v52 src0_sel:WORD_1
	v_cvt_pk_f32_fp8_e32 v[188:189], v53
	v_cvt_pk_f32_fp8_sdwa v[190:191], v53 src0_sel:WORD_1
	v_pk_mul_f32 v[200:201], v[80:81], v[184:185]
	v_cvt_pk_f32_fp8_e32 v[192:193], v54
	v_pk_mul_f32 v[202:203], v[82:83], v[186:187]
	v_cvt_pk_f32_fp8_sdwa v[194:195], v54 src0_sel:WORD_1
	v_pk_fma_f32 v[200:201], v[84:85], v[188:189], v[200:201]
	v_cvt_pk_f32_fp8_e32 v[196:197], v55
	v_pk_fma_f32 v[202:203], v[86:87], v[190:191], v[202:203]
	v_cvt_pk_f32_fp8_sdwa v[198:199], v55 src0_sel:WORD_1
	v_pk_fma_f32 v[200:201], v[88:89], v[192:193], v[200:201]
	v_pk_fma_f32 v[202:203], v[90:91], v[194:195], v[202:203]
	v_pk_fma_f32 v[200:201], v[92:93], v[196:197], v[200:201]
	v_pk_fma_f32 v[202:203], v[94:95], v[198:199], v[202:203]
	v_pk_add_f32 v[200:201], v[200:201], v[202:203]
	v_add_f32_e32 v174, v200, v201
	v_readlane_b32 s23, v120, 46
	s_lshl_b32 s23, s23, 10
	v_add_u32_e32 v205, s23, v208
	global_load_dwordx4 v[52:55], v205, s[12:13]
	s_waitcnt vmcnt(15)
	v_cvt_pk_f32_fp8_e32 v[184:185], v56
	v_cvt_pk_f32_fp8_sdwa v[186:187], v56 src0_sel:WORD_1
	v_cvt_pk_f32_fp8_e32 v[188:189], v57
	v_cvt_pk_f32_fp8_sdwa v[190:191], v57 src0_sel:WORD_1
	v_pk_mul_f32 v[200:201], v[64:65], v[184:185]
	v_cvt_pk_f32_fp8_e32 v[192:193], v58
	v_pk_mul_f32 v[202:203], v[66:67], v[186:187]
	v_cvt_pk_f32_fp8_sdwa v[194:195], v58 src0_sel:WORD_1
	v_pk_fma_f32 v[200:201], v[68:69], v[188:189], v[200:201]
	v_cvt_pk_f32_fp8_e32 v[196:197], v59
	v_pk_fma_f32 v[202:203], v[70:71], v[190:191], v[202:203]
	v_cvt_pk_f32_fp8_sdwa v[198:199], v59 src0_sel:WORD_1
	v_pk_fma_f32 v[200:201], v[72:73], v[192:193], v[200:201]
	v_pk_fma_f32 v[202:203], v[74:75], v[194:195], v[202:203]
	v_pk_fma_f32 v[200:201], v[76:77], v[196:197], v[200:201]
	v_pk_fma_f32 v[202:203], v[78:79], v[198:199], v[202:203]
	v_pk_add_f32 v[200:201], v[200:201], v[202:203]
	v_add_f32_e32 v167, v200, v201
	v_readlane_b32 s24, v112, 47
	s_lshl_b32 s24, s24, 10
	v_add_u32_e32 v206, s24, v208
	global_load_dwordx4 v[56:59], v206, s[12:13]
	s_nop 1
	v_permlane32_swap_b32_e32 v160, v164
	v_permlane32_swap_b32_e32 v161, v165
	v_permlane32_swap_b32_e32 v162, v166
	v_permlane32_swap_b32_e32 v163, v167
	v_add_f32_e32 v160, v160, v164
	v_add_f32_e32 v161, v161, v165
	v_add_f32_e32 v162, v162, v166
	v_add_f32_e32 v163, v163, v167
	v_cndmask_b32_e64 v216, v162, v160, s[26:27]
	v_cndmask_b32_e64 v218, v160, v162, s[26:27]
	v_cndmask_b32_e64 v217, v163, v161, s[26:27]
	v_cndmask_b32_e64 v219, v161, v163, s[26:27]
	ds_bpermute_b32 v220, v212, v216
	ds_bpermute_b32 v221, v212, v217
	s_waitcnt lgkmcnt(0)
	v_add_f32_e32 v218, v220, v218
	v_add_f32_e32 v219, v221, v219
	v_cndmask_b32_e64 v216, v219, v218, s[28:29]
	v_cndmask_b32_e64 v217, v218, v219, s[28:29]
	s_nop 1
	v_add_f32_dpp v222, v216, v217 row_ror:8 row_mask:0xf bank_mask:0xf
	ds_bpermute_b32 v220, v213, v222
	s_waitcnt lgkmcnt(0)
	v_add_f32_e32 v222, v220, v222
	s_nop 1
	v_add_f32_dpp v223, v222, v222 quad_perm:[2,3,0,1] row_mask:0xf bank_mask:0xf
	s_nop 1
	v_add_f32_dpp v222, v223, v223 quad_perm:[1,0,3,2] row_mask:0xf bank_mask:0xf
	ds_bpermute_b32 v220, v214, v222
	s_mov_b32 s30, 0x0
	s_mov_b32 s31, 0xff
	s_waitcnt lgkmcnt(0)
	v_cndmask_b32_e64 v176, v176, v220, s[30:31]
	s_waitcnt vmcnt(15)
	v_cvt_pk_f32_fp8_e32 v[184:185], v60
	v_cvt_pk_f32_fp8_sdwa v[186:187], v60 src0_sel:WORD_1
	v_cvt_pk_f32_fp8_e32 v[188:189], v61
	v_cvt_pk_f32_fp8_sdwa v[190:191], v61 src0_sel:WORD_1
	v_pk_mul_f32 v[200:201], v[80:81], v[184:185]
	v_cvt_pk_f32_fp8_e32 v[192:193], v62
	v_pk_mul_f32 v[202:203], v[82:83], v[186:187]
	v_cvt_pk_f32_fp8_sdwa v[194:195], v62 src0_sel:WORD_1
	v_pk_fma_f32 v[200:201], v[84:85], v[188:189], v[200:201]
	v_cvt_pk_f32_fp8_e32 v[196:197], v63
	v_pk_fma_f32 v[202:203], v[86:87], v[190:191], v[202:203]
	v_cvt_pk_f32_fp8_sdwa v[198:199], v63 src0_sel:WORD_1
	v_pk_fma_f32 v[200:201], v[88:89], v[192:193], v[200:201]
	v_pk_fma_f32 v[202:203], v[90:91], v[194:195], v[202:203]
	v_pk_fma_f32 v[200:201], v[92:93], v[196:197], v[200:201]
	v_pk_fma_f32 v[202:203], v[94:95], v[198:199], v[202:203]
	v_pk_add_f32 v[200:201], v[200:201], v[202:203]
	v_add_f32_e32 v175, v200, v201
	v_readlane_b32 s25, v120, 47
	s_lshl_b32 s25, s25, 10
	v_add_u32_e32 v207, s25, v208
	global_load_dwordx4 v[60:63], v207, s[12:13]
	s_nop 1
	v_permlane32_swap_b32_e32 v168, v172
	v_permlane32_swap_b32_e32 v169, v173
	v_permlane32_swap_b32_e32 v170, v174
	v_permlane32_swap_b32_e32 v171, v175
	v_add_f32_e32 v168, v168, v172
	v_add_f32_e32 v169, v169, v173
	v_add_f32_e32 v170, v170, v174
	v_add_f32_e32 v171, v171, v175
	v_cndmask_b32_e64 v216, v170, v168, s[26:27]
	v_cndmask_b32_e64 v218, v168, v170, s[26:27]
	v_cndmask_b32_e64 v217, v171, v169, s[26:27]
	v_cndmask_b32_e64 v219, v169, v171, s[26:27]
	ds_bpermute_b32 v220, v212, v216
	ds_bpermute_b32 v221, v212, v217
	s_waitcnt lgkmcnt(0)
	v_add_f32_e32 v218, v220, v218
	v_add_f32_e32 v219, v221, v219
	v_cndmask_b32_e64 v216, v219, v218, s[28:29]
	v_cndmask_b32_e64 v217, v218, v219, s[28:29]
	s_nop 1
	v_add_f32_dpp v222, v216, v217 row_ror:8 row_mask:0xf bank_mask:0xf
	ds_bpermute_b32 v220, v213, v222
	s_waitcnt lgkmcnt(0)
	v_add_f32_e32 v222, v220, v222
	s_nop 1
	v_add_f32_dpp v223, v222, v222 quad_perm:[2,3,0,1] row_mask:0xf bank_mask:0xf
	s_nop 1
	v_add_f32_dpp v222, v223, v223 quad_perm:[1,0,3,2] row_mask:0xf bank_mask:0xf
	ds_bpermute_b32 v220, v214, v222
	s_mov_b32 s30, 0x0
	s_mov_b32 s31, 0xff
	s_waitcnt lgkmcnt(0)
	v_cndmask_b32_e64 v179, v179, v220, s[30:31]
	s_waitcnt vmcnt(15)
	v_cvt_pk_f32_fp8_e32 v[184:185], v0
	v_cvt_pk_f32_fp8_sdwa v[186:187], v0 src0_sel:WORD_1
	v_cvt_pk_f32_fp8_e32 v[188:189], v1
	v_cvt_pk_f32_fp8_sdwa v[190:191], v1 src0_sel:WORD_1
	v_pk_mul_f32 v[200:201], v[64:65], v[184:185]
	v_cvt_pk_f32_fp8_e32 v[192:193], v2
	v_pk_mul_f32 v[202:203], v[66:67], v[186:187]
	v_cvt_pk_f32_fp8_sdwa v[194:195], v2 src0_sel:WORD_1
	v_pk_fma_f32 v[200:201], v[68:69], v[188:189], v[200:201]
	v_cvt_pk_f32_fp8_e32 v[196:197], v3
	v_pk_fma_f32 v[202:203], v[70:71], v[190:191], v[202:203]
	v_cvt_pk_f32_fp8_sdwa v[198:199], v3 src0_sel:WORD_1
	v_pk_fma_f32 v[200:201], v[72:73], v[192:193], v[200:201]
	v_pk_fma_f32 v[202:203], v[74:75], v[194:195], v[202:203]
	v_pk_fma_f32 v[200:201], v[76:77], v[196:197], v[200:201]
	v_pk_fma_f32 v[202:203], v[78:79], v[198:199], v[202:203]
	v_pk_add_f32 v[200:201], v[200:201], v[202:203]
	v_add_f32_e32 v160, v200, v201
	v_readlane_b32 s22, v112, 48
	s_lshl_b32 s22, s22, 10
	v_add_u32_e32 v204, s22, v208
	global_load_dwordx4 v[0:3], v204, s[12:13]
	s_waitcnt vmcnt(15)
	v_cvt_pk_f32_fp8_e32 v[184:185], v4
	v_cvt_pk_f32_fp8_sdwa v[186:187], v4 src0_sel:WORD_1
	v_cvt_pk_f32_fp8_e32 v[188:189], v5
	v_cvt_pk_f32_fp8_sdwa v[190:191], v5 src0_sel:WORD_1
	v_pk_mul_f32 v[200:201], v[80:81], v[184:185]
	v_cvt_pk_f32_fp8_e32 v[192:193], v6
	v_pk_mul_f32 v[202:203], v[82:83], v[186:187]
	v_cvt_pk_f32_fp8_sdwa v[194:195], v6 src0_sel:WORD_1
	v_pk_fma_f32 v[200:201], v[84:85], v[188:189], v[200:201]
	v_cvt_pk_f32_fp8_e32 v[196:197], v7
	v_pk_fma_f32 v[202:203], v[86:87], v[190:191], v[202:203]
	v_cvt_pk_f32_fp8_sdwa v[198:199], v7 src0_sel:WORD_1
	v_pk_fma_f32 v[200:201], v[88:89], v[192:193], v[200:201]
	v_pk_fma_f32 v[202:203], v[90:91], v[194:195], v[202:203]
	v_pk_fma_f32 v[200:201], v[92:93], v[196:197], v[200:201]
	v_pk_fma_f32 v[202:203], v[94:95], v[198:199], v[202:203]
	v_pk_add_f32 v[200:201], v[200:201], v[202:203]
	v_add_f32_e32 v168, v200, v201
	v_readlane_b32 s23, v120, 48
	s_lshl_b32 s23, s23, 10
	v_add_u32_e32 v205, s23, v208
	global_load_dwordx4 v[4:7], v205, s[12:13]
	s_waitcnt vmcnt(15)
	v_cvt_pk_f32_fp8_e32 v[184:185], v8
	v_cvt_pk_f32_fp8_sdwa v[186:187], v8 src0_sel:WORD_1
	v_cvt_pk_f32_fp8_e32 v[188:189], v9
	v_cvt_pk_f32_fp8_sdwa v[190:191], v9 src0_sel:WORD_1
	v_pk_mul_f32 v[200:201], v[64:65], v[184:185]
	v_cvt_pk_f32_fp8_e32 v[192:193], v10
	v_pk_mul_f32 v[202:203], v[66:67], v[186:187]
	v_cvt_pk_f32_fp8_sdwa v[194:195], v10 src0_sel:WORD_1
	v_pk_fma_f32 v[200:201], v[68:69], v[188:189], v[200:201]
	v_cvt_pk_f32_fp8_e32 v[196:197], v11
	v_pk_fma_f32 v[202:203], v[70:71], v[190:191], v[202:203]
	v_cvt_pk_f32_fp8_sdwa v[198:199], v11 src0_sel:WORD_1
	v_pk_fma_f32 v[200:201], v[72:73], v[192:193], v[200:201]
	v_pk_fma_f32 v[202:203], v[74:75], v[194:195], v[202:203]
	v_pk_fma_f32 v[200:201], v[76:77], v[196:197], v[200:201]
	v_pk_fma_f32 v[202:203], v[78:79], v[198:199], v[202:203]
	v_pk_add_f32 v[200:201], v[200:201], v[202:203]
	v_add_f32_e32 v161, v200, v201
	v_readlane_b32 s24, v112, 49
	s_lshl_b32 s24, s24, 10
	v_add_u32_e32 v206, s24, v208
	global_load_dwordx4 v[8:11], v206, s[12:13]
	s_waitcnt vmcnt(15)
	v_cvt_pk_f32_fp8_e32 v[184:185], v12
	v_cvt_pk_f32_fp8_sdwa v[186:187], v12 src0_sel:WORD_1
	v_cvt_pk_f32_fp8_e32 v[188:189], v13
	v_cvt_pk_f32_fp8_sdwa v[190:191], v13 src0_sel:WORD_1
	v_pk_mul_f32 v[200:201], v[80:81], v[184:185]
	v_cvt_pk_f32_fp8_e32 v[192:193], v14
	v_pk_mul_f32 v[202:203], v[82:83], v[186:187]
	v_cvt_pk_f32_fp8_sdwa v[194:195], v14 src0_sel:WORD_1
	v_pk_fma_f32 v[200:201], v[84:85], v[188:189], v[200:201]
	v_cvt_pk_f32_fp8_e32 v[196:197], v15
	v_pk_fma_f32 v[202:203], v[86:87], v[190:191], v[202:203]
	v_cvt_pk_f32_fp8_sdwa v[198:199], v15 src0_sel:WORD_1
	v_pk_fma_f32 v[200:201], v[88:89], v[192:193], v[200:201]
	v_pk_fma_f32 v[202:203], v[90:91], v[194:195], v[202:203]
	v_pk_fma_f32 v[200:201], v[92:93], v[196:197], v[200:201]
	v_pk_fma_f32 v[202:203], v[94:95], v[198:199], v[202:203]
	v_pk_add_f32 v[200:201], v[200:201], v[202:203]
	v_add_f32_e32 v169, v200, v201
	v_readlane_b32 s25, v120, 49
	s_lshl_b32 s25, s25, 10
	v_add_u32_e32 v207, s25, v208
	global_load_dwordx4 v[12:15], v207, s[12:13]
	s_waitcnt vmcnt(15)
	v_cvt_pk_f32_fp8_e32 v[184:185], v16
	v_cvt_pk_f32_fp8_sdwa v[186:187], v16 src0_sel:WORD_1
	v_cvt_pk_f32_fp8_e32 v[188:189], v17
	v_cvt_pk_f32_fp8_sdwa v[190:191], v17 src0_sel:WORD_1
	v_pk_mul_f32 v[200:201], v[64:65], v[184:185]
	v_cvt_pk_f32_fp8_e32 v[192:193], v18
	v_pk_mul_f32 v[202:203], v[66:67], v[186:187]
	v_cvt_pk_f32_fp8_sdwa v[194:195], v18 src0_sel:WORD_1
	v_pk_fma_f32 v[200:201], v[68:69], v[188:189], v[200:201]
	v_cvt_pk_f32_fp8_e32 v[196:197], v19
	v_pk_fma_f32 v[202:203], v[70:71], v[190:191], v[202:203]
	v_cvt_pk_f32_fp8_sdwa v[198:199], v19 src0_sel:WORD_1
	v_pk_fma_f32 v[200:201], v[72:73], v[192:193], v[200:201]
	v_pk_fma_f32 v[202:203], v[74:75], v[194:195], v[202:203]
	v_pk_fma_f32 v[200:201], v[76:77], v[196:197], v[200:201]
	v_pk_fma_f32 v[202:203], v[78:79], v[198:199], v[202:203]
	v_pk_add_f32 v[200:201], v[200:201], v[202:203]
	v_add_f32_e32 v162, v200, v201
	v_readlane_b32 s22, v112, 50
	s_lshl_b32 s22, s22, 10
	v_add_u32_e32 v204, s22, v208
	global_load_dwordx4 v[16:19], v204, s[12:13]
	s_waitcnt vmcnt(15)
	v_cvt_pk_f32_fp8_e32 v[184:185], v20
	v_cvt_pk_f32_fp8_sdwa v[186:187], v20 src0_sel:WORD_1
	v_cvt_pk_f32_fp8_e32 v[188:189], v21
	v_cvt_pk_f32_fp8_sdwa v[190:191], v21 src0_sel:WORD_1
	v_pk_mul_f32 v[200:201], v[80:81], v[184:185]
	v_cvt_pk_f32_fp8_e32 v[192:193], v22
	v_pk_mul_f32 v[202:203], v[82:83], v[186:187]
	v_cvt_pk_f32_fp8_sdwa v[194:195], v22 src0_sel:WORD_1
	v_pk_fma_f32 v[200:201], v[84:85], v[188:189], v[200:201]
	v_cvt_pk_f32_fp8_e32 v[196:197], v23
	v_pk_fma_f32 v[202:203], v[86:87], v[190:191], v[202:203]
	v_cvt_pk_f32_fp8_sdwa v[198:199], v23 src0_sel:WORD_1
	v_pk_fma_f32 v[200:201], v[88:89], v[192:193], v[200:201]
	v_pk_fma_f32 v[202:203], v[90:91], v[194:195], v[202:203]
	v_pk_fma_f32 v[200:201], v[92:93], v[196:197], v[200:201]
	v_pk_fma_f32 v[202:203], v[94:95], v[198:199], v[202:203]
	v_pk_add_f32 v[200:201], v[200:201], v[202:203]
	v_add_f32_e32 v170, v200, v201
	v_readlane_b32 s23, v120, 50
	s_lshl_b32 s23, s23, 10
	v_add_u32_e32 v205, s23, v208
	global_load_dwordx4 v[20:23], v205, s[12:13]
	s_waitcnt vmcnt(15)
	v_cvt_pk_f32_fp8_e32 v[184:185], v24
	v_cvt_pk_f32_fp8_sdwa v[186:187], v24 src0_sel:WORD_1
	v_cvt_pk_f32_fp8_e32 v[188:189], v25
	v_cvt_pk_f32_fp8_sdwa v[190:191], v25 src0_sel:WORD_1
	v_pk_mul_f32 v[200:201], v[64:65], v[184:185]
	v_cvt_pk_f32_fp8_e32 v[192:193], v26
	v_pk_mul_f32 v[202:203], v[66:67], v[186:187]
	v_cvt_pk_f32_fp8_sdwa v[194:195], v26 src0_sel:WORD_1
	v_pk_fma_f32 v[200:201], v[68:69], v[188:189], v[200:201]
	v_cvt_pk_f32_fp8_e32 v[196:197], v27
	v_pk_fma_f32 v[202:203], v[70:71], v[190:191], v[202:203]
	v_cvt_pk_f32_fp8_sdwa v[198:199], v27 src0_sel:WORD_1
	v_pk_fma_f32 v[200:201], v[72:73], v[192:193], v[200:201]
	v_pk_fma_f32 v[202:203], v[74:75], v[194:195], v[202:203]
	v_pk_fma_f32 v[200:201], v[76:77], v[196:197], v[200:201]
	v_pk_fma_f32 v[202:203], v[78:79], v[198:199], v[202:203]
	v_pk_add_f32 v[200:201], v[200:201], v[202:203]
	v_add_f32_e32 v163, v200, v201
	v_readlane_b32 s24, v112, 51
	s_lshl_b32 s24, s24, 10
	v_add_u32_e32 v206, s24, v208
	global_load_dwordx4 v[24:27], v206, s[12:13]
	s_waitcnt vmcnt(15)
	v_cvt_pk_f32_fp8_e32 v[184:185], v28
	v_cvt_pk_f32_fp8_sdwa v[186:187], v28 src0_sel:WORD_1
	v_cvt_pk_f32_fp8_e32 v[188:189], v29
	v_cvt_pk_f32_fp8_sdwa v[190:191], v29 src0_sel:WORD_1
	v_pk_mul_f32 v[200:201], v[80:81], v[184:185]
	v_cvt_pk_f32_fp8_e32 v[192:193], v30
	v_pk_mul_f32 v[202:203], v[82:83], v[186:187]
	v_cvt_pk_f32_fp8_sdwa v[194:195], v30 src0_sel:WORD_1
	v_pk_fma_f32 v[200:201], v[84:85], v[188:189], v[200:201]
	v_cvt_pk_f32_fp8_e32 v[196:197], v31
	v_pk_fma_f32 v[202:203], v[86:87], v[190:191], v[202:203]
	v_cvt_pk_f32_fp8_sdwa v[198:199], v31 src0_sel:WORD_1
	v_pk_fma_f32 v[200:201], v[88:89], v[192:193], v[200:201]
	v_pk_fma_f32 v[202:203], v[90:91], v[194:195], v[202:203]
	v_pk_fma_f32 v[200:201], v[92:93], v[196:197], v[200:201]
	v_pk_fma_f32 v[202:203], v[94:95], v[198:199], v[202:203]
	v_pk_add_f32 v[200:201], v[200:201], v[202:203]
	v_add_f32_e32 v171, v200, v201
	v_readlane_b32 s25, v120, 51
	s_lshl_b32 s25, s25, 10
	v_add_u32_e32 v207, s25, v208
	global_load_dwordx4 v[28:31], v207, s[12:13]
	s_waitcnt vmcnt(15)
	v_cvt_pk_f32_fp8_e32 v[184:185], v32
	v_cvt_pk_f32_fp8_sdwa v[186:187], v32 src0_sel:WORD_1
	v_cvt_pk_f32_fp8_e32 v[188:189], v33
	v_cvt_pk_f32_fp8_sdwa v[190:191], v33 src0_sel:WORD_1
	v_pk_mul_f32 v[200:201], v[64:65], v[184:185]
	v_cvt_pk_f32_fp8_e32 v[192:193], v34
	v_pk_mul_f32 v[202:203], v[66:67], v[186:187]
	v_cvt_pk_f32_fp8_sdwa v[194:195], v34 src0_sel:WORD_1
	v_pk_fma_f32 v[200:201], v[68:69], v[188:189], v[200:201]
	v_cvt_pk_f32_fp8_e32 v[196:197], v35
	v_pk_fma_f32 v[202:203], v[70:71], v[190:191], v[202:203]
	v_cvt_pk_f32_fp8_sdwa v[198:199], v35 src0_sel:WORD_1
	v_pk_fma_f32 v[200:201], v[72:73], v[192:193], v[200:201]
	v_pk_fma_f32 v[202:203], v[74:75], v[194:195], v[202:203]
	v_pk_fma_f32 v[200:201], v[76:77], v[196:197], v[200:201]
	v_pk_fma_f32 v[202:203], v[78:79], v[198:199], v[202:203]
	v_pk_add_f32 v[200:201], v[200:201], v[202:203]
	v_add_f32_e32 v164, v200, v201
	v_readlane_b32 s22, v112, 52
	s_lshl_b32 s22, s22, 10
	v_add_u32_e32 v204, s22, v208
	global_load_dwordx4 v[32:35], v204, s[12:13]
	s_waitcnt vmcnt(15)
	v_cvt_pk_f32_fp8_e32 v[184:185], v36
	v_cvt_pk_f32_fp8_sdwa v[186:187], v36 src0_sel:WORD_1
	v_cvt_pk_f32_fp8_e32 v[188:189], v37
	v_cvt_pk_f32_fp8_sdwa v[190:191], v37 src0_sel:WORD_1
	v_pk_mul_f32 v[200:201], v[80:81], v[184:185]
	v_cvt_pk_f32_fp8_e32 v[192:193], v38
	v_pk_mul_f32 v[202:203], v[82:83], v[186:187]
	v_cvt_pk_f32_fp8_sdwa v[194:195], v38 src0_sel:WORD_1
	v_pk_fma_f32 v[200:201], v[84:85], v[188:189], v[200:201]
	v_cvt_pk_f32_fp8_e32 v[196:197], v39
	v_pk_fma_f32 v[202:203], v[86:87], v[190:191], v[202:203]
	v_cvt_pk_f32_fp8_sdwa v[198:199], v39 src0_sel:WORD_1
	v_pk_fma_f32 v[200:201], v[88:89], v[192:193], v[200:201]
	v_pk_fma_f32 v[202:203], v[90:91], v[194:195], v[202:203]
	v_pk_fma_f32 v[200:201], v[92:93], v[196:197], v[200:201]
	v_pk_fma_f32 v[202:203], v[94:95], v[198:199], v[202:203]
	v_pk_add_f32 v[200:201], v[200:201], v[202:203]
	v_add_f32_e32 v172, v200, v201
	v_readlane_b32 s23, v120, 52
	s_lshl_b32 s23, s23, 10
	v_add_u32_e32 v205, s23, v208
	global_load_dwordx4 v[36:39], v205, s[12:13]
	s_waitcnt vmcnt(15)
	v_cvt_pk_f32_fp8_e32 v[184:185], v40
	v_cvt_pk_f32_fp8_sdwa v[186:187], v40 src0_sel:WORD_1
	v_cvt_pk_f32_fp8_e32 v[188:189], v41
	v_cvt_pk_f32_fp8_sdwa v[190:191], v41 src0_sel:WORD_1
	v_pk_mul_f32 v[200:201], v[64:65], v[184:185]
	v_cvt_pk_f32_fp8_e32 v[192:193], v42
	v_pk_mul_f32 v[202:203], v[66:67], v[186:187]
	v_cvt_pk_f32_fp8_sdwa v[194:195], v42 src0_sel:WORD_1
	v_pk_fma_f32 v[200:201], v[68:69], v[188:189], v[200:201]
	v_cvt_pk_f32_fp8_e32 v[196:197], v43
	v_pk_fma_f32 v[202:203], v[70:71], v[190:191], v[202:203]
	v_cvt_pk_f32_fp8_sdwa v[198:199], v43 src0_sel:WORD_1
	v_pk_fma_f32 v[200:201], v[72:73], v[192:193], v[200:201]
	v_pk_fma_f32 v[202:203], v[74:75], v[194:195], v[202:203]
	v_pk_fma_f32 v[200:201], v[76:77], v[196:197], v[200:201]
	v_pk_fma_f32 v[202:203], v[78:79], v[198:199], v[202:203]
	v_pk_add_f32 v[200:201], v[200:201], v[202:203]
	v_add_f32_e32 v165, v200, v201
	v_readlane_b32 s24, v112, 53
	s_lshl_b32 s24, s24, 10
	v_add_u32_e32 v206, s24, v208
	global_load_dwordx4 v[40:43], v206, s[12:13]
	s_waitcnt vmcnt(15)
	v_cvt_pk_f32_fp8_e32 v[184:185], v44
	v_cvt_pk_f32_fp8_sdwa v[186:187], v44 src0_sel:WORD_1
	v_cvt_pk_f32_fp8_e32 v[188:189], v45
	v_cvt_pk_f32_fp8_sdwa v[190:191], v45 src0_sel:WORD_1
	v_pk_mul_f32 v[200:201], v[80:81], v[184:185]
	v_cvt_pk_f32_fp8_e32 v[192:193], v46
	v_pk_mul_f32 v[202:203], v[82:83], v[186:187]
	v_cvt_pk_f32_fp8_sdwa v[194:195], v46 src0_sel:WORD_1
	v_pk_fma_f32 v[200:201], v[84:85], v[188:189], v[200:201]
	v_cvt_pk_f32_fp8_e32 v[196:197], v47
	v_pk_fma_f32 v[202:203], v[86:87], v[190:191], v[202:203]
	v_cvt_pk_f32_fp8_sdwa v[198:199], v47 src0_sel:WORD_1
	v_pk_fma_f32 v[200:201], v[88:89], v[192:193], v[200:201]
	v_pk_fma_f32 v[202:203], v[90:91], v[194:195], v[202:203]
	v_pk_fma_f32 v[200:201], v[92:93], v[196:197], v[200:201]
	v_pk_fma_f32 v[202:203], v[94:95], v[198:199], v[202:203]
	v_pk_add_f32 v[200:201], v[200:201], v[202:203]
	v_add_f32_e32 v173, v200, v201
	v_readlane_b32 s25, v120, 53
	s_lshl_b32 s25, s25, 10
	v_add_u32_e32 v207, s25, v208
	global_load_dwordx4 v[44:47], v207, s[12:13]
	s_waitcnt vmcnt(15)
	v_cvt_pk_f32_fp8_e32 v[184:185], v48
	v_cvt_pk_f32_fp8_sdwa v[186:187], v48 src0_sel:WORD_1
	v_cvt_pk_f32_fp8_e32 v[188:189], v49
	v_cvt_pk_f32_fp8_sdwa v[190:191], v49 src0_sel:WORD_1
	v_pk_mul_f32 v[200:201], v[64:65], v[184:185]
	v_cvt_pk_f32_fp8_e32 v[192:193], v50
	v_pk_mul_f32 v[202:203], v[66:67], v[186:187]
	v_cvt_pk_f32_fp8_sdwa v[194:195], v50 src0_sel:WORD_1
	v_pk_fma_f32 v[200:201], v[68:69], v[188:189], v[200:201]
	v_cvt_pk_f32_fp8_e32 v[196:197], v51
	v_pk_fma_f32 v[202:203], v[70:71], v[190:191], v[202:203]
	v_cvt_pk_f32_fp8_sdwa v[198:199], v51 src0_sel:WORD_1
	v_pk_fma_f32 v[200:201], v[72:73], v[192:193], v[200:201]
	v_pk_fma_f32 v[202:203], v[74:75], v[194:195], v[202:203]
	v_pk_fma_f32 v[200:201], v[76:77], v[196:197], v[200:201]
	v_pk_fma_f32 v[202:203], v[78:79], v[198:199], v[202:203]
	v_pk_add_f32 v[200:201], v[200:201], v[202:203]
	v_add_f32_e32 v166, v200, v201
	v_readlane_b32 s22, v112, 54
	s_lshl_b32 s22, s22, 10
	v_add_u32_e32 v204, s22, v208
	global_load_dwordx4 v[48:51], v204, s[12:13]
	s_waitcnt vmcnt(15)
	v_cvt_pk_f32_fp8_e32 v[184:185], v52
	v_cvt_pk_f32_fp8_sdwa v[186:187], v52 src0_sel:WORD_1
	v_cvt_pk_f32_fp8_e32 v[188:189], v53
	v_cvt_pk_f32_fp8_sdwa v[190:191], v53 src0_sel:WORD_1
	v_pk_mul_f32 v[200:201], v[80:81], v[184:185]
	v_cvt_pk_f32_fp8_e32 v[192:193], v54
	v_pk_mul_f32 v[202:203], v[82:83], v[186:187]
	v_cvt_pk_f32_fp8_sdwa v[194:195], v54 src0_sel:WORD_1
	v_pk_fma_f32 v[200:201], v[84:85], v[188:189], v[200:201]
	v_cvt_pk_f32_fp8_e32 v[196:197], v55
	v_pk_fma_f32 v[202:203], v[86:87], v[190:191], v[202:203]
	v_cvt_pk_f32_fp8_sdwa v[198:199], v55 src0_sel:WORD_1
	v_pk_fma_f32 v[200:201], v[88:89], v[192:193], v[200:201]
	v_pk_fma_f32 v[202:203], v[90:91], v[194:195], v[202:203]
	v_pk_fma_f32 v[200:201], v[92:93], v[196:197], v[200:201]
	v_pk_fma_f32 v[202:203], v[94:95], v[198:199], v[202:203]
	v_pk_add_f32 v[200:201], v[200:201], v[202:203]
	v_add_f32_e32 v174, v200, v201
	v_readlane_b32 s23, v120, 54
	s_lshl_b32 s23, s23, 10
	v_add_u32_e32 v205, s23, v208
	global_load_dwordx4 v[52:55], v205, s[12:13]
	s_waitcnt vmcnt(15)
	v_cvt_pk_f32_fp8_e32 v[184:185], v56
	v_cvt_pk_f32_fp8_sdwa v[186:187], v56 src0_sel:WORD_1
	v_cvt_pk_f32_fp8_e32 v[188:189], v57
	v_cvt_pk_f32_fp8_sdwa v[190:191], v57 src0_sel:WORD_1
	v_pk_mul_f32 v[200:201], v[64:65], v[184:185]
	v_cvt_pk_f32_fp8_e32 v[192:193], v58
	v_pk_mul_f32 v[202:203], v[66:67], v[186:187]
	v_cvt_pk_f32_fp8_sdwa v[194:195], v58 src0_sel:WORD_1
	v_pk_fma_f32 v[200:201], v[68:69], v[188:189], v[200:201]
	v_cvt_pk_f32_fp8_e32 v[196:197], v59
	v_pk_fma_f32 v[202:203], v[70:71], v[190:191], v[202:203]
	v_cvt_pk_f32_fp8_sdwa v[198:199], v59 src0_sel:WORD_1
	v_pk_fma_f32 v[200:201], v[72:73], v[192:193], v[200:201]
	v_pk_fma_f32 v[202:203], v[74:75], v[194:195], v[202:203]
	v_pk_fma_f32 v[200:201], v[76:77], v[196:197], v[200:201]
	v_pk_fma_f32 v[202:203], v[78:79], v[198:199], v[202:203]
	v_pk_add_f32 v[200:201], v[200:201], v[202:203]
	v_add_f32_e32 v167, v200, v201
	v_readlane_b32 s24, v112, 55
	s_lshl_b32 s24, s24, 10
	v_add_u32_e32 v206, s24, v208
	global_load_dwordx4 v[56:59], v206, s[12:13]
	s_nop 1
	v_permlane32_swap_b32_e32 v160, v164
	v_permlane32_swap_b32_e32 v161, v165
	v_permlane32_swap_b32_e32 v162, v166
	v_permlane32_swap_b32_e32 v163, v167
	v_add_f32_e32 v160, v160, v164
	v_add_f32_e32 v161, v161, v165
	v_add_f32_e32 v162, v162, v166
	v_add_f32_e32 v163, v163, v167
	v_cndmask_b32_e64 v216, v162, v160, s[26:27]
	v_cndmask_b32_e64 v218, v160, v162, s[26:27]
	v_cndmask_b32_e64 v217, v163, v161, s[26:27]
	v_cndmask_b32_e64 v219, v161, v163, s[26:27]
	ds_bpermute_b32 v220, v212, v216
	ds_bpermute_b32 v221, v212, v217
	s_waitcnt lgkmcnt(0)
	v_add_f32_e32 v218, v220, v218
	v_add_f32_e32 v219, v221, v219
	v_cndmask_b32_e64 v216, v219, v218, s[28:29]
	v_cndmask_b32_e64 v217, v218, v219, s[28:29]
	s_nop 1
	v_add_f32_dpp v222, v216, v217 row_ror:8 row_mask:0xf bank_mask:0xf
	ds_bpermute_b32 v220, v213, v222
	s_waitcnt lgkmcnt(0)
	v_add_f32_e32 v222, v220, v222
	s_nop 1
	v_add_f32_dpp v223, v222, v222 quad_perm:[2,3,0,1] row_mask:0xf bank_mask:0xf
	s_nop 1
	v_add_f32_dpp v222, v223, v223 quad_perm:[1,0,3,2] row_mask:0xf bank_mask:0xf
	ds_bpermute_b32 v220, v214, v222
	s_mov_b32 s30, 0x0
	s_mov_b32 s31, 0xff00
	s_waitcnt lgkmcnt(0)
	v_cndmask_b32_e64 v176, v176, v220, s[30:31]
	s_waitcnt vmcnt(15)
	v_cvt_pk_f32_fp8_e32 v[184:185], v60
	v_cvt_pk_f32_fp8_sdwa v[186:187], v60 src0_sel:WORD_1
	v_cvt_pk_f32_fp8_e32 v[188:189], v61
	v_cvt_pk_f32_fp8_sdwa v[190:191], v61 src0_sel:WORD_1
	v_pk_mul_f32 v[200:201], v[80:81], v[184:185]
	v_cvt_pk_f32_fp8_e32 v[192:193], v62
	v_pk_mul_f32 v[202:203], v[82:83], v[186:187]
	v_cvt_pk_f32_fp8_sdwa v[194:195], v62 src0_sel:WORD_1
	v_pk_fma_f32 v[200:201], v[84:85], v[188:189], v[200:201]
	v_cvt_pk_f32_fp8_e32 v[196:197], v63
	v_pk_fma_f32 v[202:203], v[86:87], v[190:191], v[202:203]
	v_cvt_pk_f32_fp8_sdwa v[198:199], v63 src0_sel:WORD_1
	v_pk_fma_f32 v[200:201], v[88:89], v[192:193], v[200:201]
	v_pk_fma_f32 v[202:203], v[90:91], v[194:195], v[202:203]
	v_pk_fma_f32 v[200:201], v[92:93], v[196:197], v[200:201]
	v_pk_fma_f32 v[202:203], v[94:95], v[198:199], v[202:203]
	v_pk_add_f32 v[200:201], v[200:201], v[202:203]
	v_add_f32_e32 v175, v200, v201
	v_readlane_b32 s25, v120, 55
	s_lshl_b32 s25, s25, 10
	v_add_u32_e32 v207, s25, v208
	global_load_dwordx4 v[60:63], v207, s[12:13]
	s_nop 1
	v_permlane32_swap_b32_e32 v168, v172
	v_permlane32_swap_b32_e32 v169, v173
	v_permlane32_swap_b32_e32 v170, v174
	v_permlane32_swap_b32_e32 v171, v175
	v_add_f32_e32 v168, v168, v172
	v_add_f32_e32 v169, v169, v173
	v_add_f32_e32 v170, v170, v174
	v_add_f32_e32 v171, v171, v175
	v_cndmask_b32_e64 v216, v170, v168, s[26:27]
	v_cndmask_b32_e64 v218, v168, v170, s[26:27]
	v_cndmask_b32_e64 v217, v171, v169, s[26:27]
	v_cndmask_b32_e64 v219, v169, v171, s[26:27]
	ds_bpermute_b32 v220, v212, v216
	ds_bpermute_b32 v221, v212, v217
	s_waitcnt lgkmcnt(0)
	v_add_f32_e32 v218, v220, v218
	v_add_f32_e32 v219, v221, v219
	v_cndmask_b32_e64 v216, v219, v218, s[28:29]
	v_cndmask_b32_e64 v217, v218, v219, s[28:29]
	s_nop 1
	v_add_f32_dpp v222, v216, v217 row_ror:8 row_mask:0xf bank_mask:0xf
	ds_bpermute_b32 v220, v213, v222
	s_waitcnt lgkmcnt(0)
	v_add_f32_e32 v222, v220, v222
	s_nop 1
	v_add_f32_dpp v223, v222, v222 quad_perm:[2,3,0,1] row_mask:0xf bank_mask:0xf
	s_nop 1
	v_add_f32_dpp v222, v223, v223 quad_perm:[1,0,3,2] row_mask:0xf bank_mask:0xf
	ds_bpermute_b32 v220, v214, v222
	s_mov_b32 s30, 0x0
	s_mov_b32 s31, 0xff00
	s_waitcnt lgkmcnt(0)
	v_cndmask_b32_e64 v179, v179, v220, s[30:31]
	s_waitcnt vmcnt(15)
	v_cvt_pk_f32_fp8_e32 v[184:185], v0
	v_cvt_pk_f32_fp8_sdwa v[186:187], v0 src0_sel:WORD_1
	v_cvt_pk_f32_fp8_e32 v[188:189], v1
	v_cvt_pk_f32_fp8_sdwa v[190:191], v1 src0_sel:WORD_1
	v_pk_mul_f32 v[200:201], v[64:65], v[184:185]
	v_cvt_pk_f32_fp8_e32 v[192:193], v2
	v_pk_mul_f32 v[202:203], v[66:67], v[186:187]
	v_cvt_pk_f32_fp8_sdwa v[194:195], v2 src0_sel:WORD_1
	v_pk_fma_f32 v[200:201], v[68:69], v[188:189], v[200:201]
	v_cvt_pk_f32_fp8_e32 v[196:197], v3
	v_pk_fma_f32 v[202:203], v[70:71], v[190:191], v[202:203]
	v_cvt_pk_f32_fp8_sdwa v[198:199], v3 src0_sel:WORD_1
	v_pk_fma_f32 v[200:201], v[72:73], v[192:193], v[200:201]
	v_pk_fma_f32 v[202:203], v[74:75], v[194:195], v[202:203]
	v_pk_fma_f32 v[200:201], v[76:77], v[196:197], v[200:201]
	v_pk_fma_f32 v[202:203], v[78:79], v[198:199], v[202:203]
	v_pk_add_f32 v[200:201], v[200:201], v[202:203]
	v_add_f32_e32 v160, v200, v201
	v_readlane_b32 s22, v112, 56
	s_lshl_b32 s22, s22, 10
	v_add_u32_e32 v204, s22, v208
	global_load_dwordx4 v[0:3], v204, s[12:13]
	s_waitcnt vmcnt(15)
	v_cvt_pk_f32_fp8_e32 v[184:185], v4
	v_cvt_pk_f32_fp8_sdwa v[186:187], v4 src0_sel:WORD_1
	v_cvt_pk_f32_fp8_e32 v[188:189], v5
	v_cvt_pk_f32_fp8_sdwa v[190:191], v5 src0_sel:WORD_1
	v_pk_mul_f32 v[200:201], v[80:81], v[184:185]
	v_cvt_pk_f32_fp8_e32 v[192:193], v6
	v_pk_mul_f32 v[202:203], v[82:83], v[186:187]
	v_cvt_pk_f32_fp8_sdwa v[194:195], v6 src0_sel:WORD_1
	v_pk_fma_f32 v[200:201], v[84:85], v[188:189], v[200:201]
	v_cvt_pk_f32_fp8_e32 v[196:197], v7
	v_pk_fma_f32 v[202:203], v[86:87], v[190:191], v[202:203]
	v_cvt_pk_f32_fp8_sdwa v[198:199], v7 src0_sel:WORD_1
	v_pk_fma_f32 v[200:201], v[88:89], v[192:193], v[200:201]
	v_pk_fma_f32 v[202:203], v[90:91], v[194:195], v[202:203]
	v_pk_fma_f32 v[200:201], v[92:93], v[196:197], v[200:201]
	v_pk_fma_f32 v[202:203], v[94:95], v[198:199], v[202:203]
	v_pk_add_f32 v[200:201], v[200:201], v[202:203]
	v_add_f32_e32 v168, v200, v201
	v_readlane_b32 s23, v120, 56
	s_lshl_b32 s23, s23, 10
	v_add_u32_e32 v205, s23, v208
	global_load_dwordx4 v[4:7], v205, s[12:13]
	s_waitcnt vmcnt(15)
	v_cvt_pk_f32_fp8_e32 v[184:185], v8
	v_cvt_pk_f32_fp8_sdwa v[186:187], v8 src0_sel:WORD_1
	v_cvt_pk_f32_fp8_e32 v[188:189], v9
	v_cvt_pk_f32_fp8_sdwa v[190:191], v9 src0_sel:WORD_1
	v_pk_mul_f32 v[200:201], v[64:65], v[184:185]
	v_cvt_pk_f32_fp8_e32 v[192:193], v10
	v_pk_mul_f32 v[202:203], v[66:67], v[186:187]
	v_cvt_pk_f32_fp8_sdwa v[194:195], v10 src0_sel:WORD_1
	v_pk_fma_f32 v[200:201], v[68:69], v[188:189], v[200:201]
	v_cvt_pk_f32_fp8_e32 v[196:197], v11
	v_pk_fma_f32 v[202:203], v[70:71], v[190:191], v[202:203]
	v_cvt_pk_f32_fp8_sdwa v[198:199], v11 src0_sel:WORD_1
	v_pk_fma_f32 v[200:201], v[72:73], v[192:193], v[200:201]
	v_pk_fma_f32 v[202:203], v[74:75], v[194:195], v[202:203]
	v_pk_fma_f32 v[200:201], v[76:77], v[196:197], v[200:201]
	v_pk_fma_f32 v[202:203], v[78:79], v[198:199], v[202:203]
	v_pk_add_f32 v[200:201], v[200:201], v[202:203]
	v_add_f32_e32 v161, v200, v201
	v_readlane_b32 s24, v112, 57
	s_lshl_b32 s24, s24, 10
	v_add_u32_e32 v206, s24, v208
	global_load_dwordx4 v[8:11], v206, s[12:13]
	s_waitcnt vmcnt(15)
	v_cvt_pk_f32_fp8_e32 v[184:185], v12
	v_cvt_pk_f32_fp8_sdwa v[186:187], v12 src0_sel:WORD_1
	v_cvt_pk_f32_fp8_e32 v[188:189], v13
	v_cvt_pk_f32_fp8_sdwa v[190:191], v13 src0_sel:WORD_1
	v_pk_mul_f32 v[200:201], v[80:81], v[184:185]
	v_cvt_pk_f32_fp8_e32 v[192:193], v14
	v_pk_mul_f32 v[202:203], v[82:83], v[186:187]
	v_cvt_pk_f32_fp8_sdwa v[194:195], v14 src0_sel:WORD_1
	v_pk_fma_f32 v[200:201], v[84:85], v[188:189], v[200:201]
	v_cvt_pk_f32_fp8_e32 v[196:197], v15
	v_pk_fma_f32 v[202:203], v[86:87], v[190:191], v[202:203]
	v_cvt_pk_f32_fp8_sdwa v[198:199], v15 src0_sel:WORD_1
	v_pk_fma_f32 v[200:201], v[88:89], v[192:193], v[200:201]
	v_pk_fma_f32 v[202:203], v[90:91], v[194:195], v[202:203]
	v_pk_fma_f32 v[200:201], v[92:93], v[196:197], v[200:201]
	v_pk_fma_f32 v[202:203], v[94:95], v[198:199], v[202:203]
	v_pk_add_f32 v[200:201], v[200:201], v[202:203]
	v_add_f32_e32 v169, v200, v201
	v_readlane_b32 s25, v120, 57
	s_lshl_b32 s25, s25, 10
	v_add_u32_e32 v207, s25, v208
	global_load_dwordx4 v[12:15], v207, s[12:13]
	s_waitcnt vmcnt(15)
	v_cvt_pk_f32_fp8_e32 v[184:185], v16
	v_cvt_pk_f32_fp8_sdwa v[186:187], v16 src0_sel:WORD_1
	v_cvt_pk_f32_fp8_e32 v[188:189], v17
	v_cvt_pk_f32_fp8_sdwa v[190:191], v17 src0_sel:WORD_1
	v_pk_mul_f32 v[200:201], v[64:65], v[184:185]
	v_cvt_pk_f32_fp8_e32 v[192:193], v18
	v_pk_mul_f32 v[202:203], v[66:67], v[186:187]
	v_cvt_pk_f32_fp8_sdwa v[194:195], v18 src0_sel:WORD_1
	v_pk_fma_f32 v[200:201], v[68:69], v[188:189], v[200:201]
	v_cvt_pk_f32_fp8_e32 v[196:197], v19
	v_pk_fma_f32 v[202:203], v[70:71], v[190:191], v[202:203]
	v_cvt_pk_f32_fp8_sdwa v[198:199], v19 src0_sel:WORD_1
	v_pk_fma_f32 v[200:201], v[72:73], v[192:193], v[200:201]
	v_pk_fma_f32 v[202:203], v[74:75], v[194:195], v[202:203]
	v_pk_fma_f32 v[200:201], v[76:77], v[196:197], v[200:201]
	v_pk_fma_f32 v[202:203], v[78:79], v[198:199], v[202:203]
	v_pk_add_f32 v[200:201], v[200:201], v[202:203]
	v_add_f32_e32 v162, v200, v201
	v_readlane_b32 s22, v112, 58
	s_lshl_b32 s22, s22, 10
	v_add_u32_e32 v204, s22, v208
	global_load_dwordx4 v[16:19], v204, s[12:13]
	s_waitcnt vmcnt(15)
	v_cvt_pk_f32_fp8_e32 v[184:185], v20
	v_cvt_pk_f32_fp8_sdwa v[186:187], v20 src0_sel:WORD_1
	v_cvt_pk_f32_fp8_e32 v[188:189], v21
	v_cvt_pk_f32_fp8_sdwa v[190:191], v21 src0_sel:WORD_1
	v_pk_mul_f32 v[200:201], v[80:81], v[184:185]
	v_cvt_pk_f32_fp8_e32 v[192:193], v22
	v_pk_mul_f32 v[202:203], v[82:83], v[186:187]
	v_cvt_pk_f32_fp8_sdwa v[194:195], v22 src0_sel:WORD_1
	v_pk_fma_f32 v[200:201], v[84:85], v[188:189], v[200:201]
	v_cvt_pk_f32_fp8_e32 v[196:197], v23
	v_pk_fma_f32 v[202:203], v[86:87], v[190:191], v[202:203]
	v_cvt_pk_f32_fp8_sdwa v[198:199], v23 src0_sel:WORD_1
	v_pk_fma_f32 v[200:201], v[88:89], v[192:193], v[200:201]
	v_pk_fma_f32 v[202:203], v[90:91], v[194:195], v[202:203]
	v_pk_fma_f32 v[200:201], v[92:93], v[196:197], v[200:201]
	v_pk_fma_f32 v[202:203], v[94:95], v[198:199], v[202:203]
	v_pk_add_f32 v[200:201], v[200:201], v[202:203]
	v_add_f32_e32 v170, v200, v201
	v_readlane_b32 s23, v120, 58
	s_lshl_b32 s23, s23, 10
	v_add_u32_e32 v205, s23, v208
	global_load_dwordx4 v[20:23], v205, s[12:13]
	s_waitcnt vmcnt(15)
	v_cvt_pk_f32_fp8_e32 v[184:185], v24
	v_cvt_pk_f32_fp8_sdwa v[186:187], v24 src0_sel:WORD_1
	v_cvt_pk_f32_fp8_e32 v[188:189], v25
	v_cvt_pk_f32_fp8_sdwa v[190:191], v25 src0_sel:WORD_1
	v_pk_mul_f32 v[200:201], v[64:65], v[184:185]
	v_cvt_pk_f32_fp8_e32 v[192:193], v26
	v_pk_mul_f32 v[202:203], v[66:67], v[186:187]
	v_cvt_pk_f32_fp8_sdwa v[194:195], v26 src0_sel:WORD_1
	v_pk_fma_f32 v[200:201], v[68:69], v[188:189], v[200:201]
	v_cvt_pk_f32_fp8_e32 v[196:197], v27
	v_pk_fma_f32 v[202:203], v[70:71], v[190:191], v[202:203]
	v_cvt_pk_f32_fp8_sdwa v[198:199], v27 src0_sel:WORD_1
	v_pk_fma_f32 v[200:201], v[72:73], v[192:193], v[200:201]
	v_pk_fma_f32 v[202:203], v[74:75], v[194:195], v[202:203]
	v_pk_fma_f32 v[200:201], v[76:77], v[196:197], v[200:201]
	v_pk_fma_f32 v[202:203], v[78:79], v[198:199], v[202:203]
	v_pk_add_f32 v[200:201], v[200:201], v[202:203]
	v_add_f32_e32 v163, v200, v201
	v_readlane_b32 s24, v112, 59
	s_lshl_b32 s24, s24, 10
	v_add_u32_e32 v206, s24, v208
	global_load_dwordx4 v[24:27], v206, s[12:13]
	s_waitcnt vmcnt(15)
	v_cvt_pk_f32_fp8_e32 v[184:185], v28
	v_cvt_pk_f32_fp8_sdwa v[186:187], v28 src0_sel:WORD_1
	v_cvt_pk_f32_fp8_e32 v[188:189], v29
	v_cvt_pk_f32_fp8_sdwa v[190:191], v29 src0_sel:WORD_1
	v_pk_mul_f32 v[200:201], v[80:81], v[184:185]
	v_cvt_pk_f32_fp8_e32 v[192:193], v30
	v_pk_mul_f32 v[202:203], v[82:83], v[186:187]
	v_cvt_pk_f32_fp8_sdwa v[194:195], v30 src0_sel:WORD_1
	v_pk_fma_f32 v[200:201], v[84:85], v[188:189], v[200:201]
	v_cvt_pk_f32_fp8_e32 v[196:197], v31
	v_pk_fma_f32 v[202:203], v[86:87], v[190:191], v[202:203]
	v_cvt_pk_f32_fp8_sdwa v[198:199], v31 src0_sel:WORD_1
	v_pk_fma_f32 v[200:201], v[88:89], v[192:193], v[200:201]
	v_pk_fma_f32 v[202:203], v[90:91], v[194:195], v[202:203]
	v_pk_fma_f32 v[200:201], v[92:93], v[196:197], v[200:201]
	v_pk_fma_f32 v[202:203], v[94:95], v[198:199], v[202:203]
	v_pk_add_f32 v[200:201], v[200:201], v[202:203]
	v_add_f32_e32 v171, v200, v201
	v_readlane_b32 s25, v120, 59
	s_lshl_b32 s25, s25, 10
	v_add_u32_e32 v207, s25, v208
	global_load_dwordx4 v[28:31], v207, s[12:13]
	s_waitcnt vmcnt(15)
	v_cvt_pk_f32_fp8_e32 v[184:185], v32
	v_cvt_pk_f32_fp8_sdwa v[186:187], v32 src0_sel:WORD_1
	v_cvt_pk_f32_fp8_e32 v[188:189], v33
	v_cvt_pk_f32_fp8_sdwa v[190:191], v33 src0_sel:WORD_1
	v_pk_mul_f32 v[200:201], v[64:65], v[184:185]
	v_cvt_pk_f32_fp8_e32 v[192:193], v34
	v_pk_mul_f32 v[202:203], v[66:67], v[186:187]
	v_cvt_pk_f32_fp8_sdwa v[194:195], v34 src0_sel:WORD_1
	v_pk_fma_f32 v[200:201], v[68:69], v[188:189], v[200:201]
	v_cvt_pk_f32_fp8_e32 v[196:197], v35
	v_pk_fma_f32 v[202:203], v[70:71], v[190:191], v[202:203]
	v_cvt_pk_f32_fp8_sdwa v[198:199], v35 src0_sel:WORD_1
	v_pk_fma_f32 v[200:201], v[72:73], v[192:193], v[200:201]
	v_pk_fma_f32 v[202:203], v[74:75], v[194:195], v[202:203]
	v_pk_fma_f32 v[200:201], v[76:77], v[196:197], v[200:201]
	v_pk_fma_f32 v[202:203], v[78:79], v[198:199], v[202:203]
	v_pk_add_f32 v[200:201], v[200:201], v[202:203]
	v_add_f32_e32 v164, v200, v201
	v_readlane_b32 s22, v112, 60
	s_lshl_b32 s22, s22, 10
	v_add_u32_e32 v204, s22, v208
	global_load_dwordx4 v[32:35], v204, s[12:13]
	s_waitcnt vmcnt(15)
	v_cvt_pk_f32_fp8_e32 v[184:185], v36
	v_cvt_pk_f32_fp8_sdwa v[186:187], v36 src0_sel:WORD_1
	v_cvt_pk_f32_fp8_e32 v[188:189], v37
	v_cvt_pk_f32_fp8_sdwa v[190:191], v37 src0_sel:WORD_1
	v_pk_mul_f32 v[200:201], v[80:81], v[184:185]
	v_cvt_pk_f32_fp8_e32 v[192:193], v38
	v_pk_mul_f32 v[202:203], v[82:83], v[186:187]
	v_cvt_pk_f32_fp8_sdwa v[194:195], v38 src0_sel:WORD_1
	v_pk_fma_f32 v[200:201], v[84:85], v[188:189], v[200:201]
	v_cvt_pk_f32_fp8_e32 v[196:197], v39
	v_pk_fma_f32 v[202:203], v[86:87], v[190:191], v[202:203]
	v_cvt_pk_f32_fp8_sdwa v[198:199], v39 src0_sel:WORD_1
	v_pk_fma_f32 v[200:201], v[88:89], v[192:193], v[200:201]
	v_pk_fma_f32 v[202:203], v[90:91], v[194:195], v[202:203]
	v_pk_fma_f32 v[200:201], v[92:93], v[196:197], v[200:201]
	v_pk_fma_f32 v[202:203], v[94:95], v[198:199], v[202:203]
	v_pk_add_f32 v[200:201], v[200:201], v[202:203]
	v_add_f32_e32 v172, v200, v201
	v_readlane_b32 s23, v120, 60
	s_lshl_b32 s23, s23, 10
	v_add_u32_e32 v205, s23, v208
	global_load_dwordx4 v[36:39], v205, s[12:13]
	s_waitcnt vmcnt(15)
	v_cvt_pk_f32_fp8_e32 v[184:185], v40
	v_cvt_pk_f32_fp8_sdwa v[186:187], v40 src0_sel:WORD_1
	v_cvt_pk_f32_fp8_e32 v[188:189], v41
	v_cvt_pk_f32_fp8_sdwa v[190:191], v41 src0_sel:WORD_1
	v_pk_mul_f32 v[200:201], v[64:65], v[184:185]
	v_cvt_pk_f32_fp8_e32 v[192:193], v42
	v_pk_mul_f32 v[202:203], v[66:67], v[186:187]
	v_cvt_pk_f32_fp8_sdwa v[194:195], v42 src0_sel:WORD_1
	v_pk_fma_f32 v[200:201], v[68:69], v[188:189], v[200:201]
	v_cvt_pk_f32_fp8_e32 v[196:197], v43
	v_pk_fma_f32 v[202:203], v[70:71], v[190:191], v[202:203]
	v_cvt_pk_f32_fp8_sdwa v[198:199], v43 src0_sel:WORD_1
	v_pk_fma_f32 v[200:201], v[72:73], v[192:193], v[200:201]
	v_pk_fma_f32 v[202:203], v[74:75], v[194:195], v[202:203]
	v_pk_fma_f32 v[200:201], v[76:77], v[196:197], v[200:201]
	v_pk_fma_f32 v[202:203], v[78:79], v[198:199], v[202:203]
	v_pk_add_f32 v[200:201], v[200:201], v[202:203]
	v_add_f32_e32 v165, v200, v201
	v_readlane_b32 s24, v112, 61
	s_lshl_b32 s24, s24, 10
	v_add_u32_e32 v206, s24, v208
	global_load_dwordx4 v[40:43], v206, s[12:13]
	s_waitcnt vmcnt(15)
	v_cvt_pk_f32_fp8_e32 v[184:185], v44
	v_cvt_pk_f32_fp8_sdwa v[186:187], v44 src0_sel:WORD_1
	v_cvt_pk_f32_fp8_e32 v[188:189], v45
	v_cvt_pk_f32_fp8_sdwa v[190:191], v45 src0_sel:WORD_1
	v_pk_mul_f32 v[200:201], v[80:81], v[184:185]
	v_cvt_pk_f32_fp8_e32 v[192:193], v46
	v_pk_mul_f32 v[202:203], v[82:83], v[186:187]
	v_cvt_pk_f32_fp8_sdwa v[194:195], v46 src0_sel:WORD_1
	v_pk_fma_f32 v[200:201], v[84:85], v[188:189], v[200:201]
	v_cvt_pk_f32_fp8_e32 v[196:197], v47
	v_pk_fma_f32 v[202:203], v[86:87], v[190:191], v[202:203]
	v_cvt_pk_f32_fp8_sdwa v[198:199], v47 src0_sel:WORD_1
	v_pk_fma_f32 v[200:201], v[88:89], v[192:193], v[200:201]
	v_pk_fma_f32 v[202:203], v[90:91], v[194:195], v[202:203]
	v_pk_fma_f32 v[200:201], v[92:93], v[196:197], v[200:201]
	v_pk_fma_f32 v[202:203], v[94:95], v[198:199], v[202:203]
	v_pk_add_f32 v[200:201], v[200:201], v[202:203]
	v_add_f32_e32 v173, v200, v201
	v_readlane_b32 s25, v120, 61
	s_lshl_b32 s25, s25, 10
	v_add_u32_e32 v207, s25, v208
	global_load_dwordx4 v[44:47], v207, s[12:13]
	s_waitcnt vmcnt(15)
	v_cvt_pk_f32_fp8_e32 v[184:185], v48
	v_cvt_pk_f32_fp8_sdwa v[186:187], v48 src0_sel:WORD_1
	v_cvt_pk_f32_fp8_e32 v[188:189], v49
	v_cvt_pk_f32_fp8_sdwa v[190:191], v49 src0_sel:WORD_1
	v_pk_mul_f32 v[200:201], v[64:65], v[184:185]
	v_cvt_pk_f32_fp8_e32 v[192:193], v50
	v_pk_mul_f32 v[202:203], v[66:67], v[186:187]
	v_cvt_pk_f32_fp8_sdwa v[194:195], v50 src0_sel:WORD_1
	v_pk_fma_f32 v[200:201], v[68:69], v[188:189], v[200:201]
	v_cvt_pk_f32_fp8_e32 v[196:197], v51
	v_pk_fma_f32 v[202:203], v[70:71], v[190:191], v[202:203]
	v_cvt_pk_f32_fp8_sdwa v[198:199], v51 src0_sel:WORD_1
	v_pk_fma_f32 v[200:201], v[72:73], v[192:193], v[200:201]
	v_pk_fma_f32 v[202:203], v[74:75], v[194:195], v[202:203]
	v_pk_fma_f32 v[200:201], v[76:77], v[196:197], v[200:201]
	v_pk_fma_f32 v[202:203], v[78:79], v[198:199], v[202:203]
	v_pk_add_f32 v[200:201], v[200:201], v[202:203]
	v_add_f32_e32 v166, v200, v201
	v_readlane_b32 s22, v112, 62
	s_lshl_b32 s22, s22, 10
	v_add_u32_e32 v204, s22, v208
	global_load_dwordx4 v[48:51], v204, s[12:13]
	s_waitcnt vmcnt(15)
	v_cvt_pk_f32_fp8_e32 v[184:185], v52
	v_cvt_pk_f32_fp8_sdwa v[186:187], v52 src0_sel:WORD_1
	v_cvt_pk_f32_fp8_e32 v[188:189], v53
	v_cvt_pk_f32_fp8_sdwa v[190:191], v53 src0_sel:WORD_1
	v_pk_mul_f32 v[200:201], v[80:81], v[184:185]
	v_cvt_pk_f32_fp8_e32 v[192:193], v54
	v_pk_mul_f32 v[202:203], v[82:83], v[186:187]
	v_cvt_pk_f32_fp8_sdwa v[194:195], v54 src0_sel:WORD_1
	v_pk_fma_f32 v[200:201], v[84:85], v[188:189], v[200:201]
	v_cvt_pk_f32_fp8_e32 v[196:197], v55
	v_pk_fma_f32 v[202:203], v[86:87], v[190:191], v[202:203]
	v_cvt_pk_f32_fp8_sdwa v[198:199], v55 src0_sel:WORD_1
	v_pk_fma_f32 v[200:201], v[88:89], v[192:193], v[200:201]
	v_pk_fma_f32 v[202:203], v[90:91], v[194:195], v[202:203]
	v_pk_fma_f32 v[200:201], v[92:93], v[196:197], v[200:201]
	v_pk_fma_f32 v[202:203], v[94:95], v[198:199], v[202:203]
	v_pk_add_f32 v[200:201], v[200:201], v[202:203]
	v_add_f32_e32 v174, v200, v201
	v_readlane_b32 s23, v120, 62
	s_lshl_b32 s23, s23, 10
	v_add_u32_e32 v205, s23, v208
	global_load_dwordx4 v[52:55], v205, s[12:13]
	s_waitcnt vmcnt(15)
	v_cvt_pk_f32_fp8_e32 v[184:185], v56
	v_cvt_pk_f32_fp8_sdwa v[186:187], v56 src0_sel:WORD_1
	v_cvt_pk_f32_fp8_e32 v[188:189], v57
	v_cvt_pk_f32_fp8_sdwa v[190:191], v57 src0_sel:WORD_1
	v_pk_mul_f32 v[200:201], v[64:65], v[184:185]
	v_cvt_pk_f32_fp8_e32 v[192:193], v58
	v_pk_mul_f32 v[202:203], v[66:67], v[186:187]
	v_cvt_pk_f32_fp8_sdwa v[194:195], v58 src0_sel:WORD_1
	v_pk_fma_f32 v[200:201], v[68:69], v[188:189], v[200:201]
	v_cvt_pk_f32_fp8_e32 v[196:197], v59
	v_pk_fma_f32 v[202:203], v[70:71], v[190:191], v[202:203]
	v_cvt_pk_f32_fp8_sdwa v[198:199], v59 src0_sel:WORD_1
	v_pk_fma_f32 v[200:201], v[72:73], v[192:193], v[200:201]
	v_pk_fma_f32 v[202:203], v[74:75], v[194:195], v[202:203]
	v_pk_fma_f32 v[200:201], v[76:77], v[196:197], v[200:201]
	v_pk_fma_f32 v[202:203], v[78:79], v[198:199], v[202:203]
	v_pk_add_f32 v[200:201], v[200:201], v[202:203]
	v_add_f32_e32 v167, v200, v201
	v_readlane_b32 s24, v112, 63
	s_lshl_b32 s24, s24, 10
	v_add_u32_e32 v206, s24, v208
	global_load_dwordx4 v[56:59], v206, s[12:13]
	s_nop 1
	v_permlane32_swap_b32_e32 v160, v164
	v_permlane32_swap_b32_e32 v161, v165
	v_permlane32_swap_b32_e32 v162, v166
	v_permlane32_swap_b32_e32 v163, v167
	v_add_f32_e32 v160, v160, v164
	v_add_f32_e32 v161, v161, v165
	v_add_f32_e32 v162, v162, v166
	v_add_f32_e32 v163, v163, v167
	v_cndmask_b32_e64 v216, v162, v160, s[26:27]
	v_cndmask_b32_e64 v218, v160, v162, s[26:27]
	v_cndmask_b32_e64 v217, v163, v161, s[26:27]
	v_cndmask_b32_e64 v219, v161, v163, s[26:27]
	ds_bpermute_b32 v220, v212, v216
	ds_bpermute_b32 v221, v212, v217
	s_waitcnt lgkmcnt(0)
	v_add_f32_e32 v218, v220, v218
	v_add_f32_e32 v219, v221, v219
	v_cndmask_b32_e64 v216, v219, v218, s[28:29]
	v_cndmask_b32_e64 v217, v218, v219, s[28:29]
	s_nop 1
	v_add_f32_dpp v222, v216, v217 row_ror:8 row_mask:0xf bank_mask:0xf
	ds_bpermute_b32 v220, v213, v222
	s_waitcnt lgkmcnt(0)
	v_add_f32_e32 v222, v220, v222
	s_nop 1
	v_add_f32_dpp v223, v222, v222 quad_perm:[2,3,0,1] row_mask:0xf bank_mask:0xf
	s_nop 1
	v_add_f32_dpp v222, v223, v223 quad_perm:[1,0,3,2] row_mask:0xf bank_mask:0xf
	ds_bpermute_b32 v220, v214, v222
	s_mov_b32 s30, 0x0
	s_mov_b32 s31, 0xff0000
	s_waitcnt lgkmcnt(0)
	v_cndmask_b32_e64 v176, v176, v220, s[30:31]
	s_waitcnt vmcnt(15)
	v_cvt_pk_f32_fp8_e32 v[184:185], v60
	v_cvt_pk_f32_fp8_sdwa v[186:187], v60 src0_sel:WORD_1
	v_cvt_pk_f32_fp8_e32 v[188:189], v61
	v_cvt_pk_f32_fp8_sdwa v[190:191], v61 src0_sel:WORD_1
	v_pk_mul_f32 v[200:201], v[80:81], v[184:185]
	v_cvt_pk_f32_fp8_e32 v[192:193], v62
	v_pk_mul_f32 v[202:203], v[82:83], v[186:187]
	v_cvt_pk_f32_fp8_sdwa v[194:195], v62 src0_sel:WORD_1
	v_pk_fma_f32 v[200:201], v[84:85], v[188:189], v[200:201]
	v_cvt_pk_f32_fp8_e32 v[196:197], v63
	v_pk_fma_f32 v[202:203], v[86:87], v[190:191], v[202:203]
	v_cvt_pk_f32_fp8_sdwa v[198:199], v63 src0_sel:WORD_1
	v_pk_fma_f32 v[200:201], v[88:89], v[192:193], v[200:201]
	v_pk_fma_f32 v[202:203], v[90:91], v[194:195], v[202:203]
	v_pk_fma_f32 v[200:201], v[92:93], v[196:197], v[200:201]
	v_pk_fma_f32 v[202:203], v[94:95], v[198:199], v[202:203]
	v_pk_add_f32 v[200:201], v[200:201], v[202:203]
	v_add_f32_e32 v175, v200, v201
	v_readlane_b32 s25, v120, 63
	s_lshl_b32 s25, s25, 10
	v_add_u32_e32 v207, s25, v208
	global_load_dwordx4 v[60:63], v207, s[12:13]
	s_nop 1
	v_permlane32_swap_b32_e32 v168, v172
	v_permlane32_swap_b32_e32 v169, v173
	v_permlane32_swap_b32_e32 v170, v174
	v_permlane32_swap_b32_e32 v171, v175
	v_add_f32_e32 v168, v168, v172
	v_add_f32_e32 v169, v169, v173
	v_add_f32_e32 v170, v170, v174
	v_add_f32_e32 v171, v171, v175
	v_cndmask_b32_e64 v216, v170, v168, s[26:27]
	v_cndmask_b32_e64 v218, v168, v170, s[26:27]
	v_cndmask_b32_e64 v217, v171, v169, s[26:27]
	v_cndmask_b32_e64 v219, v169, v171, s[26:27]
	ds_bpermute_b32 v220, v212, v216
	ds_bpermute_b32 v221, v212, v217
	s_waitcnt lgkmcnt(0)
	v_add_f32_e32 v218, v220, v218
	v_add_f32_e32 v219, v221, v219
	v_cndmask_b32_e64 v216, v219, v218, s[28:29]
	v_cndmask_b32_e64 v217, v218, v219, s[28:29]
	s_nop 1
	v_add_f32_dpp v222, v216, v217 row_ror:8 row_mask:0xf bank_mask:0xf
	ds_bpermute_b32 v220, v213, v222
	s_waitcnt lgkmcnt(0)
	v_add_f32_e32 v222, v220, v222
	s_nop 1
	v_add_f32_dpp v223, v222, v222 quad_perm:[2,3,0,1] row_mask:0xf bank_mask:0xf
	s_nop 1
	v_add_f32_dpp v222, v223, v223 quad_perm:[1,0,3,2] row_mask:0xf bank_mask:0xf
	ds_bpermute_b32 v220, v214, v222
	s_mov_b32 s30, 0x0
	s_mov_b32 s31, 0xff0000
	s_waitcnt lgkmcnt(0)
	v_cndmask_b32_e64 v179, v179, v220, s[30:31]
	s_waitcnt vmcnt(15)
	v_cvt_pk_f32_fp8_e32 v[184:185], v0
	v_cvt_pk_f32_fp8_sdwa v[186:187], v0 src0_sel:WORD_1
	v_cvt_pk_f32_fp8_e32 v[188:189], v1
	v_cvt_pk_f32_fp8_sdwa v[190:191], v1 src0_sel:WORD_1
	v_pk_mul_f32 v[200:201], v[64:65], v[184:185]
	v_cvt_pk_f32_fp8_e32 v[192:193], v2
	v_pk_mul_f32 v[202:203], v[66:67], v[186:187]
	v_cvt_pk_f32_fp8_sdwa v[194:195], v2 src0_sel:WORD_1
	v_pk_fma_f32 v[200:201], v[68:69], v[188:189], v[200:201]
	v_cvt_pk_f32_fp8_e32 v[196:197], v3
	v_pk_fma_f32 v[202:203], v[70:71], v[190:191], v[202:203]
	v_cvt_pk_f32_fp8_sdwa v[198:199], v3 src0_sel:WORD_1
	v_pk_fma_f32 v[200:201], v[72:73], v[192:193], v[200:201]
	v_pk_fma_f32 v[202:203], v[74:75], v[194:195], v[202:203]
	v_pk_fma_f32 v[200:201], v[76:77], v[196:197], v[200:201]
	v_pk_fma_f32 v[202:203], v[78:79], v[198:199], v[202:203]
	v_pk_add_f32 v[200:201], v[200:201], v[202:203]
	v_add_f32_e32 v160, v200, v201
	v_readlane_b32 s22, v113, 0
	s_lshl_b32 s22, s22, 10
	v_add_u32_e32 v204, s22, v208
	global_load_dwordx4 v[0:3], v204, s[12:13]
	s_waitcnt vmcnt(15)
	v_cvt_pk_f32_fp8_e32 v[184:185], v4
	v_cvt_pk_f32_fp8_sdwa v[186:187], v4 src0_sel:WORD_1
	v_cvt_pk_f32_fp8_e32 v[188:189], v5
	v_cvt_pk_f32_fp8_sdwa v[190:191], v5 src0_sel:WORD_1
	v_pk_mul_f32 v[200:201], v[80:81], v[184:185]
	v_cvt_pk_f32_fp8_e32 v[192:193], v6
	v_pk_mul_f32 v[202:203], v[82:83], v[186:187]
	v_cvt_pk_f32_fp8_sdwa v[194:195], v6 src0_sel:WORD_1
	v_pk_fma_f32 v[200:201], v[84:85], v[188:189], v[200:201]
	v_cvt_pk_f32_fp8_e32 v[196:197], v7
	v_pk_fma_f32 v[202:203], v[86:87], v[190:191], v[202:203]
	v_cvt_pk_f32_fp8_sdwa v[198:199], v7 src0_sel:WORD_1
	v_pk_fma_f32 v[200:201], v[88:89], v[192:193], v[200:201]
	v_pk_fma_f32 v[202:203], v[90:91], v[194:195], v[202:203]
	v_pk_fma_f32 v[200:201], v[92:93], v[196:197], v[200:201]
	v_pk_fma_f32 v[202:203], v[94:95], v[198:199], v[202:203]
	v_pk_add_f32 v[200:201], v[200:201], v[202:203]
	v_add_f32_e32 v168, v200, v201
	v_readlane_b32 s23, v121, 0
	s_lshl_b32 s23, s23, 10
	v_add_u32_e32 v205, s23, v208
	global_load_dwordx4 v[4:7], v205, s[12:13]
	s_waitcnt vmcnt(15)
	v_cvt_pk_f32_fp8_e32 v[184:185], v8
	v_cvt_pk_f32_fp8_sdwa v[186:187], v8 src0_sel:WORD_1
	v_cvt_pk_f32_fp8_e32 v[188:189], v9
	v_cvt_pk_f32_fp8_sdwa v[190:191], v9 src0_sel:WORD_1
	v_pk_mul_f32 v[200:201], v[64:65], v[184:185]
	v_cvt_pk_f32_fp8_e32 v[192:193], v10
	v_pk_mul_f32 v[202:203], v[66:67], v[186:187]
	v_cvt_pk_f32_fp8_sdwa v[194:195], v10 src0_sel:WORD_1
	v_pk_fma_f32 v[200:201], v[68:69], v[188:189], v[200:201]
	v_cvt_pk_f32_fp8_e32 v[196:197], v11
	v_pk_fma_f32 v[202:203], v[70:71], v[190:191], v[202:203]
	v_cvt_pk_f32_fp8_sdwa v[198:199], v11 src0_sel:WORD_1
	v_pk_fma_f32 v[200:201], v[72:73], v[192:193], v[200:201]
	v_pk_fma_f32 v[202:203], v[74:75], v[194:195], v[202:203]
	v_pk_fma_f32 v[200:201], v[76:77], v[196:197], v[200:201]
	v_pk_fma_f32 v[202:203], v[78:79], v[198:199], v[202:203]
	v_pk_add_f32 v[200:201], v[200:201], v[202:203]
	v_add_f32_e32 v161, v200, v201
	v_readlane_b32 s24, v113, 1
	s_lshl_b32 s24, s24, 10
	v_add_u32_e32 v206, s24, v208
	global_load_dwordx4 v[8:11], v206, s[12:13]
	s_waitcnt vmcnt(15)
	v_cvt_pk_f32_fp8_e32 v[184:185], v12
	v_cvt_pk_f32_fp8_sdwa v[186:187], v12 src0_sel:WORD_1
	v_cvt_pk_f32_fp8_e32 v[188:189], v13
	v_cvt_pk_f32_fp8_sdwa v[190:191], v13 src0_sel:WORD_1
	v_pk_mul_f32 v[200:201], v[80:81], v[184:185]
	v_cvt_pk_f32_fp8_e32 v[192:193], v14
	v_pk_mul_f32 v[202:203], v[82:83], v[186:187]
	v_cvt_pk_f32_fp8_sdwa v[194:195], v14 src0_sel:WORD_1
	v_pk_fma_f32 v[200:201], v[84:85], v[188:189], v[200:201]
	v_cvt_pk_f32_fp8_e32 v[196:197], v15
	v_pk_fma_f32 v[202:203], v[86:87], v[190:191], v[202:203]
	v_cvt_pk_f32_fp8_sdwa v[198:199], v15 src0_sel:WORD_1
	v_pk_fma_f32 v[200:201], v[88:89], v[192:193], v[200:201]
	v_pk_fma_f32 v[202:203], v[90:91], v[194:195], v[202:203]
	v_pk_fma_f32 v[200:201], v[92:93], v[196:197], v[200:201]
	v_pk_fma_f32 v[202:203], v[94:95], v[198:199], v[202:203]
	v_pk_add_f32 v[200:201], v[200:201], v[202:203]
	v_add_f32_e32 v169, v200, v201
	v_readlane_b32 s25, v121, 1
	s_lshl_b32 s25, s25, 10
	v_add_u32_e32 v207, s25, v208
	global_load_dwordx4 v[12:15], v207, s[12:13]
	s_waitcnt vmcnt(15)
	v_cvt_pk_f32_fp8_e32 v[184:185], v16
	v_cvt_pk_f32_fp8_sdwa v[186:187], v16 src0_sel:WORD_1
	v_cvt_pk_f32_fp8_e32 v[188:189], v17
	v_cvt_pk_f32_fp8_sdwa v[190:191], v17 src0_sel:WORD_1
	v_pk_mul_f32 v[200:201], v[64:65], v[184:185]
	v_cvt_pk_f32_fp8_e32 v[192:193], v18
	v_pk_mul_f32 v[202:203], v[66:67], v[186:187]
	v_cvt_pk_f32_fp8_sdwa v[194:195], v18 src0_sel:WORD_1
	v_pk_fma_f32 v[200:201], v[68:69], v[188:189], v[200:201]
	v_cvt_pk_f32_fp8_e32 v[196:197], v19
	v_pk_fma_f32 v[202:203], v[70:71], v[190:191], v[202:203]
	v_cvt_pk_f32_fp8_sdwa v[198:199], v19 src0_sel:WORD_1
	v_pk_fma_f32 v[200:201], v[72:73], v[192:193], v[200:201]
	v_pk_fma_f32 v[202:203], v[74:75], v[194:195], v[202:203]
	v_pk_fma_f32 v[200:201], v[76:77], v[196:197], v[200:201]
	v_pk_fma_f32 v[202:203], v[78:79], v[198:199], v[202:203]
	v_pk_add_f32 v[200:201], v[200:201], v[202:203]
	v_add_f32_e32 v162, v200, v201
	v_readlane_b32 s22, v113, 2
	s_lshl_b32 s22, s22, 10
	v_add_u32_e32 v204, s22, v208
	global_load_dwordx4 v[16:19], v204, s[12:13]
	s_waitcnt vmcnt(15)
	v_cvt_pk_f32_fp8_e32 v[184:185], v20
	v_cvt_pk_f32_fp8_sdwa v[186:187], v20 src0_sel:WORD_1
	v_cvt_pk_f32_fp8_e32 v[188:189], v21
	v_cvt_pk_f32_fp8_sdwa v[190:191], v21 src0_sel:WORD_1
	v_pk_mul_f32 v[200:201], v[80:81], v[184:185]
	v_cvt_pk_f32_fp8_e32 v[192:193], v22
	v_pk_mul_f32 v[202:203], v[82:83], v[186:187]
	v_cvt_pk_f32_fp8_sdwa v[194:195], v22 src0_sel:WORD_1
	v_pk_fma_f32 v[200:201], v[84:85], v[188:189], v[200:201]
	v_cvt_pk_f32_fp8_e32 v[196:197], v23
	v_pk_fma_f32 v[202:203], v[86:87], v[190:191], v[202:203]
	v_cvt_pk_f32_fp8_sdwa v[198:199], v23 src0_sel:WORD_1
	v_pk_fma_f32 v[200:201], v[88:89], v[192:193], v[200:201]
	v_pk_fma_f32 v[202:203], v[90:91], v[194:195], v[202:203]
	v_pk_fma_f32 v[200:201], v[92:93], v[196:197], v[200:201]
	v_pk_fma_f32 v[202:203], v[94:95], v[198:199], v[202:203]
	v_pk_add_f32 v[200:201], v[200:201], v[202:203]
	v_add_f32_e32 v170, v200, v201
	v_readlane_b32 s23, v121, 2
	s_lshl_b32 s23, s23, 10
	v_add_u32_e32 v205, s23, v208
	global_load_dwordx4 v[20:23], v205, s[12:13]
	s_waitcnt vmcnt(15)
	v_cvt_pk_f32_fp8_e32 v[184:185], v24
	v_cvt_pk_f32_fp8_sdwa v[186:187], v24 src0_sel:WORD_1
	v_cvt_pk_f32_fp8_e32 v[188:189], v25
	v_cvt_pk_f32_fp8_sdwa v[190:191], v25 src0_sel:WORD_1
	v_pk_mul_f32 v[200:201], v[64:65], v[184:185]
	v_cvt_pk_f32_fp8_e32 v[192:193], v26
	v_pk_mul_f32 v[202:203], v[66:67], v[186:187]
	v_cvt_pk_f32_fp8_sdwa v[194:195], v26 src0_sel:WORD_1
	v_pk_fma_f32 v[200:201], v[68:69], v[188:189], v[200:201]
	v_cvt_pk_f32_fp8_e32 v[196:197], v27
	v_pk_fma_f32 v[202:203], v[70:71], v[190:191], v[202:203]
	v_cvt_pk_f32_fp8_sdwa v[198:199], v27 src0_sel:WORD_1
	v_pk_fma_f32 v[200:201], v[72:73], v[192:193], v[200:201]
	v_pk_fma_f32 v[202:203], v[74:75], v[194:195], v[202:203]
	v_pk_fma_f32 v[200:201], v[76:77], v[196:197], v[200:201]
	v_pk_fma_f32 v[202:203], v[78:79], v[198:199], v[202:203]
	v_pk_add_f32 v[200:201], v[200:201], v[202:203]
	v_add_f32_e32 v163, v200, v201
	v_readlane_b32 s24, v113, 3
	s_lshl_b32 s24, s24, 10
	v_add_u32_e32 v206, s24, v208
	global_load_dwordx4 v[24:27], v206, s[12:13]
	s_waitcnt vmcnt(15)
	v_cvt_pk_f32_fp8_e32 v[184:185], v28
	v_cvt_pk_f32_fp8_sdwa v[186:187], v28 src0_sel:WORD_1
	v_cvt_pk_f32_fp8_e32 v[188:189], v29
	v_cvt_pk_f32_fp8_sdwa v[190:191], v29 src0_sel:WORD_1
	v_pk_mul_f32 v[200:201], v[80:81], v[184:185]
	v_cvt_pk_f32_fp8_e32 v[192:193], v30
	v_pk_mul_f32 v[202:203], v[82:83], v[186:187]
	v_cvt_pk_f32_fp8_sdwa v[194:195], v30 src0_sel:WORD_1
	v_pk_fma_f32 v[200:201], v[84:85], v[188:189], v[200:201]
	v_cvt_pk_f32_fp8_e32 v[196:197], v31
	v_pk_fma_f32 v[202:203], v[86:87], v[190:191], v[202:203]
	v_cvt_pk_f32_fp8_sdwa v[198:199], v31 src0_sel:WORD_1
	v_pk_fma_f32 v[200:201], v[88:89], v[192:193], v[200:201]
	v_pk_fma_f32 v[202:203], v[90:91], v[194:195], v[202:203]
	v_pk_fma_f32 v[200:201], v[92:93], v[196:197], v[200:201]
	v_pk_fma_f32 v[202:203], v[94:95], v[198:199], v[202:203]
	v_pk_add_f32 v[200:201], v[200:201], v[202:203]
	v_add_f32_e32 v171, v200, v201
	v_readlane_b32 s25, v121, 3
	s_lshl_b32 s25, s25, 10
	v_add_u32_e32 v207, s25, v208
	global_load_dwordx4 v[28:31], v207, s[12:13]
	s_waitcnt vmcnt(15)
	v_cvt_pk_f32_fp8_e32 v[184:185], v32
	v_cvt_pk_f32_fp8_sdwa v[186:187], v32 src0_sel:WORD_1
	v_cvt_pk_f32_fp8_e32 v[188:189], v33
	v_cvt_pk_f32_fp8_sdwa v[190:191], v33 src0_sel:WORD_1
	v_pk_mul_f32 v[200:201], v[64:65], v[184:185]
	v_cvt_pk_f32_fp8_e32 v[192:193], v34
	v_pk_mul_f32 v[202:203], v[66:67], v[186:187]
	v_cvt_pk_f32_fp8_sdwa v[194:195], v34 src0_sel:WORD_1
	v_pk_fma_f32 v[200:201], v[68:69], v[188:189], v[200:201]
	v_cvt_pk_f32_fp8_e32 v[196:197], v35
	v_pk_fma_f32 v[202:203], v[70:71], v[190:191], v[202:203]
	v_cvt_pk_f32_fp8_sdwa v[198:199], v35 src0_sel:WORD_1
	v_pk_fma_f32 v[200:201], v[72:73], v[192:193], v[200:201]
	v_pk_fma_f32 v[202:203], v[74:75], v[194:195], v[202:203]
	v_pk_fma_f32 v[200:201], v[76:77], v[196:197], v[200:201]
	v_pk_fma_f32 v[202:203], v[78:79], v[198:199], v[202:203]
	v_pk_add_f32 v[200:201], v[200:201], v[202:203]
	v_add_f32_e32 v164, v200, v201
	v_readlane_b32 s22, v113, 4
	s_lshl_b32 s22, s22, 10
	v_add_u32_e32 v204, s22, v208
	global_load_dwordx4 v[32:35], v204, s[12:13]
	s_waitcnt vmcnt(15)
	v_cvt_pk_f32_fp8_e32 v[184:185], v36
	v_cvt_pk_f32_fp8_sdwa v[186:187], v36 src0_sel:WORD_1
	v_cvt_pk_f32_fp8_e32 v[188:189], v37
	v_cvt_pk_f32_fp8_sdwa v[190:191], v37 src0_sel:WORD_1
	v_pk_mul_f32 v[200:201], v[80:81], v[184:185]
	v_cvt_pk_f32_fp8_e32 v[192:193], v38
	v_pk_mul_f32 v[202:203], v[82:83], v[186:187]
	v_cvt_pk_f32_fp8_sdwa v[194:195], v38 src0_sel:WORD_1
	v_pk_fma_f32 v[200:201], v[84:85], v[188:189], v[200:201]
	v_cvt_pk_f32_fp8_e32 v[196:197], v39
	v_pk_fma_f32 v[202:203], v[86:87], v[190:191], v[202:203]
	v_cvt_pk_f32_fp8_sdwa v[198:199], v39 src0_sel:WORD_1
	v_pk_fma_f32 v[200:201], v[88:89], v[192:193], v[200:201]
	v_pk_fma_f32 v[202:203], v[90:91], v[194:195], v[202:203]
	v_pk_fma_f32 v[200:201], v[92:93], v[196:197], v[200:201]
	v_pk_fma_f32 v[202:203], v[94:95], v[198:199], v[202:203]
	v_pk_add_f32 v[200:201], v[200:201], v[202:203]
	v_add_f32_e32 v172, v200, v201
	v_readlane_b32 s23, v121, 4
	s_lshl_b32 s23, s23, 10
	v_add_u32_e32 v205, s23, v208
	global_load_dwordx4 v[36:39], v205, s[12:13]
	s_waitcnt vmcnt(15)
	v_cvt_pk_f32_fp8_e32 v[184:185], v40
	v_cvt_pk_f32_fp8_sdwa v[186:187], v40 src0_sel:WORD_1
	v_cvt_pk_f32_fp8_e32 v[188:189], v41
	v_cvt_pk_f32_fp8_sdwa v[190:191], v41 src0_sel:WORD_1
	v_pk_mul_f32 v[200:201], v[64:65], v[184:185]
	v_cvt_pk_f32_fp8_e32 v[192:193], v42
	v_pk_mul_f32 v[202:203], v[66:67], v[186:187]
	v_cvt_pk_f32_fp8_sdwa v[194:195], v42 src0_sel:WORD_1
	v_pk_fma_f32 v[200:201], v[68:69], v[188:189], v[200:201]
	v_cvt_pk_f32_fp8_e32 v[196:197], v43
	v_pk_fma_f32 v[202:203], v[70:71], v[190:191], v[202:203]
	v_cvt_pk_f32_fp8_sdwa v[198:199], v43 src0_sel:WORD_1
	v_pk_fma_f32 v[200:201], v[72:73], v[192:193], v[200:201]
	v_pk_fma_f32 v[202:203], v[74:75], v[194:195], v[202:203]
	v_pk_fma_f32 v[200:201], v[76:77], v[196:197], v[200:201]
	v_pk_fma_f32 v[202:203], v[78:79], v[198:199], v[202:203]
	v_pk_add_f32 v[200:201], v[200:201], v[202:203]
	v_add_f32_e32 v165, v200, v201
	v_readlane_b32 s24, v113, 5
	s_lshl_b32 s24, s24, 10
	v_add_u32_e32 v206, s24, v208
	global_load_dwordx4 v[40:43], v206, s[12:13]
	s_waitcnt vmcnt(15)
	v_cvt_pk_f32_fp8_e32 v[184:185], v44
	v_cvt_pk_f32_fp8_sdwa v[186:187], v44 src0_sel:WORD_1
	v_cvt_pk_f32_fp8_e32 v[188:189], v45
	v_cvt_pk_f32_fp8_sdwa v[190:191], v45 src0_sel:WORD_1
	v_pk_mul_f32 v[200:201], v[80:81], v[184:185]
	v_cvt_pk_f32_fp8_e32 v[192:193], v46
	v_pk_mul_f32 v[202:203], v[82:83], v[186:187]
	v_cvt_pk_f32_fp8_sdwa v[194:195], v46 src0_sel:WORD_1
	v_pk_fma_f32 v[200:201], v[84:85], v[188:189], v[200:201]
	v_cvt_pk_f32_fp8_e32 v[196:197], v47
	v_pk_fma_f32 v[202:203], v[86:87], v[190:191], v[202:203]
	v_cvt_pk_f32_fp8_sdwa v[198:199], v47 src0_sel:WORD_1
	v_pk_fma_f32 v[200:201], v[88:89], v[192:193], v[200:201]
	v_pk_fma_f32 v[202:203], v[90:91], v[194:195], v[202:203]
	v_pk_fma_f32 v[200:201], v[92:93], v[196:197], v[200:201]
	v_pk_fma_f32 v[202:203], v[94:95], v[198:199], v[202:203]
	v_pk_add_f32 v[200:201], v[200:201], v[202:203]
	v_add_f32_e32 v173, v200, v201
	v_readlane_b32 s25, v121, 5
	s_lshl_b32 s25, s25, 10
	v_add_u32_e32 v207, s25, v208
	global_load_dwordx4 v[44:47], v207, s[12:13]
	s_waitcnt vmcnt(15)
	v_cvt_pk_f32_fp8_e32 v[184:185], v48
	v_cvt_pk_f32_fp8_sdwa v[186:187], v48 src0_sel:WORD_1
	v_cvt_pk_f32_fp8_e32 v[188:189], v49
	v_cvt_pk_f32_fp8_sdwa v[190:191], v49 src0_sel:WORD_1
	v_pk_mul_f32 v[200:201], v[64:65], v[184:185]
	v_cvt_pk_f32_fp8_e32 v[192:193], v50
	v_pk_mul_f32 v[202:203], v[66:67], v[186:187]
	v_cvt_pk_f32_fp8_sdwa v[194:195], v50 src0_sel:WORD_1
	v_pk_fma_f32 v[200:201], v[68:69], v[188:189], v[200:201]
	v_cvt_pk_f32_fp8_e32 v[196:197], v51
	v_pk_fma_f32 v[202:203], v[70:71], v[190:191], v[202:203]
	v_cvt_pk_f32_fp8_sdwa v[198:199], v51 src0_sel:WORD_1
	v_pk_fma_f32 v[200:201], v[72:73], v[192:193], v[200:201]
	v_pk_fma_f32 v[202:203], v[74:75], v[194:195], v[202:203]
	v_pk_fma_f32 v[200:201], v[76:77], v[196:197], v[200:201]
	v_pk_fma_f32 v[202:203], v[78:79], v[198:199], v[202:203]
	v_pk_add_f32 v[200:201], v[200:201], v[202:203]
	v_add_f32_e32 v166, v200, v201
	v_readlane_b32 s22, v113, 6
	s_lshl_b32 s22, s22, 10
	v_add_u32_e32 v204, s22, v208
	global_load_dwordx4 v[48:51], v204, s[12:13]
	s_waitcnt vmcnt(15)
	v_cvt_pk_f32_fp8_e32 v[184:185], v52
	v_cvt_pk_f32_fp8_sdwa v[186:187], v52 src0_sel:WORD_1
	v_cvt_pk_f32_fp8_e32 v[188:189], v53
	v_cvt_pk_f32_fp8_sdwa v[190:191], v53 src0_sel:WORD_1
	v_pk_mul_f32 v[200:201], v[80:81], v[184:185]
	v_cvt_pk_f32_fp8_e32 v[192:193], v54
	v_pk_mul_f32 v[202:203], v[82:83], v[186:187]
	v_cvt_pk_f32_fp8_sdwa v[194:195], v54 src0_sel:WORD_1
	v_pk_fma_f32 v[200:201], v[84:85], v[188:189], v[200:201]
	v_cvt_pk_f32_fp8_e32 v[196:197], v55
	v_pk_fma_f32 v[202:203], v[86:87], v[190:191], v[202:203]
	v_cvt_pk_f32_fp8_sdwa v[198:199], v55 src0_sel:WORD_1
	v_pk_fma_f32 v[200:201], v[88:89], v[192:193], v[200:201]
	v_pk_fma_f32 v[202:203], v[90:91], v[194:195], v[202:203]
	v_pk_fma_f32 v[200:201], v[92:93], v[196:197], v[200:201]
	v_pk_fma_f32 v[202:203], v[94:95], v[198:199], v[202:203]
	v_pk_add_f32 v[200:201], v[200:201], v[202:203]
	v_add_f32_e32 v174, v200, v201
	v_readlane_b32 s23, v121, 6
	s_lshl_b32 s23, s23, 10
	v_add_u32_e32 v205, s23, v208
	global_load_dwordx4 v[52:55], v205, s[12:13]
	s_waitcnt vmcnt(15)
	v_cvt_pk_f32_fp8_e32 v[184:185], v56
	v_cvt_pk_f32_fp8_sdwa v[186:187], v56 src0_sel:WORD_1
	v_cvt_pk_f32_fp8_e32 v[188:189], v57
	v_cvt_pk_f32_fp8_sdwa v[190:191], v57 src0_sel:WORD_1
	v_pk_mul_f32 v[200:201], v[64:65], v[184:185]
	v_cvt_pk_f32_fp8_e32 v[192:193], v58
	v_pk_mul_f32 v[202:203], v[66:67], v[186:187]
	v_cvt_pk_f32_fp8_sdwa v[194:195], v58 src0_sel:WORD_1
	v_pk_fma_f32 v[200:201], v[68:69], v[188:189], v[200:201]
	v_cvt_pk_f32_fp8_e32 v[196:197], v59
	v_pk_fma_f32 v[202:203], v[70:71], v[190:191], v[202:203]
	v_cvt_pk_f32_fp8_sdwa v[198:199], v59 src0_sel:WORD_1
	v_pk_fma_f32 v[200:201], v[72:73], v[192:193], v[200:201]
	v_pk_fma_f32 v[202:203], v[74:75], v[194:195], v[202:203]
	v_pk_fma_f32 v[200:201], v[76:77], v[196:197], v[200:201]
	v_pk_fma_f32 v[202:203], v[78:79], v[198:199], v[202:203]
	v_pk_add_f32 v[200:201], v[200:201], v[202:203]
	v_add_f32_e32 v167, v200, v201
	v_readlane_b32 s24, v113, 7
	s_lshl_b32 s24, s24, 10
	v_add_u32_e32 v206, s24, v208
	global_load_dwordx4 v[56:59], v206, s[12:13]
	s_nop 1
	v_permlane32_swap_b32_e32 v160, v164
	v_permlane32_swap_b32_e32 v161, v165
	v_permlane32_swap_b32_e32 v162, v166
	v_permlane32_swap_b32_e32 v163, v167
	v_add_f32_e32 v160, v160, v164
	v_add_f32_e32 v161, v161, v165
	v_add_f32_e32 v162, v162, v166
	v_add_f32_e32 v163, v163, v167
	v_cndmask_b32_e64 v216, v162, v160, s[26:27]
	v_cndmask_b32_e64 v218, v160, v162, s[26:27]
	v_cndmask_b32_e64 v217, v163, v161, s[26:27]
	v_cndmask_b32_e64 v219, v161, v163, s[26:27]
	ds_bpermute_b32 v220, v212, v216
	ds_bpermute_b32 v221, v212, v217
	s_waitcnt lgkmcnt(0)
; template <int PART>
; DEVI void phase_peer_gather(const Params& p, unsigned char* smem) {
;     ...
;       const int flip_ = (((tok - (blockIdx.x * 4 + w0_)) / (int)(gridDim.x * 4)) & 1) ? 15 : 0;
;       const int q0_ = (e0 >> 10) ^ flip_, q1_ = (e1 >> 10) ^ flip_;
; #pragma unroll
;       for (int q = 0; q < 16; ++q) {
;         const unsigned long long m0 = __ballot(q0_ == q), m1 = __ballot(q1_ == q);
;         const int c0 = __popcll(m0);
;         const int i0 = __builtin_amdgcn_mbcnt_hi((unsigned)(m0 >> 32), __builtin_amdgcn_mbcnt_lo((unsigned)m0, 0u));
;         const int i1 = __builtin_amdgcn_mbcnt_hi((unsigned)(m1 >> 32), __builtin_amdgcn_mbcnt_lo((unsigned)m1, 0u));
;         if (q0_ == q) pos0 = base + i0;
;         if (q1_ == q) pos1 = base + c0 + i1;
;         base += c0 + __popcll(m1);
;       }
	v_add_f32_e32 v218, v220, v218
	v_add_f32_e32 v219, v221, v219
	v_cndmask_b32_e64 v216, v219, v218, s[28:29]
	v_cndmask_b32_e64 v217, v218, v219, s[28:29]
	s_nop 1
	v_add_f32_dpp v222, v216, v217 row_ror:8 row_mask:0xf bank_mask:0xf
	ds_bpermute_b32 v220, v213, v222
	s_waitcnt lgkmcnt(0)
	v_add_f32_e32 v222, v220, v222
	s_nop 1
	v_add_f32_dpp v223, v222, v222 quad_perm:[2,3,0,1] row_mask:0xf bank_mask:0xf
	s_nop 1
	v_add_f32_dpp v222, v223, v223 quad_perm:[1,0,3,2] row_mask:0xf bank_mask:0xf
	ds_bpermute_b32 v220, v214, v222
	s_mov_b32 s30, 0x0
	s_mov_b32 s31, 0xff000000
	s_waitcnt lgkmcnt(0)
	v_cndmask_b32_e64 v176, v176, v220, s[30:31]
	v_mul_f32_e32 v216, v116, v176
	v_mul_f32_e32 v217, 0x3d372713, v216
	v_mul_f32_e32 v217, v216, v217
	v_fma_f32 v217, v216, v217, v216
	v_mul_f32_e32 v217, 0x3f4c422a, v217
	v_mul_f32_e32 v217, 0xc0000000, v217
	v_mul_f32_e32 v217, 0x3fb8aa3b, v217
	v_exp_f32_e32 v217, v217
	s_nop 0
	v_add_f32_e32 v217, 0x3f800000, v217
	v_rcp_f32_e32 v217, v217
	s_nop 0
	v_mul_f32_e32 v216, v216, v217
	v_mul_f32_e32 v216, v114, v216
	v_mul_f32_e32 v177, v118, v216
	s_waitcnt vmcnt(15)
	v_cvt_pk_f32_fp8_e32 v[184:185], v60
	v_cvt_pk_f32_fp8_sdwa v[186:187], v60 src0_sel:WORD_1
	v_cvt_pk_f32_fp8_e32 v[188:189], v61
	v_cvt_pk_f32_fp8_sdwa v[190:191], v61 src0_sel:WORD_1
	v_pk_mul_f32 v[200:201], v[80:81], v[184:185]
	v_cvt_pk_f32_fp8_e32 v[192:193], v62
	v_pk_mul_f32 v[202:203], v[82:83], v[186:187]
	v_cvt_pk_f32_fp8_sdwa v[194:195], v62 src0_sel:WORD_1
	v_pk_fma_f32 v[200:201], v[84:85], v[188:189], v[200:201]
	v_cvt_pk_f32_fp8_e32 v[196:197], v63
	v_pk_fma_f32 v[202:203], v[86:87], v[190:191], v[202:203]
	v_cvt_pk_f32_fp8_sdwa v[198:199], v63 src0_sel:WORD_1
	v_pk_fma_f32 v[200:201], v[88:89], v[192:193], v[200:201]
	v_pk_fma_f32 v[202:203], v[90:91], v[194:195], v[202:203]
	v_pk_fma_f32 v[200:201], v[92:93], v[196:197], v[200:201]
	v_pk_fma_f32 v[202:203], v[94:95], v[198:199], v[202:203]
	v_pk_add_f32 v[200:201], v[200:201], v[202:203]
	v_add_f32_e32 v175, v200, v201
	v_readlane_b32 s25, v121, 7
	s_lshl_b32 s25, s25, 10
	v_add_u32_e32 v207, s25, v208
	global_load_dwordx4 v[60:63], v207, s[12:13]
	s_nop 1
	v_permlane32_swap_b32_e32 v168, v172
	v_permlane32_swap_b32_e32 v169, v173
	v_permlane32_swap_b32_e32 v170, v174
	v_permlane32_swap_b32_e32 v171, v175
	v_add_f32_e32 v168, v168, v172
	v_add_f32_e32 v169, v169, v173
	v_add_f32_e32 v170, v170, v174
	v_add_f32_e32 v171, v171, v175
	v_cndmask_b32_e64 v216, v170, v168, s[26:27]
	v_cndmask_b32_e64 v218, v168, v170, s[26:27]
	v_cndmask_b32_e64 v217, v171, v169, s[26:27]
	v_cndmask_b32_e64 v219, v169, v171, s[26:27]
	ds_bpermute_b32 v220, v212, v216
	ds_bpermute_b32 v221, v212, v217
	s_waitcnt lgkmcnt(0)
	v_add_f32_e32 v218, v220, v218
	v_add_f32_e32 v219, v221, v219
	v_cndmask_b32_e64 v216, v219, v218, s[28:29]
	v_cndmask_b32_e64 v217, v218, v219, s[28:29]
	s_nop 1
	v_add_f32_dpp v222, v216, v217 row_ror:8 row_mask:0xf bank_mask:0xf
	ds_bpermute_b32 v220, v213, v222
	s_waitcnt lgkmcnt(0)
	v_add_f32_e32 v222, v220, v222
	s_nop 1
	v_add_f32_dpp v223, v222, v222 quad_perm:[2,3,0,1] row_mask:0xf bank_mask:0xf
	s_nop 1
	v_add_f32_dpp v222, v223, v223 quad_perm:[1,0,3,2] row_mask:0xf bank_mask:0xf
	ds_bpermute_b32 v220, v214, v222
	s_mov_b32 s30, 0x0
	s_mov_b32 s31, 0xff000000
	s_waitcnt lgkmcnt(0)
	v_cndmask_b32_e64 v179, v179, v220, s[30:31]
	v_mul_f32_e32 v216, v124, v179
	v_mul_f32_e32 v217, 0x3d372713, v216
	v_mul_f32_e32 v217, v216, v217
	v_fma_f32 v217, v216, v217, v216
	v_mul_f32_e32 v217, 0x3f4c422a, v217
	v_mul_f32_e32 v217, 0xc0000000, v217
	v_mul_f32_e32 v217, 0x3fb8aa3b, v217
	v_exp_f32_e32 v217, v217
	s_nop 0
	v_add_f32_e32 v217, 0x3f800000, v217
	v_rcp_f32_e32 v217, v217
	s_nop 0
	v_mul_f32_e32 v216, v216, v217
	v_mul_f32_e32 v216, v122, v216
	v_mul_f32_e32 v180, v126, v216
	s_xor_b32 s43, s43, 15
	s_xor_b32 s48, s43, 15
	s_add_u32 s40, s3, s42
	s_cmp_lt_u32 s40, 0x8000
	s_cselect_b32 s40, s40, s3
	s_cselect_b32 s48, s43, s48
	v_lshrrev_b32_e32 v226, 10, v128
	v_lshrrev_b32_e32 v227, 10, v129
	v_xor_b32_e32 v226, s48, v226
	v_xor_b32_e32 v227, s48, v227
	s_mov_b32 s38, 0
	v_cmp_eq_u32_e64 s[32:33], 0, v226
	v_cmp_eq_u32_e64 s[34:35], 0, v227
	s_bcnt1_i32_b64 s36, s[32:33]
	s_bcnt1_i32_b64 s37, s[34:35]
	s_add_u32 s36, s36, s38
	v_mbcnt_lo_u32_b32 v228, s32, 0
	v_mbcnt_hi_u32_b32 v228, s33, v228
	v_mbcnt_lo_u32_b32 v229, s34, 0
	v_mbcnt_hi_u32_b32 v229, s35, v229
	v_add_u32_e32 v228, s38, v228
	v_add_u32_e32 v229, s36, v229
	v_cndmask_b32_e64 v232, v232, v228, s[32:33]
	v_cndmask_b32_e64 v233, v233, v229, s[34:35]
	s_add_u32 s38, s36, s37
	v_cmp_eq_u32_e64 s[32:33], 1, v226
	v_cmp_eq_u32_e64 s[34:35], 1, v227
	s_bcnt1_i32_b64 s36, s[32:33]
	s_bcnt1_i32_b64 s37, s[34:35]
	s_add_u32 s36, s36, s38
	v_mbcnt_lo_u32_b32 v228, s32, 0
	v_mbcnt_hi_u32_b32 v228, s33, v228
	v_mbcnt_lo_u32_b32 v229, s34, 0
	v_mbcnt_hi_u32_b32 v229, s35, v229
	v_add_u32_e32 v228, s38, v228
	v_add_u32_e32 v229, s36, v229
	v_cndmask_b32_e64 v232, v232, v228, s[32:33]
	v_cndmask_b32_e64 v233, v233, v229, s[34:35]
	s_add_u32 s38, s36, s37
	v_cmp_eq_u32_e64 s[32:33], 2, v226
	v_cmp_eq_u32_e64 s[34:35], 2, v227
	s_bcnt1_i32_b64 s36, s[32:33]
	s_bcnt1_i32_b64 s37, s[34:35]
	s_add_u32 s36, s36, s38
	v_mbcnt_lo_u32_b32 v228, s32, 0
	v_mbcnt_hi_u32_b32 v228, s33, v228
	v_mbcnt_lo_u32_b32 v229, s34, 0
	v_mbcnt_hi_u32_b32 v229, s35, v229
	v_add_u32_e32 v228, s38, v228
	v_add_u32_e32 v229, s36, v229
	v_cndmask_b32_e64 v232, v232, v228, s[32:33]
	v_cndmask_b32_e64 v233, v233, v229, s[34:35]
	s_add_u32 s38, s36, s37
	v_cmp_eq_u32_e64 s[32:33], 3, v226
	v_cmp_eq_u32_e64 s[34:35], 3, v227
	s_bcnt1_i32_b64 s36, s[32:33]
; template <int PART>
; DEVI void phase_peer_gather(const Params& p, unsigned char* smem) {
;     ...
;       const int flip_ = (((tok - (blockIdx.x * 4 + w0_)) / (int)(gridDim.x * 4)) & 1) ? 15 : 0;
;       const int q0_ = (e0 >> 10) ^ flip_, q1_ = (e1 >> 10) ^ flip_;
; #pragma unroll
;       for (int q = 0; q < 16; ++q) {
;         const unsigned long long m0 = __ballot(q0_ == q), m1 = __ballot(q1_ == q);
;         const int c0 = __popcll(m0);
;         const int i0 = __builtin_amdgcn_mbcnt_hi((unsigned)(m0 >> 32), __builtin_amdgcn_mbcnt_lo((unsigned)m0, 0u));
;         const int i1 = __builtin_amdgcn_mbcnt_hi((unsigned)(m1 >> 32), __builtin_amdgcn_mbcnt_lo((unsigned)m1, 0u));
;         if (q0_ == q) pos0 = base + i0;
;         if (q1_ == q) pos1 = base + c0 + i1;
;         base += c0 + __popcll(m1);
;       }
	s_bcnt1_i32_b64 s37, s[34:35]
	s_add_u32 s36, s36, s38
	v_mbcnt_lo_u32_b32 v228, s32, 0
	v_mbcnt_hi_u32_b32 v228, s33, v228
	v_mbcnt_lo_u32_b32 v229, s34, 0
	v_mbcnt_hi_u32_b32 v229, s35, v229
	v_add_u32_e32 v228, s38, v228
	v_add_u32_e32 v229, s36, v229
	v_cndmask_b32_e64 v232, v232, v228, s[32:33]
	v_cndmask_b32_e64 v233, v233, v229, s[34:35]
	s_add_u32 s38, s36, s37
	v_cmp_eq_u32_e64 s[32:33], 4, v226
	v_cmp_eq_u32_e64 s[34:35], 4, v227
	s_bcnt1_i32_b64 s36, s[32:33]
	s_bcnt1_i32_b64 s37, s[34:35]
	s_add_u32 s36, s36, s38
	v_mbcnt_lo_u32_b32 v228, s32, 0
	v_mbcnt_hi_u32_b32 v228, s33, v228
	v_mbcnt_lo_u32_b32 v229, s34, 0
	v_mbcnt_hi_u32_b32 v229, s35, v229
	v_add_u32_e32 v228, s38, v228
	v_add_u32_e32 v229, s36, v229
	v_cndmask_b32_e64 v232, v232, v228, s[32:33]
	v_cndmask_b32_e64 v233, v233, v229, s[34:35]
	s_add_u32 s38, s36, s37
	v_cmp_eq_u32_e64 s[32:33], 5, v226
	v_cmp_eq_u32_e64 s[34:35], 5, v227
	s_bcnt1_i32_b64 s36, s[32:33]
	s_bcnt1_i32_b64 s37, s[34:35]
	s_add_u32 s36, s36, s38
	v_mbcnt_lo_u32_b32 v228, s32, 0
	v_mbcnt_hi_u32_b32 v228, s33, v228
	v_mbcnt_lo_u32_b32 v229, s34, 0
	v_mbcnt_hi_u32_b32 v229, s35, v229
	v_add_u32_e32 v228, s38, v228
	v_add_u32_e32 v229, s36, v229
	v_cndmask_b32_e64 v232, v232, v228, s[32:33]
	v_cndmask_b32_e64 v233, v233, v229, s[34:35]
	s_add_u32 s38, s36, s37
	v_cmp_eq_u32_e64 s[32:33], 6, v226
	v_cmp_eq_u32_e64 s[34:35], 6, v227
	s_bcnt1_i32_b64 s36, s[32:33]
	s_bcnt1_i32_b64 s37, s[34:35]
	s_add_u32 s36, s36, s38
	v_mbcnt_lo_u32_b32 v228, s32, 0
	v_mbcnt_hi_u32_b32 v228, s33, v228
	v_mbcnt_lo_u32_b32 v229, s34, 0
	v_mbcnt_hi_u32_b32 v229, s35, v229
	v_add_u32_e32 v228, s38, v228
	v_add_u32_e32 v229, s36, v229
	v_cndmask_b32_e64 v232, v232, v228, s[32:33]
	v_cndmask_b32_e64 v233, v233, v229, s[34:35]
	s_add_u32 s38, s36, s37
	v_cmp_eq_u32_e64 s[32:33], 7, v226
	v_cmp_eq_u32_e64 s[34:35], 7, v227
	s_bcnt1_i32_b64 s36, s[32:33]
	s_bcnt1_i32_b64 s37, s[34:35]
	s_add_u32 s36, s36, s38
	v_mbcnt_lo_u32_b32 v228, s32, 0
	v_mbcnt_hi_u32_b32 v228, s33, v228
	v_mbcnt_lo_u32_b32 v229, s34, 0
	v_mbcnt_hi_u32_b32 v229, s35, v229
	v_add_u32_e32 v228, s38, v228
	v_add_u32_e32 v229, s36, v229
	v_cndmask_b32_e64 v232, v232, v228, s[32:33]
	v_cndmask_b32_e64 v233, v233, v229, s[34:35]
	s_add_u32 s38, s36, s37
	v_cmp_eq_u32_e64 s[32:33], 8, v226
	v_cmp_eq_u32_e64 s[34:35], 8, v227
	s_bcnt1_i32_b64 s36, s[32:33]
	s_bcnt1_i32_b64 s37, s[34:35]
	s_add_u32 s36, s36, s38
	v_mbcnt_lo_u32_b32 v228, s32, 0
	v_mbcnt_hi_u32_b32 v228, s33, v228
	v_mbcnt_lo_u32_b32 v229, s34, 0
	v_mbcnt_hi_u32_b32 v229, s35, v229
	v_add_u32_e32 v228, s38, v228
	v_add_u32_e32 v229, s36, v229
	v_cndmask_b32_e64 v232, v232, v228, s[32:33]
	v_cndmask_b32_e64 v233, v233, v229, s[34:35]
	s_add_u32 s38, s36, s37
	v_cmp_eq_u32_e64 s[32:33], 9, v226
	v_cmp_eq_u32_e64 s[34:35], 9, v227
	s_bcnt1_i32_b64 s36, s[32:33]
	s_bcnt1_i32_b64 s37, s[34:35]
	s_add_u32 s36, s36, s38
	v_mbcnt_lo_u32_b32 v228, s32, 0
	v_mbcnt_hi_u32_b32 v228, s33, v228
	v_mbcnt_lo_u32_b32 v229, s34, 0
	v_mbcnt_hi_u32_b32 v229, s35, v229
	v_add_u32_e32 v228, s38, v228
	v_add_u32_e32 v229, s36, v229
	v_cndmask_b32_e64 v232, v232, v228, s[32:33]
	v_cndmask_b32_e64 v233, v233, v229, s[34:35]
	s_add_u32 s38, s36, s37
	v_cmp_eq_u32_e64 s[32:33], 10, v226
	v_cmp_eq_u32_e64 s[34:35], 10, v227
	s_bcnt1_i32_b64 s36, s[32:33]
	s_bcnt1_i32_b64 s37, s[34:35]
	s_add_u32 s36, s36, s38
	v_mbcnt_lo_u32_b32 v228, s32, 0
	v_mbcnt_hi_u32_b32 v228, s33, v228
	v_mbcnt_lo_u32_b32 v229, s34, 0
	v_mbcnt_hi_u32_b32 v229, s35, v229
	v_add_u32_e32 v228, s38, v228
	v_add_u32_e32 v229, s36, v229
	v_cndmask_b32_e64 v232, v232, v228, s[32:33]
	v_cndmask_b32_e64 v233, v233, v229, s[34:35]
	s_add_u32 s38, s36, s37
	v_cmp_eq_u32_e64 s[32:33], 11, v226
	v_cmp_eq_u32_e64 s[34:35], 11, v227
	s_bcnt1_i32_b64 s36, s[32:33]
	s_bcnt1_i32_b64 s37, s[34:35]
	s_add_u32 s36, s36, s38
	v_mbcnt_lo_u32_b32 v228, s32, 0
	v_mbcnt_hi_u32_b32 v228, s33, v228
	v_mbcnt_lo_u32_b32 v229, s34, 0
	v_mbcnt_hi_u32_b32 v229, s35, v229
	v_add_u32_e32 v228, s38, v228
	v_add_u32_e32 v229, s36, v229
	v_cndmask_b32_e64 v232, v232, v228, s[32:33]
	v_cndmask_b32_e64 v233, v233, v229, s[34:35]
	s_add_u32 s38, s36, s37
	v_cmp_eq_u32_e64 s[32:33], 12, v226
	v_cmp_eq_u32_e64 s[34:35], 12, v227
	s_bcnt1_i32_b64 s36, s[32:33]
	s_bcnt1_i32_b64 s37, s[34:35]
	s_add_u32 s36, s36, s38
	v_mbcnt_lo_u32_b32 v228, s32, 0
	v_mbcnt_hi_u32_b32 v228, s33, v228
	v_mbcnt_lo_u32_b32 v229, s34, 0
	v_mbcnt_hi_u32_b32 v229, s35, v229
	v_add_u32_e32 v228, s38, v228
	v_add_u32_e32 v229, s36, v229
	v_cndmask_b32_e64 v232, v232, v228, s[32:33]
	v_cndmask_b32_e64 v233, v233, v229, s[34:35]
	s_add_u32 s38, s36, s37
	v_cmp_eq_u32_e64 s[32:33], 13, v226
	v_cmp_eq_u32_e64 s[34:35], 13, v227
	s_bcnt1_i32_b64 s36, s[32:33]
	s_bcnt1_i32_b64 s37, s[34:35]
	s_add_u32 s36, s36, s38
	v_mbcnt_lo_u32_b32 v228, s32, 0
	v_mbcnt_hi_u32_b32 v228, s33, v228
	v_mbcnt_lo_u32_b32 v229, s34, 0
	v_mbcnt_hi_u32_b32 v229, s35, v229
	v_add_u32_e32 v228, s38, v228
	v_add_u32_e32 v229, s36, v229
	v_cndmask_b32_e64 v232, v232, v228, s[32:33]
	v_cndmask_b32_e64 v233, v233, v229, s[34:35]
	s_add_u32 s38, s36, s37
	v_cmp_eq_u32_e64 s[32:33], 14, v226
	v_cmp_eq_u32_e64 s[34:35], 14, v227
	s_bcnt1_i32_b64 s36, s[32:33]
	s_bcnt1_i32_b64 s37, s[34:35]
	s_add_u32 s36, s36, s38
	v_mbcnt_lo_u32_b32 v228, s32, 0
	v_mbcnt_hi_u32_b32 v228, s33, v228
	v_mbcnt_lo_u32_b32 v229, s34, 0
	v_mbcnt_hi_u32_b32 v229, s35, v229
	v_add_u32_e32 v228, s38, v228
	v_add_u32_e32 v229, s36, v229
	v_cndmask_b32_e64 v232, v232, v228, s[32:33]
	v_cndmask_b32_e64 v233, v233, v229, s[34:35]
	s_add_u32 s38, s36, s37
	v_cmp_eq_u32_e64 s[32:33], 15, v226
	v_cmp_eq_u32_e64 s[34:35], 15, v227
	s_bcnt1_i32_b64 s36, s[32:33]
	s_bcnt1_i32_b64 s37, s[34:35]
	s_add_u32 s36, s36, s38
	v_mbcnt_lo_u32_b32 v228, s32, 0
	v_mbcnt_hi_u32_b32 v228, s33, v228
	v_mbcnt_lo_u32_b32 v229, s34, 0
	v_mbcnt_hi_u32_b32 v229, s35, v229
	v_add_u32_e32 v228, s38, v228
	v_add_u32_e32 v229, s36, v229
	v_cndmask_b32_e64 v232, v232, v228, s[32:33]
	v_cndmask_b32_e64 v233, v233, v229, s[34:35]
	s_add_u32 s38, s36, s37
	v_lshl_add_u32 v232, v232, 2, v215
	v_lshl_add_u32 v233, v233, 2, v215
	ds_write_b32 v232, v128
	ds_write_b32 v232, v130 offset:512
	ds_write_b32 v233, v129
	ds_write_b32 v233, v131 offset:512
	v_add_u32_e32 v228, v209, v215
	s_waitcnt lgkmcnt(0)
; template <int PART>
; DEVI void phase_peer_gather(const Params& p, unsigned char* smem) {
;     ...
;       const int flip_ = (((tok - (blockIdx.x * 4 + w0_)) / (int)(gridDim.x * 4)) & 1) ? 15 : 0;
;       const int q0_ = (e0 >> 10) ^ flip_, q1_ = (e1 >> 10) ^ flip_;
; #pragma unroll
;       for (int q = 0; q < 16; ++q) {
;         const unsigned long long m0 = __ballot(q0_ == q), m1 = __ballot(q1_ == q);
;         const int c0 = __popcll(m0);
;         const int i0 = __builtin_amdgcn_mbcnt_hi((unsigned)(m0 >> 32), __builtin_amdgcn_mbcnt_lo((unsigned)m0, 0u));
;         const int i1 = __builtin_amdgcn_mbcnt_hi((unsigned)(m1 >> 32), __builtin_amdgcn_mbcnt_lo((unsigned)m1, 0u));
;         if (q0_ == q) pos0 = base + i0;
;         if (q1_ == q) pos1 = base + c0 + i1;
;         base += c0 + __popcll(m1);
;       }
;       __builtin_amdgcn_fence(__ATOMIC_RELEASE, "wavefront");
;       __builtin_amdgcn_wave_barrier();
;       sE[pos0] = e0; sG[pos0] = g0;
;       sE[pos1] = e1; sG[pos1] = g1;
;       __builtin_amdgcn_fence(__ATOMIC_RELEASE, "wavefront");
;       __builtin_amdgcn_wave_barrier();
;       __builtin_amdgcn_fence(__ATOMIC_ACQUIRE, "wavefront");
;       e0 = sE[lane]; e1 = sE[64 + lane];
;       g0 = sG[lane]; g1 = sG[64 + lane];
;       p.experts[(size_t)tok * 128 + lane] = e0;
;       p.experts[(size_t)tok * 128 + 64 + lane] = e1;
;     }
;     const float su0 = p.uscale[e0], su1 = p.uscale[e1];
;     const float sv0 = p.vscale[e0], sv1 = p.vscale[e1];
	ds_read_b32 v128, v228
	ds_read_b32 v129, v228 offset:256
	ds_read_b32 v130, v228 offset:512
	ds_read_b32 v131, v228 offset:768
	s_waitcnt lgkmcnt(0)
	s_lshl_b32 s20, s40, 9
	v_add_u32_e32 v224, s20, v209
	global_store_dword v224, v128, s[8:9]
	global_store_dword v224, v129, s[8:9] offset:256
	v_lshlrev_b32_e32 v228, 2, v128
	v_lshlrev_b32_e32 v229, 2, v129
	global_load_dword v132, v228, s[14:15]
	global_load_dword v133, v229, s[14:15]
	global_load_dword v134, v228, s[16:17]
	global_load_dword v135, v229, s[16:17]
	s_xor_b32 s48, s43, 15
	s_add_u32 s40, s3, s42
	s_add_u32 s40, s40, s2
	s_add_u32 s40, s40, s2
	s_cmp_lt_u32 s40, 0x8000
	s_cselect_b32 s40, s40, s3
	s_cselect_b32 s48, s43, s48
	v_lshrrev_b32_e32 v226, 10, v136
	v_lshrrev_b32_e32 v227, 10, v137
	v_xor_b32_e32 v226, s48, v226
	v_xor_b32_e32 v227, s48, v227
	s_mov_b32 s38, 0
	v_cmp_eq_u32_e64 s[32:33], 0, v226
	v_cmp_eq_u32_e64 s[34:35], 0, v227
	s_bcnt1_i32_b64 s36, s[32:33]
	s_bcnt1_i32_b64 s37, s[34:35]
	s_add_u32 s36, s36, s38
	v_mbcnt_lo_u32_b32 v228, s32, 0
	v_mbcnt_hi_u32_b32 v228, s33, v228
	v_mbcnt_lo_u32_b32 v229, s34, 0
	v_mbcnt_hi_u32_b32 v229, s35, v229
	v_add_u32_e32 v228, s38, v228
	v_add_u32_e32 v229, s36, v229
	v_cndmask_b32_e64 v232, v232, v228, s[32:33]
	v_cndmask_b32_e64 v233, v233, v229, s[34:35]
	s_add_u32 s38, s36, s37
	v_cmp_eq_u32_e64 s[32:33], 1, v226
	v_cmp_eq_u32_e64 s[34:35], 1, v227
	s_bcnt1_i32_b64 s36, s[32:33]
	s_bcnt1_i32_b64 s37, s[34:35]
	s_add_u32 s36, s36, s38
	v_mbcnt_lo_u32_b32 v228, s32, 0
	v_mbcnt_hi_u32_b32 v228, s33, v228
	v_mbcnt_lo_u32_b32 v229, s34, 0
	v_mbcnt_hi_u32_b32 v229, s35, v229
	v_add_u32_e32 v228, s38, v228
	v_add_u32_e32 v229, s36, v229
	v_cndmask_b32_e64 v232, v232, v228, s[32:33]
	v_cndmask_b32_e64 v233, v233, v229, s[34:35]
	s_add_u32 s38, s36, s37
	v_cmp_eq_u32_e64 s[32:33], 2, v226
	v_cmp_eq_u32_e64 s[34:35], 2, v227
	s_bcnt1_i32_b64 s36, s[32:33]
	s_bcnt1_i32_b64 s37, s[34:35]
	s_add_u32 s36, s36, s38
	v_mbcnt_lo_u32_b32 v228, s32, 0
	v_mbcnt_hi_u32_b32 v228, s33, v228
	v_mbcnt_lo_u32_b32 v229, s34, 0
	v_mbcnt_hi_u32_b32 v229, s35, v229
	v_add_u32_e32 v228, s38, v228
	v_add_u32_e32 v229, s36, v229
	v_cndmask_b32_e64 v232, v232, v228, s[32:33]
	v_cndmask_b32_e64 v233, v233, v229, s[34:35]
	s_add_u32 s38, s36, s37
	v_cmp_eq_u32_e64 s[32:33], 3, v226
	v_cmp_eq_u32_e64 s[34:35], 3, v227
	s_bcnt1_i32_b64 s36, s[32:33]
	s_bcnt1_i32_b64 s37, s[34:35]
	s_add_u32 s36, s36, s38
	v_mbcnt_lo_u32_b32 v228, s32, 0
	v_mbcnt_hi_u32_b32 v228, s33, v228
	v_mbcnt_lo_u32_b32 v229, s34, 0
	v_mbcnt_hi_u32_b32 v229, s35, v229
	v_add_u32_e32 v228, s38, v228
	v_add_u32_e32 v229, s36, v229
	v_cndmask_b32_e64 v232, v232, v228, s[32:33]
	v_cndmask_b32_e64 v233, v233, v229, s[34:35]
	s_add_u32 s38, s36, s37
	v_cmp_eq_u32_e64 s[32:33], 4, v226
	v_cmp_eq_u32_e64 s[34:35], 4, v227
	s_bcnt1_i32_b64 s36, s[32:33]
	s_bcnt1_i32_b64 s37, s[34:35]
	s_add_u32 s36, s36, s38
	v_mbcnt_lo_u32_b32 v228, s32, 0
	v_mbcnt_hi_u32_b32 v228, s33, v228
	v_mbcnt_lo_u32_b32 v229, s34, 0
	v_mbcnt_hi_u32_b32 v229, s35, v229
	v_add_u32_e32 v228, s38, v228
	v_add_u32_e32 v229, s36, v229
	v_cndmask_b32_e64 v232, v232, v228, s[32:33]
	v_cndmask_b32_e64 v233, v233, v229, s[34:35]
	s_add_u32 s38, s36, s37
	v_cmp_eq_u32_e64 s[32:33], 5, v226
	v_cmp_eq_u32_e64 s[34:35], 5, v227
	s_bcnt1_i32_b64 s36, s[32:33]
	s_bcnt1_i32_b64 s37, s[34:35]
	s_add_u32 s36, s36, s38
	v_mbcnt_lo_u32_b32 v228, s32, 0
	v_mbcnt_hi_u32_b32 v228, s33, v228
	v_mbcnt_lo_u32_b32 v229, s34, 0
	v_mbcnt_hi_u32_b32 v229, s35, v229
	v_add_u32_e32 v228, s38, v228
	v_add_u32_e32 v229, s36, v229
	v_cndmask_b32_e64 v232, v232, v228, s[32:33]
	v_cndmask_b32_e64 v233, v233, v229, s[34:35]
	s_add_u32 s38, s36, s37
	v_cmp_eq_u32_e64 s[32:33], 6, v226
	v_cmp_eq_u32_e64 s[34:35], 6, v227
	s_bcnt1_i32_b64 s36, s[32:33]
	s_bcnt1_i32_b64 s37, s[34:35]
	s_add_u32 s36, s36, s38
	v_mbcnt_lo_u32_b32 v228, s32, 0
	v_mbcnt_hi_u32_b32 v228, s33, v228
	v_mbcnt_lo_u32_b32 v229, s34, 0
	v_mbcnt_hi_u32_b32 v229, s35, v229
	v_add_u32_e32 v228, s38, v228
	v_add_u32_e32 v229, s36, v229
	v_cndmask_b32_e64 v232, v232, v228, s[32:33]
	v_cndmask_b32_e64 v233, v233, v229, s[34:35]
	s_add_u32 s38, s36, s37
	v_cmp_eq_u32_e64 s[32:33], 7, v226
	v_cmp_eq_u32_e64 s[34:35], 7, v227
	s_bcnt1_i32_b64 s36, s[32:33]
	s_bcnt1_i32_b64 s37, s[34:35]
	s_add_u32 s36, s36, s38
	v_mbcnt_lo_u32_b32 v228, s32, 0
	v_mbcnt_hi_u32_b32 v228, s33, v228
	v_mbcnt_lo_u32_b32 v229, s34, 0
	v_mbcnt_hi_u32_b32 v229, s35, v229
	v_add_u32_e32 v228, s38, v228
	v_add_u32_e32 v229, s36, v229
	v_cndmask_b32_e64 v232, v232, v228, s[32:33]
	v_cndmask_b32_e64 v233, v233, v229, s[34:35]
	s_add_u32 s38, s36, s37
	v_cmp_eq_u32_e64 s[32:33], 8, v226
	v_cmp_eq_u32_e64 s[34:35], 8, v227
	s_bcnt1_i32_b64 s36, s[32:33]
	s_bcnt1_i32_b64 s37, s[34:35]
	s_add_u32 s36, s36, s38
	v_mbcnt_lo_u32_b32 v228, s32, 0
	v_mbcnt_hi_u32_b32 v228, s33, v228
	v_mbcnt_lo_u32_b32 v229, s34, 0
	v_mbcnt_hi_u32_b32 v229, s35, v229
	v_add_u32_e32 v228, s38, v228
	v_add_u32_e32 v229, s36, v229
	v_cndmask_b32_e64 v232, v232, v228, s[32:33]
	v_cndmask_b32_e64 v233, v233, v229, s[34:35]
	s_add_u32 s38, s36, s37
	v_cmp_eq_u32_e64 s[32:33], 9, v226
	v_cmp_eq_u32_e64 s[34:35], 9, v227
	s_bcnt1_i32_b64 s36, s[32:33]
	s_bcnt1_i32_b64 s37, s[34:35]
	s_add_u32 s36, s36, s38
	v_mbcnt_lo_u32_b32 v228, s32, 0
	v_mbcnt_hi_u32_b32 v228, s33, v228
	v_mbcnt_lo_u32_b32 v229, s34, 0
	v_mbcnt_hi_u32_b32 v229, s35, v229
	v_add_u32_e32 v228, s38, v228
	v_add_u32_e32 v229, s36, v229
	v_cndmask_b32_e64 v232, v232, v228, s[32:33]
	v_cndmask_b32_e64 v233, v233, v229, s[34:35]
	s_add_u32 s38, s36, s37
	v_cmp_eq_u32_e64 s[32:33], 10, v226
; template <int PART>
; DEVI void phase_peer_gather(const Params& p, unsigned char* smem) {
;     ...
;       const int q0_ = (e0 >> 10) ^ flip_, q1_ = (e1 >> 10) ^ flip_;
; #pragma unroll
;       for (int q = 0; q < 16; ++q) {
;         const unsigned long long m0 = __ballot(q0_ == q), m1 = __ballot(q1_ == q);
;         const int c0 = __popcll(m0);
;         const int i0 = __builtin_amdgcn_mbcnt_hi((unsigned)(m0 >> 32), __builtin_amdgcn_mbcnt_lo((unsigned)m0, 0u));
;         const int i1 = __builtin_amdgcn_mbcnt_hi((unsigned)(m1 >> 32), __builtin_amdgcn_mbcnt_lo((unsigned)m1, 0u));
;         if (q0_ == q) pos0 = base + i0;
;         if (q1_ == q) pos1 = base + c0 + i1;
;         base += c0 + __popcll(m1);
;       }
;       __builtin_amdgcn_fence(__ATOMIC_RELEASE, "wavefront");
;       __builtin_amdgcn_wave_barrier();
;       sE[pos0] = e0; sG[pos0] = g0;
;       sE[pos1] = e1; sG[pos1] = g1;
;       __builtin_amdgcn_fence(__ATOMIC_RELEASE, "wavefront");
;       __builtin_amdgcn_wave_barrier();
;       __builtin_amdgcn_fence(__ATOMIC_ACQUIRE, "wavefront");
;       e0 = sE[lane]; e1 = sE[64 + lane];
;       g0 = sG[lane]; g1 = sG[64 + lane];
;       p.experts[(size_t)tok * 128 + lane] = e0;
;       p.experts[(size_t)tok * 128 + 64 + lane] = e1;
;     }
;     const float su0 = p.uscale[e0], su1 = p.uscale[e1];
;     const float sv0 = p.vscale[e0], sv1 = p.vscale[e1];
	v_cmp_eq_u32_e64 s[34:35], 10, v227
	s_bcnt1_i32_b64 s36, s[32:33]
	s_bcnt1_i32_b64 s37, s[34:35]
	s_add_u32 s36, s36, s38
	v_mbcnt_lo_u32_b32 v228, s32, 0
	v_mbcnt_hi_u32_b32 v228, s33, v228
	v_mbcnt_lo_u32_b32 v229, s34, 0
	v_mbcnt_hi_u32_b32 v229, s35, v229
	v_add_u32_e32 v228, s38, v228
	v_add_u32_e32 v229, s36, v229
	v_cndmask_b32_e64 v232, v232, v228, s[32:33]
	v_cndmask_b32_e64 v233, v233, v229, s[34:35]
	s_add_u32 s38, s36, s37
	v_cmp_eq_u32_e64 s[32:33], 11, v226
	v_cmp_eq_u32_e64 s[34:35], 11, v227
	s_bcnt1_i32_b64 s36, s[32:33]
	s_bcnt1_i32_b64 s37, s[34:35]
	s_add_u32 s36, s36, s38
	v_mbcnt_lo_u32_b32 v228, s32, 0
	v_mbcnt_hi_u32_b32 v228, s33, v228
	v_mbcnt_lo_u32_b32 v229, s34, 0
	v_mbcnt_hi_u32_b32 v229, s35, v229
	v_add_u32_e32 v228, s38, v228
	v_add_u32_e32 v229, s36, v229
	v_cndmask_b32_e64 v232, v232, v228, s[32:33]
	v_cndmask_b32_e64 v233, v233, v229, s[34:35]
	s_add_u32 s38, s36, s37
	v_cmp_eq_u32_e64 s[32:33], 12, v226
	v_cmp_eq_u32_e64 s[34:35], 12, v227
	s_bcnt1_i32_b64 s36, s[32:33]
	s_bcnt1_i32_b64 s37, s[34:35]
	s_add_u32 s36, s36, s38
	v_mbcnt_lo_u32_b32 v228, s32, 0
	v_mbcnt_hi_u32_b32 v228, s33, v228
	v_mbcnt_lo_u32_b32 v229, s34, 0
	v_mbcnt_hi_u32_b32 v229, s35, v229
	v_add_u32_e32 v228, s38, v228
	v_add_u32_e32 v229, s36, v229
	v_cndmask_b32_e64 v232, v232, v228, s[32:33]
	v_cndmask_b32_e64 v233, v233, v229, s[34:35]
	s_add_u32 s38, s36, s37
	v_cmp_eq_u32_e64 s[32:33], 13, v226
	v_cmp_eq_u32_e64 s[34:35], 13, v227
	s_bcnt1_i32_b64 s36, s[32:33]
	s_bcnt1_i32_b64 s37, s[34:35]
	s_add_u32 s36, s36, s38
	v_mbcnt_lo_u32_b32 v228, s32, 0
	v_mbcnt_hi_u32_b32 v228, s33, v228
	v_mbcnt_lo_u32_b32 v229, s34, 0
	v_mbcnt_hi_u32_b32 v229, s35, v229
	v_add_u32_e32 v228, s38, v228
	v_add_u32_e32 v229, s36, v229
	v_cndmask_b32_e64 v232, v232, v228, s[32:33]
	v_cndmask_b32_e64 v233, v233, v229, s[34:35]
	s_add_u32 s38, s36, s37
	v_cmp_eq_u32_e64 s[32:33], 14, v226
	v_cmp_eq_u32_e64 s[34:35], 14, v227
	s_bcnt1_i32_b64 s36, s[32:33]
	s_bcnt1_i32_b64 s37, s[34:35]
	s_add_u32 s36, s36, s38
	v_mbcnt_lo_u32_b32 v228, s32, 0
	v_mbcnt_hi_u32_b32 v228, s33, v228
	v_mbcnt_lo_u32_b32 v229, s34, 0
	v_mbcnt_hi_u32_b32 v229, s35, v229
	v_add_u32_e32 v228, s38, v228
	v_add_u32_e32 v229, s36, v229
	v_cndmask_b32_e64 v232, v232, v228, s[32:33]
	v_cndmask_b32_e64 v233, v233, v229, s[34:35]
	s_add_u32 s38, s36, s37
	v_cmp_eq_u32_e64 s[32:33], 15, v226
	v_cmp_eq_u32_e64 s[34:35], 15, v227
	s_bcnt1_i32_b64 s36, s[32:33]
	s_bcnt1_i32_b64 s37, s[34:35]
	s_add_u32 s36, s36, s38
	v_mbcnt_lo_u32_b32 v228, s32, 0
	v_mbcnt_hi_u32_b32 v228, s33, v228
	v_mbcnt_lo_u32_b32 v229, s34, 0
	v_mbcnt_hi_u32_b32 v229, s35, v229
	v_add_u32_e32 v228, s38, v228
	v_add_u32_e32 v229, s36, v229
	v_cndmask_b32_e64 v232, v232, v228, s[32:33]
	v_cndmask_b32_e64 v233, v233, v229, s[34:35]
	s_add_u32 s38, s36, s37
	v_lshl_add_u32 v232, v232, 2, v215
	v_lshl_add_u32 v233, v233, 2, v215
	ds_write_b32 v232, v136
	ds_write_b32 v232, v138 offset:512
	ds_write_b32 v233, v137
	ds_write_b32 v233, v139 offset:512
	v_add_u32_e32 v228, v209, v215
	s_waitcnt lgkmcnt(0)
	ds_read_b32 v136, v228
	ds_read_b32 v137, v228 offset:256
	ds_read_b32 v138, v228 offset:512
	ds_read_b32 v139, v228 offset:768
	s_waitcnt lgkmcnt(0)
	s_lshl_b32 s20, s40, 9
	v_add_u32_e32 v224, s20, v209
	global_store_dword v224, v136, s[8:9]
	global_store_dword v224, v137, s[8:9] offset:256
	v_lshlrev_b32_e32 v228, 2, v136
	v_lshlrev_b32_e32 v229, 2, v137
	global_load_dword v140, v228, s[14:15]
	global_load_dword v141, v229, s[14:15]
	global_load_dword v142, v228, s[16:17]
	global_load_dword v143, v229, s[16:17]
	s_waitcnt vmcnt(27)
	v_cvt_pk_f32_fp8_e32 v[184:185], v0
	v_cvt_pk_f32_fp8_sdwa v[186:187], v0 src0_sel:WORD_1
	v_cvt_pk_f32_fp8_e32 v[188:189], v1
	v_cvt_pk_f32_fp8_sdwa v[190:191], v1 src0_sel:WORD_1
	v_pk_mul_f32 v[200:201], v[64:65], v[184:185]
	v_cvt_pk_f32_fp8_e32 v[192:193], v2
	v_pk_mul_f32 v[202:203], v[66:67], v[186:187]
	v_cvt_pk_f32_fp8_sdwa v[194:195], v2 src0_sel:WORD_1
	v_pk_fma_f32 v[200:201], v[68:69], v[188:189], v[200:201]
	v_cvt_pk_f32_fp8_e32 v[196:197], v3
	v_pk_fma_f32 v[202:203], v[70:71], v[190:191], v[202:203]
	v_cvt_pk_f32_fp8_sdwa v[198:199], v3 src0_sel:WORD_1
	v_pk_fma_f32 v[200:201], v[72:73], v[192:193], v[200:201]
	v_pk_fma_f32 v[202:203], v[74:75], v[194:195], v[202:203]
	v_pk_fma_f32 v[200:201], v[76:77], v[196:197], v[200:201]
	v_pk_fma_f32 v[202:203], v[78:79], v[198:199], v[202:203]
	v_pk_add_f32 v[200:201], v[200:201], v[202:203]
	v_add_f32_e32 v160, v200, v201
	v_readlane_b32 s22, v113, 8
	s_lshl_b32 s22, s22, 10
	v_add_u32_e32 v204, s22, v208
	global_load_dwordx4 v[0:3], v204, s[12:13]
	s_waitcnt vmcnt(27)
	v_cvt_pk_f32_fp8_e32 v[184:185], v4
	v_cvt_pk_f32_fp8_sdwa v[186:187], v4 src0_sel:WORD_1
	v_cvt_pk_f32_fp8_e32 v[188:189], v5
	v_cvt_pk_f32_fp8_sdwa v[190:191], v5 src0_sel:WORD_1
	v_pk_mul_f32 v[200:201], v[80:81], v[184:185]
	v_cvt_pk_f32_fp8_e32 v[192:193], v6
	v_pk_mul_f32 v[202:203], v[82:83], v[186:187]
	v_cvt_pk_f32_fp8_sdwa v[194:195], v6 src0_sel:WORD_1
	v_pk_fma_f32 v[200:201], v[84:85], v[188:189], v[200:201]
	v_cvt_pk_f32_fp8_e32 v[196:197], v7
	v_pk_fma_f32 v[202:203], v[86:87], v[190:191], v[202:203]
	v_cvt_pk_f32_fp8_sdwa v[198:199], v7 src0_sel:WORD_1
	v_pk_fma_f32 v[200:201], v[88:89], v[192:193], v[200:201]
	v_pk_fma_f32 v[202:203], v[90:91], v[194:195], v[202:203]
	v_pk_fma_f32 v[200:201], v[92:93], v[196:197], v[200:201]
	v_pk_fma_f32 v[202:203], v[94:95], v[198:199], v[202:203]
	v_pk_add_f32 v[200:201], v[200:201], v[202:203]
	v_add_f32_e32 v168, v200, v201
	v_readlane_b32 s23, v121, 8
	s_lshl_b32 s23, s23, 10
	v_add_u32_e32 v205, s23, v208
	global_load_dwordx4 v[4:7], v205, s[12:13]
	s_waitcnt vmcnt(27)
	v_cvt_pk_f32_fp8_e32 v[184:185], v8
	v_cvt_pk_f32_fp8_sdwa v[186:187], v8 src0_sel:WORD_1
	v_cvt_pk_f32_fp8_e32 v[188:189], v9
	v_cvt_pk_f32_fp8_sdwa v[190:191], v9 src0_sel:WORD_1
	v_pk_mul_f32 v[200:201], v[64:65], v[184:185]
	v_cvt_pk_f32_fp8_e32 v[192:193], v10
	v_pk_mul_f32 v[202:203], v[66:67], v[186:187]
	v_cvt_pk_f32_fp8_sdwa v[194:195], v10 src0_sel:WORD_1
	v_pk_fma_f32 v[200:201], v[68:69], v[188:189], v[200:201]
	v_cvt_pk_f32_fp8_e32 v[196:197], v11
	v_pk_fma_f32 v[202:203], v[70:71], v[190:191], v[202:203]
	v_cvt_pk_f32_fp8_sdwa v[198:199], v11 src0_sel:WORD_1
	v_pk_fma_f32 v[200:201], v[72:73], v[192:193], v[200:201]
	v_pk_fma_f32 v[202:203], v[74:75], v[194:195], v[202:203]
	v_pk_fma_f32 v[200:201], v[76:77], v[196:197], v[200:201]
	v_pk_fma_f32 v[202:203], v[78:79], v[198:199], v[202:203]
	v_pk_add_f32 v[200:201], v[200:201], v[202:203]
	v_add_f32_e32 v161, v200, v201
	v_readlane_b32 s24, v113, 9
	s_lshl_b32 s24, s24, 10
	v_add_u32_e32 v206, s24, v208
	global_load_dwordx4 v[8:11], v206, s[12:13]
	s_waitcnt vmcnt(27)
	v_cvt_pk_f32_fp8_e32 v[184:185], v12
	v_cvt_pk_f32_fp8_sdwa v[186:187], v12 src0_sel:WORD_1
	v_cvt_pk_f32_fp8_e32 v[188:189], v13
	v_cvt_pk_f32_fp8_sdwa v[190:191], v13 src0_sel:WORD_1
	v_pk_mul_f32 v[200:201], v[80:81], v[184:185]
	v_cvt_pk_f32_fp8_e32 v[192:193], v14
	v_pk_mul_f32 v[202:203], v[82:83], v[186:187]
	v_cvt_pk_f32_fp8_sdwa v[194:195], v14 src0_sel:WORD_1
	v_pk_fma_f32 v[200:201], v[84:85], v[188:189], v[200:201]
	v_cvt_pk_f32_fp8_e32 v[196:197], v15
	v_pk_fma_f32 v[202:203], v[86:87], v[190:191], v[202:203]
	v_cvt_pk_f32_fp8_sdwa v[198:199], v15 src0_sel:WORD_1
	v_pk_fma_f32 v[200:201], v[88:89], v[192:193], v[200:201]
	v_pk_fma_f32 v[202:203], v[90:91], v[194:195], v[202:203]
	v_pk_fma_f32 v[200:201], v[92:93], v[196:197], v[200:201]
	v_pk_fma_f32 v[202:203], v[94:95], v[198:199], v[202:203]
	v_pk_add_f32 v[200:201], v[200:201], v[202:203]
	v_add_f32_e32 v169, v200, v201
	v_readlane_b32 s25, v121, 9
	s_lshl_b32 s25, s25, 10
	v_add_u32_e32 v207, s25, v208
	global_load_dwordx4 v[12:15], v207, s[12:13]
	s_waitcnt vmcnt(27)
	v_cvt_pk_f32_fp8_e32 v[184:185], v16
	v_cvt_pk_f32_fp8_sdwa v[186:187], v16 src0_sel:WORD_1
	v_cvt_pk_f32_fp8_e32 v[188:189], v17
	v_cvt_pk_f32_fp8_sdwa v[190:191], v17 src0_sel:WORD_1
	v_pk_mul_f32 v[200:201], v[64:65], v[184:185]
	v_cvt_pk_f32_fp8_e32 v[192:193], v18
	v_pk_mul_f32 v[202:203], v[66:67], v[186:187]
	v_cvt_pk_f32_fp8_sdwa v[194:195], v18 src0_sel:WORD_1
	v_pk_fma_f32 v[200:201], v[68:69], v[188:189], v[200:201]
	v_cvt_pk_f32_fp8_e32 v[196:197], v19
	v_pk_fma_f32 v[202:203], v[70:71], v[190:191], v[202:203]
	v_cvt_pk_f32_fp8_sdwa v[198:199], v19 src0_sel:WORD_1
	v_pk_fma_f32 v[200:201], v[72:73], v[192:193], v[200:201]
	v_pk_fma_f32 v[202:203], v[74:75], v[194:195], v[202:203]
	v_pk_fma_f32 v[200:201], v[76:77], v[196:197], v[200:201]
	v_pk_fma_f32 v[202:203], v[78:79], v[198:199], v[202:203]
	v_pk_add_f32 v[200:201], v[200:201], v[202:203]
	v_add_f32_e32 v162, v200, v201
	v_readlane_b32 s22, v113, 10
	s_lshl_b32 s22, s22, 10
	v_add_u32_e32 v204, s22, v208
	global_load_dwordx4 v[16:19], v204, s[12:13]
	s_waitcnt vmcnt(27)
	v_cvt_pk_f32_fp8_e32 v[184:185], v20
	v_cvt_pk_f32_fp8_sdwa v[186:187], v20 src0_sel:WORD_1
	v_cvt_pk_f32_fp8_e32 v[188:189], v21
	v_cvt_pk_f32_fp8_sdwa v[190:191], v21 src0_sel:WORD_1
	v_pk_mul_f32 v[200:201], v[80:81], v[184:185]
	v_cvt_pk_f32_fp8_e32 v[192:193], v22
	v_pk_mul_f32 v[202:203], v[82:83], v[186:187]
	v_cvt_pk_f32_fp8_sdwa v[194:195], v22 src0_sel:WORD_1
	v_pk_fma_f32 v[200:201], v[84:85], v[188:189], v[200:201]
	v_cvt_pk_f32_fp8_e32 v[196:197], v23
	v_pk_fma_f32 v[202:203], v[86:87], v[190:191], v[202:203]
	v_cvt_pk_f32_fp8_sdwa v[198:199], v23 src0_sel:WORD_1
	v_pk_fma_f32 v[200:201], v[88:89], v[192:193], v[200:201]
	v_pk_fma_f32 v[202:203], v[90:91], v[194:195], v[202:203]
	v_pk_fma_f32 v[200:201], v[92:93], v[196:197], v[200:201]
	v_pk_fma_f32 v[202:203], v[94:95], v[198:199], v[202:203]
	v_pk_add_f32 v[200:201], v[200:201], v[202:203]
	v_add_f32_e32 v170, v200, v201
	v_readlane_b32 s23, v121, 10
	s_lshl_b32 s23, s23, 10
	v_add_u32_e32 v205, s23, v208
	global_load_dwordx4 v[20:23], v205, s[12:13]
	s_waitcnt vmcnt(27)
	v_cvt_pk_f32_fp8_e32 v[184:185], v24
	v_cvt_pk_f32_fp8_sdwa v[186:187], v24 src0_sel:WORD_1
	v_cvt_pk_f32_fp8_e32 v[188:189], v25
	v_cvt_pk_f32_fp8_sdwa v[190:191], v25 src0_sel:WORD_1
	v_pk_mul_f32 v[200:201], v[64:65], v[184:185]
	v_cvt_pk_f32_fp8_e32 v[192:193], v26
	v_pk_mul_f32 v[202:203], v[66:67], v[186:187]
	v_cvt_pk_f32_fp8_sdwa v[194:195], v26 src0_sel:WORD_1
	v_pk_fma_f32 v[200:201], v[68:69], v[188:189], v[200:201]
	v_cvt_pk_f32_fp8_e32 v[196:197], v27
	v_pk_fma_f32 v[202:203], v[70:71], v[190:191], v[202:203]
	v_cvt_pk_f32_fp8_sdwa v[198:199], v27 src0_sel:WORD_1
	v_pk_fma_f32 v[200:201], v[72:73], v[192:193], v[200:201]
	v_pk_fma_f32 v[202:203], v[74:75], v[194:195], v[202:203]
	v_pk_fma_f32 v[200:201], v[76:77], v[196:197], v[200:201]
	v_pk_fma_f32 v[202:203], v[78:79], v[198:199], v[202:203]
	v_pk_add_f32 v[200:201], v[200:201], v[202:203]
	v_add_f32_e32 v163, v200, v201
	v_readlane_b32 s24, v113, 11
	s_lshl_b32 s24, s24, 10
	v_add_u32_e32 v206, s24, v208
	global_load_dwordx4 v[24:27], v206, s[12:13]
	s_waitcnt vmcnt(27)
	v_cvt_pk_f32_fp8_e32 v[184:185], v28
	v_cvt_pk_f32_fp8_sdwa v[186:187], v28 src0_sel:WORD_1
	v_cvt_pk_f32_fp8_e32 v[188:189], v29
	v_cvt_pk_f32_fp8_sdwa v[190:191], v29 src0_sel:WORD_1
	v_pk_mul_f32 v[200:201], v[80:81], v[184:185]
	v_cvt_pk_f32_fp8_e32 v[192:193], v30
	v_pk_mul_f32 v[202:203], v[82:83], v[186:187]
	v_cvt_pk_f32_fp8_sdwa v[194:195], v30 src0_sel:WORD_1
	v_pk_fma_f32 v[200:201], v[84:85], v[188:189], v[200:201]
	v_cvt_pk_f32_fp8_e32 v[196:197], v31
	v_pk_fma_f32 v[202:203], v[86:87], v[190:191], v[202:203]
	v_cvt_pk_f32_fp8_sdwa v[198:199], v31 src0_sel:WORD_1
	v_pk_fma_f32 v[200:201], v[88:89], v[192:193], v[200:201]
	v_pk_fma_f32 v[202:203], v[90:91], v[194:195], v[202:203]
	v_pk_fma_f32 v[200:201], v[92:93], v[196:197], v[200:201]
	v_pk_fma_f32 v[202:203], v[94:95], v[198:199], v[202:203]
	v_pk_add_f32 v[200:201], v[200:201], v[202:203]
	v_add_f32_e32 v171, v200, v201
	v_readlane_b32 s25, v121, 11
	s_lshl_b32 s25, s25, 10
	v_add_u32_e32 v207, s25, v208
	global_load_dwordx4 v[28:31], v207, s[12:13]
	s_waitcnt vmcnt(27)
	v_cvt_pk_f32_fp8_e32 v[184:185], v32
	v_cvt_pk_f32_fp8_sdwa v[186:187], v32 src0_sel:WORD_1
	v_cvt_pk_f32_fp8_e32 v[188:189], v33
	v_cvt_pk_f32_fp8_sdwa v[190:191], v33 src0_sel:WORD_1
	v_pk_mul_f32 v[200:201], v[64:65], v[184:185]
	v_cvt_pk_f32_fp8_e32 v[192:193], v34
	v_pk_mul_f32 v[202:203], v[66:67], v[186:187]
	v_cvt_pk_f32_fp8_sdwa v[194:195], v34 src0_sel:WORD_1
	v_pk_fma_f32 v[200:201], v[68:69], v[188:189], v[200:201]
	v_cvt_pk_f32_fp8_e32 v[196:197], v35
	v_pk_fma_f32 v[202:203], v[70:71], v[190:191], v[202:203]
	v_cvt_pk_f32_fp8_sdwa v[198:199], v35 src0_sel:WORD_1
	v_pk_fma_f32 v[200:201], v[72:73], v[192:193], v[200:201]
	v_pk_fma_f32 v[202:203], v[74:75], v[194:195], v[202:203]
	v_pk_fma_f32 v[200:201], v[76:77], v[196:197], v[200:201]
	v_pk_fma_f32 v[202:203], v[78:79], v[198:199], v[202:203]
	v_pk_add_f32 v[200:201], v[200:201], v[202:203]
	v_add_f32_e32 v164, v200, v201
	v_readlane_b32 s22, v113, 12
	s_lshl_b32 s22, s22, 10
	v_add_u32_e32 v204, s22, v208
	global_load_dwordx4 v[32:35], v204, s[12:13]
	s_waitcnt vmcnt(27)
	v_cvt_pk_f32_fp8_e32 v[184:185], v36
	v_cvt_pk_f32_fp8_sdwa v[186:187], v36 src0_sel:WORD_1
	v_cvt_pk_f32_fp8_e32 v[188:189], v37
	v_cvt_pk_f32_fp8_sdwa v[190:191], v37 src0_sel:WORD_1
	v_pk_mul_f32 v[200:201], v[80:81], v[184:185]
	v_cvt_pk_f32_fp8_e32 v[192:193], v38
	v_pk_mul_f32 v[202:203], v[82:83], v[186:187]
	v_cvt_pk_f32_fp8_sdwa v[194:195], v38 src0_sel:WORD_1
	v_pk_fma_f32 v[200:201], v[84:85], v[188:189], v[200:201]
	v_cvt_pk_f32_fp8_e32 v[196:197], v39
	v_pk_fma_f32 v[202:203], v[86:87], v[190:191], v[202:203]
	v_cvt_pk_f32_fp8_sdwa v[198:199], v39 src0_sel:WORD_1
	v_pk_fma_f32 v[200:201], v[88:89], v[192:193], v[200:201]
	v_pk_fma_f32 v[202:203], v[90:91], v[194:195], v[202:203]
	v_pk_fma_f32 v[200:201], v[92:93], v[196:197], v[200:201]
	v_pk_fma_f32 v[202:203], v[94:95], v[198:199], v[202:203]
	v_pk_add_f32 v[200:201], v[200:201], v[202:203]
	v_add_f32_e32 v172, v200, v201
	v_readlane_b32 s23, v121, 12
	s_lshl_b32 s23, s23, 10
	v_add_u32_e32 v205, s23, v208
	global_load_dwordx4 v[36:39], v205, s[12:13]
	s_waitcnt vmcnt(27)
	v_cvt_pk_f32_fp8_e32 v[184:185], v40
	v_cvt_pk_f32_fp8_sdwa v[186:187], v40 src0_sel:WORD_1
	v_cvt_pk_f32_fp8_e32 v[188:189], v41
	v_cvt_pk_f32_fp8_sdwa v[190:191], v41 src0_sel:WORD_1
	v_pk_mul_f32 v[200:201], v[64:65], v[184:185]
	v_cvt_pk_f32_fp8_e32 v[192:193], v42
	v_pk_mul_f32 v[202:203], v[66:67], v[186:187]
	v_cvt_pk_f32_fp8_sdwa v[194:195], v42 src0_sel:WORD_1
	v_pk_fma_f32 v[200:201], v[68:69], v[188:189], v[200:201]
	v_cvt_pk_f32_fp8_e32 v[196:197], v43
	v_pk_fma_f32 v[202:203], v[70:71], v[190:191], v[202:203]
	v_cvt_pk_f32_fp8_sdwa v[198:199], v43 src0_sel:WORD_1
	v_pk_fma_f32 v[200:201], v[72:73], v[192:193], v[200:201]
	v_pk_fma_f32 v[202:203], v[74:75], v[194:195], v[202:203]
	v_pk_fma_f32 v[200:201], v[76:77], v[196:197], v[200:201]
	v_pk_fma_f32 v[202:203], v[78:79], v[198:199], v[202:203]
	v_pk_add_f32 v[200:201], v[200:201], v[202:203]
	v_add_f32_e32 v165, v200, v201
	v_readlane_b32 s24, v113, 13
	s_lshl_b32 s24, s24, 10
	v_add_u32_e32 v206, s24, v208
	global_load_dwordx4 v[40:43], v206, s[12:13]
	s_waitcnt vmcnt(27)
	v_cvt_pk_f32_fp8_e32 v[184:185], v44
	v_cvt_pk_f32_fp8_sdwa v[186:187], v44 src0_sel:WORD_1
	v_cvt_pk_f32_fp8_e32 v[188:189], v45
	v_cvt_pk_f32_fp8_sdwa v[190:191], v45 src0_sel:WORD_1
	v_pk_mul_f32 v[200:201], v[80:81], v[184:185]
	v_cvt_pk_f32_fp8_e32 v[192:193], v46
	v_pk_mul_f32 v[202:203], v[82:83], v[186:187]
	v_cvt_pk_f32_fp8_sdwa v[194:195], v46 src0_sel:WORD_1
	v_pk_fma_f32 v[200:201], v[84:85], v[188:189], v[200:201]
	v_cvt_pk_f32_fp8_e32 v[196:197], v47
	v_pk_fma_f32 v[202:203], v[86:87], v[190:191], v[202:203]
	v_cvt_pk_f32_fp8_sdwa v[198:199], v47 src0_sel:WORD_1
	v_pk_fma_f32 v[200:201], v[88:89], v[192:193], v[200:201]
	v_pk_fma_f32 v[202:203], v[90:91], v[194:195], v[202:203]
	v_pk_fma_f32 v[200:201], v[92:93], v[196:197], v[200:201]
	v_pk_fma_f32 v[202:203], v[94:95], v[198:199], v[202:203]
	v_pk_add_f32 v[200:201], v[200:201], v[202:203]
	v_add_f32_e32 v173, v200, v201
	v_readlane_b32 s25, v121, 13
	s_lshl_b32 s25, s25, 10
	v_add_u32_e32 v207, s25, v208
	global_load_dwordx4 v[44:47], v207, s[12:13]
	s_waitcnt vmcnt(27)
	v_cvt_pk_f32_fp8_e32 v[184:185], v48
	v_cvt_pk_f32_fp8_sdwa v[186:187], v48 src0_sel:WORD_1
	v_cvt_pk_f32_fp8_e32 v[188:189], v49
	v_cvt_pk_f32_fp8_sdwa v[190:191], v49 src0_sel:WORD_1
	v_pk_mul_f32 v[200:201], v[64:65], v[184:185]
	v_cvt_pk_f32_fp8_e32 v[192:193], v50
	v_pk_mul_f32 v[202:203], v[66:67], v[186:187]
	v_cvt_pk_f32_fp8_sdwa v[194:195], v50 src0_sel:WORD_1
	v_pk_fma_f32 v[200:201], v[68:69], v[188:189], v[200:201]
	v_cvt_pk_f32_fp8_e32 v[196:197], v51
	v_pk_fma_f32 v[202:203], v[70:71], v[190:191], v[202:203]
	v_cvt_pk_f32_fp8_sdwa v[198:199], v51 src0_sel:WORD_1
	v_pk_fma_f32 v[200:201], v[72:73], v[192:193], v[200:201]
	v_pk_fma_f32 v[202:203], v[74:75], v[194:195], v[202:203]
	v_pk_fma_f32 v[200:201], v[76:77], v[196:197], v[200:201]
	v_pk_fma_f32 v[202:203], v[78:79], v[198:199], v[202:203]
	v_pk_add_f32 v[200:201], v[200:201], v[202:203]
	v_add_f32_e32 v166, v200, v201
	v_readlane_b32 s22, v113, 14
	s_lshl_b32 s22, s22, 10
	v_add_u32_e32 v204, s22, v208
	global_load_dwordx4 v[48:51], v204, s[12:13]
	s_waitcnt vmcnt(27)
	v_cvt_pk_f32_fp8_e32 v[184:185], v52
	v_cvt_pk_f32_fp8_sdwa v[186:187], v52 src0_sel:WORD_1
	v_cvt_pk_f32_fp8_e32 v[188:189], v53
	v_cvt_pk_f32_fp8_sdwa v[190:191], v53 src0_sel:WORD_1
	v_pk_mul_f32 v[200:201], v[80:81], v[184:185]
	v_cvt_pk_f32_fp8_e32 v[192:193], v54
	v_pk_mul_f32 v[202:203], v[82:83], v[186:187]
	v_cvt_pk_f32_fp8_sdwa v[194:195], v54 src0_sel:WORD_1
	v_pk_fma_f32 v[200:201], v[84:85], v[188:189], v[200:201]
	v_cvt_pk_f32_fp8_e32 v[196:197], v55
	v_pk_fma_f32 v[202:203], v[86:87], v[190:191], v[202:203]
	v_cvt_pk_f32_fp8_sdwa v[198:199], v55 src0_sel:WORD_1
	v_pk_fma_f32 v[200:201], v[88:89], v[192:193], v[200:201]
	v_pk_fma_f32 v[202:203], v[90:91], v[194:195], v[202:203]
	v_pk_fma_f32 v[200:201], v[92:93], v[196:197], v[200:201]
	v_pk_fma_f32 v[202:203], v[94:95], v[198:199], v[202:203]
	v_pk_add_f32 v[200:201], v[200:201], v[202:203]
	v_add_f32_e32 v174, v200, v201
	v_readlane_b32 s23, v121, 14
	s_lshl_b32 s23, s23, 10
	v_add_u32_e32 v205, s23, v208
	global_load_dwordx4 v[52:55], v205, s[12:13]
	s_waitcnt vmcnt(27)
	v_cvt_pk_f32_fp8_e32 v[184:185], v56
	v_cvt_pk_f32_fp8_sdwa v[186:187], v56 src0_sel:WORD_1
	v_cvt_pk_f32_fp8_e32 v[188:189], v57
	v_cvt_pk_f32_fp8_sdwa v[190:191], v57 src0_sel:WORD_1
	v_pk_mul_f32 v[200:201], v[64:65], v[184:185]
	v_cvt_pk_f32_fp8_e32 v[192:193], v58
	v_pk_mul_f32 v[202:203], v[66:67], v[186:187]
	v_cvt_pk_f32_fp8_sdwa v[194:195], v58 src0_sel:WORD_1
	v_pk_fma_f32 v[200:201], v[68:69], v[188:189], v[200:201]
	v_cvt_pk_f32_fp8_e32 v[196:197], v59
	v_pk_fma_f32 v[202:203], v[70:71], v[190:191], v[202:203]
	v_cvt_pk_f32_fp8_sdwa v[198:199], v59 src0_sel:WORD_1
	v_pk_fma_f32 v[200:201], v[72:73], v[192:193], v[200:201]
	v_pk_fma_f32 v[202:203], v[74:75], v[194:195], v[202:203]
	v_pk_fma_f32 v[200:201], v[76:77], v[196:197], v[200:201]
	v_pk_fma_f32 v[202:203], v[78:79], v[198:199], v[202:203]
	v_pk_add_f32 v[200:201], v[200:201], v[202:203]
	v_add_f32_e32 v167, v200, v201
	v_readlane_b32 s24, v113, 15
	s_lshl_b32 s24, s24, 10
	v_add_u32_e32 v206, s24, v208
	global_load_dwordx4 v[56:59], v206, s[12:13]
	s_nop 1
	v_permlane32_swap_b32_e32 v160, v164
	v_permlane32_swap_b32_e32 v161, v165
	v_permlane32_swap_b32_e32 v162, v166
	v_permlane32_swap_b32_e32 v163, v167
	v_add_f32_e32 v160, v160, v164
	v_add_f32_e32 v161, v161, v165
	v_add_f32_e32 v162, v162, v166
	v_add_f32_e32 v163, v163, v167
	v_cndmask_b32_e64 v216, v162, v160, s[26:27]
	v_cndmask_b32_e64 v218, v160, v162, s[26:27]
	v_cndmask_b32_e64 v217, v163, v161, s[26:27]
	v_cndmask_b32_e64 v219, v161, v163, s[26:27]
	ds_bpermute_b32 v220, v212, v216
	ds_bpermute_b32 v221, v212, v217
	s_waitcnt lgkmcnt(0)
	v_add_f32_e32 v218, v220, v218
	v_add_f32_e32 v219, v221, v219
	v_cndmask_b32_e64 v216, v219, v218, s[28:29]
	v_cndmask_b32_e64 v217, v218, v219, s[28:29]
	s_nop 1
	v_add_f32_dpp v222, v216, v217 row_ror:8 row_mask:0xf bank_mask:0xf
	ds_bpermute_b32 v220, v213, v222
	s_waitcnt lgkmcnt(0)
	v_add_f32_e32 v222, v220, v222
	s_nop 1
	v_add_f32_dpp v223, v222, v222 quad_perm:[2,3,0,1] row_mask:0xf bank_mask:0xf
	s_nop 1
	v_add_f32_dpp v222, v223, v223 quad_perm:[1,0,3,2] row_mask:0xf bank_mask:0xf
	ds_bpermute_b32 v220, v214, v222
	s_mov_b32 s30, 0xff
	s_mov_b32 s31, 0x0
	s_waitcnt lgkmcnt(0)
	v_cndmask_b32_e64 v176, v176, v220, s[30:31]
	s_waitcnt vmcnt(27)
	v_cvt_pk_f32_fp8_e32 v[184:185], v60
	v_cvt_pk_f32_fp8_sdwa v[186:187], v60 src0_sel:WORD_1
	v_cvt_pk_f32_fp8_e32 v[188:189], v61
	v_cvt_pk_f32_fp8_sdwa v[190:191], v61 src0_sel:WORD_1
	v_pk_mul_f32 v[200:201], v[80:81], v[184:185]
	v_cvt_pk_f32_fp8_e32 v[192:193], v62
	v_pk_mul_f32 v[202:203], v[82:83], v[186:187]
	v_cvt_pk_f32_fp8_sdwa v[194:195], v62 src0_sel:WORD_1
	v_pk_fma_f32 v[200:201], v[84:85], v[188:189], v[200:201]
	v_cvt_pk_f32_fp8_e32 v[196:197], v63
	v_pk_fma_f32 v[202:203], v[86:87], v[190:191], v[202:203]
	v_cvt_pk_f32_fp8_sdwa v[198:199], v63 src0_sel:WORD_1
	v_pk_fma_f32 v[200:201], v[88:89], v[192:193], v[200:201]
	v_pk_fma_f32 v[202:203], v[90:91], v[194:195], v[202:203]
	v_pk_fma_f32 v[200:201], v[92:93], v[196:197], v[200:201]
	v_pk_fma_f32 v[202:203], v[94:95], v[198:199], v[202:203]
	v_pk_add_f32 v[200:201], v[200:201], v[202:203]
	v_add_f32_e32 v175, v200, v201
	v_readlane_b32 s25, v121, 15
	s_lshl_b32 s25, s25, 10
	v_add_u32_e32 v207, s25, v208
	global_load_dwordx4 v[60:63], v207, s[12:13]
	s_nop 1
	v_permlane32_swap_b32_e32 v168, v172
	v_permlane32_swap_b32_e32 v169, v173
	v_permlane32_swap_b32_e32 v170, v174
	v_permlane32_swap_b32_e32 v171, v175
	v_add_f32_e32 v168, v168, v172
	v_add_f32_e32 v169, v169, v173
	v_add_f32_e32 v170, v170, v174
	v_add_f32_e32 v171, v171, v175
	v_cndmask_b32_e64 v216, v170, v168, s[26:27]
	v_cndmask_b32_e64 v218, v168, v170, s[26:27]
	v_cndmask_b32_e64 v217, v171, v169, s[26:27]
	v_cndmask_b32_e64 v219, v169, v171, s[26:27]
	ds_bpermute_b32 v220, v212, v216
	ds_bpermute_b32 v221, v212, v217
	s_waitcnt lgkmcnt(0)
	v_add_f32_e32 v218, v220, v218
	v_add_f32_e32 v219, v221, v219
	v_cndmask_b32_e64 v216, v219, v218, s[28:29]
	v_cndmask_b32_e64 v217, v218, v219, s[28:29]
	s_nop 1
	v_add_f32_dpp v222, v216, v217 row_ror:8 row_mask:0xf bank_mask:0xf
	ds_bpermute_b32 v220, v213, v222
	s_waitcnt lgkmcnt(0)
	v_add_f32_e32 v222, v220, v222
	s_nop 1
	v_add_f32_dpp v223, v222, v222 quad_perm:[2,3,0,1] row_mask:0xf bank_mask:0xf
	s_nop 1
	v_add_f32_dpp v222, v223, v223 quad_perm:[1,0,3,2] row_mask:0xf bank_mask:0xf
	ds_bpermute_b32 v220, v214, v222
	s_mov_b32 s30, 0xff
	s_mov_b32 s31, 0x0
	s_waitcnt lgkmcnt(0)
	v_cndmask_b32_e64 v179, v179, v220, s[30:31]
	s_waitcnt vmcnt(15)
	v_cvt_pk_f32_fp8_e32 v[184:185], v0
	v_cvt_pk_f32_fp8_sdwa v[186:187], v0 src0_sel:WORD_1
	v_cvt_pk_f32_fp8_e32 v[188:189], v1
	v_cvt_pk_f32_fp8_sdwa v[190:191], v1 src0_sel:WORD_1
	v_pk_mul_f32 v[200:201], v[64:65], v[184:185]
	v_cvt_pk_f32_fp8_e32 v[192:193], v2
	v_pk_mul_f32 v[202:203], v[66:67], v[186:187]
	v_cvt_pk_f32_fp8_sdwa v[194:195], v2 src0_sel:WORD_1
	v_pk_fma_f32 v[200:201], v[68:69], v[188:189], v[200:201]
	v_cvt_pk_f32_fp8_e32 v[196:197], v3
	v_pk_fma_f32 v[202:203], v[70:71], v[190:191], v[202:203]
	v_cvt_pk_f32_fp8_sdwa v[198:199], v3 src0_sel:WORD_1
	v_pk_fma_f32 v[200:201], v[72:73], v[192:193], v[200:201]
	v_pk_fma_f32 v[202:203], v[74:75], v[194:195], v[202:203]
	v_pk_fma_f32 v[200:201], v[76:77], v[196:197], v[200:201]
	v_pk_fma_f32 v[202:203], v[78:79], v[198:199], v[202:203]
	v_pk_add_f32 v[200:201], v[200:201], v[202:203]
	v_add_f32_e32 v160, v200, v201
	v_readlane_b32 s22, v113, 16
	s_lshl_b32 s22, s22, 10
	v_add_u32_e32 v204, s22, v208
	global_load_dwordx4 v[0:3], v204, s[12:13]
	s_waitcnt vmcnt(15)
	v_cvt_pk_f32_fp8_e32 v[184:185], v4
	v_cvt_pk_f32_fp8_sdwa v[186:187], v4 src0_sel:WORD_1
	v_cvt_pk_f32_fp8_e32 v[188:189], v5
	v_cvt_pk_f32_fp8_sdwa v[190:191], v5 src0_sel:WORD_1
	v_pk_mul_f32 v[200:201], v[80:81], v[184:185]
	v_cvt_pk_f32_fp8_e32 v[192:193], v6
	v_pk_mul_f32 v[202:203], v[82:83], v[186:187]
	v_cvt_pk_f32_fp8_sdwa v[194:195], v6 src0_sel:WORD_1
	v_pk_fma_f32 v[200:201], v[84:85], v[188:189], v[200:201]
	v_cvt_pk_f32_fp8_e32 v[196:197], v7
	v_pk_fma_f32 v[202:203], v[86:87], v[190:191], v[202:203]
	v_cvt_pk_f32_fp8_sdwa v[198:199], v7 src0_sel:WORD_1
	v_pk_fma_f32 v[200:201], v[88:89], v[192:193], v[200:201]
	v_pk_fma_f32 v[202:203], v[90:91], v[194:195], v[202:203]
	v_pk_fma_f32 v[200:201], v[92:93], v[196:197], v[200:201]
	v_pk_fma_f32 v[202:203], v[94:95], v[198:199], v[202:203]
	v_pk_add_f32 v[200:201], v[200:201], v[202:203]
	v_add_f32_e32 v168, v200, v201
	v_readlane_b32 s23, v121, 16
	s_lshl_b32 s23, s23, 10
	v_add_u32_e32 v205, s23, v208
	global_load_dwordx4 v[4:7], v205, s[12:13]
	s_waitcnt vmcnt(15)
	v_cvt_pk_f32_fp8_e32 v[184:185], v8
	v_cvt_pk_f32_fp8_sdwa v[186:187], v8 src0_sel:WORD_1
	v_cvt_pk_f32_fp8_e32 v[188:189], v9
	v_cvt_pk_f32_fp8_sdwa v[190:191], v9 src0_sel:WORD_1
	v_pk_mul_f32 v[200:201], v[64:65], v[184:185]
	v_cvt_pk_f32_fp8_e32 v[192:193], v10
	v_pk_mul_f32 v[202:203], v[66:67], v[186:187]
	v_cvt_pk_f32_fp8_sdwa v[194:195], v10 src0_sel:WORD_1
	v_pk_fma_f32 v[200:201], v[68:69], v[188:189], v[200:201]
	v_cvt_pk_f32_fp8_e32 v[196:197], v11
	v_pk_fma_f32 v[202:203], v[70:71], v[190:191], v[202:203]
	v_cvt_pk_f32_fp8_sdwa v[198:199], v11 src0_sel:WORD_1
	v_pk_fma_f32 v[200:201], v[72:73], v[192:193], v[200:201]
	v_pk_fma_f32 v[202:203], v[74:75], v[194:195], v[202:203]
	v_pk_fma_f32 v[200:201], v[76:77], v[196:197], v[200:201]
	v_pk_fma_f32 v[202:203], v[78:79], v[198:199], v[202:203]
	v_pk_add_f32 v[200:201], v[200:201], v[202:203]
	v_add_f32_e32 v161, v200, v201
	v_readlane_b32 s24, v113, 17
	s_lshl_b32 s24, s24, 10
	v_add_u32_e32 v206, s24, v208
	global_load_dwordx4 v[8:11], v206, s[12:13]
	s_waitcnt vmcnt(15)
	v_cvt_pk_f32_fp8_e32 v[184:185], v12
	v_cvt_pk_f32_fp8_sdwa v[186:187], v12 src0_sel:WORD_1
	v_cvt_pk_f32_fp8_e32 v[188:189], v13
	v_cvt_pk_f32_fp8_sdwa v[190:191], v13 src0_sel:WORD_1
	v_pk_mul_f32 v[200:201], v[80:81], v[184:185]
	v_cvt_pk_f32_fp8_e32 v[192:193], v14
	v_pk_mul_f32 v[202:203], v[82:83], v[186:187]
	v_cvt_pk_f32_fp8_sdwa v[194:195], v14 src0_sel:WORD_1
	v_pk_fma_f32 v[200:201], v[84:85], v[188:189], v[200:201]
	v_cvt_pk_f32_fp8_e32 v[196:197], v15
	v_pk_fma_f32 v[202:203], v[86:87], v[190:191], v[202:203]
	v_cvt_pk_f32_fp8_sdwa v[198:199], v15 src0_sel:WORD_1
	v_pk_fma_f32 v[200:201], v[88:89], v[192:193], v[200:201]
	v_pk_fma_f32 v[202:203], v[90:91], v[194:195], v[202:203]
	v_pk_fma_f32 v[200:201], v[92:93], v[196:197], v[200:201]
	v_pk_fma_f32 v[202:203], v[94:95], v[198:199], v[202:203]
	v_pk_add_f32 v[200:201], v[200:201], v[202:203]
	v_add_f32_e32 v169, v200, v201
	v_readlane_b32 s25, v121, 17
	s_lshl_b32 s25, s25, 10
	v_add_u32_e32 v207, s25, v208
	global_load_dwordx4 v[12:15], v207, s[12:13]
	s_waitcnt vmcnt(15)
	v_cvt_pk_f32_fp8_e32 v[184:185], v16
	v_cvt_pk_f32_fp8_sdwa v[186:187], v16 src0_sel:WORD_1
	v_cvt_pk_f32_fp8_e32 v[188:189], v17
	v_cvt_pk_f32_fp8_sdwa v[190:191], v17 src0_sel:WORD_1
	v_pk_mul_f32 v[200:201], v[64:65], v[184:185]
	v_cvt_pk_f32_fp8_e32 v[192:193], v18
	v_pk_mul_f32 v[202:203], v[66:67], v[186:187]
	v_cvt_pk_f32_fp8_sdwa v[194:195], v18 src0_sel:WORD_1
	v_pk_fma_f32 v[200:201], v[68:69], v[188:189], v[200:201]
	v_cvt_pk_f32_fp8_e32 v[196:197], v19
	v_pk_fma_f32 v[202:203], v[70:71], v[190:191], v[202:203]
	v_cvt_pk_f32_fp8_sdwa v[198:199], v19 src0_sel:WORD_1
	v_pk_fma_f32 v[200:201], v[72:73], v[192:193], v[200:201]
	v_pk_fma_f32 v[202:203], v[74:75], v[194:195], v[202:203]
	v_pk_fma_f32 v[200:201], v[76:77], v[196:197], v[200:201]
	v_pk_fma_f32 v[202:203], v[78:79], v[198:199], v[202:203]
	v_pk_add_f32 v[200:201], v[200:201], v[202:203]
	v_add_f32_e32 v162, v200, v201
	v_readlane_b32 s22, v113, 18
	s_lshl_b32 s22, s22, 10
	v_add_u32_e32 v204, s22, v208
	global_load_dwordx4 v[16:19], v204, s[12:13]
	s_waitcnt vmcnt(15)
	v_cvt_pk_f32_fp8_e32 v[184:185], v20
	v_cvt_pk_f32_fp8_sdwa v[186:187], v20 src0_sel:WORD_1
	v_cvt_pk_f32_fp8_e32 v[188:189], v21
	v_cvt_pk_f32_fp8_sdwa v[190:191], v21 src0_sel:WORD_1
	v_pk_mul_f32 v[200:201], v[80:81], v[184:185]
	v_cvt_pk_f32_fp8_e32 v[192:193], v22
	v_pk_mul_f32 v[202:203], v[82:83], v[186:187]
	v_cvt_pk_f32_fp8_sdwa v[194:195], v22 src0_sel:WORD_1
	v_pk_fma_f32 v[200:201], v[84:85], v[188:189], v[200:201]
	v_cvt_pk_f32_fp8_e32 v[196:197], v23
	v_pk_fma_f32 v[202:203], v[86:87], v[190:191], v[202:203]
	v_cvt_pk_f32_fp8_sdwa v[198:199], v23 src0_sel:WORD_1
	v_pk_fma_f32 v[200:201], v[88:89], v[192:193], v[200:201]
	v_pk_fma_f32 v[202:203], v[90:91], v[194:195], v[202:203]
	v_pk_fma_f32 v[200:201], v[92:93], v[196:197], v[200:201]
	v_pk_fma_f32 v[202:203], v[94:95], v[198:199], v[202:203]
	v_pk_add_f32 v[200:201], v[200:201], v[202:203]
	v_add_f32_e32 v170, v200, v201
	v_readlane_b32 s23, v121, 18
	s_lshl_b32 s23, s23, 10
	v_add_u32_e32 v205, s23, v208
	global_load_dwordx4 v[20:23], v205, s[12:13]
	s_waitcnt vmcnt(15)
	v_cvt_pk_f32_fp8_e32 v[184:185], v24
	v_cvt_pk_f32_fp8_sdwa v[186:187], v24 src0_sel:WORD_1
	v_cvt_pk_f32_fp8_e32 v[188:189], v25
	v_cvt_pk_f32_fp8_sdwa v[190:191], v25 src0_sel:WORD_1
	v_pk_mul_f32 v[200:201], v[64:65], v[184:185]
	v_cvt_pk_f32_fp8_e32 v[192:193], v26
	v_pk_mul_f32 v[202:203], v[66:67], v[186:187]
	v_cvt_pk_f32_fp8_sdwa v[194:195], v26 src0_sel:WORD_1
	v_pk_fma_f32 v[200:201], v[68:69], v[188:189], v[200:201]
	v_cvt_pk_f32_fp8_e32 v[196:197], v27
	v_pk_fma_f32 v[202:203], v[70:71], v[190:191], v[202:203]
	v_cvt_pk_f32_fp8_sdwa v[198:199], v27 src0_sel:WORD_1
	v_pk_fma_f32 v[200:201], v[72:73], v[192:193], v[200:201]
	v_pk_fma_f32 v[202:203], v[74:75], v[194:195], v[202:203]
	v_pk_fma_f32 v[200:201], v[76:77], v[196:197], v[200:201]
	v_pk_fma_f32 v[202:203], v[78:79], v[198:199], v[202:203]
	v_pk_add_f32 v[200:201], v[200:201], v[202:203]
	v_add_f32_e32 v163, v200, v201
	v_readlane_b32 s24, v113, 19
	s_lshl_b32 s24, s24, 10
	v_add_u32_e32 v206, s24, v208
	global_load_dwordx4 v[24:27], v206, s[12:13]
	s_waitcnt vmcnt(15)
	v_cvt_pk_f32_fp8_e32 v[184:185], v28
	v_cvt_pk_f32_fp8_sdwa v[186:187], v28 src0_sel:WORD_1
	v_cvt_pk_f32_fp8_e32 v[188:189], v29
	v_cvt_pk_f32_fp8_sdwa v[190:191], v29 src0_sel:WORD_1
	v_pk_mul_f32 v[200:201], v[80:81], v[184:185]
	v_cvt_pk_f32_fp8_e32 v[192:193], v30
	v_pk_mul_f32 v[202:203], v[82:83], v[186:187]
	v_cvt_pk_f32_fp8_sdwa v[194:195], v30 src0_sel:WORD_1
	v_pk_fma_f32 v[200:201], v[84:85], v[188:189], v[200:201]
	v_cvt_pk_f32_fp8_e32 v[196:197], v31
	v_pk_fma_f32 v[202:203], v[86:87], v[190:191], v[202:203]
	v_cvt_pk_f32_fp8_sdwa v[198:199], v31 src0_sel:WORD_1
	v_pk_fma_f32 v[200:201], v[88:89], v[192:193], v[200:201]
	v_pk_fma_f32 v[202:203], v[90:91], v[194:195], v[202:203]
	v_pk_fma_f32 v[200:201], v[92:93], v[196:197], v[200:201]
	v_pk_fma_f32 v[202:203], v[94:95], v[198:199], v[202:203]
	v_pk_add_f32 v[200:201], v[200:201], v[202:203]
	v_add_f32_e32 v171, v200, v201
	v_readlane_b32 s25, v121, 19
	s_lshl_b32 s25, s25, 10
	v_add_u32_e32 v207, s25, v208
	global_load_dwordx4 v[28:31], v207, s[12:13]
	s_waitcnt vmcnt(15)
	v_cvt_pk_f32_fp8_e32 v[184:185], v32
	v_cvt_pk_f32_fp8_sdwa v[186:187], v32 src0_sel:WORD_1
	v_cvt_pk_f32_fp8_e32 v[188:189], v33
	v_cvt_pk_f32_fp8_sdwa v[190:191], v33 src0_sel:WORD_1
	v_pk_mul_f32 v[200:201], v[64:65], v[184:185]
	v_cvt_pk_f32_fp8_e32 v[192:193], v34
	v_pk_mul_f32 v[202:203], v[66:67], v[186:187]
	v_cvt_pk_f32_fp8_sdwa v[194:195], v34 src0_sel:WORD_1
	v_pk_fma_f32 v[200:201], v[68:69], v[188:189], v[200:201]
	v_cvt_pk_f32_fp8_e32 v[196:197], v35
	v_pk_fma_f32 v[202:203], v[70:71], v[190:191], v[202:203]
	v_cvt_pk_f32_fp8_sdwa v[198:199], v35 src0_sel:WORD_1
	v_pk_fma_f32 v[200:201], v[72:73], v[192:193], v[200:201]
	v_pk_fma_f32 v[202:203], v[74:75], v[194:195], v[202:203]
	v_pk_fma_f32 v[200:201], v[76:77], v[196:197], v[200:201]
	v_pk_fma_f32 v[202:203], v[78:79], v[198:199], v[202:203]
	v_pk_add_f32 v[200:201], v[200:201], v[202:203]
	v_add_f32_e32 v164, v200, v201
	v_readlane_b32 s22, v113, 20
	s_lshl_b32 s22, s22, 10
	v_add_u32_e32 v204, s22, v208
	global_load_dwordx4 v[32:35], v204, s[12:13]
	s_waitcnt vmcnt(15)
	v_cvt_pk_f32_fp8_e32 v[184:185], v36
	v_cvt_pk_f32_fp8_sdwa v[186:187], v36 src0_sel:WORD_1
	v_cvt_pk_f32_fp8_e32 v[188:189], v37
	v_cvt_pk_f32_fp8_sdwa v[190:191], v37 src0_sel:WORD_1
	v_pk_mul_f32 v[200:201], v[80:81], v[184:185]
	v_cvt_pk_f32_fp8_e32 v[192:193], v38
	v_pk_mul_f32 v[202:203], v[82:83], v[186:187]
	v_cvt_pk_f32_fp8_sdwa v[194:195], v38 src0_sel:WORD_1
	v_pk_fma_f32 v[200:201], v[84:85], v[188:189], v[200:201]
	v_cvt_pk_f32_fp8_e32 v[196:197], v39
	v_pk_fma_f32 v[202:203], v[86:87], v[190:191], v[202:203]
	v_cvt_pk_f32_fp8_sdwa v[198:199], v39 src0_sel:WORD_1
	v_pk_fma_f32 v[200:201], v[88:89], v[192:193], v[200:201]
	v_pk_fma_f32 v[202:203], v[90:91], v[194:195], v[202:203]
	v_pk_fma_f32 v[200:201], v[92:93], v[196:197], v[200:201]
	v_pk_fma_f32 v[202:203], v[94:95], v[198:199], v[202:203]
	v_pk_add_f32 v[200:201], v[200:201], v[202:203]
	v_add_f32_e32 v172, v200, v201
	v_readlane_b32 s23, v121, 20
	s_lshl_b32 s23, s23, 10
	v_add_u32_e32 v205, s23, v208
	global_load_dwordx4 v[36:39], v205, s[12:13]
	s_waitcnt vmcnt(15)
	v_cvt_pk_f32_fp8_e32 v[184:185], v40
	v_cvt_pk_f32_fp8_sdwa v[186:187], v40 src0_sel:WORD_1
	v_cvt_pk_f32_fp8_e32 v[188:189], v41
	v_cvt_pk_f32_fp8_sdwa v[190:191], v41 src0_sel:WORD_1
	v_pk_mul_f32 v[200:201], v[64:65], v[184:185]
	v_cvt_pk_f32_fp8_e32 v[192:193], v42
	v_pk_mul_f32 v[202:203], v[66:67], v[186:187]
	v_cvt_pk_f32_fp8_sdwa v[194:195], v42 src0_sel:WORD_1
	v_pk_fma_f32 v[200:201], v[68:69], v[188:189], v[200:201]
	v_cvt_pk_f32_fp8_e32 v[196:197], v43
	v_pk_fma_f32 v[202:203], v[70:71], v[190:191], v[202:203]
	v_cvt_pk_f32_fp8_sdwa v[198:199], v43 src0_sel:WORD_1
	v_pk_fma_f32 v[200:201], v[72:73], v[192:193], v[200:201]
	v_pk_fma_f32 v[202:203], v[74:75], v[194:195], v[202:203]
	v_pk_fma_f32 v[200:201], v[76:77], v[196:197], v[200:201]
	v_pk_fma_f32 v[202:203], v[78:79], v[198:199], v[202:203]
	v_pk_add_f32 v[200:201], v[200:201], v[202:203]
	v_add_f32_e32 v165, v200, v201
	v_readlane_b32 s24, v113, 21
	s_lshl_b32 s24, s24, 10
	v_add_u32_e32 v206, s24, v208
	global_load_dwordx4 v[40:43], v206, s[12:13]
	s_waitcnt vmcnt(15)
	v_cvt_pk_f32_fp8_e32 v[184:185], v44
	v_cvt_pk_f32_fp8_sdwa v[186:187], v44 src0_sel:WORD_1
	v_cvt_pk_f32_fp8_e32 v[188:189], v45
	v_cvt_pk_f32_fp8_sdwa v[190:191], v45 src0_sel:WORD_1
	v_pk_mul_f32 v[200:201], v[80:81], v[184:185]
	v_cvt_pk_f32_fp8_e32 v[192:193], v46
	v_pk_mul_f32 v[202:203], v[82:83], v[186:187]
	v_cvt_pk_f32_fp8_sdwa v[194:195], v46 src0_sel:WORD_1
	v_pk_fma_f32 v[200:201], v[84:85], v[188:189], v[200:201]
	v_cvt_pk_f32_fp8_e32 v[196:197], v47
	v_pk_fma_f32 v[202:203], v[86:87], v[190:191], v[202:203]
	v_cvt_pk_f32_fp8_sdwa v[198:199], v47 src0_sel:WORD_1
	v_pk_fma_f32 v[200:201], v[88:89], v[192:193], v[200:201]
	v_pk_fma_f32 v[202:203], v[90:91], v[194:195], v[202:203]
	v_pk_fma_f32 v[200:201], v[92:93], v[196:197], v[200:201]
	v_pk_fma_f32 v[202:203], v[94:95], v[198:199], v[202:203]
	v_pk_add_f32 v[200:201], v[200:201], v[202:203]
	v_add_f32_e32 v173, v200, v201
	v_readlane_b32 s25, v121, 21
	s_lshl_b32 s25, s25, 10
	v_add_u32_e32 v207, s25, v208
	global_load_dwordx4 v[44:47], v207, s[12:13]
	s_waitcnt vmcnt(15)
	v_cvt_pk_f32_fp8_e32 v[184:185], v48
	v_cvt_pk_f32_fp8_sdwa v[186:187], v48 src0_sel:WORD_1
	v_cvt_pk_f32_fp8_e32 v[188:189], v49
	v_cvt_pk_f32_fp8_sdwa v[190:191], v49 src0_sel:WORD_1
	v_pk_mul_f32 v[200:201], v[64:65], v[184:185]
	v_cvt_pk_f32_fp8_e32 v[192:193], v50
	v_pk_mul_f32 v[202:203], v[66:67], v[186:187]
	v_cvt_pk_f32_fp8_sdwa v[194:195], v50 src0_sel:WORD_1
	v_pk_fma_f32 v[200:201], v[68:69], v[188:189], v[200:201]
	v_cvt_pk_f32_fp8_e32 v[196:197], v51
	v_pk_fma_f32 v[202:203], v[70:71], v[190:191], v[202:203]
	v_cvt_pk_f32_fp8_sdwa v[198:199], v51 src0_sel:WORD_1
	v_pk_fma_f32 v[200:201], v[72:73], v[192:193], v[200:201]
	v_pk_fma_f32 v[202:203], v[74:75], v[194:195], v[202:203]
	v_pk_fma_f32 v[200:201], v[76:77], v[196:197], v[200:201]
	v_pk_fma_f32 v[202:203], v[78:79], v[198:199], v[202:203]
	v_pk_add_f32 v[200:201], v[200:201], v[202:203]
	v_add_f32_e32 v166, v200, v201
	v_readlane_b32 s22, v113, 22
	s_lshl_b32 s22, s22, 10
	v_add_u32_e32 v204, s22, v208
	global_load_dwordx4 v[48:51], v204, s[12:13]
	s_waitcnt vmcnt(15)
	v_cvt_pk_f32_fp8_e32 v[184:185], v52
	v_cvt_pk_f32_fp8_sdwa v[186:187], v52 src0_sel:WORD_1
	v_cvt_pk_f32_fp8_e32 v[188:189], v53
	v_cvt_pk_f32_fp8_sdwa v[190:191], v53 src0_sel:WORD_1
	v_pk_mul_f32 v[200:201], v[80:81], v[184:185]
	v_cvt_pk_f32_fp8_e32 v[192:193], v54
	v_pk_mul_f32 v[202:203], v[82:83], v[186:187]
	v_cvt_pk_f32_fp8_sdwa v[194:195], v54 src0_sel:WORD_1
	v_pk_fma_f32 v[200:201], v[84:85], v[188:189], v[200:201]
	v_cvt_pk_f32_fp8_e32 v[196:197], v55
	v_pk_fma_f32 v[202:203], v[86:87], v[190:191], v[202:203]
	v_cvt_pk_f32_fp8_sdwa v[198:199], v55 src0_sel:WORD_1
	v_pk_fma_f32 v[200:201], v[88:89], v[192:193], v[200:201]
	v_pk_fma_f32 v[202:203], v[90:91], v[194:195], v[202:203]
	v_pk_fma_f32 v[200:201], v[92:93], v[196:197], v[200:201]
	v_pk_fma_f32 v[202:203], v[94:95], v[198:199], v[202:203]
	v_pk_add_f32 v[200:201], v[200:201], v[202:203]
	v_add_f32_e32 v174, v200, v201
	v_readlane_b32 s23, v121, 22
	s_lshl_b32 s23, s23, 10
	v_add_u32_e32 v205, s23, v208
	global_load_dwordx4 v[52:55], v205, s[12:13]
	s_waitcnt vmcnt(15)
	v_cvt_pk_f32_fp8_e32 v[184:185], v56
	v_cvt_pk_f32_fp8_sdwa v[186:187], v56 src0_sel:WORD_1
	v_cvt_pk_f32_fp8_e32 v[188:189], v57
	v_cvt_pk_f32_fp8_sdwa v[190:191], v57 src0_sel:WORD_1
	v_pk_mul_f32 v[200:201], v[64:65], v[184:185]
	v_cvt_pk_f32_fp8_e32 v[192:193], v58
	v_pk_mul_f32 v[202:203], v[66:67], v[186:187]
	v_cvt_pk_f32_fp8_sdwa v[194:195], v58 src0_sel:WORD_1
	v_pk_fma_f32 v[200:201], v[68:69], v[188:189], v[200:201]
	v_cvt_pk_f32_fp8_e32 v[196:197], v59
	v_pk_fma_f32 v[202:203], v[70:71], v[190:191], v[202:203]
	v_cvt_pk_f32_fp8_sdwa v[198:199], v59 src0_sel:WORD_1
	v_pk_fma_f32 v[200:201], v[72:73], v[192:193], v[200:201]
	v_pk_fma_f32 v[202:203], v[74:75], v[194:195], v[202:203]
	v_pk_fma_f32 v[200:201], v[76:77], v[196:197], v[200:201]
	v_pk_fma_f32 v[202:203], v[78:79], v[198:199], v[202:203]
	v_pk_add_f32 v[200:201], v[200:201], v[202:203]
	v_add_f32_e32 v167, v200, v201
	v_readlane_b32 s24, v113, 23
	s_lshl_b32 s24, s24, 10
	v_add_u32_e32 v206, s24, v208
	global_load_dwordx4 v[56:59], v206, s[12:13]
	s_nop 1
	v_permlane32_swap_b32_e32 v160, v164
	v_permlane32_swap_b32_e32 v161, v165
	v_permlane32_swap_b32_e32 v162, v166
	v_permlane32_swap_b32_e32 v163, v167
	v_add_f32_e32 v160, v160, v164
	v_add_f32_e32 v161, v161, v165
	v_add_f32_e32 v162, v162, v166
	v_add_f32_e32 v163, v163, v167
	v_cndmask_b32_e64 v216, v162, v160, s[26:27]
	v_cndmask_b32_e64 v218, v160, v162, s[26:27]
	v_cndmask_b32_e64 v217, v163, v161, s[26:27]
	v_cndmask_b32_e64 v219, v161, v163, s[26:27]
	ds_bpermute_b32 v220, v212, v216
	ds_bpermute_b32 v221, v212, v217
	s_waitcnt lgkmcnt(0)
	v_add_f32_e32 v218, v220, v218
	v_add_f32_e32 v219, v221, v219
	v_cndmask_b32_e64 v216, v219, v218, s[28:29]
	v_cndmask_b32_e64 v217, v218, v219, s[28:29]
	s_nop 1
	v_add_f32_dpp v222, v216, v217 row_ror:8 row_mask:0xf bank_mask:0xf
	ds_bpermute_b32 v220, v213, v222
	s_waitcnt lgkmcnt(0)
	v_add_f32_e32 v222, v220, v222
	s_nop 1
	v_add_f32_dpp v223, v222, v222 quad_perm:[2,3,0,1] row_mask:0xf bank_mask:0xf
	s_nop 1
	v_add_f32_dpp v222, v223, v223 quad_perm:[1,0,3,2] row_mask:0xf bank_mask:0xf
	ds_bpermute_b32 v220, v214, v222
	s_mov_b32 s30, 0xff00
	s_mov_b32 s31, 0x0
	s_waitcnt lgkmcnt(0)
	v_cndmask_b32_e64 v176, v176, v220, s[30:31]
	s_waitcnt vmcnt(15)
	v_cvt_pk_f32_fp8_e32 v[184:185], v60
	v_cvt_pk_f32_fp8_sdwa v[186:187], v60 src0_sel:WORD_1
	v_cvt_pk_f32_fp8_e32 v[188:189], v61
	v_cvt_pk_f32_fp8_sdwa v[190:191], v61 src0_sel:WORD_1
	v_pk_mul_f32 v[200:201], v[80:81], v[184:185]
	v_cvt_pk_f32_fp8_e32 v[192:193], v62
	v_pk_mul_f32 v[202:203], v[82:83], v[186:187]
	v_cvt_pk_f32_fp8_sdwa v[194:195], v62 src0_sel:WORD_1
	v_pk_fma_f32 v[200:201], v[84:85], v[188:189], v[200:201]
	v_cvt_pk_f32_fp8_e32 v[196:197], v63
	v_pk_fma_f32 v[202:203], v[86:87], v[190:191], v[202:203]
	v_cvt_pk_f32_fp8_sdwa v[198:199], v63 src0_sel:WORD_1
	v_pk_fma_f32 v[200:201], v[88:89], v[192:193], v[200:201]
	v_pk_fma_f32 v[202:203], v[90:91], v[194:195], v[202:203]
	v_pk_fma_f32 v[200:201], v[92:93], v[196:197], v[200:201]
	v_pk_fma_f32 v[202:203], v[94:95], v[198:199], v[202:203]
	v_pk_add_f32 v[200:201], v[200:201], v[202:203]
	v_add_f32_e32 v175, v200, v201
	v_readlane_b32 s25, v121, 23
	s_lshl_b32 s25, s25, 10
	v_add_u32_e32 v207, s25, v208
	global_load_dwordx4 v[60:63], v207, s[12:13]
	s_nop 1
	v_permlane32_swap_b32_e32 v168, v172
	v_permlane32_swap_b32_e32 v169, v173
	v_permlane32_swap_b32_e32 v170, v174
	v_permlane32_swap_b32_e32 v171, v175
	v_add_f32_e32 v168, v168, v172
	v_add_f32_e32 v169, v169, v173
	v_add_f32_e32 v170, v170, v174
	v_add_f32_e32 v171, v171, v175
	v_cndmask_b32_e64 v216, v170, v168, s[26:27]
	v_cndmask_b32_e64 v218, v168, v170, s[26:27]
	v_cndmask_b32_e64 v217, v171, v169, s[26:27]
	v_cndmask_b32_e64 v219, v169, v171, s[26:27]
	ds_bpermute_b32 v220, v212, v216
	ds_bpermute_b32 v221, v212, v217
	s_waitcnt lgkmcnt(0)
	v_add_f32_e32 v218, v220, v218
	v_add_f32_e32 v219, v221, v219
	v_cndmask_b32_e64 v216, v219, v218, s[28:29]
	v_cndmask_b32_e64 v217, v218, v219, s[28:29]
	s_nop 1
	v_add_f32_dpp v222, v216, v217 row_ror:8 row_mask:0xf bank_mask:0xf
	ds_bpermute_b32 v220, v213, v222
	s_waitcnt lgkmcnt(0)
	v_add_f32_e32 v222, v220, v222
	s_nop 1
	v_add_f32_dpp v223, v222, v222 quad_perm:[2,3,0,1] row_mask:0xf bank_mask:0xf
	s_nop 1
	v_add_f32_dpp v222, v223, v223 quad_perm:[1,0,3,2] row_mask:0xf bank_mask:0xf
	ds_bpermute_b32 v220, v214, v222
	s_mov_b32 s30, 0xff00
	s_mov_b32 s31, 0x0
	s_waitcnt lgkmcnt(0)
	v_cndmask_b32_e64 v179, v179, v220, s[30:31]
	s_waitcnt vmcnt(15)
	v_cvt_pk_f32_fp8_e32 v[184:185], v0
	v_cvt_pk_f32_fp8_sdwa v[186:187], v0 src0_sel:WORD_1
	v_cvt_pk_f32_fp8_e32 v[188:189], v1
	v_cvt_pk_f32_fp8_sdwa v[190:191], v1 src0_sel:WORD_1
	v_pk_mul_f32 v[200:201], v[64:65], v[184:185]
	v_cvt_pk_f32_fp8_e32 v[192:193], v2
	v_pk_mul_f32 v[202:203], v[66:67], v[186:187]
	v_cvt_pk_f32_fp8_sdwa v[194:195], v2 src0_sel:WORD_1
	v_pk_fma_f32 v[200:201], v[68:69], v[188:189], v[200:201]
	v_cvt_pk_f32_fp8_e32 v[196:197], v3
	v_pk_fma_f32 v[202:203], v[70:71], v[190:191], v[202:203]
	v_cvt_pk_f32_fp8_sdwa v[198:199], v3 src0_sel:WORD_1
	v_pk_fma_f32 v[200:201], v[72:73], v[192:193], v[200:201]
	v_pk_fma_f32 v[202:203], v[74:75], v[194:195], v[202:203]
	v_pk_fma_f32 v[200:201], v[76:77], v[196:197], v[200:201]
	v_pk_fma_f32 v[202:203], v[78:79], v[198:199], v[202:203]
	v_pk_add_f32 v[200:201], v[200:201], v[202:203]
	v_add_f32_e32 v160, v200, v201
	v_readlane_b32 s22, v113, 24
	s_lshl_b32 s22, s22, 10
	v_add_u32_e32 v204, s22, v208
	global_load_dwordx4 v[0:3], v204, s[12:13]
	s_waitcnt vmcnt(15)
	v_cvt_pk_f32_fp8_e32 v[184:185], v4
	v_cvt_pk_f32_fp8_sdwa v[186:187], v4 src0_sel:WORD_1
	v_cvt_pk_f32_fp8_e32 v[188:189], v5
	v_cvt_pk_f32_fp8_sdwa v[190:191], v5 src0_sel:WORD_1
	v_pk_mul_f32 v[200:201], v[80:81], v[184:185]
	v_cvt_pk_f32_fp8_e32 v[192:193], v6
	v_pk_mul_f32 v[202:203], v[82:83], v[186:187]
	v_cvt_pk_f32_fp8_sdwa v[194:195], v6 src0_sel:WORD_1
	v_pk_fma_f32 v[200:201], v[84:85], v[188:189], v[200:201]
	v_cvt_pk_f32_fp8_e32 v[196:197], v7
	v_pk_fma_f32 v[202:203], v[86:87], v[190:191], v[202:203]
	v_cvt_pk_f32_fp8_sdwa v[198:199], v7 src0_sel:WORD_1
	v_pk_fma_f32 v[200:201], v[88:89], v[192:193], v[200:201]
	v_pk_fma_f32 v[202:203], v[90:91], v[194:195], v[202:203]
	v_pk_fma_f32 v[200:201], v[92:93], v[196:197], v[200:201]
	v_pk_fma_f32 v[202:203], v[94:95], v[198:199], v[202:203]
	v_pk_add_f32 v[200:201], v[200:201], v[202:203]
	v_add_f32_e32 v168, v200, v201
	v_readlane_b32 s23, v121, 24
	s_lshl_b32 s23, s23, 10
	v_add_u32_e32 v205, s23, v208
	global_load_dwordx4 v[4:7], v205, s[12:13]
	s_waitcnt vmcnt(15)
	v_cvt_pk_f32_fp8_e32 v[184:185], v8
	v_cvt_pk_f32_fp8_sdwa v[186:187], v8 src0_sel:WORD_1
	v_cvt_pk_f32_fp8_e32 v[188:189], v9
	v_cvt_pk_f32_fp8_sdwa v[190:191], v9 src0_sel:WORD_1
	v_pk_mul_f32 v[200:201], v[64:65], v[184:185]
	v_cvt_pk_f32_fp8_e32 v[192:193], v10
	v_pk_mul_f32 v[202:203], v[66:67], v[186:187]
	v_cvt_pk_f32_fp8_sdwa v[194:195], v10 src0_sel:WORD_1
	v_pk_fma_f32 v[200:201], v[68:69], v[188:189], v[200:201]
	v_cvt_pk_f32_fp8_e32 v[196:197], v11
	v_pk_fma_f32 v[202:203], v[70:71], v[190:191], v[202:203]
	v_cvt_pk_f32_fp8_sdwa v[198:199], v11 src0_sel:WORD_1
	v_pk_fma_f32 v[200:201], v[72:73], v[192:193], v[200:201]
	v_pk_fma_f32 v[202:203], v[74:75], v[194:195], v[202:203]
	v_pk_fma_f32 v[200:201], v[76:77], v[196:197], v[200:201]
	v_pk_fma_f32 v[202:203], v[78:79], v[198:199], v[202:203]
	v_pk_add_f32 v[200:201], v[200:201], v[202:203]
	v_add_f32_e32 v161, v200, v201
	v_readlane_b32 s24, v113, 25
	s_lshl_b32 s24, s24, 10
	v_add_u32_e32 v206, s24, v208
	global_load_dwordx4 v[8:11], v206, s[12:13]
	s_waitcnt vmcnt(15)
	v_cvt_pk_f32_fp8_e32 v[184:185], v12
	v_cvt_pk_f32_fp8_sdwa v[186:187], v12 src0_sel:WORD_1
	v_cvt_pk_f32_fp8_e32 v[188:189], v13
	v_cvt_pk_f32_fp8_sdwa v[190:191], v13 src0_sel:WORD_1
	v_pk_mul_f32 v[200:201], v[80:81], v[184:185]
	v_cvt_pk_f32_fp8_e32 v[192:193], v14
	v_pk_mul_f32 v[202:203], v[82:83], v[186:187]
	v_cvt_pk_f32_fp8_sdwa v[194:195], v14 src0_sel:WORD_1
	v_pk_fma_f32 v[200:201], v[84:85], v[188:189], v[200:201]
	v_cvt_pk_f32_fp8_e32 v[196:197], v15
	v_pk_fma_f32 v[202:203], v[86:87], v[190:191], v[202:203]
	v_cvt_pk_f32_fp8_sdwa v[198:199], v15 src0_sel:WORD_1
	v_pk_fma_f32 v[200:201], v[88:89], v[192:193], v[200:201]
	v_pk_fma_f32 v[202:203], v[90:91], v[194:195], v[202:203]
	v_pk_fma_f32 v[200:201], v[92:93], v[196:197], v[200:201]
	v_pk_fma_f32 v[202:203], v[94:95], v[198:199], v[202:203]
	v_pk_add_f32 v[200:201], v[200:201], v[202:203]
	v_add_f32_e32 v169, v200, v201
	v_readlane_b32 s25, v121, 25
	s_lshl_b32 s25, s25, 10
	v_add_u32_e32 v207, s25, v208
	global_load_dwordx4 v[12:15], v207, s[12:13]
	s_waitcnt vmcnt(15)
	v_cvt_pk_f32_fp8_e32 v[184:185], v16
	v_cvt_pk_f32_fp8_sdwa v[186:187], v16 src0_sel:WORD_1
	v_cvt_pk_f32_fp8_e32 v[188:189], v17
	v_cvt_pk_f32_fp8_sdwa v[190:191], v17 src0_sel:WORD_1
	v_pk_mul_f32 v[200:201], v[64:65], v[184:185]
	v_cvt_pk_f32_fp8_e32 v[192:193], v18
	v_pk_mul_f32 v[202:203], v[66:67], v[186:187]
	v_cvt_pk_f32_fp8_sdwa v[194:195], v18 src0_sel:WORD_1
	v_pk_fma_f32 v[200:201], v[68:69], v[188:189], v[200:201]
	v_cvt_pk_f32_fp8_e32 v[196:197], v19
	v_pk_fma_f32 v[202:203], v[70:71], v[190:191], v[202:203]
	v_cvt_pk_f32_fp8_sdwa v[198:199], v19 src0_sel:WORD_1
	v_pk_fma_f32 v[200:201], v[72:73], v[192:193], v[200:201]
	v_pk_fma_f32 v[202:203], v[74:75], v[194:195], v[202:203]
	v_pk_fma_f32 v[200:201], v[76:77], v[196:197], v[200:201]
	v_pk_fma_f32 v[202:203], v[78:79], v[198:199], v[202:203]
	v_pk_add_f32 v[200:201], v[200:201], v[202:203]
	v_add_f32_e32 v162, v200, v201
	v_readlane_b32 s22, v113, 26
	s_lshl_b32 s22, s22, 10
	v_add_u32_e32 v204, s22, v208
	global_load_dwordx4 v[16:19], v204, s[12:13]
	s_waitcnt vmcnt(15)
	v_cvt_pk_f32_fp8_e32 v[184:185], v20
	v_cvt_pk_f32_fp8_sdwa v[186:187], v20 src0_sel:WORD_1
	v_cvt_pk_f32_fp8_e32 v[188:189], v21
	v_cvt_pk_f32_fp8_sdwa v[190:191], v21 src0_sel:WORD_1
	v_pk_mul_f32 v[200:201], v[80:81], v[184:185]
	v_cvt_pk_f32_fp8_e32 v[192:193], v22
	v_pk_mul_f32 v[202:203], v[82:83], v[186:187]
	v_cvt_pk_f32_fp8_sdwa v[194:195], v22 src0_sel:WORD_1
	v_pk_fma_f32 v[200:201], v[84:85], v[188:189], v[200:201]
	v_cvt_pk_f32_fp8_e32 v[196:197], v23
	v_pk_fma_f32 v[202:203], v[86:87], v[190:191], v[202:203]
	v_cvt_pk_f32_fp8_sdwa v[198:199], v23 src0_sel:WORD_1
	v_pk_fma_f32 v[200:201], v[88:89], v[192:193], v[200:201]
	v_pk_fma_f32 v[202:203], v[90:91], v[194:195], v[202:203]
	v_pk_fma_f32 v[200:201], v[92:93], v[196:197], v[200:201]
	v_pk_fma_f32 v[202:203], v[94:95], v[198:199], v[202:203]
	v_pk_add_f32 v[200:201], v[200:201], v[202:203]
	v_add_f32_e32 v170, v200, v201
	v_readlane_b32 s23, v121, 26
	s_lshl_b32 s23, s23, 10
	v_add_u32_e32 v205, s23, v208
	global_load_dwordx4 v[20:23], v205, s[12:13]
	s_waitcnt vmcnt(15)
	v_cvt_pk_f32_fp8_e32 v[184:185], v24
	v_cvt_pk_f32_fp8_sdwa v[186:187], v24 src0_sel:WORD_1
	v_cvt_pk_f32_fp8_e32 v[188:189], v25
	v_cvt_pk_f32_fp8_sdwa v[190:191], v25 src0_sel:WORD_1
	v_pk_mul_f32 v[200:201], v[64:65], v[184:185]
	v_cvt_pk_f32_fp8_e32 v[192:193], v26
	v_pk_mul_f32 v[202:203], v[66:67], v[186:187]
	v_cvt_pk_f32_fp8_sdwa v[194:195], v26 src0_sel:WORD_1
	v_pk_fma_f32 v[200:201], v[68:69], v[188:189], v[200:201]
	v_cvt_pk_f32_fp8_e32 v[196:197], v27
	v_pk_fma_f32 v[202:203], v[70:71], v[190:191], v[202:203]
	v_cvt_pk_f32_fp8_sdwa v[198:199], v27 src0_sel:WORD_1
	v_pk_fma_f32 v[200:201], v[72:73], v[192:193], v[200:201]
	v_pk_fma_f32 v[202:203], v[74:75], v[194:195], v[202:203]
	v_pk_fma_f32 v[200:201], v[76:77], v[196:197], v[200:201]
	v_pk_fma_f32 v[202:203], v[78:79], v[198:199], v[202:203]
	v_pk_add_f32 v[200:201], v[200:201], v[202:203]
	v_add_f32_e32 v163, v200, v201
	v_readlane_b32 s24, v113, 27
	s_lshl_b32 s24, s24, 10
	v_add_u32_e32 v206, s24, v208
	global_load_dwordx4 v[24:27], v206, s[12:13]
	s_waitcnt vmcnt(15)
	v_cvt_pk_f32_fp8_e32 v[184:185], v28
	v_cvt_pk_f32_fp8_sdwa v[186:187], v28 src0_sel:WORD_1
	v_cvt_pk_f32_fp8_e32 v[188:189], v29
	v_cvt_pk_f32_fp8_sdwa v[190:191], v29 src0_sel:WORD_1
	v_pk_mul_f32 v[200:201], v[80:81], v[184:185]
	v_cvt_pk_f32_fp8_e32 v[192:193], v30
	v_pk_mul_f32 v[202:203], v[82:83], v[186:187]
	v_cvt_pk_f32_fp8_sdwa v[194:195], v30 src0_sel:WORD_1
	v_pk_fma_f32 v[200:201], v[84:85], v[188:189], v[200:201]
	v_cvt_pk_f32_fp8_e32 v[196:197], v31
	v_pk_fma_f32 v[202:203], v[86:87], v[190:191], v[202:203]
	v_cvt_pk_f32_fp8_sdwa v[198:199], v31 src0_sel:WORD_1
	v_pk_fma_f32 v[200:201], v[88:89], v[192:193], v[200:201]
	v_pk_fma_f32 v[202:203], v[90:91], v[194:195], v[202:203]
	v_pk_fma_f32 v[200:201], v[92:93], v[196:197], v[200:201]
	v_pk_fma_f32 v[202:203], v[94:95], v[198:199], v[202:203]
	v_pk_add_f32 v[200:201], v[200:201], v[202:203]
	v_add_f32_e32 v171, v200, v201
	v_readlane_b32 s25, v121, 27
	s_lshl_b32 s25, s25, 10
	v_add_u32_e32 v207, s25, v208
	global_load_dwordx4 v[28:31], v207, s[12:13]
	s_waitcnt vmcnt(15)
	v_cvt_pk_f32_fp8_e32 v[184:185], v32
	v_cvt_pk_f32_fp8_sdwa v[186:187], v32 src0_sel:WORD_1
	v_cvt_pk_f32_fp8_e32 v[188:189], v33
	v_cvt_pk_f32_fp8_sdwa v[190:191], v33 src0_sel:WORD_1
	v_pk_mul_f32 v[200:201], v[64:65], v[184:185]
	v_cvt_pk_f32_fp8_e32 v[192:193], v34
	v_pk_mul_f32 v[202:203], v[66:67], v[186:187]
	v_cvt_pk_f32_fp8_sdwa v[194:195], v34 src0_sel:WORD_1
	v_pk_fma_f32 v[200:201], v[68:69], v[188:189], v[200:201]
	v_cvt_pk_f32_fp8_e32 v[196:197], v35
	v_pk_fma_f32 v[202:203], v[70:71], v[190:191], v[202:203]
	v_cvt_pk_f32_fp8_sdwa v[198:199], v35 src0_sel:WORD_1
	v_pk_fma_f32 v[200:201], v[72:73], v[192:193], v[200:201]
	v_pk_fma_f32 v[202:203], v[74:75], v[194:195], v[202:203]
	v_pk_fma_f32 v[200:201], v[76:77], v[196:197], v[200:201]
	v_pk_fma_f32 v[202:203], v[78:79], v[198:199], v[202:203]
	v_pk_add_f32 v[200:201], v[200:201], v[202:203]
	v_add_f32_e32 v164, v200, v201
	v_readlane_b32 s22, v113, 28
	s_lshl_b32 s22, s22, 10
	v_add_u32_e32 v204, s22, v208
	global_load_dwordx4 v[32:35], v204, s[12:13]
	s_waitcnt vmcnt(15)
	v_cvt_pk_f32_fp8_e32 v[184:185], v36
	v_cvt_pk_f32_fp8_sdwa v[186:187], v36 src0_sel:WORD_1
	v_cvt_pk_f32_fp8_e32 v[188:189], v37
	v_cvt_pk_f32_fp8_sdwa v[190:191], v37 src0_sel:WORD_1
	v_pk_mul_f32 v[200:201], v[80:81], v[184:185]
	v_cvt_pk_f32_fp8_e32 v[192:193], v38
	v_pk_mul_f32 v[202:203], v[82:83], v[186:187]
	v_cvt_pk_f32_fp8_sdwa v[194:195], v38 src0_sel:WORD_1
	v_pk_fma_f32 v[200:201], v[84:85], v[188:189], v[200:201]
	v_cvt_pk_f32_fp8_e32 v[196:197], v39
	v_pk_fma_f32 v[202:203], v[86:87], v[190:191], v[202:203]
	v_cvt_pk_f32_fp8_sdwa v[198:199], v39 src0_sel:WORD_1
	v_pk_fma_f32 v[200:201], v[88:89], v[192:193], v[200:201]
	v_pk_fma_f32 v[202:203], v[90:91], v[194:195], v[202:203]
	v_pk_fma_f32 v[200:201], v[92:93], v[196:197], v[200:201]
	v_pk_fma_f32 v[202:203], v[94:95], v[198:199], v[202:203]
	v_pk_add_f32 v[200:201], v[200:201], v[202:203]
	v_add_f32_e32 v172, v200, v201
	v_readlane_b32 s23, v121, 28
	s_lshl_b32 s23, s23, 10
	v_add_u32_e32 v205, s23, v208
	global_load_dwordx4 v[36:39], v205, s[12:13]
	s_waitcnt vmcnt(15)
	v_cvt_pk_f32_fp8_e32 v[184:185], v40
	v_cvt_pk_f32_fp8_sdwa v[186:187], v40 src0_sel:WORD_1
	v_cvt_pk_f32_fp8_e32 v[188:189], v41
	v_cvt_pk_f32_fp8_sdwa v[190:191], v41 src0_sel:WORD_1
	v_pk_mul_f32 v[200:201], v[64:65], v[184:185]
	v_cvt_pk_f32_fp8_e32 v[192:193], v42
	v_pk_mul_f32 v[202:203], v[66:67], v[186:187]
	v_cvt_pk_f32_fp8_sdwa v[194:195], v42 src0_sel:WORD_1
	v_pk_fma_f32 v[200:201], v[68:69], v[188:189], v[200:201]
	v_cvt_pk_f32_fp8_e32 v[196:197], v43
	v_pk_fma_f32 v[202:203], v[70:71], v[190:191], v[202:203]
	v_cvt_pk_f32_fp8_sdwa v[198:199], v43 src0_sel:WORD_1
	v_pk_fma_f32 v[200:201], v[72:73], v[192:193], v[200:201]
	v_pk_fma_f32 v[202:203], v[74:75], v[194:195], v[202:203]
	v_pk_fma_f32 v[200:201], v[76:77], v[196:197], v[200:201]
	v_pk_fma_f32 v[202:203], v[78:79], v[198:199], v[202:203]
	v_pk_add_f32 v[200:201], v[200:201], v[202:203]
	v_add_f32_e32 v165, v200, v201
	v_readlane_b32 s24, v113, 29
	s_lshl_b32 s24, s24, 10
	v_add_u32_e32 v206, s24, v208
	global_load_dwordx4 v[40:43], v206, s[12:13]
	s_waitcnt vmcnt(15)
	v_cvt_pk_f32_fp8_e32 v[184:185], v44
	v_cvt_pk_f32_fp8_sdwa v[186:187], v44 src0_sel:WORD_1
	v_cvt_pk_f32_fp8_e32 v[188:189], v45
	v_cvt_pk_f32_fp8_sdwa v[190:191], v45 src0_sel:WORD_1
	v_pk_mul_f32 v[200:201], v[80:81], v[184:185]
	v_cvt_pk_f32_fp8_e32 v[192:193], v46
	v_pk_mul_f32 v[202:203], v[82:83], v[186:187]
	v_cvt_pk_f32_fp8_sdwa v[194:195], v46 src0_sel:WORD_1
	v_pk_fma_f32 v[200:201], v[84:85], v[188:189], v[200:201]
	v_cvt_pk_f32_fp8_e32 v[196:197], v47
	v_pk_fma_f32 v[202:203], v[86:87], v[190:191], v[202:203]
	v_cvt_pk_f32_fp8_sdwa v[198:199], v47 src0_sel:WORD_1
	v_pk_fma_f32 v[200:201], v[88:89], v[192:193], v[200:201]
	v_pk_fma_f32 v[202:203], v[90:91], v[194:195], v[202:203]
	v_pk_fma_f32 v[200:201], v[92:93], v[196:197], v[200:201]
	v_pk_fma_f32 v[202:203], v[94:95], v[198:199], v[202:203]
	v_pk_add_f32 v[200:201], v[200:201], v[202:203]
	v_add_f32_e32 v173, v200, v201
	v_readlane_b32 s25, v121, 29
	s_lshl_b32 s25, s25, 10
	v_add_u32_e32 v207, s25, v208
	global_load_dwordx4 v[44:47], v207, s[12:13]
	s_waitcnt vmcnt(15)
	v_cvt_pk_f32_fp8_e32 v[184:185], v48
	v_cvt_pk_f32_fp8_sdwa v[186:187], v48 src0_sel:WORD_1
	v_cvt_pk_f32_fp8_e32 v[188:189], v49
	v_cvt_pk_f32_fp8_sdwa v[190:191], v49 src0_sel:WORD_1
	v_pk_mul_f32 v[200:201], v[64:65], v[184:185]
	v_cvt_pk_f32_fp8_e32 v[192:193], v50
	v_pk_mul_f32 v[202:203], v[66:67], v[186:187]
	v_cvt_pk_f32_fp8_sdwa v[194:195], v50 src0_sel:WORD_1
	v_pk_fma_f32 v[200:201], v[68:69], v[188:189], v[200:201]
	v_cvt_pk_f32_fp8_e32 v[196:197], v51
	v_pk_fma_f32 v[202:203], v[70:71], v[190:191], v[202:203]
	v_cvt_pk_f32_fp8_sdwa v[198:199], v51 src0_sel:WORD_1
	v_pk_fma_f32 v[200:201], v[72:73], v[192:193], v[200:201]
	v_pk_fma_f32 v[202:203], v[74:75], v[194:195], v[202:203]
	v_pk_fma_f32 v[200:201], v[76:77], v[196:197], v[200:201]
	v_pk_fma_f32 v[202:203], v[78:79], v[198:199], v[202:203]
	v_pk_add_f32 v[200:201], v[200:201], v[202:203]
	v_add_f32_e32 v166, v200, v201
	v_readlane_b32 s22, v113, 30
	s_lshl_b32 s22, s22, 10
	v_add_u32_e32 v204, s22, v208
	global_load_dwordx4 v[48:51], v204, s[12:13]
	s_waitcnt vmcnt(15)
	v_cvt_pk_f32_fp8_e32 v[184:185], v52
	v_cvt_pk_f32_fp8_sdwa v[186:187], v52 src0_sel:WORD_1
	v_cvt_pk_f32_fp8_e32 v[188:189], v53
	v_cvt_pk_f32_fp8_sdwa v[190:191], v53 src0_sel:WORD_1
	v_pk_mul_f32 v[200:201], v[80:81], v[184:185]
	v_cvt_pk_f32_fp8_e32 v[192:193], v54
	v_pk_mul_f32 v[202:203], v[82:83], v[186:187]
	v_cvt_pk_f32_fp8_sdwa v[194:195], v54 src0_sel:WORD_1
	v_pk_fma_f32 v[200:201], v[84:85], v[188:189], v[200:201]
	v_cvt_pk_f32_fp8_e32 v[196:197], v55
	v_pk_fma_f32 v[202:203], v[86:87], v[190:191], v[202:203]
	v_cvt_pk_f32_fp8_sdwa v[198:199], v55 src0_sel:WORD_1
	v_pk_fma_f32 v[200:201], v[88:89], v[192:193], v[200:201]
	v_pk_fma_f32 v[202:203], v[90:91], v[194:195], v[202:203]
	v_pk_fma_f32 v[200:201], v[92:93], v[196:197], v[200:201]
	v_pk_fma_f32 v[202:203], v[94:95], v[198:199], v[202:203]
	v_pk_add_f32 v[200:201], v[200:201], v[202:203]
	v_add_f32_e32 v174, v200, v201
	v_readlane_b32 s23, v121, 30
	s_lshl_b32 s23, s23, 10
	v_add_u32_e32 v205, s23, v208
	global_load_dwordx4 v[52:55], v205, s[12:13]
	s_waitcnt vmcnt(15)
	v_cvt_pk_f32_fp8_e32 v[184:185], v56
	v_cvt_pk_f32_fp8_sdwa v[186:187], v56 src0_sel:WORD_1
	v_cvt_pk_f32_fp8_e32 v[188:189], v57
	v_cvt_pk_f32_fp8_sdwa v[190:191], v57 src0_sel:WORD_1
	v_pk_mul_f32 v[200:201], v[64:65], v[184:185]
	v_cvt_pk_f32_fp8_e32 v[192:193], v58
	v_pk_mul_f32 v[202:203], v[66:67], v[186:187]
	v_cvt_pk_f32_fp8_sdwa v[194:195], v58 src0_sel:WORD_1
	v_pk_fma_f32 v[200:201], v[68:69], v[188:189], v[200:201]
	v_cvt_pk_f32_fp8_e32 v[196:197], v59
	v_pk_fma_f32 v[202:203], v[70:71], v[190:191], v[202:203]
	v_cvt_pk_f32_fp8_sdwa v[198:199], v59 src0_sel:WORD_1
	v_pk_fma_f32 v[200:201], v[72:73], v[192:193], v[200:201]
	v_pk_fma_f32 v[202:203], v[74:75], v[194:195], v[202:203]
	v_pk_fma_f32 v[200:201], v[76:77], v[196:197], v[200:201]
	v_pk_fma_f32 v[202:203], v[78:79], v[198:199], v[202:203]
	v_pk_add_f32 v[200:201], v[200:201], v[202:203]
	v_add_f32_e32 v167, v200, v201
	v_readlane_b32 s24, v113, 31
	s_lshl_b32 s24, s24, 10
	v_add_u32_e32 v206, s24, v208
	global_load_dwordx4 v[56:59], v206, s[12:13]
	s_nop 1
	v_permlane32_swap_b32_e32 v160, v164
	v_permlane32_swap_b32_e32 v161, v165
	v_permlane32_swap_b32_e32 v162, v166
	v_permlane32_swap_b32_e32 v163, v167
	v_add_f32_e32 v160, v160, v164
	v_add_f32_e32 v161, v161, v165
	v_add_f32_e32 v162, v162, v166
	v_add_f32_e32 v163, v163, v167
	v_cndmask_b32_e64 v216, v162, v160, s[26:27]
	v_cndmask_b32_e64 v218, v160, v162, s[26:27]
	v_cndmask_b32_e64 v217, v163, v161, s[26:27]
	v_cndmask_b32_e64 v219, v161, v163, s[26:27]
	ds_bpermute_b32 v220, v212, v216
	ds_bpermute_b32 v221, v212, v217
	s_waitcnt lgkmcnt(0)
	v_add_f32_e32 v218, v220, v218
	v_add_f32_e32 v219, v221, v219
	v_cndmask_b32_e64 v216, v219, v218, s[28:29]
	v_cndmask_b32_e64 v217, v218, v219, s[28:29]
	s_nop 1
	v_add_f32_dpp v222, v216, v217 row_ror:8 row_mask:0xf bank_mask:0xf
	ds_bpermute_b32 v220, v213, v222
	s_waitcnt lgkmcnt(0)
	v_add_f32_e32 v222, v220, v222
	s_nop 1
	v_add_f32_dpp v223, v222, v222 quad_perm:[2,3,0,1] row_mask:0xf bank_mask:0xf
	s_nop 1
	v_add_f32_dpp v222, v223, v223 quad_perm:[1,0,3,2] row_mask:0xf bank_mask:0xf
	ds_bpermute_b32 v220, v214, v222
	s_mov_b32 s30, 0xff0000
	s_mov_b32 s31, 0x0
	s_waitcnt lgkmcnt(0)
	v_cndmask_b32_e64 v176, v176, v220, s[30:31]
	s_waitcnt vmcnt(15)
	v_cvt_pk_f32_fp8_e32 v[184:185], v60
	v_cvt_pk_f32_fp8_sdwa v[186:187], v60 src0_sel:WORD_1
	v_cvt_pk_f32_fp8_e32 v[188:189], v61
	v_cvt_pk_f32_fp8_sdwa v[190:191], v61 src0_sel:WORD_1
	v_pk_mul_f32 v[200:201], v[80:81], v[184:185]
	v_cvt_pk_f32_fp8_e32 v[192:193], v62
	v_pk_mul_f32 v[202:203], v[82:83], v[186:187]
	v_cvt_pk_f32_fp8_sdwa v[194:195], v62 src0_sel:WORD_1
	v_pk_fma_f32 v[200:201], v[84:85], v[188:189], v[200:201]
	v_cvt_pk_f32_fp8_e32 v[196:197], v63
	v_pk_fma_f32 v[202:203], v[86:87], v[190:191], v[202:203]
	v_cvt_pk_f32_fp8_sdwa v[198:199], v63 src0_sel:WORD_1
	v_pk_fma_f32 v[200:201], v[88:89], v[192:193], v[200:201]
	v_pk_fma_f32 v[202:203], v[90:91], v[194:195], v[202:203]
	v_pk_fma_f32 v[200:201], v[92:93], v[196:197], v[200:201]
	v_pk_fma_f32 v[202:203], v[94:95], v[198:199], v[202:203]
	v_pk_add_f32 v[200:201], v[200:201], v[202:203]
	v_add_f32_e32 v175, v200, v201
	v_readlane_b32 s25, v121, 31
	s_lshl_b32 s25, s25, 10
	v_add_u32_e32 v207, s25, v208
	global_load_dwordx4 v[60:63], v207, s[12:13]
	s_nop 1
	v_permlane32_swap_b32_e32 v168, v172
	v_permlane32_swap_b32_e32 v169, v173
	v_permlane32_swap_b32_e32 v170, v174
	v_permlane32_swap_b32_e32 v171, v175
	v_add_f32_e32 v168, v168, v172
	v_add_f32_e32 v169, v169, v173
	v_add_f32_e32 v170, v170, v174
	v_add_f32_e32 v171, v171, v175
	v_cndmask_b32_e64 v216, v170, v168, s[26:27]
	v_cndmask_b32_e64 v218, v168, v170, s[26:27]
	v_cndmask_b32_e64 v217, v171, v169, s[26:27]
	v_cndmask_b32_e64 v219, v169, v171, s[26:27]
	ds_bpermute_b32 v220, v212, v216
	ds_bpermute_b32 v221, v212, v217
	s_waitcnt lgkmcnt(0)
	v_add_f32_e32 v218, v220, v218
	v_add_f32_e32 v219, v221, v219
	v_cndmask_b32_e64 v216, v219, v218, s[28:29]
	v_cndmask_b32_e64 v217, v218, v219, s[28:29]
	s_nop 1
	v_add_f32_dpp v222, v216, v217 row_ror:8 row_mask:0xf bank_mask:0xf
	ds_bpermute_b32 v220, v213, v222
	s_waitcnt lgkmcnt(0)
	v_add_f32_e32 v222, v220, v222
	s_nop 1
	v_add_f32_dpp v223, v222, v222 quad_perm:[2,3,0,1] row_mask:0xf bank_mask:0xf
	s_nop 1
	v_add_f32_dpp v222, v223, v223 quad_perm:[1,0,3,2] row_mask:0xf bank_mask:0xf
	ds_bpermute_b32 v220, v214, v222
	s_mov_b32 s30, 0xff0000
	s_mov_b32 s31, 0x0
	s_waitcnt lgkmcnt(0)
	v_cndmask_b32_e64 v179, v179, v220, s[30:31]
	s_waitcnt vmcnt(15)
	v_cvt_pk_f32_fp8_e32 v[184:185], v0
	v_cvt_pk_f32_fp8_sdwa v[186:187], v0 src0_sel:WORD_1
	v_cvt_pk_f32_fp8_e32 v[188:189], v1
	v_cvt_pk_f32_fp8_sdwa v[190:191], v1 src0_sel:WORD_1
	v_pk_mul_f32 v[200:201], v[64:65], v[184:185]
	v_cvt_pk_f32_fp8_e32 v[192:193], v2
	v_pk_mul_f32 v[202:203], v[66:67], v[186:187]
	v_cvt_pk_f32_fp8_sdwa v[194:195], v2 src0_sel:WORD_1
	v_pk_fma_f32 v[200:201], v[68:69], v[188:189], v[200:201]
	v_cvt_pk_f32_fp8_e32 v[196:197], v3
	v_pk_fma_f32 v[202:203], v[70:71], v[190:191], v[202:203]
	v_cvt_pk_f32_fp8_sdwa v[198:199], v3 src0_sel:WORD_1
	v_pk_fma_f32 v[200:201], v[72:73], v[192:193], v[200:201]
	v_pk_fma_f32 v[202:203], v[74:75], v[194:195], v[202:203]
	v_pk_fma_f32 v[200:201], v[76:77], v[196:197], v[200:201]
	v_pk_fma_f32 v[202:203], v[78:79], v[198:199], v[202:203]
	v_pk_add_f32 v[200:201], v[200:201], v[202:203]
	v_add_f32_e32 v160, v200, v201
	v_readlane_b32 s22, v113, 32
	s_lshl_b32 s22, s22, 10
	v_add_u32_e32 v204, s22, v208
	global_load_dwordx4 v[0:3], v204, s[12:13]
	s_waitcnt vmcnt(15)
	v_cvt_pk_f32_fp8_e32 v[184:185], v4
	v_cvt_pk_f32_fp8_sdwa v[186:187], v4 src0_sel:WORD_1
	v_cvt_pk_f32_fp8_e32 v[188:189], v5
	v_cvt_pk_f32_fp8_sdwa v[190:191], v5 src0_sel:WORD_1
	v_pk_mul_f32 v[200:201], v[80:81], v[184:185]
	v_cvt_pk_f32_fp8_e32 v[192:193], v6
	v_pk_mul_f32 v[202:203], v[82:83], v[186:187]
	v_cvt_pk_f32_fp8_sdwa v[194:195], v6 src0_sel:WORD_1
	v_pk_fma_f32 v[200:201], v[84:85], v[188:189], v[200:201]
	v_cvt_pk_f32_fp8_e32 v[196:197], v7
	v_pk_fma_f32 v[202:203], v[86:87], v[190:191], v[202:203]
	v_cvt_pk_f32_fp8_sdwa v[198:199], v7 src0_sel:WORD_1
	v_pk_fma_f32 v[200:201], v[88:89], v[192:193], v[200:201]
	v_pk_fma_f32 v[202:203], v[90:91], v[194:195], v[202:203]
	v_pk_fma_f32 v[200:201], v[92:93], v[196:197], v[200:201]
	v_pk_fma_f32 v[202:203], v[94:95], v[198:199], v[202:203]
	v_pk_add_f32 v[200:201], v[200:201], v[202:203]
	v_add_f32_e32 v168, v200, v201
	v_readlane_b32 s23, v121, 32
	s_lshl_b32 s23, s23, 10
	v_add_u32_e32 v205, s23, v208
	global_load_dwordx4 v[4:7], v205, s[12:13]
	s_waitcnt vmcnt(15)
	v_cvt_pk_f32_fp8_e32 v[184:185], v8
	v_cvt_pk_f32_fp8_sdwa v[186:187], v8 src0_sel:WORD_1
	v_cvt_pk_f32_fp8_e32 v[188:189], v9
	v_cvt_pk_f32_fp8_sdwa v[190:191], v9 src0_sel:WORD_1
	v_pk_mul_f32 v[200:201], v[64:65], v[184:185]
	v_cvt_pk_f32_fp8_e32 v[192:193], v10
	v_pk_mul_f32 v[202:203], v[66:67], v[186:187]
	v_cvt_pk_f32_fp8_sdwa v[194:195], v10 src0_sel:WORD_1
	v_pk_fma_f32 v[200:201], v[68:69], v[188:189], v[200:201]
	v_cvt_pk_f32_fp8_e32 v[196:197], v11
	v_pk_fma_f32 v[202:203], v[70:71], v[190:191], v[202:203]
	v_cvt_pk_f32_fp8_sdwa v[198:199], v11 src0_sel:WORD_1
	v_pk_fma_f32 v[200:201], v[72:73], v[192:193], v[200:201]
	v_pk_fma_f32 v[202:203], v[74:75], v[194:195], v[202:203]
	v_pk_fma_f32 v[200:201], v[76:77], v[196:197], v[200:201]
	v_pk_fma_f32 v[202:203], v[78:79], v[198:199], v[202:203]
	v_pk_add_f32 v[200:201], v[200:201], v[202:203]
	v_add_f32_e32 v161, v200, v201
	v_readlane_b32 s24, v113, 33
	s_lshl_b32 s24, s24, 10
	v_add_u32_e32 v206, s24, v208
	global_load_dwordx4 v[8:11], v206, s[12:13]
	s_waitcnt vmcnt(15)
	v_cvt_pk_f32_fp8_e32 v[184:185], v12
	v_cvt_pk_f32_fp8_sdwa v[186:187], v12 src0_sel:WORD_1
	v_cvt_pk_f32_fp8_e32 v[188:189], v13
	v_cvt_pk_f32_fp8_sdwa v[190:191], v13 src0_sel:WORD_1
	v_pk_mul_f32 v[200:201], v[80:81], v[184:185]
	v_cvt_pk_f32_fp8_e32 v[192:193], v14
	v_pk_mul_f32 v[202:203], v[82:83], v[186:187]
	v_cvt_pk_f32_fp8_sdwa v[194:195], v14 src0_sel:WORD_1
	v_pk_fma_f32 v[200:201], v[84:85], v[188:189], v[200:201]
	v_cvt_pk_f32_fp8_e32 v[196:197], v15
	v_pk_fma_f32 v[202:203], v[86:87], v[190:191], v[202:203]
	v_cvt_pk_f32_fp8_sdwa v[198:199], v15 src0_sel:WORD_1
	v_pk_fma_f32 v[200:201], v[88:89], v[192:193], v[200:201]
	v_pk_fma_f32 v[202:203], v[90:91], v[194:195], v[202:203]
	v_pk_fma_f32 v[200:201], v[92:93], v[196:197], v[200:201]
	v_pk_fma_f32 v[202:203], v[94:95], v[198:199], v[202:203]
	v_pk_add_f32 v[200:201], v[200:201], v[202:203]
	v_add_f32_e32 v169, v200, v201
	v_readlane_b32 s25, v121, 33
	s_lshl_b32 s25, s25, 10
	v_add_u32_e32 v207, s25, v208
	global_load_dwordx4 v[12:15], v207, s[12:13]
	s_waitcnt vmcnt(15)
	v_cvt_pk_f32_fp8_e32 v[184:185], v16
	v_cvt_pk_f32_fp8_sdwa v[186:187], v16 src0_sel:WORD_1
	v_cvt_pk_f32_fp8_e32 v[188:189], v17
	v_cvt_pk_f32_fp8_sdwa v[190:191], v17 src0_sel:WORD_1
	v_pk_mul_f32 v[200:201], v[64:65], v[184:185]
	v_cvt_pk_f32_fp8_e32 v[192:193], v18
	v_pk_mul_f32 v[202:203], v[66:67], v[186:187]
	v_cvt_pk_f32_fp8_sdwa v[194:195], v18 src0_sel:WORD_1
	v_pk_fma_f32 v[200:201], v[68:69], v[188:189], v[200:201]
	v_cvt_pk_f32_fp8_e32 v[196:197], v19
	v_pk_fma_f32 v[202:203], v[70:71], v[190:191], v[202:203]
	v_cvt_pk_f32_fp8_sdwa v[198:199], v19 src0_sel:WORD_1
	v_pk_fma_f32 v[200:201], v[72:73], v[192:193], v[200:201]
	v_pk_fma_f32 v[202:203], v[74:75], v[194:195], v[202:203]
	v_pk_fma_f32 v[200:201], v[76:77], v[196:197], v[200:201]
	v_pk_fma_f32 v[202:203], v[78:79], v[198:199], v[202:203]
	v_pk_add_f32 v[200:201], v[200:201], v[202:203]
	v_add_f32_e32 v162, v200, v201
	v_readlane_b32 s22, v113, 34
	s_lshl_b32 s22, s22, 10
	v_add_u32_e32 v204, s22, v208
	global_load_dwordx4 v[16:19], v204, s[12:13]
	s_waitcnt vmcnt(15)
	v_cvt_pk_f32_fp8_e32 v[184:185], v20
	v_cvt_pk_f32_fp8_sdwa v[186:187], v20 src0_sel:WORD_1
	v_cvt_pk_f32_fp8_e32 v[188:189], v21
	v_cvt_pk_f32_fp8_sdwa v[190:191], v21 src0_sel:WORD_1
	v_pk_mul_f32 v[200:201], v[80:81], v[184:185]
	v_cvt_pk_f32_fp8_e32 v[192:193], v22
	v_pk_mul_f32 v[202:203], v[82:83], v[186:187]
	v_cvt_pk_f32_fp8_sdwa v[194:195], v22 src0_sel:WORD_1
	v_pk_fma_f32 v[200:201], v[84:85], v[188:189], v[200:201]
	v_cvt_pk_f32_fp8_e32 v[196:197], v23
	v_pk_fma_f32 v[202:203], v[86:87], v[190:191], v[202:203]
	v_cvt_pk_f32_fp8_sdwa v[198:199], v23 src0_sel:WORD_1
	v_pk_fma_f32 v[200:201], v[88:89], v[192:193], v[200:201]
	v_pk_fma_f32 v[202:203], v[90:91], v[194:195], v[202:203]
	v_pk_fma_f32 v[200:201], v[92:93], v[196:197], v[200:201]
	v_pk_fma_f32 v[202:203], v[94:95], v[198:199], v[202:203]
	v_pk_add_f32 v[200:201], v[200:201], v[202:203]
	v_add_f32_e32 v170, v200, v201
	v_readlane_b32 s23, v121, 34
	s_lshl_b32 s23, s23, 10
	v_add_u32_e32 v205, s23, v208
	global_load_dwordx4 v[20:23], v205, s[12:13]
	s_waitcnt vmcnt(15)
	v_cvt_pk_f32_fp8_e32 v[184:185], v24
	v_cvt_pk_f32_fp8_sdwa v[186:187], v24 src0_sel:WORD_1
	v_cvt_pk_f32_fp8_e32 v[188:189], v25
	v_cvt_pk_f32_fp8_sdwa v[190:191], v25 src0_sel:WORD_1
	v_pk_mul_f32 v[200:201], v[64:65], v[184:185]
	v_cvt_pk_f32_fp8_e32 v[192:193], v26
	v_pk_mul_f32 v[202:203], v[66:67], v[186:187]
	v_cvt_pk_f32_fp8_sdwa v[194:195], v26 src0_sel:WORD_1
	v_pk_fma_f32 v[200:201], v[68:69], v[188:189], v[200:201]
	v_cvt_pk_f32_fp8_e32 v[196:197], v27
	v_pk_fma_f32 v[202:203], v[70:71], v[190:191], v[202:203]
	v_cvt_pk_f32_fp8_sdwa v[198:199], v27 src0_sel:WORD_1
	v_pk_fma_f32 v[200:201], v[72:73], v[192:193], v[200:201]
	v_pk_fma_f32 v[202:203], v[74:75], v[194:195], v[202:203]
	v_pk_fma_f32 v[200:201], v[76:77], v[196:197], v[200:201]
	v_pk_fma_f32 v[202:203], v[78:79], v[198:199], v[202:203]
	v_pk_add_f32 v[200:201], v[200:201], v[202:203]
	v_add_f32_e32 v163, v200, v201
	v_readlane_b32 s24, v113, 35
	s_lshl_b32 s24, s24, 10
	v_add_u32_e32 v206, s24, v208
	global_load_dwordx4 v[24:27], v206, s[12:13]
	s_waitcnt vmcnt(15)
	v_cvt_pk_f32_fp8_e32 v[184:185], v28
	v_cvt_pk_f32_fp8_sdwa v[186:187], v28 src0_sel:WORD_1
	v_cvt_pk_f32_fp8_e32 v[188:189], v29
	v_cvt_pk_f32_fp8_sdwa v[190:191], v29 src0_sel:WORD_1
	v_pk_mul_f32 v[200:201], v[80:81], v[184:185]
	v_cvt_pk_f32_fp8_e32 v[192:193], v30
	v_pk_mul_f32 v[202:203], v[82:83], v[186:187]
	v_cvt_pk_f32_fp8_sdwa v[194:195], v30 src0_sel:WORD_1
	v_pk_fma_f32 v[200:201], v[84:85], v[188:189], v[200:201]
	v_cvt_pk_f32_fp8_e32 v[196:197], v31
	v_pk_fma_f32 v[202:203], v[86:87], v[190:191], v[202:203]
	v_cvt_pk_f32_fp8_sdwa v[198:199], v31 src0_sel:WORD_1
	v_pk_fma_f32 v[200:201], v[88:89], v[192:193], v[200:201]
	v_pk_fma_f32 v[202:203], v[90:91], v[194:195], v[202:203]
	v_pk_fma_f32 v[200:201], v[92:93], v[196:197], v[200:201]
	v_pk_fma_f32 v[202:203], v[94:95], v[198:199], v[202:203]
	v_pk_add_f32 v[200:201], v[200:201], v[202:203]
	v_add_f32_e32 v171, v200, v201
	v_readlane_b32 s25, v121, 35
	s_lshl_b32 s25, s25, 10
	v_add_u32_e32 v207, s25, v208
	global_load_dwordx4 v[28:31], v207, s[12:13]
	s_waitcnt vmcnt(15)
	v_cvt_pk_f32_fp8_e32 v[184:185], v32
	v_cvt_pk_f32_fp8_sdwa v[186:187], v32 src0_sel:WORD_1
	v_cvt_pk_f32_fp8_e32 v[188:189], v33
	v_cvt_pk_f32_fp8_sdwa v[190:191], v33 src0_sel:WORD_1
	v_pk_mul_f32 v[200:201], v[64:65], v[184:185]
	v_cvt_pk_f32_fp8_e32 v[192:193], v34
	v_pk_mul_f32 v[202:203], v[66:67], v[186:187]
	v_cvt_pk_f32_fp8_sdwa v[194:195], v34 src0_sel:WORD_1
	v_pk_fma_f32 v[200:201], v[68:69], v[188:189], v[200:201]
	v_cvt_pk_f32_fp8_e32 v[196:197], v35
	v_pk_fma_f32 v[202:203], v[70:71], v[190:191], v[202:203]
	v_cvt_pk_f32_fp8_sdwa v[198:199], v35 src0_sel:WORD_1
	v_pk_fma_f32 v[200:201], v[72:73], v[192:193], v[200:201]
	v_pk_fma_f32 v[202:203], v[74:75], v[194:195], v[202:203]
	v_pk_fma_f32 v[200:201], v[76:77], v[196:197], v[200:201]
	v_pk_fma_f32 v[202:203], v[78:79], v[198:199], v[202:203]
	v_pk_add_f32 v[200:201], v[200:201], v[202:203]
	v_add_f32_e32 v164, v200, v201
	v_readlane_b32 s22, v113, 36
	s_lshl_b32 s22, s22, 10
	v_add_u32_e32 v204, s22, v208
	global_load_dwordx4 v[32:35], v204, s[12:13]
	s_waitcnt vmcnt(15)
	v_cvt_pk_f32_fp8_e32 v[184:185], v36
	v_cvt_pk_f32_fp8_sdwa v[186:187], v36 src0_sel:WORD_1
	v_cvt_pk_f32_fp8_e32 v[188:189], v37
	v_cvt_pk_f32_fp8_sdwa v[190:191], v37 src0_sel:WORD_1
	v_pk_mul_f32 v[200:201], v[80:81], v[184:185]
	v_cvt_pk_f32_fp8_e32 v[192:193], v38
	v_pk_mul_f32 v[202:203], v[82:83], v[186:187]
	v_cvt_pk_f32_fp8_sdwa v[194:195], v38 src0_sel:WORD_1
	v_pk_fma_f32 v[200:201], v[84:85], v[188:189], v[200:201]
	v_cvt_pk_f32_fp8_e32 v[196:197], v39
	v_pk_fma_f32 v[202:203], v[86:87], v[190:191], v[202:203]
	v_cvt_pk_f32_fp8_sdwa v[198:199], v39 src0_sel:WORD_1
	v_pk_fma_f32 v[200:201], v[88:89], v[192:193], v[200:201]
	v_pk_fma_f32 v[202:203], v[90:91], v[194:195], v[202:203]
	v_pk_fma_f32 v[200:201], v[92:93], v[196:197], v[200:201]
	v_pk_fma_f32 v[202:203], v[94:95], v[198:199], v[202:203]
	v_pk_add_f32 v[200:201], v[200:201], v[202:203]
	v_add_f32_e32 v172, v200, v201
	v_readlane_b32 s23, v121, 36
	s_lshl_b32 s23, s23, 10
	v_add_u32_e32 v205, s23, v208
	global_load_dwordx4 v[36:39], v205, s[12:13]
	s_waitcnt vmcnt(15)
	v_cvt_pk_f32_fp8_e32 v[184:185], v40
	v_cvt_pk_f32_fp8_sdwa v[186:187], v40 src0_sel:WORD_1
	v_cvt_pk_f32_fp8_e32 v[188:189], v41
	v_cvt_pk_f32_fp8_sdwa v[190:191], v41 src0_sel:WORD_1
	v_pk_mul_f32 v[200:201], v[64:65], v[184:185]
	v_cvt_pk_f32_fp8_e32 v[192:193], v42
	v_pk_mul_f32 v[202:203], v[66:67], v[186:187]
	v_cvt_pk_f32_fp8_sdwa v[194:195], v42 src0_sel:WORD_1
	v_pk_fma_f32 v[200:201], v[68:69], v[188:189], v[200:201]
	v_cvt_pk_f32_fp8_e32 v[196:197], v43
	v_pk_fma_f32 v[202:203], v[70:71], v[190:191], v[202:203]
	v_cvt_pk_f32_fp8_sdwa v[198:199], v43 src0_sel:WORD_1
	v_pk_fma_f32 v[200:201], v[72:73], v[192:193], v[200:201]
	v_pk_fma_f32 v[202:203], v[74:75], v[194:195], v[202:203]
	v_pk_fma_f32 v[200:201], v[76:77], v[196:197], v[200:201]
	v_pk_fma_f32 v[202:203], v[78:79], v[198:199], v[202:203]
	v_pk_add_f32 v[200:201], v[200:201], v[202:203]
	v_add_f32_e32 v165, v200, v201
	v_readlane_b32 s24, v113, 37
	s_lshl_b32 s24, s24, 10
	v_add_u32_e32 v206, s24, v208
	global_load_dwordx4 v[40:43], v206, s[12:13]
	s_waitcnt vmcnt(15)
	v_cvt_pk_f32_fp8_e32 v[184:185], v44
	v_cvt_pk_f32_fp8_sdwa v[186:187], v44 src0_sel:WORD_1
	v_cvt_pk_f32_fp8_e32 v[188:189], v45
	v_cvt_pk_f32_fp8_sdwa v[190:191], v45 src0_sel:WORD_1
	v_pk_mul_f32 v[200:201], v[80:81], v[184:185]
	v_cvt_pk_f32_fp8_e32 v[192:193], v46
	v_pk_mul_f32 v[202:203], v[82:83], v[186:187]
	v_cvt_pk_f32_fp8_sdwa v[194:195], v46 src0_sel:WORD_1
	v_pk_fma_f32 v[200:201], v[84:85], v[188:189], v[200:201]
	v_cvt_pk_f32_fp8_e32 v[196:197], v47
	v_pk_fma_f32 v[202:203], v[86:87], v[190:191], v[202:203]
	v_cvt_pk_f32_fp8_sdwa v[198:199], v47 src0_sel:WORD_1
	v_pk_fma_f32 v[200:201], v[88:89], v[192:193], v[200:201]
	v_pk_fma_f32 v[202:203], v[90:91], v[194:195], v[202:203]
	v_pk_fma_f32 v[200:201], v[92:93], v[196:197], v[200:201]
	v_pk_fma_f32 v[202:203], v[94:95], v[198:199], v[202:203]
	v_pk_add_f32 v[200:201], v[200:201], v[202:203]
	v_add_f32_e32 v173, v200, v201
	v_readlane_b32 s25, v121, 37
	s_lshl_b32 s25, s25, 10
	v_add_u32_e32 v207, s25, v208
	global_load_dwordx4 v[44:47], v207, s[12:13]
	s_waitcnt vmcnt(15)
	v_cvt_pk_f32_fp8_e32 v[184:185], v48
	v_cvt_pk_f32_fp8_sdwa v[186:187], v48 src0_sel:WORD_1
	v_cvt_pk_f32_fp8_e32 v[188:189], v49
	v_cvt_pk_f32_fp8_sdwa v[190:191], v49 src0_sel:WORD_1
	v_pk_mul_f32 v[200:201], v[64:65], v[184:185]
	v_cvt_pk_f32_fp8_e32 v[192:193], v50
	v_pk_mul_f32 v[202:203], v[66:67], v[186:187]
	v_cvt_pk_f32_fp8_sdwa v[194:195], v50 src0_sel:WORD_1
	v_pk_fma_f32 v[200:201], v[68:69], v[188:189], v[200:201]
	v_cvt_pk_f32_fp8_e32 v[196:197], v51
	v_pk_fma_f32 v[202:203], v[70:71], v[190:191], v[202:203]
	v_cvt_pk_f32_fp8_sdwa v[198:199], v51 src0_sel:WORD_1
	v_pk_fma_f32 v[200:201], v[72:73], v[192:193], v[200:201]
	v_pk_fma_f32 v[202:203], v[74:75], v[194:195], v[202:203]
	v_pk_fma_f32 v[200:201], v[76:77], v[196:197], v[200:201]
	v_pk_fma_f32 v[202:203], v[78:79], v[198:199], v[202:203]
	v_pk_add_f32 v[200:201], v[200:201], v[202:203]
	v_add_f32_e32 v166, v200, v201
	v_readlane_b32 s22, v113, 38
	s_lshl_b32 s22, s22, 10
	v_add_u32_e32 v204, s22, v208
	global_load_dwordx4 v[48:51], v204, s[12:13]
	s_waitcnt vmcnt(15)
	v_cvt_pk_f32_fp8_e32 v[184:185], v52
	v_cvt_pk_f32_fp8_sdwa v[186:187], v52 src0_sel:WORD_1
	v_cvt_pk_f32_fp8_e32 v[188:189], v53
	v_cvt_pk_f32_fp8_sdwa v[190:191], v53 src0_sel:WORD_1
	v_pk_mul_f32 v[200:201], v[80:81], v[184:185]
	v_cvt_pk_f32_fp8_e32 v[192:193], v54
	v_pk_mul_f32 v[202:203], v[82:83], v[186:187]
	v_cvt_pk_f32_fp8_sdwa v[194:195], v54 src0_sel:WORD_1
	v_pk_fma_f32 v[200:201], v[84:85], v[188:189], v[200:201]
	v_cvt_pk_f32_fp8_e32 v[196:197], v55
	v_pk_fma_f32 v[202:203], v[86:87], v[190:191], v[202:203]
	v_cvt_pk_f32_fp8_sdwa v[198:199], v55 src0_sel:WORD_1
	v_pk_fma_f32 v[200:201], v[88:89], v[192:193], v[200:201]
	v_pk_fma_f32 v[202:203], v[90:91], v[194:195], v[202:203]
	v_pk_fma_f32 v[200:201], v[92:93], v[196:197], v[200:201]
	v_pk_fma_f32 v[202:203], v[94:95], v[198:199], v[202:203]
	v_pk_add_f32 v[200:201], v[200:201], v[202:203]
	v_add_f32_e32 v174, v200, v201
	v_readlane_b32 s23, v121, 38
	s_lshl_b32 s23, s23, 10
	v_add_u32_e32 v205, s23, v208
	global_load_dwordx4 v[52:55], v205, s[12:13]
	s_waitcnt vmcnt(15)
	v_cvt_pk_f32_fp8_e32 v[184:185], v56
	v_cvt_pk_f32_fp8_sdwa v[186:187], v56 src0_sel:WORD_1
	v_cvt_pk_f32_fp8_e32 v[188:189], v57
	v_cvt_pk_f32_fp8_sdwa v[190:191], v57 src0_sel:WORD_1
	v_pk_mul_f32 v[200:201], v[64:65], v[184:185]
	v_cvt_pk_f32_fp8_e32 v[192:193], v58
	v_pk_mul_f32 v[202:203], v[66:67], v[186:187]
	v_cvt_pk_f32_fp8_sdwa v[194:195], v58 src0_sel:WORD_1
	v_pk_fma_f32 v[200:201], v[68:69], v[188:189], v[200:201]
	v_cvt_pk_f32_fp8_e32 v[196:197], v59
	v_pk_fma_f32 v[202:203], v[70:71], v[190:191], v[202:203]
	v_cvt_pk_f32_fp8_sdwa v[198:199], v59 src0_sel:WORD_1
	v_pk_fma_f32 v[200:201], v[72:73], v[192:193], v[200:201]
	v_pk_fma_f32 v[202:203], v[74:75], v[194:195], v[202:203]
	v_pk_fma_f32 v[200:201], v[76:77], v[196:197], v[200:201]
	v_pk_fma_f32 v[202:203], v[78:79], v[198:199], v[202:203]
	v_pk_add_f32 v[200:201], v[200:201], v[202:203]
	v_add_f32_e32 v167, v200, v201
	v_readlane_b32 s24, v113, 39
	s_lshl_b32 s24, s24, 10
	v_add_u32_e32 v206, s24, v208
	global_load_dwordx4 v[56:59], v206, s[12:13]
	s_nop 1
	v_permlane32_swap_b32_e32 v160, v164
	v_permlane32_swap_b32_e32 v161, v165
	v_permlane32_swap_b32_e32 v162, v166
	v_permlane32_swap_b32_e32 v163, v167
	v_add_f32_e32 v160, v160, v164
	v_add_f32_e32 v161, v161, v165
	v_add_f32_e32 v162, v162, v166
	v_add_f32_e32 v163, v163, v167
	v_cndmask_b32_e64 v216, v162, v160, s[26:27]
	v_cndmask_b32_e64 v218, v160, v162, s[26:27]
	v_cndmask_b32_e64 v217, v163, v161, s[26:27]
	v_cndmask_b32_e64 v219, v161, v163, s[26:27]
	ds_bpermute_b32 v220, v212, v216
	ds_bpermute_b32 v221, v212, v217
	s_waitcnt lgkmcnt(0)
	v_add_f32_e32 v218, v220, v218
	v_add_f32_e32 v219, v221, v219
	v_cndmask_b32_e64 v216, v219, v218, s[28:29]
	v_cndmask_b32_e64 v217, v218, v219, s[28:29]
	s_nop 1
	v_add_f32_dpp v222, v216, v217 row_ror:8 row_mask:0xf bank_mask:0xf
	ds_bpermute_b32 v220, v213, v222
	s_waitcnt lgkmcnt(0)
	v_add_f32_e32 v222, v220, v222
	s_nop 1
	v_add_f32_dpp v223, v222, v222 quad_perm:[2,3,0,1] row_mask:0xf bank_mask:0xf
	s_nop 1
	v_add_f32_dpp v222, v223, v223 quad_perm:[1,0,3,2] row_mask:0xf bank_mask:0xf
	ds_bpermute_b32 v220, v214, v222
	s_mov_b32 s30, 0xff000000
	s_mov_b32 s31, 0x0
	s_waitcnt lgkmcnt(0)
	v_cndmask_b32_e64 v176, v176, v220, s[30:31]
	s_waitcnt vmcnt(15)
	v_cvt_pk_f32_fp8_e32 v[184:185], v60
	v_cvt_pk_f32_fp8_sdwa v[186:187], v60 src0_sel:WORD_1
	v_cvt_pk_f32_fp8_e32 v[188:189], v61
	v_cvt_pk_f32_fp8_sdwa v[190:191], v61 src0_sel:WORD_1
	v_pk_mul_f32 v[200:201], v[80:81], v[184:185]
	v_cvt_pk_f32_fp8_e32 v[192:193], v62
	v_pk_mul_f32 v[202:203], v[82:83], v[186:187]
	v_cvt_pk_f32_fp8_sdwa v[194:195], v62 src0_sel:WORD_1
	v_pk_fma_f32 v[200:201], v[84:85], v[188:189], v[200:201]
	v_cvt_pk_f32_fp8_e32 v[196:197], v63
	v_pk_fma_f32 v[202:203], v[86:87], v[190:191], v[202:203]
	v_cvt_pk_f32_fp8_sdwa v[198:199], v63 src0_sel:WORD_1
	v_pk_fma_f32 v[200:201], v[88:89], v[192:193], v[200:201]
	v_pk_fma_f32 v[202:203], v[90:91], v[194:195], v[202:203]
	v_pk_fma_f32 v[200:201], v[92:93], v[196:197], v[200:201]
	v_pk_fma_f32 v[202:203], v[94:95], v[198:199], v[202:203]
	v_pk_add_f32 v[200:201], v[200:201], v[202:203]
	v_add_f32_e32 v175, v200, v201
	v_readlane_b32 s25, v121, 39
	s_lshl_b32 s25, s25, 10
	v_add_u32_e32 v207, s25, v208
	global_load_dwordx4 v[60:63], v207, s[12:13]
	s_nop 1
	v_permlane32_swap_b32_e32 v168, v172
	v_permlane32_swap_b32_e32 v169, v173
	v_permlane32_swap_b32_e32 v170, v174
	v_permlane32_swap_b32_e32 v171, v175
	v_add_f32_e32 v168, v168, v172
	v_add_f32_e32 v169, v169, v173
	v_add_f32_e32 v170, v170, v174
	v_add_f32_e32 v171, v171, v175
	v_cndmask_b32_e64 v216, v170, v168, s[26:27]
	v_cndmask_b32_e64 v218, v168, v170, s[26:27]
	v_cndmask_b32_e64 v217, v171, v169, s[26:27]
	v_cndmask_b32_e64 v219, v169, v171, s[26:27]
	ds_bpermute_b32 v220, v212, v216
	ds_bpermute_b32 v221, v212, v217
	s_waitcnt lgkmcnt(0)
	v_add_f32_e32 v218, v220, v218
	v_add_f32_e32 v219, v221, v219
	v_cndmask_b32_e64 v216, v219, v218, s[28:29]
	v_cndmask_b32_e64 v217, v218, v219, s[28:29]
	s_nop 1
	v_add_f32_dpp v222, v216, v217 row_ror:8 row_mask:0xf bank_mask:0xf
	ds_bpermute_b32 v220, v213, v222
	s_waitcnt lgkmcnt(0)
	v_add_f32_e32 v222, v220, v222
	s_nop 1
	v_add_f32_dpp v223, v222, v222 quad_perm:[2,3,0,1] row_mask:0xf bank_mask:0xf
	s_nop 1
	v_add_f32_dpp v222, v223, v223 quad_perm:[1,0,3,2] row_mask:0xf bank_mask:0xf
	ds_bpermute_b32 v220, v214, v222
	s_mov_b32 s30, 0xff000000
	s_mov_b32 s31, 0x0
	s_waitcnt lgkmcnt(0)
	v_cndmask_b32_e64 v179, v179, v220, s[30:31]
	s_waitcnt vmcnt(15)
	v_cvt_pk_f32_fp8_e32 v[184:185], v0
	v_cvt_pk_f32_fp8_sdwa v[186:187], v0 src0_sel:WORD_1
	v_cvt_pk_f32_fp8_e32 v[188:189], v1
	v_cvt_pk_f32_fp8_sdwa v[190:191], v1 src0_sel:WORD_1
	v_pk_mul_f32 v[200:201], v[64:65], v[184:185]
	v_cvt_pk_f32_fp8_e32 v[192:193], v2
	v_pk_mul_f32 v[202:203], v[66:67], v[186:187]
	v_cvt_pk_f32_fp8_sdwa v[194:195], v2 src0_sel:WORD_1
	v_pk_fma_f32 v[200:201], v[68:69], v[188:189], v[200:201]
	v_cvt_pk_f32_fp8_e32 v[196:197], v3
	v_pk_fma_f32 v[202:203], v[70:71], v[190:191], v[202:203]
	v_cvt_pk_f32_fp8_sdwa v[198:199], v3 src0_sel:WORD_1
	v_pk_fma_f32 v[200:201], v[72:73], v[192:193], v[200:201]
	v_pk_fma_f32 v[202:203], v[74:75], v[194:195], v[202:203]
	v_pk_fma_f32 v[200:201], v[76:77], v[196:197], v[200:201]
	v_pk_fma_f32 v[202:203], v[78:79], v[198:199], v[202:203]
	v_pk_add_f32 v[200:201], v[200:201], v[202:203]
	v_add_f32_e32 v160, v200, v201
	v_readlane_b32 s22, v113, 40
	s_lshl_b32 s22, s22, 10
	v_add_u32_e32 v204, s22, v208
	global_load_dwordx4 v[0:3], v204, s[12:13]
	s_waitcnt vmcnt(15)
	v_cvt_pk_f32_fp8_e32 v[184:185], v4
	v_cvt_pk_f32_fp8_sdwa v[186:187], v4 src0_sel:WORD_1
	v_cvt_pk_f32_fp8_e32 v[188:189], v5
	v_cvt_pk_f32_fp8_sdwa v[190:191], v5 src0_sel:WORD_1
	v_pk_mul_f32 v[200:201], v[80:81], v[184:185]
	v_cvt_pk_f32_fp8_e32 v[192:193], v6
	v_pk_mul_f32 v[202:203], v[82:83], v[186:187]
	v_cvt_pk_f32_fp8_sdwa v[194:195], v6 src0_sel:WORD_1
	v_pk_fma_f32 v[200:201], v[84:85], v[188:189], v[200:201]
	v_cvt_pk_f32_fp8_e32 v[196:197], v7
	v_pk_fma_f32 v[202:203], v[86:87], v[190:191], v[202:203]
	v_cvt_pk_f32_fp8_sdwa v[198:199], v7 src0_sel:WORD_1
	v_pk_fma_f32 v[200:201], v[88:89], v[192:193], v[200:201]
	v_pk_fma_f32 v[202:203], v[90:91], v[194:195], v[202:203]
	v_pk_fma_f32 v[200:201], v[92:93], v[196:197], v[200:201]
	v_pk_fma_f32 v[202:203], v[94:95], v[198:199], v[202:203]
	v_pk_add_f32 v[200:201], v[200:201], v[202:203]
	v_add_f32_e32 v168, v200, v201
	v_readlane_b32 s23, v121, 40
	s_lshl_b32 s23, s23, 10
	v_add_u32_e32 v205, s23, v208
	global_load_dwordx4 v[4:7], v205, s[12:13]
	s_waitcnt vmcnt(15)
	v_cvt_pk_f32_fp8_e32 v[184:185], v8
	v_cvt_pk_f32_fp8_sdwa v[186:187], v8 src0_sel:WORD_1
	v_cvt_pk_f32_fp8_e32 v[188:189], v9
	v_cvt_pk_f32_fp8_sdwa v[190:191], v9 src0_sel:WORD_1
	v_pk_mul_f32 v[200:201], v[64:65], v[184:185]
	v_cvt_pk_f32_fp8_e32 v[192:193], v10
	v_pk_mul_f32 v[202:203], v[66:67], v[186:187]
	v_cvt_pk_f32_fp8_sdwa v[194:195], v10 src0_sel:WORD_1
	v_pk_fma_f32 v[200:201], v[68:69], v[188:189], v[200:201]
	v_cvt_pk_f32_fp8_e32 v[196:197], v11
	v_pk_fma_f32 v[202:203], v[70:71], v[190:191], v[202:203]
	v_cvt_pk_f32_fp8_sdwa v[198:199], v11 src0_sel:WORD_1
	v_pk_fma_f32 v[200:201], v[72:73], v[192:193], v[200:201]
	v_pk_fma_f32 v[202:203], v[74:75], v[194:195], v[202:203]
	v_pk_fma_f32 v[200:201], v[76:77], v[196:197], v[200:201]
	v_pk_fma_f32 v[202:203], v[78:79], v[198:199], v[202:203]
	v_pk_add_f32 v[200:201], v[200:201], v[202:203]
	v_add_f32_e32 v161, v200, v201
	v_readlane_b32 s24, v113, 41
	s_lshl_b32 s24, s24, 10
	v_add_u32_e32 v206, s24, v208
	global_load_dwordx4 v[8:11], v206, s[12:13]
	s_waitcnt vmcnt(15)
	v_cvt_pk_f32_fp8_e32 v[184:185], v12
	v_cvt_pk_f32_fp8_sdwa v[186:187], v12 src0_sel:WORD_1
	v_cvt_pk_f32_fp8_e32 v[188:189], v13
	v_cvt_pk_f32_fp8_sdwa v[190:191], v13 src0_sel:WORD_1
	v_pk_mul_f32 v[200:201], v[80:81], v[184:185]
	v_cvt_pk_f32_fp8_e32 v[192:193], v14
	v_pk_mul_f32 v[202:203], v[82:83], v[186:187]
	v_cvt_pk_f32_fp8_sdwa v[194:195], v14 src0_sel:WORD_1
	v_pk_fma_f32 v[200:201], v[84:85], v[188:189], v[200:201]
	v_cvt_pk_f32_fp8_e32 v[196:197], v15
	v_pk_fma_f32 v[202:203], v[86:87], v[190:191], v[202:203]
	v_cvt_pk_f32_fp8_sdwa v[198:199], v15 src0_sel:WORD_1
	v_pk_fma_f32 v[200:201], v[88:89], v[192:193], v[200:201]
	v_pk_fma_f32 v[202:203], v[90:91], v[194:195], v[202:203]
	v_pk_fma_f32 v[200:201], v[92:93], v[196:197], v[200:201]
	v_pk_fma_f32 v[202:203], v[94:95], v[198:199], v[202:203]
	v_pk_add_f32 v[200:201], v[200:201], v[202:203]
	v_add_f32_e32 v169, v200, v201
	v_readlane_b32 s25, v121, 41
	s_lshl_b32 s25, s25, 10
	v_add_u32_e32 v207, s25, v208
	global_load_dwordx4 v[12:15], v207, s[12:13]
	s_waitcnt vmcnt(15)
	v_cvt_pk_f32_fp8_e32 v[184:185], v16
	v_cvt_pk_f32_fp8_sdwa v[186:187], v16 src0_sel:WORD_1
	v_cvt_pk_f32_fp8_e32 v[188:189], v17
	v_cvt_pk_f32_fp8_sdwa v[190:191], v17 src0_sel:WORD_1
	v_pk_mul_f32 v[200:201], v[64:65], v[184:185]
	v_cvt_pk_f32_fp8_e32 v[192:193], v18
	v_pk_mul_f32 v[202:203], v[66:67], v[186:187]
	v_cvt_pk_f32_fp8_sdwa v[194:195], v18 src0_sel:WORD_1
	v_pk_fma_f32 v[200:201], v[68:69], v[188:189], v[200:201]
	v_cvt_pk_f32_fp8_e32 v[196:197], v19
	v_pk_fma_f32 v[202:203], v[70:71], v[190:191], v[202:203]
	v_cvt_pk_f32_fp8_sdwa v[198:199], v19 src0_sel:WORD_1
	v_pk_fma_f32 v[200:201], v[72:73], v[192:193], v[200:201]
	v_pk_fma_f32 v[202:203], v[74:75], v[194:195], v[202:203]
	v_pk_fma_f32 v[200:201], v[76:77], v[196:197], v[200:201]
	v_pk_fma_f32 v[202:203], v[78:79], v[198:199], v[202:203]
	v_pk_add_f32 v[200:201], v[200:201], v[202:203]
	v_add_f32_e32 v162, v200, v201
	v_readlane_b32 s22, v113, 42
	s_lshl_b32 s22, s22, 10
	v_add_u32_e32 v204, s22, v208
	global_load_dwordx4 v[16:19], v204, s[12:13]
	s_waitcnt vmcnt(15)
	v_cvt_pk_f32_fp8_e32 v[184:185], v20
	v_cvt_pk_f32_fp8_sdwa v[186:187], v20 src0_sel:WORD_1
	v_cvt_pk_f32_fp8_e32 v[188:189], v21
	v_cvt_pk_f32_fp8_sdwa v[190:191], v21 src0_sel:WORD_1
	v_pk_mul_f32 v[200:201], v[80:81], v[184:185]
	v_cvt_pk_f32_fp8_e32 v[192:193], v22
	v_pk_mul_f32 v[202:203], v[82:83], v[186:187]
	v_cvt_pk_f32_fp8_sdwa v[194:195], v22 src0_sel:WORD_1
	v_pk_fma_f32 v[200:201], v[84:85], v[188:189], v[200:201]
	v_cvt_pk_f32_fp8_e32 v[196:197], v23
	v_pk_fma_f32 v[202:203], v[86:87], v[190:191], v[202:203]
	v_cvt_pk_f32_fp8_sdwa v[198:199], v23 src0_sel:WORD_1
	v_pk_fma_f32 v[200:201], v[88:89], v[192:193], v[200:201]
	v_pk_fma_f32 v[202:203], v[90:91], v[194:195], v[202:203]
	v_pk_fma_f32 v[200:201], v[92:93], v[196:197], v[200:201]
	v_pk_fma_f32 v[202:203], v[94:95], v[198:199], v[202:203]
	v_pk_add_f32 v[200:201], v[200:201], v[202:203]
	v_add_f32_e32 v170, v200, v201
	v_readlane_b32 s23, v121, 42
	s_lshl_b32 s23, s23, 10
	v_add_u32_e32 v205, s23, v208
	global_load_dwordx4 v[20:23], v205, s[12:13]
	s_waitcnt vmcnt(15)
	v_cvt_pk_f32_fp8_e32 v[184:185], v24
	v_cvt_pk_f32_fp8_sdwa v[186:187], v24 src0_sel:WORD_1
	v_cvt_pk_f32_fp8_e32 v[188:189], v25
	v_cvt_pk_f32_fp8_sdwa v[190:191], v25 src0_sel:WORD_1
	v_pk_mul_f32 v[200:201], v[64:65], v[184:185]
	v_cvt_pk_f32_fp8_e32 v[192:193], v26
	v_pk_mul_f32 v[202:203], v[66:67], v[186:187]
	v_cvt_pk_f32_fp8_sdwa v[194:195], v26 src0_sel:WORD_1
	v_pk_fma_f32 v[200:201], v[68:69], v[188:189], v[200:201]
	v_cvt_pk_f32_fp8_e32 v[196:197], v27
	v_pk_fma_f32 v[202:203], v[70:71], v[190:191], v[202:203]
	v_cvt_pk_f32_fp8_sdwa v[198:199], v27 src0_sel:WORD_1
	v_pk_fma_f32 v[200:201], v[72:73], v[192:193], v[200:201]
	v_pk_fma_f32 v[202:203], v[74:75], v[194:195], v[202:203]
	v_pk_fma_f32 v[200:201], v[76:77], v[196:197], v[200:201]
	v_pk_fma_f32 v[202:203], v[78:79], v[198:199], v[202:203]
	v_pk_add_f32 v[200:201], v[200:201], v[202:203]
	v_add_f32_e32 v163, v200, v201
	v_readlane_b32 s24, v113, 43
	s_lshl_b32 s24, s24, 10
	v_add_u32_e32 v206, s24, v208
	global_load_dwordx4 v[24:27], v206, s[12:13]
	s_waitcnt vmcnt(15)
	v_cvt_pk_f32_fp8_e32 v[184:185], v28
	v_cvt_pk_f32_fp8_sdwa v[186:187], v28 src0_sel:WORD_1
	v_cvt_pk_f32_fp8_e32 v[188:189], v29
	v_cvt_pk_f32_fp8_sdwa v[190:191], v29 src0_sel:WORD_1
	v_pk_mul_f32 v[200:201], v[80:81], v[184:185]
	v_cvt_pk_f32_fp8_e32 v[192:193], v30
	v_pk_mul_f32 v[202:203], v[82:83], v[186:187]
	v_cvt_pk_f32_fp8_sdwa v[194:195], v30 src0_sel:WORD_1
	v_pk_fma_f32 v[200:201], v[84:85], v[188:189], v[200:201]
	v_cvt_pk_f32_fp8_e32 v[196:197], v31
	v_pk_fma_f32 v[202:203], v[86:87], v[190:191], v[202:203]
	v_cvt_pk_f32_fp8_sdwa v[198:199], v31 src0_sel:WORD_1
	v_pk_fma_f32 v[200:201], v[88:89], v[192:193], v[200:201]
	v_pk_fma_f32 v[202:203], v[90:91], v[194:195], v[202:203]
	v_pk_fma_f32 v[200:201], v[92:93], v[196:197], v[200:201]
	v_pk_fma_f32 v[202:203], v[94:95], v[198:199], v[202:203]
	v_pk_add_f32 v[200:201], v[200:201], v[202:203]
	v_add_f32_e32 v171, v200, v201
	v_readlane_b32 s25, v121, 43
	s_lshl_b32 s25, s25, 10
	v_add_u32_e32 v207, s25, v208
	global_load_dwordx4 v[28:31], v207, s[12:13]
	s_waitcnt vmcnt(15)
	v_cvt_pk_f32_fp8_e32 v[184:185], v32
	v_cvt_pk_f32_fp8_sdwa v[186:187], v32 src0_sel:WORD_1
	v_cvt_pk_f32_fp8_e32 v[188:189], v33
	v_cvt_pk_f32_fp8_sdwa v[190:191], v33 src0_sel:WORD_1
	v_pk_mul_f32 v[200:201], v[64:65], v[184:185]
	v_cvt_pk_f32_fp8_e32 v[192:193], v34
	v_pk_mul_f32 v[202:203], v[66:67], v[186:187]
	v_cvt_pk_f32_fp8_sdwa v[194:195], v34 src0_sel:WORD_1
	v_pk_fma_f32 v[200:201], v[68:69], v[188:189], v[200:201]
	v_cvt_pk_f32_fp8_e32 v[196:197], v35
	v_pk_fma_f32 v[202:203], v[70:71], v[190:191], v[202:203]
	v_cvt_pk_f32_fp8_sdwa v[198:199], v35 src0_sel:WORD_1
	v_pk_fma_f32 v[200:201], v[72:73], v[192:193], v[200:201]
	v_pk_fma_f32 v[202:203], v[74:75], v[194:195], v[202:203]
	v_pk_fma_f32 v[200:201], v[76:77], v[196:197], v[200:201]
	v_pk_fma_f32 v[202:203], v[78:79], v[198:199], v[202:203]
	v_pk_add_f32 v[200:201], v[200:201], v[202:203]
	v_add_f32_e32 v164, v200, v201
	v_readlane_b32 s22, v113, 44
	s_lshl_b32 s22, s22, 10
	v_add_u32_e32 v204, s22, v208
	global_load_dwordx4 v[32:35], v204, s[12:13]
	s_waitcnt vmcnt(15)
	v_cvt_pk_f32_fp8_e32 v[184:185], v36
	v_cvt_pk_f32_fp8_sdwa v[186:187], v36 src0_sel:WORD_1
	v_cvt_pk_f32_fp8_e32 v[188:189], v37
	v_cvt_pk_f32_fp8_sdwa v[190:191], v37 src0_sel:WORD_1
	v_pk_mul_f32 v[200:201], v[80:81], v[184:185]
	v_cvt_pk_f32_fp8_e32 v[192:193], v38
	v_pk_mul_f32 v[202:203], v[82:83], v[186:187]
	v_cvt_pk_f32_fp8_sdwa v[194:195], v38 src0_sel:WORD_1
	v_pk_fma_f32 v[200:201], v[84:85], v[188:189], v[200:201]
	v_cvt_pk_f32_fp8_e32 v[196:197], v39
	v_pk_fma_f32 v[202:203], v[86:87], v[190:191], v[202:203]
	v_cvt_pk_f32_fp8_sdwa v[198:199], v39 src0_sel:WORD_1
	v_pk_fma_f32 v[200:201], v[88:89], v[192:193], v[200:201]
	v_pk_fma_f32 v[202:203], v[90:91], v[194:195], v[202:203]
	v_pk_fma_f32 v[200:201], v[92:93], v[196:197], v[200:201]
	v_pk_fma_f32 v[202:203], v[94:95], v[198:199], v[202:203]
	v_pk_add_f32 v[200:201], v[200:201], v[202:203]
	v_add_f32_e32 v172, v200, v201
	v_readlane_b32 s23, v121, 44
	s_lshl_b32 s23, s23, 10
	v_add_u32_e32 v205, s23, v208
	global_load_dwordx4 v[36:39], v205, s[12:13]
	s_waitcnt vmcnt(15)
	v_cvt_pk_f32_fp8_e32 v[184:185], v40
	v_cvt_pk_f32_fp8_sdwa v[186:187], v40 src0_sel:WORD_1
	v_cvt_pk_f32_fp8_e32 v[188:189], v41
	v_cvt_pk_f32_fp8_sdwa v[190:191], v41 src0_sel:WORD_1
	v_pk_mul_f32 v[200:201], v[64:65], v[184:185]
	v_cvt_pk_f32_fp8_e32 v[192:193], v42
	v_pk_mul_f32 v[202:203], v[66:67], v[186:187]
	v_cvt_pk_f32_fp8_sdwa v[194:195], v42 src0_sel:WORD_1
	v_pk_fma_f32 v[200:201], v[68:69], v[188:189], v[200:201]
	v_cvt_pk_f32_fp8_e32 v[196:197], v43
	v_pk_fma_f32 v[202:203], v[70:71], v[190:191], v[202:203]
	v_cvt_pk_f32_fp8_sdwa v[198:199], v43 src0_sel:WORD_1
	v_pk_fma_f32 v[200:201], v[72:73], v[192:193], v[200:201]
	v_pk_fma_f32 v[202:203], v[74:75], v[194:195], v[202:203]
	v_pk_fma_f32 v[200:201], v[76:77], v[196:197], v[200:201]
	v_pk_fma_f32 v[202:203], v[78:79], v[198:199], v[202:203]
	v_pk_add_f32 v[200:201], v[200:201], v[202:203]
	v_add_f32_e32 v165, v200, v201
	v_readlane_b32 s24, v113, 45
	s_lshl_b32 s24, s24, 10
	v_add_u32_e32 v206, s24, v208
	global_load_dwordx4 v[40:43], v206, s[12:13]
	s_waitcnt vmcnt(15)
	v_cvt_pk_f32_fp8_e32 v[184:185], v44
	v_cvt_pk_f32_fp8_sdwa v[186:187], v44 src0_sel:WORD_1
	v_cvt_pk_f32_fp8_e32 v[188:189], v45
	v_cvt_pk_f32_fp8_sdwa v[190:191], v45 src0_sel:WORD_1
	v_pk_mul_f32 v[200:201], v[80:81], v[184:185]
	v_cvt_pk_f32_fp8_e32 v[192:193], v46
	v_pk_mul_f32 v[202:203], v[82:83], v[186:187]
	v_cvt_pk_f32_fp8_sdwa v[194:195], v46 src0_sel:WORD_1
	v_pk_fma_f32 v[200:201], v[84:85], v[188:189], v[200:201]
	v_cvt_pk_f32_fp8_e32 v[196:197], v47
	v_pk_fma_f32 v[202:203], v[86:87], v[190:191], v[202:203]
	v_cvt_pk_f32_fp8_sdwa v[198:199], v47 src0_sel:WORD_1
	v_pk_fma_f32 v[200:201], v[88:89], v[192:193], v[200:201]
	v_pk_fma_f32 v[202:203], v[90:91], v[194:195], v[202:203]
	v_pk_fma_f32 v[200:201], v[92:93], v[196:197], v[200:201]
	v_pk_fma_f32 v[202:203], v[94:95], v[198:199], v[202:203]
	v_pk_add_f32 v[200:201], v[200:201], v[202:203]
	v_add_f32_e32 v173, v200, v201
	v_readlane_b32 s25, v121, 45
	s_lshl_b32 s25, s25, 10
	v_add_u32_e32 v207, s25, v208
	global_load_dwordx4 v[44:47], v207, s[12:13]
	s_waitcnt vmcnt(15)
	v_cvt_pk_f32_fp8_e32 v[184:185], v48
	v_cvt_pk_f32_fp8_sdwa v[186:187], v48 src0_sel:WORD_1
	v_cvt_pk_f32_fp8_e32 v[188:189], v49
	v_cvt_pk_f32_fp8_sdwa v[190:191], v49 src0_sel:WORD_1
	v_pk_mul_f32 v[200:201], v[64:65], v[184:185]
	v_cvt_pk_f32_fp8_e32 v[192:193], v50
	v_pk_mul_f32 v[202:203], v[66:67], v[186:187]
	v_cvt_pk_f32_fp8_sdwa v[194:195], v50 src0_sel:WORD_1
	v_pk_fma_f32 v[200:201], v[68:69], v[188:189], v[200:201]
	v_cvt_pk_f32_fp8_e32 v[196:197], v51
	v_pk_fma_f32 v[202:203], v[70:71], v[190:191], v[202:203]
	v_cvt_pk_f32_fp8_sdwa v[198:199], v51 src0_sel:WORD_1
	v_pk_fma_f32 v[200:201], v[72:73], v[192:193], v[200:201]
	v_pk_fma_f32 v[202:203], v[74:75], v[194:195], v[202:203]
	v_pk_fma_f32 v[200:201], v[76:77], v[196:197], v[200:201]
	v_pk_fma_f32 v[202:203], v[78:79], v[198:199], v[202:203]
	v_pk_add_f32 v[200:201], v[200:201], v[202:203]
	v_add_f32_e32 v166, v200, v201
	v_readlane_b32 s22, v113, 46
	s_lshl_b32 s22, s22, 10
	v_add_u32_e32 v204, s22, v208
	global_load_dwordx4 v[48:51], v204, s[12:13]
	s_waitcnt vmcnt(15)
	v_cvt_pk_f32_fp8_e32 v[184:185], v52
	v_cvt_pk_f32_fp8_sdwa v[186:187], v52 src0_sel:WORD_1
	v_cvt_pk_f32_fp8_e32 v[188:189], v53
	v_cvt_pk_f32_fp8_sdwa v[190:191], v53 src0_sel:WORD_1
	v_pk_mul_f32 v[200:201], v[80:81], v[184:185]
	v_cvt_pk_f32_fp8_e32 v[192:193], v54
	v_pk_mul_f32 v[202:203], v[82:83], v[186:187]
	v_cvt_pk_f32_fp8_sdwa v[194:195], v54 src0_sel:WORD_1
	v_pk_fma_f32 v[200:201], v[84:85], v[188:189], v[200:201]
	v_cvt_pk_f32_fp8_e32 v[196:197], v55
	v_pk_fma_f32 v[202:203], v[86:87], v[190:191], v[202:203]
	v_cvt_pk_f32_fp8_sdwa v[198:199], v55 src0_sel:WORD_1
	v_pk_fma_f32 v[200:201], v[88:89], v[192:193], v[200:201]
	v_pk_fma_f32 v[202:203], v[90:91], v[194:195], v[202:203]
	v_pk_fma_f32 v[200:201], v[92:93], v[196:197], v[200:201]
	v_pk_fma_f32 v[202:203], v[94:95], v[198:199], v[202:203]
	v_pk_add_f32 v[200:201], v[200:201], v[202:203]
	v_add_f32_e32 v174, v200, v201
	v_readlane_b32 s23, v121, 46
	s_lshl_b32 s23, s23, 10
	v_add_u32_e32 v205, s23, v208
	global_load_dwordx4 v[52:55], v205, s[12:13]
	s_waitcnt vmcnt(15)
	v_cvt_pk_f32_fp8_e32 v[184:185], v56
	v_cvt_pk_f32_fp8_sdwa v[186:187], v56 src0_sel:WORD_1
	v_cvt_pk_f32_fp8_e32 v[188:189], v57
	v_cvt_pk_f32_fp8_sdwa v[190:191], v57 src0_sel:WORD_1
	v_pk_mul_f32 v[200:201], v[64:65], v[184:185]
	v_cvt_pk_f32_fp8_e32 v[192:193], v58
	v_pk_mul_f32 v[202:203], v[66:67], v[186:187]
	v_cvt_pk_f32_fp8_sdwa v[194:195], v58 src0_sel:WORD_1
	v_pk_fma_f32 v[200:201], v[68:69], v[188:189], v[200:201]
	v_cvt_pk_f32_fp8_e32 v[196:197], v59
	v_pk_fma_f32 v[202:203], v[70:71], v[190:191], v[202:203]
	v_cvt_pk_f32_fp8_sdwa v[198:199], v59 src0_sel:WORD_1
	v_pk_fma_f32 v[200:201], v[72:73], v[192:193], v[200:201]
	v_pk_fma_f32 v[202:203], v[74:75], v[194:195], v[202:203]
	v_pk_fma_f32 v[200:201], v[76:77], v[196:197], v[200:201]
	v_pk_fma_f32 v[202:203], v[78:79], v[198:199], v[202:203]
	v_pk_add_f32 v[200:201], v[200:201], v[202:203]
	v_add_f32_e32 v167, v200, v201
	v_readlane_b32 s24, v113, 47
	s_lshl_b32 s24, s24, 10
	v_add_u32_e32 v206, s24, v208
	global_load_dwordx4 v[56:59], v206, s[12:13]
	s_nop 1
	v_permlane32_swap_b32_e32 v160, v164
	v_permlane32_swap_b32_e32 v161, v165
	v_permlane32_swap_b32_e32 v162, v166
	v_permlane32_swap_b32_e32 v163, v167
	v_add_f32_e32 v160, v160, v164
	v_add_f32_e32 v161, v161, v165
	v_add_f32_e32 v162, v162, v166
	v_add_f32_e32 v163, v163, v167
	v_cndmask_b32_e64 v216, v162, v160, s[26:27]
	v_cndmask_b32_e64 v218, v160, v162, s[26:27]
	v_cndmask_b32_e64 v217, v163, v161, s[26:27]
	v_cndmask_b32_e64 v219, v161, v163, s[26:27]
	ds_bpermute_b32 v220, v212, v216
	ds_bpermute_b32 v221, v212, v217
	s_waitcnt lgkmcnt(0)
	v_add_f32_e32 v218, v220, v218
	v_add_f32_e32 v219, v221, v219
	v_cndmask_b32_e64 v216, v219, v218, s[28:29]
	v_cndmask_b32_e64 v217, v218, v219, s[28:29]
	s_nop 1
	v_add_f32_dpp v222, v216, v217 row_ror:8 row_mask:0xf bank_mask:0xf
	ds_bpermute_b32 v220, v213, v222
	s_waitcnt lgkmcnt(0)
	v_add_f32_e32 v222, v220, v222
	s_nop 1
	v_add_f32_dpp v223, v222, v222 quad_perm:[2,3,0,1] row_mask:0xf bank_mask:0xf
	s_nop 1
	v_add_f32_dpp v222, v223, v223 quad_perm:[1,0,3,2] row_mask:0xf bank_mask:0xf
	ds_bpermute_b32 v220, v214, v222
	s_mov_b32 s30, 0x0
	s_mov_b32 s31, 0xff
	s_waitcnt lgkmcnt(0)
	v_cndmask_b32_e64 v176, v176, v220, s[30:31]
	s_waitcnt vmcnt(15)
	v_cvt_pk_f32_fp8_e32 v[184:185], v60
	v_cvt_pk_f32_fp8_sdwa v[186:187], v60 src0_sel:WORD_1
	v_cvt_pk_f32_fp8_e32 v[188:189], v61
	v_cvt_pk_f32_fp8_sdwa v[190:191], v61 src0_sel:WORD_1
	v_pk_mul_f32 v[200:201], v[80:81], v[184:185]
	v_cvt_pk_f32_fp8_e32 v[192:193], v62
	v_pk_mul_f32 v[202:203], v[82:83], v[186:187]
	v_cvt_pk_f32_fp8_sdwa v[194:195], v62 src0_sel:WORD_1
	v_pk_fma_f32 v[200:201], v[84:85], v[188:189], v[200:201]
	v_cvt_pk_f32_fp8_e32 v[196:197], v63
	v_pk_fma_f32 v[202:203], v[86:87], v[190:191], v[202:203]
	v_cvt_pk_f32_fp8_sdwa v[198:199], v63 src0_sel:WORD_1
	v_pk_fma_f32 v[200:201], v[88:89], v[192:193], v[200:201]
	v_pk_fma_f32 v[202:203], v[90:91], v[194:195], v[202:203]
	v_pk_fma_f32 v[200:201], v[92:93], v[196:197], v[200:201]
	v_pk_fma_f32 v[202:203], v[94:95], v[198:199], v[202:203]
	v_pk_add_f32 v[200:201], v[200:201], v[202:203]
	v_add_f32_e32 v175, v200, v201
	v_readlane_b32 s25, v121, 47
	s_lshl_b32 s25, s25, 10
	v_add_u32_e32 v207, s25, v208
	global_load_dwordx4 v[60:63], v207, s[12:13]
	s_nop 1
	v_permlane32_swap_b32_e32 v168, v172
	v_permlane32_swap_b32_e32 v169, v173
	v_permlane32_swap_b32_e32 v170, v174
	v_permlane32_swap_b32_e32 v171, v175
	v_add_f32_e32 v168, v168, v172
	v_add_f32_e32 v169, v169, v173
	v_add_f32_e32 v170, v170, v174
	v_add_f32_e32 v171, v171, v175
	v_cndmask_b32_e64 v216, v170, v168, s[26:27]
	v_cndmask_b32_e64 v218, v168, v170, s[26:27]
	v_cndmask_b32_e64 v217, v171, v169, s[26:27]
	v_cndmask_b32_e64 v219, v169, v171, s[26:27]
	ds_bpermute_b32 v220, v212, v216
	ds_bpermute_b32 v221, v212, v217
	s_waitcnt lgkmcnt(0)
	v_add_f32_e32 v218, v220, v218
	v_add_f32_e32 v219, v221, v219
	v_cndmask_b32_e64 v216, v219, v218, s[28:29]
	v_cndmask_b32_e64 v217, v218, v219, s[28:29]
	s_nop 1
	v_add_f32_dpp v222, v216, v217 row_ror:8 row_mask:0xf bank_mask:0xf
	ds_bpermute_b32 v220, v213, v222
	s_waitcnt lgkmcnt(0)
	v_add_f32_e32 v222, v220, v222
	s_nop 1
	v_add_f32_dpp v223, v222, v222 quad_perm:[2,3,0,1] row_mask:0xf bank_mask:0xf
	s_nop 1
	v_add_f32_dpp v222, v223, v223 quad_perm:[1,0,3,2] row_mask:0xf bank_mask:0xf
	ds_bpermute_b32 v220, v214, v222
	s_mov_b32 s30, 0x0
	s_mov_b32 s31, 0xff
	s_waitcnt lgkmcnt(0)
	v_cndmask_b32_e64 v179, v179, v220, s[30:31]
	s_waitcnt vmcnt(15)
	v_cvt_pk_f32_fp8_e32 v[184:185], v0
	v_cvt_pk_f32_fp8_sdwa v[186:187], v0 src0_sel:WORD_1
	v_cvt_pk_f32_fp8_e32 v[188:189], v1
	v_cvt_pk_f32_fp8_sdwa v[190:191], v1 src0_sel:WORD_1
	v_pk_mul_f32 v[200:201], v[64:65], v[184:185]
	v_cvt_pk_f32_fp8_e32 v[192:193], v2
	v_pk_mul_f32 v[202:203], v[66:67], v[186:187]
	v_cvt_pk_f32_fp8_sdwa v[194:195], v2 src0_sel:WORD_1
	v_pk_fma_f32 v[200:201], v[68:69], v[188:189], v[200:201]
	v_cvt_pk_f32_fp8_e32 v[196:197], v3
	v_pk_fma_f32 v[202:203], v[70:71], v[190:191], v[202:203]
	v_cvt_pk_f32_fp8_sdwa v[198:199], v3 src0_sel:WORD_1
	v_pk_fma_f32 v[200:201], v[72:73], v[192:193], v[200:201]
	v_pk_fma_f32 v[202:203], v[74:75], v[194:195], v[202:203]
	v_pk_fma_f32 v[200:201], v[76:77], v[196:197], v[200:201]
	v_pk_fma_f32 v[202:203], v[78:79], v[198:199], v[202:203]
	v_pk_add_f32 v[200:201], v[200:201], v[202:203]
	v_add_f32_e32 v160, v200, v201
	v_readlane_b32 s22, v113, 48
	s_lshl_b32 s22, s22, 10
	v_add_u32_e32 v204, s22, v208
	global_load_dwordx4 v[0:3], v204, s[12:13]
	s_waitcnt vmcnt(15)
	v_cvt_pk_f32_fp8_e32 v[184:185], v4
	v_cvt_pk_f32_fp8_sdwa v[186:187], v4 src0_sel:WORD_1
	v_cvt_pk_f32_fp8_e32 v[188:189], v5
	v_cvt_pk_f32_fp8_sdwa v[190:191], v5 src0_sel:WORD_1
	v_pk_mul_f32 v[200:201], v[80:81], v[184:185]
	v_cvt_pk_f32_fp8_e32 v[192:193], v6
	v_pk_mul_f32 v[202:203], v[82:83], v[186:187]
	v_cvt_pk_f32_fp8_sdwa v[194:195], v6 src0_sel:WORD_1
	v_pk_fma_f32 v[200:201], v[84:85], v[188:189], v[200:201]
	v_cvt_pk_f32_fp8_e32 v[196:197], v7
	v_pk_fma_f32 v[202:203], v[86:87], v[190:191], v[202:203]
	v_cvt_pk_f32_fp8_sdwa v[198:199], v7 src0_sel:WORD_1
	v_pk_fma_f32 v[200:201], v[88:89], v[192:193], v[200:201]
	v_pk_fma_f32 v[202:203], v[90:91], v[194:195], v[202:203]
	v_pk_fma_f32 v[200:201], v[92:93], v[196:197], v[200:201]
	v_pk_fma_f32 v[202:203], v[94:95], v[198:199], v[202:203]
	v_pk_add_f32 v[200:201], v[200:201], v[202:203]
	v_add_f32_e32 v168, v200, v201
	v_readlane_b32 s23, v121, 48
	s_lshl_b32 s23, s23, 10
	v_add_u32_e32 v205, s23, v208
	global_load_dwordx4 v[4:7], v205, s[12:13]
	s_waitcnt vmcnt(15)
	v_cvt_pk_f32_fp8_e32 v[184:185], v8
	v_cvt_pk_f32_fp8_sdwa v[186:187], v8 src0_sel:WORD_1
	v_cvt_pk_f32_fp8_e32 v[188:189], v9
	v_cvt_pk_f32_fp8_sdwa v[190:191], v9 src0_sel:WORD_1
	v_pk_mul_f32 v[200:201], v[64:65], v[184:185]
	v_cvt_pk_f32_fp8_e32 v[192:193], v10
	v_pk_mul_f32 v[202:203], v[66:67], v[186:187]
	v_cvt_pk_f32_fp8_sdwa v[194:195], v10 src0_sel:WORD_1
	v_pk_fma_f32 v[200:201], v[68:69], v[188:189], v[200:201]
	v_cvt_pk_f32_fp8_e32 v[196:197], v11
	v_pk_fma_f32 v[202:203], v[70:71], v[190:191], v[202:203]
	v_cvt_pk_f32_fp8_sdwa v[198:199], v11 src0_sel:WORD_1
	v_pk_fma_f32 v[200:201], v[72:73], v[192:193], v[200:201]
	v_pk_fma_f32 v[202:203], v[74:75], v[194:195], v[202:203]
	v_pk_fma_f32 v[200:201], v[76:77], v[196:197], v[200:201]
	v_pk_fma_f32 v[202:203], v[78:79], v[198:199], v[202:203]
	v_pk_add_f32 v[200:201], v[200:201], v[202:203]
	v_add_f32_e32 v161, v200, v201
	v_readlane_b32 s24, v113, 49
	s_lshl_b32 s24, s24, 10
	v_add_u32_e32 v206, s24, v208
	global_load_dwordx4 v[8:11], v206, s[12:13]
	s_waitcnt vmcnt(15)
	v_cvt_pk_f32_fp8_e32 v[184:185], v12
	v_cvt_pk_f32_fp8_sdwa v[186:187], v12 src0_sel:WORD_1
	v_cvt_pk_f32_fp8_e32 v[188:189], v13
	v_cvt_pk_f32_fp8_sdwa v[190:191], v13 src0_sel:WORD_1
	v_pk_mul_f32 v[200:201], v[80:81], v[184:185]
	v_cvt_pk_f32_fp8_e32 v[192:193], v14
	v_pk_mul_f32 v[202:203], v[82:83], v[186:187]
	v_cvt_pk_f32_fp8_sdwa v[194:195], v14 src0_sel:WORD_1
	v_pk_fma_f32 v[200:201], v[84:85], v[188:189], v[200:201]
	v_cvt_pk_f32_fp8_e32 v[196:197], v15
	v_pk_fma_f32 v[202:203], v[86:87], v[190:191], v[202:203]
	v_cvt_pk_f32_fp8_sdwa v[198:199], v15 src0_sel:WORD_1
	v_pk_fma_f32 v[200:201], v[88:89], v[192:193], v[200:201]
	v_pk_fma_f32 v[202:203], v[90:91], v[194:195], v[202:203]
	v_pk_fma_f32 v[200:201], v[92:93], v[196:197], v[200:201]
	v_pk_fma_f32 v[202:203], v[94:95], v[198:199], v[202:203]
	v_pk_add_f32 v[200:201], v[200:201], v[202:203]
	v_add_f32_e32 v169, v200, v201
	v_readlane_b32 s25, v121, 49
	s_lshl_b32 s25, s25, 10
	v_add_u32_e32 v207, s25, v208
	global_load_dwordx4 v[12:15], v207, s[12:13]
	s_waitcnt vmcnt(15)
	v_cvt_pk_f32_fp8_e32 v[184:185], v16
	v_cvt_pk_f32_fp8_sdwa v[186:187], v16 src0_sel:WORD_1
	v_cvt_pk_f32_fp8_e32 v[188:189], v17
	v_cvt_pk_f32_fp8_sdwa v[190:191], v17 src0_sel:WORD_1
	v_pk_mul_f32 v[200:201], v[64:65], v[184:185]
	v_cvt_pk_f32_fp8_e32 v[192:193], v18
	v_pk_mul_f32 v[202:203], v[66:67], v[186:187]
	v_cvt_pk_f32_fp8_sdwa v[194:195], v18 src0_sel:WORD_1
	v_pk_fma_f32 v[200:201], v[68:69], v[188:189], v[200:201]
	v_cvt_pk_f32_fp8_e32 v[196:197], v19
	v_pk_fma_f32 v[202:203], v[70:71], v[190:191], v[202:203]
	v_cvt_pk_f32_fp8_sdwa v[198:199], v19 src0_sel:WORD_1
	v_pk_fma_f32 v[200:201], v[72:73], v[192:193], v[200:201]
	v_pk_fma_f32 v[202:203], v[74:75], v[194:195], v[202:203]
	v_pk_fma_f32 v[200:201], v[76:77], v[196:197], v[200:201]
	v_pk_fma_f32 v[202:203], v[78:79], v[198:199], v[202:203]
	v_pk_add_f32 v[200:201], v[200:201], v[202:203]
	v_add_f32_e32 v162, v200, v201
	v_readlane_b32 s22, v113, 50
	s_lshl_b32 s22, s22, 10
	v_add_u32_e32 v204, s22, v208
	global_load_dwordx4 v[16:19], v204, s[12:13]
	s_waitcnt vmcnt(15)
	v_cvt_pk_f32_fp8_e32 v[184:185], v20
	v_cvt_pk_f32_fp8_sdwa v[186:187], v20 src0_sel:WORD_1
	v_cvt_pk_f32_fp8_e32 v[188:189], v21
	v_cvt_pk_f32_fp8_sdwa v[190:191], v21 src0_sel:WORD_1
	v_pk_mul_f32 v[200:201], v[80:81], v[184:185]
	v_cvt_pk_f32_fp8_e32 v[192:193], v22
	v_pk_mul_f32 v[202:203], v[82:83], v[186:187]
	v_cvt_pk_f32_fp8_sdwa v[194:195], v22 src0_sel:WORD_1
	v_pk_fma_f32 v[200:201], v[84:85], v[188:189], v[200:201]
	v_cvt_pk_f32_fp8_e32 v[196:197], v23
	v_pk_fma_f32 v[202:203], v[86:87], v[190:191], v[202:203]
	v_cvt_pk_f32_fp8_sdwa v[198:199], v23 src0_sel:WORD_1
	v_pk_fma_f32 v[200:201], v[88:89], v[192:193], v[200:201]
	v_pk_fma_f32 v[202:203], v[90:91], v[194:195], v[202:203]
	v_pk_fma_f32 v[200:201], v[92:93], v[196:197], v[200:201]
	v_pk_fma_f32 v[202:203], v[94:95], v[198:199], v[202:203]
	v_pk_add_f32 v[200:201], v[200:201], v[202:203]
	v_add_f32_e32 v170, v200, v201
	v_readlane_b32 s23, v121, 50
	s_lshl_b32 s23, s23, 10
	v_add_u32_e32 v205, s23, v208
	global_load_dwordx4 v[20:23], v205, s[12:13]
	s_waitcnt vmcnt(15)
	v_cvt_pk_f32_fp8_e32 v[184:185], v24
	v_cvt_pk_f32_fp8_sdwa v[186:187], v24 src0_sel:WORD_1
	v_cvt_pk_f32_fp8_e32 v[188:189], v25
	v_cvt_pk_f32_fp8_sdwa v[190:191], v25 src0_sel:WORD_1
	v_pk_mul_f32 v[200:201], v[64:65], v[184:185]
	v_cvt_pk_f32_fp8_e32 v[192:193], v26
	v_pk_mul_f32 v[202:203], v[66:67], v[186:187]
	v_cvt_pk_f32_fp8_sdwa v[194:195], v26 src0_sel:WORD_1
	v_pk_fma_f32 v[200:201], v[68:69], v[188:189], v[200:201]
	v_cvt_pk_f32_fp8_e32 v[196:197], v27
	v_pk_fma_f32 v[202:203], v[70:71], v[190:191], v[202:203]
	v_cvt_pk_f32_fp8_sdwa v[198:199], v27 src0_sel:WORD_1
	v_pk_fma_f32 v[200:201], v[72:73], v[192:193], v[200:201]
	v_pk_fma_f32 v[202:203], v[74:75], v[194:195], v[202:203]
	v_pk_fma_f32 v[200:201], v[76:77], v[196:197], v[200:201]
	v_pk_fma_f32 v[202:203], v[78:79], v[198:199], v[202:203]
	v_pk_add_f32 v[200:201], v[200:201], v[202:203]
	v_add_f32_e32 v163, v200, v201
	v_readlane_b32 s24, v113, 51
	s_lshl_b32 s24, s24, 10
	v_add_u32_e32 v206, s24, v208
	global_load_dwordx4 v[24:27], v206, s[12:13]
	s_waitcnt vmcnt(15)
	v_cvt_pk_f32_fp8_e32 v[184:185], v28
	v_cvt_pk_f32_fp8_sdwa v[186:187], v28 src0_sel:WORD_1
	v_cvt_pk_f32_fp8_e32 v[188:189], v29
	v_cvt_pk_f32_fp8_sdwa v[190:191], v29 src0_sel:WORD_1
	v_pk_mul_f32 v[200:201], v[80:81], v[184:185]
	v_cvt_pk_f32_fp8_e32 v[192:193], v30
	v_pk_mul_f32 v[202:203], v[82:83], v[186:187]
	v_cvt_pk_f32_fp8_sdwa v[194:195], v30 src0_sel:WORD_1
	v_pk_fma_f32 v[200:201], v[84:85], v[188:189], v[200:201]
	v_cvt_pk_f32_fp8_e32 v[196:197], v31
	v_pk_fma_f32 v[202:203], v[86:87], v[190:191], v[202:203]
	v_cvt_pk_f32_fp8_sdwa v[198:199], v31 src0_sel:WORD_1
	v_pk_fma_f32 v[200:201], v[88:89], v[192:193], v[200:201]
	v_pk_fma_f32 v[202:203], v[90:91], v[194:195], v[202:203]
	v_pk_fma_f32 v[200:201], v[92:93], v[196:197], v[200:201]
	v_pk_fma_f32 v[202:203], v[94:95], v[198:199], v[202:203]
	v_pk_add_f32 v[200:201], v[200:201], v[202:203]
	v_add_f32_e32 v171, v200, v201
	v_readlane_b32 s25, v121, 51
	s_lshl_b32 s25, s25, 10
	v_add_u32_e32 v207, s25, v208
	global_load_dwordx4 v[28:31], v207, s[12:13]
	s_waitcnt vmcnt(15)
	v_cvt_pk_f32_fp8_e32 v[184:185], v32
	v_cvt_pk_f32_fp8_sdwa v[186:187], v32 src0_sel:WORD_1
	v_cvt_pk_f32_fp8_e32 v[188:189], v33
	v_cvt_pk_f32_fp8_sdwa v[190:191], v33 src0_sel:WORD_1
	v_pk_mul_f32 v[200:201], v[64:65], v[184:185]
	v_cvt_pk_f32_fp8_e32 v[192:193], v34
	v_pk_mul_f32 v[202:203], v[66:67], v[186:187]
	v_cvt_pk_f32_fp8_sdwa v[194:195], v34 src0_sel:WORD_1
	v_pk_fma_f32 v[200:201], v[68:69], v[188:189], v[200:201]
	v_cvt_pk_f32_fp8_e32 v[196:197], v35
	v_pk_fma_f32 v[202:203], v[70:71], v[190:191], v[202:203]
	v_cvt_pk_f32_fp8_sdwa v[198:199], v35 src0_sel:WORD_1
	v_pk_fma_f32 v[200:201], v[72:73], v[192:193], v[200:201]
	v_pk_fma_f32 v[202:203], v[74:75], v[194:195], v[202:203]
	v_pk_fma_f32 v[200:201], v[76:77], v[196:197], v[200:201]
	v_pk_fma_f32 v[202:203], v[78:79], v[198:199], v[202:203]
	v_pk_add_f32 v[200:201], v[200:201], v[202:203]
	v_add_f32_e32 v164, v200, v201
	v_readlane_b32 s22, v113, 52
	s_lshl_b32 s22, s22, 10
	v_add_u32_e32 v204, s22, v208
	global_load_dwordx4 v[32:35], v204, s[12:13]
	s_waitcnt vmcnt(15)
	v_cvt_pk_f32_fp8_e32 v[184:185], v36
	v_cvt_pk_f32_fp8_sdwa v[186:187], v36 src0_sel:WORD_1
	v_cvt_pk_f32_fp8_e32 v[188:189], v37
	v_cvt_pk_f32_fp8_sdwa v[190:191], v37 src0_sel:WORD_1
	v_pk_mul_f32 v[200:201], v[80:81], v[184:185]
	v_cvt_pk_f32_fp8_e32 v[192:193], v38
	v_pk_mul_f32 v[202:203], v[82:83], v[186:187]
	v_cvt_pk_f32_fp8_sdwa v[194:195], v38 src0_sel:WORD_1
	v_pk_fma_f32 v[200:201], v[84:85], v[188:189], v[200:201]
	v_cvt_pk_f32_fp8_e32 v[196:197], v39
	v_pk_fma_f32 v[202:203], v[86:87], v[190:191], v[202:203]
	v_cvt_pk_f32_fp8_sdwa v[198:199], v39 src0_sel:WORD_1
	v_pk_fma_f32 v[200:201], v[88:89], v[192:193], v[200:201]
	v_pk_fma_f32 v[202:203], v[90:91], v[194:195], v[202:203]
	v_pk_fma_f32 v[200:201], v[92:93], v[196:197], v[200:201]
	v_pk_fma_f32 v[202:203], v[94:95], v[198:199], v[202:203]
	v_pk_add_f32 v[200:201], v[200:201], v[202:203]
	v_add_f32_e32 v172, v200, v201
	v_readlane_b32 s23, v121, 52
	s_lshl_b32 s23, s23, 10
	v_add_u32_e32 v205, s23, v208
	global_load_dwordx4 v[36:39], v205, s[12:13]
	s_waitcnt vmcnt(15)
	v_cvt_pk_f32_fp8_e32 v[184:185], v40
	v_cvt_pk_f32_fp8_sdwa v[186:187], v40 src0_sel:WORD_1
	v_cvt_pk_f32_fp8_e32 v[188:189], v41
	v_cvt_pk_f32_fp8_sdwa v[190:191], v41 src0_sel:WORD_1
	v_pk_mul_f32 v[200:201], v[64:65], v[184:185]
	v_cvt_pk_f32_fp8_e32 v[192:193], v42
	v_pk_mul_f32 v[202:203], v[66:67], v[186:187]
	v_cvt_pk_f32_fp8_sdwa v[194:195], v42 src0_sel:WORD_1
	v_pk_fma_f32 v[200:201], v[68:69], v[188:189], v[200:201]
	v_cvt_pk_f32_fp8_e32 v[196:197], v43
	v_pk_fma_f32 v[202:203], v[70:71], v[190:191], v[202:203]
	v_cvt_pk_f32_fp8_sdwa v[198:199], v43 src0_sel:WORD_1
	v_pk_fma_f32 v[200:201], v[72:73], v[192:193], v[200:201]
	v_pk_fma_f32 v[202:203], v[74:75], v[194:195], v[202:203]
	v_pk_fma_f32 v[200:201], v[76:77], v[196:197], v[200:201]
	v_pk_fma_f32 v[202:203], v[78:79], v[198:199], v[202:203]
	v_pk_add_f32 v[200:201], v[200:201], v[202:203]
	v_add_f32_e32 v165, v200, v201
	v_readlane_b32 s24, v113, 53
	s_lshl_b32 s24, s24, 10
	v_add_u32_e32 v206, s24, v208
	global_load_dwordx4 v[40:43], v206, s[12:13]
	s_waitcnt vmcnt(15)
	v_cvt_pk_f32_fp8_e32 v[184:185], v44
	v_cvt_pk_f32_fp8_sdwa v[186:187], v44 src0_sel:WORD_1
	v_cvt_pk_f32_fp8_e32 v[188:189], v45
	v_cvt_pk_f32_fp8_sdwa v[190:191], v45 src0_sel:WORD_1
	v_pk_mul_f32 v[200:201], v[80:81], v[184:185]
	v_cvt_pk_f32_fp8_e32 v[192:193], v46
	v_pk_mul_f32 v[202:203], v[82:83], v[186:187]
	v_cvt_pk_f32_fp8_sdwa v[194:195], v46 src0_sel:WORD_1
	v_pk_fma_f32 v[200:201], v[84:85], v[188:189], v[200:201]
	v_cvt_pk_f32_fp8_e32 v[196:197], v47
	v_pk_fma_f32 v[202:203], v[86:87], v[190:191], v[202:203]
	v_cvt_pk_f32_fp8_sdwa v[198:199], v47 src0_sel:WORD_1
	v_pk_fma_f32 v[200:201], v[88:89], v[192:193], v[200:201]
	v_pk_fma_f32 v[202:203], v[90:91], v[194:195], v[202:203]
	v_pk_fma_f32 v[200:201], v[92:93], v[196:197], v[200:201]
	v_pk_fma_f32 v[202:203], v[94:95], v[198:199], v[202:203]
	v_pk_add_f32 v[200:201], v[200:201], v[202:203]
	v_add_f32_e32 v173, v200, v201
	v_readlane_b32 s25, v121, 53
	s_lshl_b32 s25, s25, 10
	v_add_u32_e32 v207, s25, v208
	global_load_dwordx4 v[44:47], v207, s[12:13]
	s_waitcnt vmcnt(15)
	v_cvt_pk_f32_fp8_e32 v[184:185], v48
	v_cvt_pk_f32_fp8_sdwa v[186:187], v48 src0_sel:WORD_1
	v_cvt_pk_f32_fp8_e32 v[188:189], v49
	v_cvt_pk_f32_fp8_sdwa v[190:191], v49 src0_sel:WORD_1
	v_pk_mul_f32 v[200:201], v[64:65], v[184:185]
	v_cvt_pk_f32_fp8_e32 v[192:193], v50
	v_pk_mul_f32 v[202:203], v[66:67], v[186:187]
	v_cvt_pk_f32_fp8_sdwa v[194:195], v50 src0_sel:WORD_1
	v_pk_fma_f32 v[200:201], v[68:69], v[188:189], v[200:201]
	v_cvt_pk_f32_fp8_e32 v[196:197], v51
	v_pk_fma_f32 v[202:203], v[70:71], v[190:191], v[202:203]
	v_cvt_pk_f32_fp8_sdwa v[198:199], v51 src0_sel:WORD_1
	v_pk_fma_f32 v[200:201], v[72:73], v[192:193], v[200:201]
	v_pk_fma_f32 v[202:203], v[74:75], v[194:195], v[202:203]
	v_pk_fma_f32 v[200:201], v[76:77], v[196:197], v[200:201]
	v_pk_fma_f32 v[202:203], v[78:79], v[198:199], v[202:203]
	v_pk_add_f32 v[200:201], v[200:201], v[202:203]
	v_add_f32_e32 v166, v200, v201
	v_readlane_b32 s22, v113, 54
	s_lshl_b32 s22, s22, 10
	v_add_u32_e32 v204, s22, v208
	global_load_dwordx4 v[48:51], v204, s[12:13]
	s_waitcnt vmcnt(15)
	v_cvt_pk_f32_fp8_e32 v[184:185], v52
	v_cvt_pk_f32_fp8_sdwa v[186:187], v52 src0_sel:WORD_1
	v_cvt_pk_f32_fp8_e32 v[188:189], v53
	v_cvt_pk_f32_fp8_sdwa v[190:191], v53 src0_sel:WORD_1
	v_pk_mul_f32 v[200:201], v[80:81], v[184:185]
	v_cvt_pk_f32_fp8_e32 v[192:193], v54
	v_pk_mul_f32 v[202:203], v[82:83], v[186:187]
	v_cvt_pk_f32_fp8_sdwa v[194:195], v54 src0_sel:WORD_1
	v_pk_fma_f32 v[200:201], v[84:85], v[188:189], v[200:201]
	v_cvt_pk_f32_fp8_e32 v[196:197], v55
	v_pk_fma_f32 v[202:203], v[86:87], v[190:191], v[202:203]
	v_cvt_pk_f32_fp8_sdwa v[198:199], v55 src0_sel:WORD_1
	v_pk_fma_f32 v[200:201], v[88:89], v[192:193], v[200:201]
	v_pk_fma_f32 v[202:203], v[90:91], v[194:195], v[202:203]
	v_pk_fma_f32 v[200:201], v[92:93], v[196:197], v[200:201]
	v_pk_fma_f32 v[202:203], v[94:95], v[198:199], v[202:203]
	v_pk_add_f32 v[200:201], v[200:201], v[202:203]
	v_add_f32_e32 v174, v200, v201
	v_readlane_b32 s23, v121, 54
	s_lshl_b32 s23, s23, 10
	v_add_u32_e32 v205, s23, v208
	global_load_dwordx4 v[52:55], v205, s[12:13]
	s_waitcnt vmcnt(15)
	v_cvt_pk_f32_fp8_e32 v[184:185], v56
	v_cvt_pk_f32_fp8_sdwa v[186:187], v56 src0_sel:WORD_1
	v_cvt_pk_f32_fp8_e32 v[188:189], v57
	v_cvt_pk_f32_fp8_sdwa v[190:191], v57 src0_sel:WORD_1
	v_pk_mul_f32 v[200:201], v[64:65], v[184:185]
	v_cvt_pk_f32_fp8_e32 v[192:193], v58
	v_pk_mul_f32 v[202:203], v[66:67], v[186:187]
	v_cvt_pk_f32_fp8_sdwa v[194:195], v58 src0_sel:WORD_1
	v_pk_fma_f32 v[200:201], v[68:69], v[188:189], v[200:201]
	v_cvt_pk_f32_fp8_e32 v[196:197], v59
	v_pk_fma_f32 v[202:203], v[70:71], v[190:191], v[202:203]
	v_cvt_pk_f32_fp8_sdwa v[198:199], v59 src0_sel:WORD_1
	v_pk_fma_f32 v[200:201], v[72:73], v[192:193], v[200:201]
	v_pk_fma_f32 v[202:203], v[74:75], v[194:195], v[202:203]
	v_pk_fma_f32 v[200:201], v[76:77], v[196:197], v[200:201]
	v_pk_fma_f32 v[202:203], v[78:79], v[198:199], v[202:203]
	v_pk_add_f32 v[200:201], v[200:201], v[202:203]
	v_add_f32_e32 v167, v200, v201
	v_readlane_b32 s24, v113, 55
	s_lshl_b32 s24, s24, 10
	v_add_u32_e32 v206, s24, v208
	global_load_dwordx4 v[56:59], v206, s[12:13]
	s_nop 1
	v_permlane32_swap_b32_e32 v160, v164
	v_permlane32_swap_b32_e32 v161, v165
	v_permlane32_swap_b32_e32 v162, v166
	v_permlane32_swap_b32_e32 v163, v167
	v_add_f32_e32 v160, v160, v164
	v_add_f32_e32 v161, v161, v165
	v_add_f32_e32 v162, v162, v166
	v_add_f32_e32 v163, v163, v167
	v_cndmask_b32_e64 v216, v162, v160, s[26:27]
	v_cndmask_b32_e64 v218, v160, v162, s[26:27]
	v_cndmask_b32_e64 v217, v163, v161, s[26:27]
	v_cndmask_b32_e64 v219, v161, v163, s[26:27]
	ds_bpermute_b32 v220, v212, v216
	ds_bpermute_b32 v221, v212, v217
	s_waitcnt lgkmcnt(0)
	v_add_f32_e32 v218, v220, v218
	v_add_f32_e32 v219, v221, v219
	v_cndmask_b32_e64 v216, v219, v218, s[28:29]
	v_cndmask_b32_e64 v217, v218, v219, s[28:29]
	s_nop 1
	v_add_f32_dpp v222, v216, v217 row_ror:8 row_mask:0xf bank_mask:0xf
	ds_bpermute_b32 v220, v213, v222
	s_waitcnt lgkmcnt(0)
	v_add_f32_e32 v222, v220, v222
	s_nop 1
	v_add_f32_dpp v223, v222, v222 quad_perm:[2,3,0,1] row_mask:0xf bank_mask:0xf
	s_nop 1
	v_add_f32_dpp v222, v223, v223 quad_perm:[1,0,3,2] row_mask:0xf bank_mask:0xf
	ds_bpermute_b32 v220, v214, v222
	s_mov_b32 s30, 0x0
	s_mov_b32 s31, 0xff00
	s_waitcnt lgkmcnt(0)
	v_cndmask_b32_e64 v176, v176, v220, s[30:31]
	s_waitcnt vmcnt(15)
	v_cvt_pk_f32_fp8_e32 v[184:185], v60
	v_cvt_pk_f32_fp8_sdwa v[186:187], v60 src0_sel:WORD_1
	v_cvt_pk_f32_fp8_e32 v[188:189], v61
	v_cvt_pk_f32_fp8_sdwa v[190:191], v61 src0_sel:WORD_1
	v_pk_mul_f32 v[200:201], v[80:81], v[184:185]
	v_cvt_pk_f32_fp8_e32 v[192:193], v62
	v_pk_mul_f32 v[202:203], v[82:83], v[186:187]
	v_cvt_pk_f32_fp8_sdwa v[194:195], v62 src0_sel:WORD_1
	v_pk_fma_f32 v[200:201], v[84:85], v[188:189], v[200:201]
	v_cvt_pk_f32_fp8_e32 v[196:197], v63
	v_pk_fma_f32 v[202:203], v[86:87], v[190:191], v[202:203]
	v_cvt_pk_f32_fp8_sdwa v[198:199], v63 src0_sel:WORD_1
	v_pk_fma_f32 v[200:201], v[88:89], v[192:193], v[200:201]
	v_pk_fma_f32 v[202:203], v[90:91], v[194:195], v[202:203]
	v_pk_fma_f32 v[200:201], v[92:93], v[196:197], v[200:201]
	v_pk_fma_f32 v[202:203], v[94:95], v[198:199], v[202:203]
	v_pk_add_f32 v[200:201], v[200:201], v[202:203]
	v_add_f32_e32 v175, v200, v201
	v_readlane_b32 s25, v121, 55
	s_lshl_b32 s25, s25, 10
	v_add_u32_e32 v207, s25, v208
	global_load_dwordx4 v[60:63], v207, s[12:13]
	s_nop 1
	v_permlane32_swap_b32_e32 v168, v172
	v_permlane32_swap_b32_e32 v169, v173
	v_permlane32_swap_b32_e32 v170, v174
	v_permlane32_swap_b32_e32 v171, v175
	v_add_f32_e32 v168, v168, v172
	v_add_f32_e32 v169, v169, v173
	v_add_f32_e32 v170, v170, v174
	v_add_f32_e32 v171, v171, v175
	v_cndmask_b32_e64 v216, v170, v168, s[26:27]
	v_cndmask_b32_e64 v218, v168, v170, s[26:27]
	v_cndmask_b32_e64 v217, v171, v169, s[26:27]
	v_cndmask_b32_e64 v219, v169, v171, s[26:27]
	ds_bpermute_b32 v220, v212, v216
	ds_bpermute_b32 v221, v212, v217
	s_waitcnt lgkmcnt(0)
	v_add_f32_e32 v218, v220, v218
	v_add_f32_e32 v219, v221, v219
	v_cndmask_b32_e64 v216, v219, v218, s[28:29]
	v_cndmask_b32_e64 v217, v218, v219, s[28:29]
	s_nop 1
	v_add_f32_dpp v222, v216, v217 row_ror:8 row_mask:0xf bank_mask:0xf
	ds_bpermute_b32 v220, v213, v222
	s_waitcnt lgkmcnt(0)
	v_add_f32_e32 v222, v220, v222
	s_nop 1
	v_add_f32_dpp v223, v222, v222 quad_perm:[2,3,0,1] row_mask:0xf bank_mask:0xf
	s_nop 1
	v_add_f32_dpp v222, v223, v223 quad_perm:[1,0,3,2] row_mask:0xf bank_mask:0xf
	ds_bpermute_b32 v220, v214, v222
	s_mov_b32 s30, 0x0
	s_mov_b32 s31, 0xff00
	s_waitcnt lgkmcnt(0)
	v_cndmask_b32_e64 v179, v179, v220, s[30:31]
	s_waitcnt vmcnt(15)
	v_cvt_pk_f32_fp8_e32 v[184:185], v0
	v_cvt_pk_f32_fp8_sdwa v[186:187], v0 src0_sel:WORD_1
	v_cvt_pk_f32_fp8_e32 v[188:189], v1
	v_cvt_pk_f32_fp8_sdwa v[190:191], v1 src0_sel:WORD_1
	v_pk_mul_f32 v[200:201], v[64:65], v[184:185]
	v_cvt_pk_f32_fp8_e32 v[192:193], v2
	v_pk_mul_f32 v[202:203], v[66:67], v[186:187]
	v_cvt_pk_f32_fp8_sdwa v[194:195], v2 src0_sel:WORD_1
	v_pk_fma_f32 v[200:201], v[68:69], v[188:189], v[200:201]
	v_cvt_pk_f32_fp8_e32 v[196:197], v3
	v_pk_fma_f32 v[202:203], v[70:71], v[190:191], v[202:203]
	v_cvt_pk_f32_fp8_sdwa v[198:199], v3 src0_sel:WORD_1
	v_pk_fma_f32 v[200:201], v[72:73], v[192:193], v[200:201]
	v_pk_fma_f32 v[202:203], v[74:75], v[194:195], v[202:203]
	v_pk_fma_f32 v[200:201], v[76:77], v[196:197], v[200:201]
	v_pk_fma_f32 v[202:203], v[78:79], v[198:199], v[202:203]
	v_pk_add_f32 v[200:201], v[200:201], v[202:203]
	v_add_f32_e32 v160, v200, v201
	v_readlane_b32 s22, v113, 56
	s_lshl_b32 s22, s22, 10
	v_add_u32_e32 v204, s22, v208
	global_load_dwordx4 v[0:3], v204, s[12:13]
	s_waitcnt vmcnt(15)
	v_cvt_pk_f32_fp8_e32 v[184:185], v4
	v_cvt_pk_f32_fp8_sdwa v[186:187], v4 src0_sel:WORD_1
	v_cvt_pk_f32_fp8_e32 v[188:189], v5
	v_cvt_pk_f32_fp8_sdwa v[190:191], v5 src0_sel:WORD_1
	v_pk_mul_f32 v[200:201], v[80:81], v[184:185]
	v_cvt_pk_f32_fp8_e32 v[192:193], v6
	v_pk_mul_f32 v[202:203], v[82:83], v[186:187]
	v_cvt_pk_f32_fp8_sdwa v[194:195], v6 src0_sel:WORD_1
	v_pk_fma_f32 v[200:201], v[84:85], v[188:189], v[200:201]
	v_cvt_pk_f32_fp8_e32 v[196:197], v7
	v_pk_fma_f32 v[202:203], v[86:87], v[190:191], v[202:203]
	v_cvt_pk_f32_fp8_sdwa v[198:199], v7 src0_sel:WORD_1
	v_pk_fma_f32 v[200:201], v[88:89], v[192:193], v[200:201]
	v_pk_fma_f32 v[202:203], v[90:91], v[194:195], v[202:203]
	v_pk_fma_f32 v[200:201], v[92:93], v[196:197], v[200:201]
	v_pk_fma_f32 v[202:203], v[94:95], v[198:199], v[202:203]
	v_pk_add_f32 v[200:201], v[200:201], v[202:203]
	v_add_f32_e32 v168, v200, v201
	v_readlane_b32 s23, v121, 56
	s_lshl_b32 s23, s23, 10
	v_add_u32_e32 v205, s23, v208
	global_load_dwordx4 v[4:7], v205, s[12:13]
	s_waitcnt vmcnt(15)
	v_cvt_pk_f32_fp8_e32 v[184:185], v8
	v_cvt_pk_f32_fp8_sdwa v[186:187], v8 src0_sel:WORD_1
	v_cvt_pk_f32_fp8_e32 v[188:189], v9
	v_cvt_pk_f32_fp8_sdwa v[190:191], v9 src0_sel:WORD_1
	v_pk_mul_f32 v[200:201], v[64:65], v[184:185]
	v_cvt_pk_f32_fp8_e32 v[192:193], v10
	v_pk_mul_f32 v[202:203], v[66:67], v[186:187]
	v_cvt_pk_f32_fp8_sdwa v[194:195], v10 src0_sel:WORD_1
	v_pk_fma_f32 v[200:201], v[68:69], v[188:189], v[200:201]
	v_cvt_pk_f32_fp8_e32 v[196:197], v11
	v_pk_fma_f32 v[202:203], v[70:71], v[190:191], v[202:203]
	v_cvt_pk_f32_fp8_sdwa v[198:199], v11 src0_sel:WORD_1
	v_pk_fma_f32 v[200:201], v[72:73], v[192:193], v[200:201]
	v_pk_fma_f32 v[202:203], v[74:75], v[194:195], v[202:203]
	v_pk_fma_f32 v[200:201], v[76:77], v[196:197], v[200:201]
	v_pk_fma_f32 v[202:203], v[78:79], v[198:199], v[202:203]
	v_pk_add_f32 v[200:201], v[200:201], v[202:203]
	v_add_f32_e32 v161, v200, v201
	v_readlane_b32 s24, v113, 57
	s_lshl_b32 s24, s24, 10
	v_add_u32_e32 v206, s24, v208
	global_load_dwordx4 v[8:11], v206, s[12:13]
	s_waitcnt vmcnt(15)
	v_cvt_pk_f32_fp8_e32 v[184:185], v12
	v_cvt_pk_f32_fp8_sdwa v[186:187], v12 src0_sel:WORD_1
	v_cvt_pk_f32_fp8_e32 v[188:189], v13
	v_cvt_pk_f32_fp8_sdwa v[190:191], v13 src0_sel:WORD_1
	v_pk_mul_f32 v[200:201], v[80:81], v[184:185]
	v_cvt_pk_f32_fp8_e32 v[192:193], v14
	v_pk_mul_f32 v[202:203], v[82:83], v[186:187]
	v_cvt_pk_f32_fp8_sdwa v[194:195], v14 src0_sel:WORD_1
	v_pk_fma_f32 v[200:201], v[84:85], v[188:189], v[200:201]
	v_cvt_pk_f32_fp8_e32 v[196:197], v15
	v_pk_fma_f32 v[202:203], v[86:87], v[190:191], v[202:203]
	v_cvt_pk_f32_fp8_sdwa v[198:199], v15 src0_sel:WORD_1
	v_pk_fma_f32 v[200:201], v[88:89], v[192:193], v[200:201]
	v_pk_fma_f32 v[202:203], v[90:91], v[194:195], v[202:203]
	v_pk_fma_f32 v[200:201], v[92:93], v[196:197], v[200:201]
	v_pk_fma_f32 v[202:203], v[94:95], v[198:199], v[202:203]
	v_pk_add_f32 v[200:201], v[200:201], v[202:203]
	v_add_f32_e32 v169, v200, v201
	v_readlane_b32 s25, v121, 57
	s_lshl_b32 s25, s25, 10
	v_add_u32_e32 v207, s25, v208
	global_load_dwordx4 v[12:15], v207, s[12:13]
	s_waitcnt vmcnt(15)
	v_cvt_pk_f32_fp8_e32 v[184:185], v16
	v_cvt_pk_f32_fp8_sdwa v[186:187], v16 src0_sel:WORD_1
	v_cvt_pk_f32_fp8_e32 v[188:189], v17
	v_cvt_pk_f32_fp8_sdwa v[190:191], v17 src0_sel:WORD_1
	v_pk_mul_f32 v[200:201], v[64:65], v[184:185]
	v_cvt_pk_f32_fp8_e32 v[192:193], v18
	v_pk_mul_f32 v[202:203], v[66:67], v[186:187]
	v_cvt_pk_f32_fp8_sdwa v[194:195], v18 src0_sel:WORD_1
	v_pk_fma_f32 v[200:201], v[68:69], v[188:189], v[200:201]
	v_cvt_pk_f32_fp8_e32 v[196:197], v19
	v_pk_fma_f32 v[202:203], v[70:71], v[190:191], v[202:203]
	v_cvt_pk_f32_fp8_sdwa v[198:199], v19 src0_sel:WORD_1
	v_pk_fma_f32 v[200:201], v[72:73], v[192:193], v[200:201]
	v_pk_fma_f32 v[202:203], v[74:75], v[194:195], v[202:203]
	v_pk_fma_f32 v[200:201], v[76:77], v[196:197], v[200:201]
	v_pk_fma_f32 v[202:203], v[78:79], v[198:199], v[202:203]
	v_pk_add_f32 v[200:201], v[200:201], v[202:203]
	v_add_f32_e32 v162, v200, v201
	v_readlane_b32 s22, v113, 58
	s_lshl_b32 s22, s22, 10
	v_add_u32_e32 v204, s22, v208
	global_load_dwordx4 v[16:19], v204, s[12:13]
	s_waitcnt vmcnt(15)
	v_cvt_pk_f32_fp8_e32 v[184:185], v20
	v_cvt_pk_f32_fp8_sdwa v[186:187], v20 src0_sel:WORD_1
	v_cvt_pk_f32_fp8_e32 v[188:189], v21
	v_cvt_pk_f32_fp8_sdwa v[190:191], v21 src0_sel:WORD_1
	v_pk_mul_f32 v[200:201], v[80:81], v[184:185]
	v_cvt_pk_f32_fp8_e32 v[192:193], v22
	v_pk_mul_f32 v[202:203], v[82:83], v[186:187]
	v_cvt_pk_f32_fp8_sdwa v[194:195], v22 src0_sel:WORD_1
	v_pk_fma_f32 v[200:201], v[84:85], v[188:189], v[200:201]
	v_cvt_pk_f32_fp8_e32 v[196:197], v23
	v_pk_fma_f32 v[202:203], v[86:87], v[190:191], v[202:203]
	v_cvt_pk_f32_fp8_sdwa v[198:199], v23 src0_sel:WORD_1
	v_pk_fma_f32 v[200:201], v[88:89], v[192:193], v[200:201]
	v_pk_fma_f32 v[202:203], v[90:91], v[194:195], v[202:203]
	v_pk_fma_f32 v[200:201], v[92:93], v[196:197], v[200:201]
	v_pk_fma_f32 v[202:203], v[94:95], v[198:199], v[202:203]
	v_pk_add_f32 v[200:201], v[200:201], v[202:203]
	v_add_f32_e32 v170, v200, v201
	v_readlane_b32 s23, v121, 58
	s_lshl_b32 s23, s23, 10
	v_add_u32_e32 v205, s23, v208
	global_load_dwordx4 v[20:23], v205, s[12:13]
	s_waitcnt vmcnt(15)
	v_cvt_pk_f32_fp8_e32 v[184:185], v24
	v_cvt_pk_f32_fp8_sdwa v[186:187], v24 src0_sel:WORD_1
	v_cvt_pk_f32_fp8_e32 v[188:189], v25
	v_cvt_pk_f32_fp8_sdwa v[190:191], v25 src0_sel:WORD_1
	v_pk_mul_f32 v[200:201], v[64:65], v[184:185]
	v_cvt_pk_f32_fp8_e32 v[192:193], v26
	v_pk_mul_f32 v[202:203], v[66:67], v[186:187]
	v_cvt_pk_f32_fp8_sdwa v[194:195], v26 src0_sel:WORD_1
	v_pk_fma_f32 v[200:201], v[68:69], v[188:189], v[200:201]
	v_cvt_pk_f32_fp8_e32 v[196:197], v27
	v_pk_fma_f32 v[202:203], v[70:71], v[190:191], v[202:203]
	v_cvt_pk_f32_fp8_sdwa v[198:199], v27 src0_sel:WORD_1
	v_pk_fma_f32 v[200:201], v[72:73], v[192:193], v[200:201]
	v_pk_fma_f32 v[202:203], v[74:75], v[194:195], v[202:203]
	v_pk_fma_f32 v[200:201], v[76:77], v[196:197], v[200:201]
	v_pk_fma_f32 v[202:203], v[78:79], v[198:199], v[202:203]
	v_pk_add_f32 v[200:201], v[200:201], v[202:203]
	v_add_f32_e32 v163, v200, v201
	v_readlane_b32 s24, v113, 59
	s_lshl_b32 s24, s24, 10
	v_add_u32_e32 v206, s24, v208
	global_load_dwordx4 v[24:27], v206, s[12:13]
	s_waitcnt vmcnt(15)
	v_cvt_pk_f32_fp8_e32 v[184:185], v28
	v_cvt_pk_f32_fp8_sdwa v[186:187], v28 src0_sel:WORD_1
	v_cvt_pk_f32_fp8_e32 v[188:189], v29
	v_cvt_pk_f32_fp8_sdwa v[190:191], v29 src0_sel:WORD_1
	v_pk_mul_f32 v[200:201], v[80:81], v[184:185]
	v_cvt_pk_f32_fp8_e32 v[192:193], v30
	v_pk_mul_f32 v[202:203], v[82:83], v[186:187]
	v_cvt_pk_f32_fp8_sdwa v[194:195], v30 src0_sel:WORD_1
	v_pk_fma_f32 v[200:201], v[84:85], v[188:189], v[200:201]
	v_cvt_pk_f32_fp8_e32 v[196:197], v31
	v_pk_fma_f32 v[202:203], v[86:87], v[190:191], v[202:203]
	v_cvt_pk_f32_fp8_sdwa v[198:199], v31 src0_sel:WORD_1
	v_pk_fma_f32 v[200:201], v[88:89], v[192:193], v[200:201]
	v_pk_fma_f32 v[202:203], v[90:91], v[194:195], v[202:203]
	v_pk_fma_f32 v[200:201], v[92:93], v[196:197], v[200:201]
	v_pk_fma_f32 v[202:203], v[94:95], v[198:199], v[202:203]
	v_pk_add_f32 v[200:201], v[200:201], v[202:203]
	v_add_f32_e32 v171, v200, v201
	v_readlane_b32 s25, v121, 59
	s_lshl_b32 s25, s25, 10
	v_add_u32_e32 v207, s25, v208
	global_load_dwordx4 v[28:31], v207, s[12:13]
	s_waitcnt vmcnt(15)
	v_cvt_pk_f32_fp8_e32 v[184:185], v32
	v_cvt_pk_f32_fp8_sdwa v[186:187], v32 src0_sel:WORD_1
	v_cvt_pk_f32_fp8_e32 v[188:189], v33
	v_cvt_pk_f32_fp8_sdwa v[190:191], v33 src0_sel:WORD_1
	v_pk_mul_f32 v[200:201], v[64:65], v[184:185]
	v_cvt_pk_f32_fp8_e32 v[192:193], v34
	v_pk_mul_f32 v[202:203], v[66:67], v[186:187]
	v_cvt_pk_f32_fp8_sdwa v[194:195], v34 src0_sel:WORD_1
	v_pk_fma_f32 v[200:201], v[68:69], v[188:189], v[200:201]
	v_cvt_pk_f32_fp8_e32 v[196:197], v35
	v_pk_fma_f32 v[202:203], v[70:71], v[190:191], v[202:203]
	v_cvt_pk_f32_fp8_sdwa v[198:199], v35 src0_sel:WORD_1
	v_pk_fma_f32 v[200:201], v[72:73], v[192:193], v[200:201]
	v_pk_fma_f32 v[202:203], v[74:75], v[194:195], v[202:203]
	v_pk_fma_f32 v[200:201], v[76:77], v[196:197], v[200:201]
	v_pk_fma_f32 v[202:203], v[78:79], v[198:199], v[202:203]
	v_pk_add_f32 v[200:201], v[200:201], v[202:203]
	v_add_f32_e32 v164, v200, v201
	v_readlane_b32 s22, v113, 60
	s_lshl_b32 s22, s22, 10
	v_add_u32_e32 v204, s22, v208
	global_load_dwordx4 v[32:35], v204, s[12:13]
	s_waitcnt vmcnt(15)
	v_cvt_pk_f32_fp8_e32 v[184:185], v36
	v_cvt_pk_f32_fp8_sdwa v[186:187], v36 src0_sel:WORD_1
	v_cvt_pk_f32_fp8_e32 v[188:189], v37
	v_cvt_pk_f32_fp8_sdwa v[190:191], v37 src0_sel:WORD_1
	v_pk_mul_f32 v[200:201], v[80:81], v[184:185]
	v_cvt_pk_f32_fp8_e32 v[192:193], v38
	v_pk_mul_f32 v[202:203], v[82:83], v[186:187]
	v_cvt_pk_f32_fp8_sdwa v[194:195], v38 src0_sel:WORD_1
	v_pk_fma_f32 v[200:201], v[84:85], v[188:189], v[200:201]
	v_cvt_pk_f32_fp8_e32 v[196:197], v39
	v_pk_fma_f32 v[202:203], v[86:87], v[190:191], v[202:203]
	v_cvt_pk_f32_fp8_sdwa v[198:199], v39 src0_sel:WORD_1
	v_pk_fma_f32 v[200:201], v[88:89], v[192:193], v[200:201]
	v_pk_fma_f32 v[202:203], v[90:91], v[194:195], v[202:203]
	v_pk_fma_f32 v[200:201], v[92:93], v[196:197], v[200:201]
	v_pk_fma_f32 v[202:203], v[94:95], v[198:199], v[202:203]
	v_pk_add_f32 v[200:201], v[200:201], v[202:203]
	v_add_f32_e32 v172, v200, v201
	v_readlane_b32 s23, v121, 60
	s_lshl_b32 s23, s23, 10
	v_add_u32_e32 v205, s23, v208
	global_load_dwordx4 v[36:39], v205, s[12:13]
	s_waitcnt vmcnt(15)
	v_cvt_pk_f32_fp8_e32 v[184:185], v40
	v_cvt_pk_f32_fp8_sdwa v[186:187], v40 src0_sel:WORD_1
	v_cvt_pk_f32_fp8_e32 v[188:189], v41
	v_cvt_pk_f32_fp8_sdwa v[190:191], v41 src0_sel:WORD_1
	v_pk_mul_f32 v[200:201], v[64:65], v[184:185]
	v_cvt_pk_f32_fp8_e32 v[192:193], v42
	v_pk_mul_f32 v[202:203], v[66:67], v[186:187]
	v_cvt_pk_f32_fp8_sdwa v[194:195], v42 src0_sel:WORD_1
	v_pk_fma_f32 v[200:201], v[68:69], v[188:189], v[200:201]
	v_cvt_pk_f32_fp8_e32 v[196:197], v43
	v_pk_fma_f32 v[202:203], v[70:71], v[190:191], v[202:203]
	v_cvt_pk_f32_fp8_sdwa v[198:199], v43 src0_sel:WORD_1
	v_pk_fma_f32 v[200:201], v[72:73], v[192:193], v[200:201]
	v_pk_fma_f32 v[202:203], v[74:75], v[194:195], v[202:203]
	v_pk_fma_f32 v[200:201], v[76:77], v[196:197], v[200:201]
	v_pk_fma_f32 v[202:203], v[78:79], v[198:199], v[202:203]
	v_pk_add_f32 v[200:201], v[200:201], v[202:203]
	v_add_f32_e32 v165, v200, v201
	v_readlane_b32 s24, v113, 61
	s_lshl_b32 s24, s24, 10
	v_add_u32_e32 v206, s24, v208
	global_load_dwordx4 v[40:43], v206, s[12:13]
	s_waitcnt vmcnt(15)
	v_cvt_pk_f32_fp8_e32 v[184:185], v44
	v_cvt_pk_f32_fp8_sdwa v[186:187], v44 src0_sel:WORD_1
	v_cvt_pk_f32_fp8_e32 v[188:189], v45
	v_cvt_pk_f32_fp8_sdwa v[190:191], v45 src0_sel:WORD_1
	v_pk_mul_f32 v[200:201], v[80:81], v[184:185]
	v_cvt_pk_f32_fp8_e32 v[192:193], v46
	v_pk_mul_f32 v[202:203], v[82:83], v[186:187]
	v_cvt_pk_f32_fp8_sdwa v[194:195], v46 src0_sel:WORD_1
	v_pk_fma_f32 v[200:201], v[84:85], v[188:189], v[200:201]
	v_cvt_pk_f32_fp8_e32 v[196:197], v47
	v_pk_fma_f32 v[202:203], v[86:87], v[190:191], v[202:203]
	v_cvt_pk_f32_fp8_sdwa v[198:199], v47 src0_sel:WORD_1
	v_pk_fma_f32 v[200:201], v[88:89], v[192:193], v[200:201]
	v_pk_fma_f32 v[202:203], v[90:91], v[194:195], v[202:203]
	v_pk_fma_f32 v[200:201], v[92:93], v[196:197], v[200:201]
	v_pk_fma_f32 v[202:203], v[94:95], v[198:199], v[202:203]
	v_pk_add_f32 v[200:201], v[200:201], v[202:203]
	v_add_f32_e32 v173, v200, v201
	v_readlane_b32 s25, v121, 61
	s_lshl_b32 s25, s25, 10
	v_add_u32_e32 v207, s25, v208
	global_load_dwordx4 v[44:47], v207, s[12:13]
	s_waitcnt vmcnt(15)
	v_cvt_pk_f32_fp8_e32 v[184:185], v48
	v_cvt_pk_f32_fp8_sdwa v[186:187], v48 src0_sel:WORD_1
	v_cvt_pk_f32_fp8_e32 v[188:189], v49
	v_cvt_pk_f32_fp8_sdwa v[190:191], v49 src0_sel:WORD_1
	v_pk_mul_f32 v[200:201], v[64:65], v[184:185]
	v_cvt_pk_f32_fp8_e32 v[192:193], v50
	v_pk_mul_f32 v[202:203], v[66:67], v[186:187]
	v_cvt_pk_f32_fp8_sdwa v[194:195], v50 src0_sel:WORD_1
	v_pk_fma_f32 v[200:201], v[68:69], v[188:189], v[200:201]
	v_cvt_pk_f32_fp8_e32 v[196:197], v51
	v_pk_fma_f32 v[202:203], v[70:71], v[190:191], v[202:203]
	v_cvt_pk_f32_fp8_sdwa v[198:199], v51 src0_sel:WORD_1
	v_pk_fma_f32 v[200:201], v[72:73], v[192:193], v[200:201]
	v_pk_fma_f32 v[202:203], v[74:75], v[194:195], v[202:203]
	v_pk_fma_f32 v[200:201], v[76:77], v[196:197], v[200:201]
	v_pk_fma_f32 v[202:203], v[78:79], v[198:199], v[202:203]
	v_pk_add_f32 v[200:201], v[200:201], v[202:203]
	v_add_f32_e32 v166, v200, v201
	v_readlane_b32 s22, v113, 62
	s_lshl_b32 s22, s22, 10
	v_add_u32_e32 v204, s22, v208
	global_load_dwordx4 v[48:51], v204, s[12:13]
	s_waitcnt vmcnt(15)
	v_cvt_pk_f32_fp8_e32 v[184:185], v52
	v_cvt_pk_f32_fp8_sdwa v[186:187], v52 src0_sel:WORD_1
	v_cvt_pk_f32_fp8_e32 v[188:189], v53
	v_cvt_pk_f32_fp8_sdwa v[190:191], v53 src0_sel:WORD_1
	v_pk_mul_f32 v[200:201], v[80:81], v[184:185]
	v_cvt_pk_f32_fp8_e32 v[192:193], v54
	v_pk_mul_f32 v[202:203], v[82:83], v[186:187]
	v_cvt_pk_f32_fp8_sdwa v[194:195], v54 src0_sel:WORD_1
	v_pk_fma_f32 v[200:201], v[84:85], v[188:189], v[200:201]
	v_cvt_pk_f32_fp8_e32 v[196:197], v55
	v_pk_fma_f32 v[202:203], v[86:87], v[190:191], v[202:203]
	v_cvt_pk_f32_fp8_sdwa v[198:199], v55 src0_sel:WORD_1
	v_pk_fma_f32 v[200:201], v[88:89], v[192:193], v[200:201]
	v_pk_fma_f32 v[202:203], v[90:91], v[194:195], v[202:203]
	v_pk_fma_f32 v[200:201], v[92:93], v[196:197], v[200:201]
	v_pk_fma_f32 v[202:203], v[94:95], v[198:199], v[202:203]
	v_pk_add_f32 v[200:201], v[200:201], v[202:203]
	v_add_f32_e32 v174, v200, v201
	v_readlane_b32 s23, v121, 62
	s_lshl_b32 s23, s23, 10
	v_add_u32_e32 v205, s23, v208
	global_load_dwordx4 v[52:55], v205, s[12:13]
	s_waitcnt vmcnt(15)
	v_cvt_pk_f32_fp8_e32 v[184:185], v56
	v_cvt_pk_f32_fp8_sdwa v[186:187], v56 src0_sel:WORD_1
	v_cvt_pk_f32_fp8_e32 v[188:189], v57
	v_cvt_pk_f32_fp8_sdwa v[190:191], v57 src0_sel:WORD_1
	v_pk_mul_f32 v[200:201], v[64:65], v[184:185]
	v_cvt_pk_f32_fp8_e32 v[192:193], v58
	v_pk_mul_f32 v[202:203], v[66:67], v[186:187]
	v_cvt_pk_f32_fp8_sdwa v[194:195], v58 src0_sel:WORD_1
	v_pk_fma_f32 v[200:201], v[68:69], v[188:189], v[200:201]
	v_cvt_pk_f32_fp8_e32 v[196:197], v59
	v_pk_fma_f32 v[202:203], v[70:71], v[190:191], v[202:203]
	v_cvt_pk_f32_fp8_sdwa v[198:199], v59 src0_sel:WORD_1
	v_pk_fma_f32 v[200:201], v[72:73], v[192:193], v[200:201]
	v_pk_fma_f32 v[202:203], v[74:75], v[194:195], v[202:203]
	v_pk_fma_f32 v[200:201], v[76:77], v[196:197], v[200:201]
	v_pk_fma_f32 v[202:203], v[78:79], v[198:199], v[202:203]
	v_pk_add_f32 v[200:201], v[200:201], v[202:203]
	v_add_f32_e32 v167, v200, v201
	v_readlane_b32 s24, v113, 63
	s_lshl_b32 s24, s24, 10
	v_add_u32_e32 v206, s24, v208
	global_load_dwordx4 v[56:59], v206, s[12:13]
	s_nop 1
	v_permlane32_swap_b32_e32 v160, v164
	v_permlane32_swap_b32_e32 v161, v165
	v_permlane32_swap_b32_e32 v162, v166
	v_permlane32_swap_b32_e32 v163, v167
	v_add_f32_e32 v160, v160, v164
	v_add_f32_e32 v161, v161, v165
	v_add_f32_e32 v162, v162, v166
	v_add_f32_e32 v163, v163, v167
	v_cndmask_b32_e64 v216, v162, v160, s[26:27]
	v_cndmask_b32_e64 v218, v160, v162, s[26:27]
	v_cndmask_b32_e64 v217, v163, v161, s[26:27]
	v_cndmask_b32_e64 v219, v161, v163, s[26:27]
	ds_bpermute_b32 v220, v212, v216
	ds_bpermute_b32 v221, v212, v217
	s_waitcnt lgkmcnt(0)
	v_add_f32_e32 v218, v220, v218
	v_add_f32_e32 v219, v221, v219
	v_cndmask_b32_e64 v216, v219, v218, s[28:29]
	v_cndmask_b32_e64 v217, v218, v219, s[28:29]
	s_nop 1
	v_add_f32_dpp v222, v216, v217 row_ror:8 row_mask:0xf bank_mask:0xf
	ds_bpermute_b32 v220, v213, v222
	s_waitcnt lgkmcnt(0)
	v_add_f32_e32 v222, v220, v222
	s_nop 1
	v_add_f32_dpp v223, v222, v222 quad_perm:[2,3,0,1] row_mask:0xf bank_mask:0xf
	s_nop 1
	v_add_f32_dpp v222, v223, v223 quad_perm:[1,0,3,2] row_mask:0xf bank_mask:0xf
	ds_bpermute_b32 v220, v214, v222
	s_mov_b32 s30, 0x0
	s_mov_b32 s31, 0xff0000
	s_waitcnt lgkmcnt(0)
	v_cndmask_b32_e64 v176, v176, v220, s[30:31]
	s_waitcnt vmcnt(15)
	v_cvt_pk_f32_fp8_e32 v[184:185], v60
	v_cvt_pk_f32_fp8_sdwa v[186:187], v60 src0_sel:WORD_1
	v_cvt_pk_f32_fp8_e32 v[188:189], v61
	v_cvt_pk_f32_fp8_sdwa v[190:191], v61 src0_sel:WORD_1
	v_pk_mul_f32 v[200:201], v[80:81], v[184:185]
	v_cvt_pk_f32_fp8_e32 v[192:193], v62
	v_pk_mul_f32 v[202:203], v[82:83], v[186:187]
	v_cvt_pk_f32_fp8_sdwa v[194:195], v62 src0_sel:WORD_1
	v_pk_fma_f32 v[200:201], v[84:85], v[188:189], v[200:201]
	v_cvt_pk_f32_fp8_e32 v[196:197], v63
	v_pk_fma_f32 v[202:203], v[86:87], v[190:191], v[202:203]
	v_cvt_pk_f32_fp8_sdwa v[198:199], v63 src0_sel:WORD_1
	v_pk_fma_f32 v[200:201], v[88:89], v[192:193], v[200:201]
	v_pk_fma_f32 v[202:203], v[90:91], v[194:195], v[202:203]
	v_pk_fma_f32 v[200:201], v[92:93], v[196:197], v[200:201]
	v_pk_fma_f32 v[202:203], v[94:95], v[198:199], v[202:203]
	v_pk_add_f32 v[200:201], v[200:201], v[202:203]
	v_add_f32_e32 v175, v200, v201
	v_readlane_b32 s25, v121, 63
	s_lshl_b32 s25, s25, 10
	v_add_u32_e32 v207, s25, v208
	global_load_dwordx4 v[60:63], v207, s[12:13]
	s_nop 1
	v_permlane32_swap_b32_e32 v168, v172
	v_permlane32_swap_b32_e32 v169, v173
	v_permlane32_swap_b32_e32 v170, v174
	v_permlane32_swap_b32_e32 v171, v175
	v_add_f32_e32 v168, v168, v172
	v_add_f32_e32 v169, v169, v173
	v_add_f32_e32 v170, v170, v174
	v_add_f32_e32 v171, v171, v175
	v_cndmask_b32_e64 v216, v170, v168, s[26:27]
	v_cndmask_b32_e64 v218, v168, v170, s[26:27]
	v_cndmask_b32_e64 v217, v171, v169, s[26:27]
	v_cndmask_b32_e64 v219, v169, v171, s[26:27]
	ds_bpermute_b32 v220, v212, v216
	ds_bpermute_b32 v221, v212, v217
	s_waitcnt lgkmcnt(0)
	v_add_f32_e32 v218, v220, v218
	v_add_f32_e32 v219, v221, v219
	v_cndmask_b32_e64 v216, v219, v218, s[28:29]
	v_cndmask_b32_e64 v217, v218, v219, s[28:29]
	s_nop 1
	v_add_f32_dpp v222, v216, v217 row_ror:8 row_mask:0xf bank_mask:0xf
	ds_bpermute_b32 v220, v213, v222
	s_waitcnt lgkmcnt(0)
	v_add_f32_e32 v222, v220, v222
	s_nop 1
	v_add_f32_dpp v223, v222, v222 quad_perm:[2,3,0,1] row_mask:0xf bank_mask:0xf
	s_nop 1
	v_add_f32_dpp v222, v223, v223 quad_perm:[1,0,3,2] row_mask:0xf bank_mask:0xf
	ds_bpermute_b32 v220, v214, v222
	s_mov_b32 s30, 0x0
	s_mov_b32 s31, 0xff0000
	s_waitcnt lgkmcnt(0)
	v_cndmask_b32_e64 v179, v179, v220, s[30:31]
	s_waitcnt vmcnt(15)
	v_cvt_pk_f32_fp8_e32 v[184:185], v0
	v_cvt_pk_f32_fp8_sdwa v[186:187], v0 src0_sel:WORD_1
	v_cvt_pk_f32_fp8_e32 v[188:189], v1
	v_cvt_pk_f32_fp8_sdwa v[190:191], v1 src0_sel:WORD_1
	v_pk_mul_f32 v[200:201], v[64:65], v[184:185]
	v_cvt_pk_f32_fp8_e32 v[192:193], v2
	v_pk_mul_f32 v[202:203], v[66:67], v[186:187]
	v_cvt_pk_f32_fp8_sdwa v[194:195], v2 src0_sel:WORD_1
	v_pk_fma_f32 v[200:201], v[68:69], v[188:189], v[200:201]
	v_cvt_pk_f32_fp8_e32 v[196:197], v3
	v_pk_fma_f32 v[202:203], v[70:71], v[190:191], v[202:203]
	v_cvt_pk_f32_fp8_sdwa v[198:199], v3 src0_sel:WORD_1
	v_pk_fma_f32 v[200:201], v[72:73], v[192:193], v[200:201]
	v_pk_fma_f32 v[202:203], v[74:75], v[194:195], v[202:203]
	v_pk_fma_f32 v[200:201], v[76:77], v[196:197], v[200:201]
	v_pk_fma_f32 v[202:203], v[78:79], v[198:199], v[202:203]
	v_pk_add_f32 v[200:201], v[200:201], v[202:203]
	v_add_f32_e32 v160, v200, v201
	v_readlane_b32 s22, v128, 0
	s_lshl_b32 s22, s22, 10
	v_add_u32_e32 v204, s22, v208
	global_load_dwordx4 v[0:3], v204, s[12:13]
	s_waitcnt vmcnt(15)
	v_cvt_pk_f32_fp8_e32 v[184:185], v4
	v_cvt_pk_f32_fp8_sdwa v[186:187], v4 src0_sel:WORD_1
	v_cvt_pk_f32_fp8_e32 v[188:189], v5
	v_cvt_pk_f32_fp8_sdwa v[190:191], v5 src0_sel:WORD_1
	v_pk_mul_f32 v[200:201], v[80:81], v[184:185]
	v_cvt_pk_f32_fp8_e32 v[192:193], v6
	v_pk_mul_f32 v[202:203], v[82:83], v[186:187]
	v_cvt_pk_f32_fp8_sdwa v[194:195], v6 src0_sel:WORD_1
	v_pk_fma_f32 v[200:201], v[84:85], v[188:189], v[200:201]
	v_cvt_pk_f32_fp8_e32 v[196:197], v7
	v_pk_fma_f32 v[202:203], v[86:87], v[190:191], v[202:203]
	v_cvt_pk_f32_fp8_sdwa v[198:199], v7 src0_sel:WORD_1
	v_pk_fma_f32 v[200:201], v[88:89], v[192:193], v[200:201]
	v_pk_fma_f32 v[202:203], v[90:91], v[194:195], v[202:203]
	v_pk_fma_f32 v[200:201], v[92:93], v[196:197], v[200:201]
	v_pk_fma_f32 v[202:203], v[94:95], v[198:199], v[202:203]
	v_pk_add_f32 v[200:201], v[200:201], v[202:203]
	v_add_f32_e32 v168, v200, v201
	v_readlane_b32 s23, v136, 0
	s_lshl_b32 s23, s23, 10
	v_add_u32_e32 v205, s23, v208
	global_load_dwordx4 v[4:7], v205, s[12:13]
	s_waitcnt vmcnt(15)
	v_cvt_pk_f32_fp8_e32 v[184:185], v8
	v_cvt_pk_f32_fp8_sdwa v[186:187], v8 src0_sel:WORD_1
	v_cvt_pk_f32_fp8_e32 v[188:189], v9
	v_cvt_pk_f32_fp8_sdwa v[190:191], v9 src0_sel:WORD_1
	v_pk_mul_f32 v[200:201], v[64:65], v[184:185]
	v_cvt_pk_f32_fp8_e32 v[192:193], v10
	v_pk_mul_f32 v[202:203], v[66:67], v[186:187]
	v_cvt_pk_f32_fp8_sdwa v[194:195], v10 src0_sel:WORD_1
	v_pk_fma_f32 v[200:201], v[68:69], v[188:189], v[200:201]
	v_cvt_pk_f32_fp8_e32 v[196:197], v11
	v_pk_fma_f32 v[202:203], v[70:71], v[190:191], v[202:203]
	v_cvt_pk_f32_fp8_sdwa v[198:199], v11 src0_sel:WORD_1
	v_pk_fma_f32 v[200:201], v[72:73], v[192:193], v[200:201]
	v_pk_fma_f32 v[202:203], v[74:75], v[194:195], v[202:203]
	v_pk_fma_f32 v[200:201], v[76:77], v[196:197], v[200:201]
	v_pk_fma_f32 v[202:203], v[78:79], v[198:199], v[202:203]
	v_pk_add_f32 v[200:201], v[200:201], v[202:203]
	v_add_f32_e32 v161, v200, v201
	v_readlane_b32 s24, v128, 1
	s_lshl_b32 s24, s24, 10
	v_add_u32_e32 v206, s24, v208
	global_load_dwordx4 v[8:11], v206, s[12:13]
	s_waitcnt vmcnt(15)
	v_cvt_pk_f32_fp8_e32 v[184:185], v12
	v_cvt_pk_f32_fp8_sdwa v[186:187], v12 src0_sel:WORD_1
	v_cvt_pk_f32_fp8_e32 v[188:189], v13
	v_cvt_pk_f32_fp8_sdwa v[190:191], v13 src0_sel:WORD_1
	v_pk_mul_f32 v[200:201], v[80:81], v[184:185]
	v_cvt_pk_f32_fp8_e32 v[192:193], v14
	v_pk_mul_f32 v[202:203], v[82:83], v[186:187]
	v_cvt_pk_f32_fp8_sdwa v[194:195], v14 src0_sel:WORD_1
	v_pk_fma_f32 v[200:201], v[84:85], v[188:189], v[200:201]
	v_cvt_pk_f32_fp8_e32 v[196:197], v15
	v_pk_fma_f32 v[202:203], v[86:87], v[190:191], v[202:203]
	v_cvt_pk_f32_fp8_sdwa v[198:199], v15 src0_sel:WORD_1
	v_pk_fma_f32 v[200:201], v[88:89], v[192:193], v[200:201]
	v_pk_fma_f32 v[202:203], v[90:91], v[194:195], v[202:203]
	v_pk_fma_f32 v[200:201], v[92:93], v[196:197], v[200:201]
	v_pk_fma_f32 v[202:203], v[94:95], v[198:199], v[202:203]
	v_pk_add_f32 v[200:201], v[200:201], v[202:203]
	v_add_f32_e32 v169, v200, v201
	v_readlane_b32 s25, v136, 1
	s_lshl_b32 s25, s25, 10
	v_add_u32_e32 v207, s25, v208
	global_load_dwordx4 v[12:15], v207, s[12:13]
	s_waitcnt vmcnt(15)
	v_cvt_pk_f32_fp8_e32 v[184:185], v16
	v_cvt_pk_f32_fp8_sdwa v[186:187], v16 src0_sel:WORD_1
	v_cvt_pk_f32_fp8_e32 v[188:189], v17
	v_cvt_pk_f32_fp8_sdwa v[190:191], v17 src0_sel:WORD_1
	v_pk_mul_f32 v[200:201], v[64:65], v[184:185]
	v_cvt_pk_f32_fp8_e32 v[192:193], v18
	v_pk_mul_f32 v[202:203], v[66:67], v[186:187]
	v_cvt_pk_f32_fp8_sdwa v[194:195], v18 src0_sel:WORD_1
	v_pk_fma_f32 v[200:201], v[68:69], v[188:189], v[200:201]
	v_cvt_pk_f32_fp8_e32 v[196:197], v19
	v_pk_fma_f32 v[202:203], v[70:71], v[190:191], v[202:203]
	v_cvt_pk_f32_fp8_sdwa v[198:199], v19 src0_sel:WORD_1
	v_pk_fma_f32 v[200:201], v[72:73], v[192:193], v[200:201]
	v_pk_fma_f32 v[202:203], v[74:75], v[194:195], v[202:203]
	v_pk_fma_f32 v[200:201], v[76:77], v[196:197], v[200:201]
	v_pk_fma_f32 v[202:203], v[78:79], v[198:199], v[202:203]
	v_pk_add_f32 v[200:201], v[200:201], v[202:203]
	v_add_f32_e32 v162, v200, v201
	v_readlane_b32 s22, v128, 2
	s_lshl_b32 s22, s22, 10
	v_add_u32_e32 v204, s22, v208
	global_load_dwordx4 v[16:19], v204, s[12:13]
	s_waitcnt vmcnt(15)
	v_cvt_pk_f32_fp8_e32 v[184:185], v20
	v_cvt_pk_f32_fp8_sdwa v[186:187], v20 src0_sel:WORD_1
	v_cvt_pk_f32_fp8_e32 v[188:189], v21
	v_cvt_pk_f32_fp8_sdwa v[190:191], v21 src0_sel:WORD_1
	v_pk_mul_f32 v[200:201], v[80:81], v[184:185]
	v_cvt_pk_f32_fp8_e32 v[192:193], v22
	v_pk_mul_f32 v[202:203], v[82:83], v[186:187]
	v_cvt_pk_f32_fp8_sdwa v[194:195], v22 src0_sel:WORD_1
	v_pk_fma_f32 v[200:201], v[84:85], v[188:189], v[200:201]
	v_cvt_pk_f32_fp8_e32 v[196:197], v23
	v_pk_fma_f32 v[202:203], v[86:87], v[190:191], v[202:203]
	v_cvt_pk_f32_fp8_sdwa v[198:199], v23 src0_sel:WORD_1
	v_pk_fma_f32 v[200:201], v[88:89], v[192:193], v[200:201]
	v_pk_fma_f32 v[202:203], v[90:91], v[194:195], v[202:203]
	v_pk_fma_f32 v[200:201], v[92:93], v[196:197], v[200:201]
	v_pk_fma_f32 v[202:203], v[94:95], v[198:199], v[202:203]
	v_pk_add_f32 v[200:201], v[200:201], v[202:203]
	v_add_f32_e32 v170, v200, v201
	v_readlane_b32 s23, v136, 2
	s_lshl_b32 s23, s23, 10
	v_add_u32_e32 v205, s23, v208
	global_load_dwordx4 v[20:23], v205, s[12:13]
	s_waitcnt vmcnt(15)
	v_cvt_pk_f32_fp8_e32 v[184:185], v24
	v_cvt_pk_f32_fp8_sdwa v[186:187], v24 src0_sel:WORD_1
	v_cvt_pk_f32_fp8_e32 v[188:189], v25
	v_cvt_pk_f32_fp8_sdwa v[190:191], v25 src0_sel:WORD_1
	v_pk_mul_f32 v[200:201], v[64:65], v[184:185]
	v_cvt_pk_f32_fp8_e32 v[192:193], v26
	v_pk_mul_f32 v[202:203], v[66:67], v[186:187]
	v_cvt_pk_f32_fp8_sdwa v[194:195], v26 src0_sel:WORD_1
	v_pk_fma_f32 v[200:201], v[68:69], v[188:189], v[200:201]
	v_cvt_pk_f32_fp8_e32 v[196:197], v27
	v_pk_fma_f32 v[202:203], v[70:71], v[190:191], v[202:203]
	v_cvt_pk_f32_fp8_sdwa v[198:199], v27 src0_sel:WORD_1
	v_pk_fma_f32 v[200:201], v[72:73], v[192:193], v[200:201]
	v_pk_fma_f32 v[202:203], v[74:75], v[194:195], v[202:203]
	v_pk_fma_f32 v[200:201], v[76:77], v[196:197], v[200:201]
	v_pk_fma_f32 v[202:203], v[78:79], v[198:199], v[202:203]
	v_pk_add_f32 v[200:201], v[200:201], v[202:203]
	v_add_f32_e32 v163, v200, v201
	v_readlane_b32 s24, v128, 3
	s_lshl_b32 s24, s24, 10
	v_add_u32_e32 v206, s24, v208
	global_load_dwordx4 v[24:27], v206, s[12:13]
	s_waitcnt vmcnt(15)
	v_cvt_pk_f32_fp8_e32 v[184:185], v28
	v_cvt_pk_f32_fp8_sdwa v[186:187], v28 src0_sel:WORD_1
	v_cvt_pk_f32_fp8_e32 v[188:189], v29
	v_cvt_pk_f32_fp8_sdwa v[190:191], v29 src0_sel:WORD_1
	v_pk_mul_f32 v[200:201], v[80:81], v[184:185]
	v_cvt_pk_f32_fp8_e32 v[192:193], v30
	v_pk_mul_f32 v[202:203], v[82:83], v[186:187]
	v_cvt_pk_f32_fp8_sdwa v[194:195], v30 src0_sel:WORD_1
	v_pk_fma_f32 v[200:201], v[84:85], v[188:189], v[200:201]
	v_cvt_pk_f32_fp8_e32 v[196:197], v31
	v_pk_fma_f32 v[202:203], v[86:87], v[190:191], v[202:203]
	v_cvt_pk_f32_fp8_sdwa v[198:199], v31 src0_sel:WORD_1
	v_pk_fma_f32 v[200:201], v[88:89], v[192:193], v[200:201]
	v_pk_fma_f32 v[202:203], v[90:91], v[194:195], v[202:203]
	v_pk_fma_f32 v[200:201], v[92:93], v[196:197], v[200:201]
	v_pk_fma_f32 v[202:203], v[94:95], v[198:199], v[202:203]
	v_pk_add_f32 v[200:201], v[200:201], v[202:203]
	v_add_f32_e32 v171, v200, v201
	v_readlane_b32 s25, v136, 3
	s_lshl_b32 s25, s25, 10
	v_add_u32_e32 v207, s25, v208
	global_load_dwordx4 v[28:31], v207, s[12:13]
	s_waitcnt vmcnt(15)
	v_cvt_pk_f32_fp8_e32 v[184:185], v32
	v_cvt_pk_f32_fp8_sdwa v[186:187], v32 src0_sel:WORD_1
	v_cvt_pk_f32_fp8_e32 v[188:189], v33
	v_cvt_pk_f32_fp8_sdwa v[190:191], v33 src0_sel:WORD_1
	v_pk_mul_f32 v[200:201], v[64:65], v[184:185]
	v_cvt_pk_f32_fp8_e32 v[192:193], v34
	v_pk_mul_f32 v[202:203], v[66:67], v[186:187]
	v_cvt_pk_f32_fp8_sdwa v[194:195], v34 src0_sel:WORD_1
	v_pk_fma_f32 v[200:201], v[68:69], v[188:189], v[200:201]
	v_cvt_pk_f32_fp8_e32 v[196:197], v35
	v_pk_fma_f32 v[202:203], v[70:71], v[190:191], v[202:203]
	v_cvt_pk_f32_fp8_sdwa v[198:199], v35 src0_sel:WORD_1
	v_pk_fma_f32 v[200:201], v[72:73], v[192:193], v[200:201]
	v_pk_fma_f32 v[202:203], v[74:75], v[194:195], v[202:203]
	v_pk_fma_f32 v[200:201], v[76:77], v[196:197], v[200:201]
	v_pk_fma_f32 v[202:203], v[78:79], v[198:199], v[202:203]
	v_pk_add_f32 v[200:201], v[200:201], v[202:203]
	v_add_f32_e32 v164, v200, v201
	v_readlane_b32 s22, v128, 4
	s_lshl_b32 s22, s22, 10
	v_add_u32_e32 v204, s22, v208
	global_load_dwordx4 v[32:35], v204, s[12:13]
	s_waitcnt vmcnt(15)
	v_cvt_pk_f32_fp8_e32 v[184:185], v36
	v_cvt_pk_f32_fp8_sdwa v[186:187], v36 src0_sel:WORD_1
	v_cvt_pk_f32_fp8_e32 v[188:189], v37
	v_cvt_pk_f32_fp8_sdwa v[190:191], v37 src0_sel:WORD_1
	v_pk_mul_f32 v[200:201], v[80:81], v[184:185]
	v_cvt_pk_f32_fp8_e32 v[192:193], v38
	v_pk_mul_f32 v[202:203], v[82:83], v[186:187]
	v_cvt_pk_f32_fp8_sdwa v[194:195], v38 src0_sel:WORD_1
	v_pk_fma_f32 v[200:201], v[84:85], v[188:189], v[200:201]
	v_cvt_pk_f32_fp8_e32 v[196:197], v39
	v_pk_fma_f32 v[202:203], v[86:87], v[190:191], v[202:203]
	v_cvt_pk_f32_fp8_sdwa v[198:199], v39 src0_sel:WORD_1
	v_pk_fma_f32 v[200:201], v[88:89], v[192:193], v[200:201]
	v_pk_fma_f32 v[202:203], v[90:91], v[194:195], v[202:203]
	v_pk_fma_f32 v[200:201], v[92:93], v[196:197], v[200:201]
	v_pk_fma_f32 v[202:203], v[94:95], v[198:199], v[202:203]
	v_pk_add_f32 v[200:201], v[200:201], v[202:203]
	v_add_f32_e32 v172, v200, v201
	v_readlane_b32 s23, v136, 4
	s_lshl_b32 s23, s23, 10
	v_add_u32_e32 v205, s23, v208
	global_load_dwordx4 v[36:39], v205, s[12:13]
	s_waitcnt vmcnt(15)
	v_cvt_pk_f32_fp8_e32 v[184:185], v40
	v_cvt_pk_f32_fp8_sdwa v[186:187], v40 src0_sel:WORD_1
	v_cvt_pk_f32_fp8_e32 v[188:189], v41
	v_cvt_pk_f32_fp8_sdwa v[190:191], v41 src0_sel:WORD_1
	v_pk_mul_f32 v[200:201], v[64:65], v[184:185]
	v_cvt_pk_f32_fp8_e32 v[192:193], v42
	v_pk_mul_f32 v[202:203], v[66:67], v[186:187]
	v_cvt_pk_f32_fp8_sdwa v[194:195], v42 src0_sel:WORD_1
	v_pk_fma_f32 v[200:201], v[68:69], v[188:189], v[200:201]
	v_cvt_pk_f32_fp8_e32 v[196:197], v43
	v_pk_fma_f32 v[202:203], v[70:71], v[190:191], v[202:203]
	v_cvt_pk_f32_fp8_sdwa v[198:199], v43 src0_sel:WORD_1
	v_pk_fma_f32 v[200:201], v[72:73], v[192:193], v[200:201]
	v_pk_fma_f32 v[202:203], v[74:75], v[194:195], v[202:203]
	v_pk_fma_f32 v[200:201], v[76:77], v[196:197], v[200:201]
	v_pk_fma_f32 v[202:203], v[78:79], v[198:199], v[202:203]
	v_pk_add_f32 v[200:201], v[200:201], v[202:203]
	v_add_f32_e32 v165, v200, v201
	v_readlane_b32 s24, v128, 5
	s_lshl_b32 s24, s24, 10
	v_add_u32_e32 v206, s24, v208
	global_load_dwordx4 v[40:43], v206, s[12:13]
	s_waitcnt vmcnt(15)
	v_cvt_pk_f32_fp8_e32 v[184:185], v44
	v_cvt_pk_f32_fp8_sdwa v[186:187], v44 src0_sel:WORD_1
	v_cvt_pk_f32_fp8_e32 v[188:189], v45
	v_cvt_pk_f32_fp8_sdwa v[190:191], v45 src0_sel:WORD_1
	v_pk_mul_f32 v[200:201], v[80:81], v[184:185]
	v_cvt_pk_f32_fp8_e32 v[192:193], v46
	v_pk_mul_f32 v[202:203], v[82:83], v[186:187]
	v_cvt_pk_f32_fp8_sdwa v[194:195], v46 src0_sel:WORD_1
	v_pk_fma_f32 v[200:201], v[84:85], v[188:189], v[200:201]
	v_cvt_pk_f32_fp8_e32 v[196:197], v47
	v_pk_fma_f32 v[202:203], v[86:87], v[190:191], v[202:203]
	v_cvt_pk_f32_fp8_sdwa v[198:199], v47 src0_sel:WORD_1
	v_pk_fma_f32 v[200:201], v[88:89], v[192:193], v[200:201]
	v_pk_fma_f32 v[202:203], v[90:91], v[194:195], v[202:203]
	v_pk_fma_f32 v[200:201], v[92:93], v[196:197], v[200:201]
	v_pk_fma_f32 v[202:203], v[94:95], v[198:199], v[202:203]
	v_pk_add_f32 v[200:201], v[200:201], v[202:203]
	v_add_f32_e32 v173, v200, v201
	v_readlane_b32 s25, v136, 5
	s_lshl_b32 s25, s25, 10
	v_add_u32_e32 v207, s25, v208
	global_load_dwordx4 v[44:47], v207, s[12:13]
	s_waitcnt vmcnt(15)
	v_cvt_pk_f32_fp8_e32 v[184:185], v48
	v_cvt_pk_f32_fp8_sdwa v[186:187], v48 src0_sel:WORD_1
	v_cvt_pk_f32_fp8_e32 v[188:189], v49
	v_cvt_pk_f32_fp8_sdwa v[190:191], v49 src0_sel:WORD_1
	v_pk_mul_f32 v[200:201], v[64:65], v[184:185]
	v_cvt_pk_f32_fp8_e32 v[192:193], v50
	v_pk_mul_f32 v[202:203], v[66:67], v[186:187]
	v_cvt_pk_f32_fp8_sdwa v[194:195], v50 src0_sel:WORD_1
	v_pk_fma_f32 v[200:201], v[68:69], v[188:189], v[200:201]
	v_cvt_pk_f32_fp8_e32 v[196:197], v51
	v_pk_fma_f32 v[202:203], v[70:71], v[190:191], v[202:203]
	v_cvt_pk_f32_fp8_sdwa v[198:199], v51 src0_sel:WORD_1
	v_pk_fma_f32 v[200:201], v[72:73], v[192:193], v[200:201]
	v_pk_fma_f32 v[202:203], v[74:75], v[194:195], v[202:203]
	v_pk_fma_f32 v[200:201], v[76:77], v[196:197], v[200:201]
	v_pk_fma_f32 v[202:203], v[78:79], v[198:199], v[202:203]
	v_pk_add_f32 v[200:201], v[200:201], v[202:203]
	v_add_f32_e32 v166, v200, v201
	v_readlane_b32 s22, v128, 6
	s_lshl_b32 s22, s22, 10
	v_add_u32_e32 v204, s22, v208
	global_load_dwordx4 v[48:51], v204, s[12:13]
	s_waitcnt vmcnt(15)
	v_cvt_pk_f32_fp8_e32 v[184:185], v52
	v_cvt_pk_f32_fp8_sdwa v[186:187], v52 src0_sel:WORD_1
	v_cvt_pk_f32_fp8_e32 v[188:189], v53
	v_cvt_pk_f32_fp8_sdwa v[190:191], v53 src0_sel:WORD_1
	v_pk_mul_f32 v[200:201], v[80:81], v[184:185]
	v_cvt_pk_f32_fp8_e32 v[192:193], v54
	v_pk_mul_f32 v[202:203], v[82:83], v[186:187]
	v_cvt_pk_f32_fp8_sdwa v[194:195], v54 src0_sel:WORD_1
	v_pk_fma_f32 v[200:201], v[84:85], v[188:189], v[200:201]
	v_cvt_pk_f32_fp8_e32 v[196:197], v55
	v_pk_fma_f32 v[202:203], v[86:87], v[190:191], v[202:203]
	v_cvt_pk_f32_fp8_sdwa v[198:199], v55 src0_sel:WORD_1
	v_pk_fma_f32 v[200:201], v[88:89], v[192:193], v[200:201]
	v_pk_fma_f32 v[202:203], v[90:91], v[194:195], v[202:203]
	v_pk_fma_f32 v[200:201], v[92:93], v[196:197], v[200:201]
	v_pk_fma_f32 v[202:203], v[94:95], v[198:199], v[202:203]
	v_pk_add_f32 v[200:201], v[200:201], v[202:203]
	v_add_f32_e32 v174, v200, v201
	v_readlane_b32 s23, v136, 6
	s_lshl_b32 s23, s23, 10
	v_add_u32_e32 v205, s23, v208
	global_load_dwordx4 v[52:55], v205, s[12:13]
	s_waitcnt vmcnt(15)
	v_cvt_pk_f32_fp8_e32 v[184:185], v56
	v_cvt_pk_f32_fp8_sdwa v[186:187], v56 src0_sel:WORD_1
	v_cvt_pk_f32_fp8_e32 v[188:189], v57
	v_cvt_pk_f32_fp8_sdwa v[190:191], v57 src0_sel:WORD_1
	v_pk_mul_f32 v[200:201], v[64:65], v[184:185]
	v_cvt_pk_f32_fp8_e32 v[192:193], v58
	v_pk_mul_f32 v[202:203], v[66:67], v[186:187]
	v_cvt_pk_f32_fp8_sdwa v[194:195], v58 src0_sel:WORD_1
	v_pk_fma_f32 v[200:201], v[68:69], v[188:189], v[200:201]
	v_cvt_pk_f32_fp8_e32 v[196:197], v59
	v_pk_fma_f32 v[202:203], v[70:71], v[190:191], v[202:203]
	v_cvt_pk_f32_fp8_sdwa v[198:199], v59 src0_sel:WORD_1
	v_pk_fma_f32 v[200:201], v[72:73], v[192:193], v[200:201]
	v_pk_fma_f32 v[202:203], v[74:75], v[194:195], v[202:203]
	v_pk_fma_f32 v[200:201], v[76:77], v[196:197], v[200:201]
	v_pk_fma_f32 v[202:203], v[78:79], v[198:199], v[202:203]
	v_pk_add_f32 v[200:201], v[200:201], v[202:203]
	v_add_f32_e32 v167, v200, v201
	v_readlane_b32 s24, v128, 7
	s_lshl_b32 s24, s24, 10
	v_add_u32_e32 v206, s24, v208
	global_load_dwordx4 v[56:59], v206, s[12:13]
	s_nop 1
	v_permlane32_swap_b32_e32 v160, v164
	v_permlane32_swap_b32_e32 v161, v165
	v_permlane32_swap_b32_e32 v162, v166
	v_permlane32_swap_b32_e32 v163, v167
	v_add_f32_e32 v160, v160, v164
	v_add_f32_e32 v161, v161, v165
	v_add_f32_e32 v162, v162, v166
	v_add_f32_e32 v163, v163, v167
	v_cndmask_b32_e64 v216, v162, v160, s[26:27]
	v_cndmask_b32_e64 v218, v160, v162, s[26:27]
	v_cndmask_b32_e64 v217, v163, v161, s[26:27]
	v_cndmask_b32_e64 v219, v161, v163, s[26:27]
	ds_bpermute_b32 v220, v212, v216
	ds_bpermute_b32 v221, v212, v217
	s_waitcnt lgkmcnt(0)
; template <int PART>
; DEVI void phase_peer_gather(const Params& p, unsigned char* smem) {
;     ...
;       p.gates[(size_t)tok * 128 + lane] = cf0;
;       p.gates[(size_t)tok * 128 + 64 + lane] = cf1;
	v_add_f32_e32 v218, v220, v218
	v_add_f32_e32 v219, v221, v219
	v_cndmask_b32_e64 v216, v219, v218, s[28:29]
	v_cndmask_b32_e64 v217, v218, v219, s[28:29]
	s_nop 1
	v_add_f32_dpp v222, v216, v217 row_ror:8 row_mask:0xf bank_mask:0xf
	ds_bpermute_b32 v220, v213, v222
	s_waitcnt lgkmcnt(0)
	v_add_f32_e32 v222, v220, v222
	s_nop 1
	v_add_f32_dpp v223, v222, v222 quad_perm:[2,3,0,1] row_mask:0xf bank_mask:0xf
	s_nop 1
	v_add_f32_dpp v222, v223, v223 quad_perm:[1,0,3,2] row_mask:0xf bank_mask:0xf
	ds_bpermute_b32 v220, v214, v222
	s_mov_b32 s30, 0x0
	s_mov_b32 s31, 0xff000000
	s_waitcnt lgkmcnt(0)
	v_cndmask_b32_e64 v176, v176, v220, s[30:31]
	v_mul_f32_e32 v216, v117, v176
	v_mul_f32_e32 v217, 0x3d372713, v216
	v_mul_f32_e32 v217, v216, v217
	v_fma_f32 v217, v216, v217, v216
	v_mul_f32_e32 v217, 0x3f4c422a, v217
	v_mul_f32_e32 v217, 0xc0000000, v217
	v_mul_f32_e32 v217, 0x3fb8aa3b, v217
	v_exp_f32_e32 v217, v217
	s_nop 0
	v_add_f32_e32 v217, 0x3f800000, v217
	v_rcp_f32_e32 v217, v217
	s_nop 0
	v_mul_f32_e32 v216, v216, v217
	v_mul_f32_e32 v216, v115, v216
	v_mul_f32_e32 v178, v119, v216
	s_waitcnt vmcnt(15)
	v_cvt_pk_f32_fp8_e32 v[184:185], v60
	v_cvt_pk_f32_fp8_sdwa v[186:187], v60 src0_sel:WORD_1
	v_cvt_pk_f32_fp8_e32 v[188:189], v61
	v_cvt_pk_f32_fp8_sdwa v[190:191], v61 src0_sel:WORD_1
	v_pk_mul_f32 v[200:201], v[80:81], v[184:185]
	v_cvt_pk_f32_fp8_e32 v[192:193], v62
	v_pk_mul_f32 v[202:203], v[82:83], v[186:187]
	v_cvt_pk_f32_fp8_sdwa v[194:195], v62 src0_sel:WORD_1
	v_pk_fma_f32 v[200:201], v[84:85], v[188:189], v[200:201]
	v_cvt_pk_f32_fp8_e32 v[196:197], v63
	v_pk_fma_f32 v[202:203], v[86:87], v[190:191], v[202:203]
	v_cvt_pk_f32_fp8_sdwa v[198:199], v63 src0_sel:WORD_1
	v_pk_fma_f32 v[200:201], v[88:89], v[192:193], v[200:201]
	v_pk_fma_f32 v[202:203], v[90:91], v[194:195], v[202:203]
	v_pk_fma_f32 v[200:201], v[92:93], v[196:197], v[200:201]
	v_pk_fma_f32 v[202:203], v[94:95], v[198:199], v[202:203]
	v_pk_add_f32 v[200:201], v[200:201], v[202:203]
	v_add_f32_e32 v175, v200, v201
	v_readlane_b32 s25, v136, 7
	s_lshl_b32 s25, s25, 10
	v_add_u32_e32 v207, s25, v208
	global_load_dwordx4 v[60:63], v207, s[12:13]
	s_nop 1
	v_permlane32_swap_b32_e32 v168, v172
	v_permlane32_swap_b32_e32 v169, v173
	v_permlane32_swap_b32_e32 v170, v174
	v_permlane32_swap_b32_e32 v171, v175
	v_add_f32_e32 v168, v168, v172
	v_add_f32_e32 v169, v169, v173
	v_add_f32_e32 v170, v170, v174
	v_add_f32_e32 v171, v171, v175
	v_cndmask_b32_e64 v216, v170, v168, s[26:27]
	v_cndmask_b32_e64 v218, v168, v170, s[26:27]
	v_cndmask_b32_e64 v217, v171, v169, s[26:27]
	v_cndmask_b32_e64 v219, v169, v171, s[26:27]
	ds_bpermute_b32 v220, v212, v216
	ds_bpermute_b32 v221, v212, v217
	s_waitcnt lgkmcnt(0)
	v_add_f32_e32 v218, v220, v218
	v_add_f32_e32 v219, v221, v219
	v_cndmask_b32_e64 v216, v219, v218, s[28:29]
	v_cndmask_b32_e64 v217, v218, v219, s[28:29]
	s_nop 1
	v_add_f32_dpp v222, v216, v217 row_ror:8 row_mask:0xf bank_mask:0xf
	ds_bpermute_b32 v220, v213, v222
	s_waitcnt lgkmcnt(0)
	v_add_f32_e32 v222, v220, v222
	s_nop 1
	v_add_f32_dpp v223, v222, v222 quad_perm:[2,3,0,1] row_mask:0xf bank_mask:0xf
	s_nop 1
	v_add_f32_dpp v222, v223, v223 quad_perm:[1,0,3,2] row_mask:0xf bank_mask:0xf
	ds_bpermute_b32 v220, v214, v222
	s_mov_b32 s30, 0x0
	s_mov_b32 s31, 0xff000000
	s_waitcnt lgkmcnt(0)
	v_cndmask_b32_e64 v179, v179, v220, s[30:31]
	v_mul_f32_e32 v216, v125, v179
	v_mul_f32_e32 v217, 0x3d372713, v216
	v_mul_f32_e32 v217, v216, v217
	v_fma_f32 v217, v216, v217, v216
	v_mul_f32_e32 v217, 0x3f4c422a, v217
	v_mul_f32_e32 v217, 0xc0000000, v217
	v_mul_f32_e32 v217, 0x3fb8aa3b, v217
	v_exp_f32_e32 v217, v217
	s_nop 0
	v_add_f32_e32 v217, 0x3f800000, v217
	v_rcp_f32_e32 v217, v217
	s_nop 0
	v_mul_f32_e32 v216, v216, v217
	v_mul_f32_e32 v216, v123, v216
	v_mul_f32_e32 v181, v127, v216
	s_mov_b32 s40, s3
	s_cmp_lt_u32 s40, 0x8000
	s_cbranch_scc0 .Lp11_skip0
	s_lshl_b32 s20, s40, 9
	v_add_u32_e32 v224, s20, v209
	global_store_dword v224, v177, s[10:11]
	global_store_dword v224, v178, s[10:11] offset:256
.Lp11_skip0:
	s_mov_b32 s40, s3
	s_add_u32 s40, s40, s2
	s_add_u32 s40, s40, s2
	s_cmp_lt_u32 s40, 0x8000
	s_cbranch_scc0 .Lp11_skip1
	s_lshl_b32 s20, s40, 9
	v_add_u32_e32 v224, s20, v209
	global_store_dword v224, v180, s[10:11]
	global_store_dword v224, v181, s[10:11] offset:256
; template <int PART>
; DEVI void phase_peer_gather(const Params& p, unsigned char* smem) {
;     ...
;     const uint4* hp4 = (const uint4*)(p.hn + (size_t)tok * LDA + lane * 16);
;     float hv[16], xn[16], y[16];
;     {
;       const uint4 a0 = hp4[0], a1 = hp4[1];
;       const unsigned hu[8] = {a0.x, a0.y, a0.z, a0.w, a1.x, a1.y, a1.z, a1.w};
; #pragma unroll
;       for (int i = 0; i < 8; ++i) { hv[2 * i] = __uint_as_float(hu[i] << 16); hv[2 * i + 1] = __uint_as_float(hu[i] & 0xffff0000u); }
;     }
;     float ss = 0.f;
; #pragma unroll
;     for (int i = 0; i < 16; ++i) ss += hv[i] * hv[i];
;     ss = wave_sum(ss);
;     const float rstd = rsqrtf(ss * (1.f / D) + 1e-6f);
;     {
;       const float4* g4 = (const float4*)p.peer_g + lane * 4;
;       const float4 a0 = g4[0], a1 = g4[1], a2 = g4[2], a3 = g4[3];
;       const float gg[16] = {a0.x, a0.y, a0.z, a0.w, a1.x, a1.y, a1.z, a1.w, a2.x, a2.y, a2.z, a2.w, a3.x, a3.y, a3.z, a3.w};
; #pragma unroll
;       for (int i = 0; i < 16; ++i) { xn[i] = hv[i] * rstd * gg[i]; y[i] = 0.f; }
;     }
.Lp11_skip1:
	v_mov_b32_e32 v112, v128
	v_mov_b32_e32 v113, v129
	v_mov_b32_e32 v114, v130
	v_mov_b32_e32 v115, v131
	v_mov_b32_e32 v116, v132
	v_mov_b32_e32 v117, v133
	v_mov_b32_e32 v118, v134
	v_mov_b32_e32 v119, v135
	v_mov_b32_e32 v120, v136
	v_mov_b32_e32 v121, v137
	v_mov_b32_e32 v122, v138
	v_mov_b32_e32 v123, v139
	v_mov_b32_e32 v124, v140
	v_mov_b32_e32 v125, v141
	v_mov_b32_e32 v126, v142
	v_mov_b32_e32 v127, v143
	s_waitcnt vmcnt(63)
	v_lshlrev_b32_e32 v64, 16, v144
	v_and_b32_e32 v65, 0xffff0000, v144
	v_lshlrev_b32_e32 v66, 16, v145
	v_and_b32_e32 v67, 0xffff0000, v145
	v_lshlrev_b32_e32 v68, 16, v146
	v_and_b32_e32 v69, 0xffff0000, v146
	v_lshlrev_b32_e32 v70, 16, v147
	v_and_b32_e32 v71, 0xffff0000, v147
	v_lshlrev_b32_e32 v72, 16, v148
	v_and_b32_e32 v73, 0xffff0000, v148
	v_lshlrev_b32_e32 v74, 16, v149
	v_and_b32_e32 v75, 0xffff0000, v149
	v_lshlrev_b32_e32 v76, 16, v150
	v_and_b32_e32 v77, 0xffff0000, v150
	v_lshlrev_b32_e32 v78, 16, v151
	v_and_b32_e32 v79, 0xffff0000, v151
	v_mul_f32_e32 v226, v64, v64
	v_fmac_f32_e32 v226, v65, v65
	v_fmac_f32_e32 v226, v66, v66
	v_fmac_f32_e32 v226, v67, v67
	v_fmac_f32_e32 v226, v68, v68
	v_fmac_f32_e32 v226, v69, v69
	v_fmac_f32_e32 v226, v70, v70
	v_fmac_f32_e32 v226, v71, v71
	v_fmac_f32_e32 v226, v72, v72
	v_fmac_f32_e32 v226, v73, v73
	v_fmac_f32_e32 v226, v74, v74
	v_fmac_f32_e32 v226, v75, v75
	v_fmac_f32_e32 v226, v76, v76
	v_fmac_f32_e32 v226, v77, v77
	v_fmac_f32_e32 v226, v78, v78
	v_fmac_f32_e32 v226, v79, v79
	s_nop 1
	v_add_f32_dpp v227, v226, v226 quad_perm:[1,0,3,2] row_mask:0xf bank_mask:0xf
	v_mov_b32_e32 v226, v227
	s_nop 1
	v_add_f32_dpp v227, v226, v226 quad_perm:[2,3,0,1] row_mask:0xf bank_mask:0xf
	v_mov_b32_e32 v226, v227
	s_nop 1
	v_add_f32_dpp v227, v226, v226 row_half_mirror row_mask:0xf bank_mask:0xf
	v_mov_b32_e32 v226, v227
	s_nop 1
	v_add_f32_dpp v227, v226, v226 row_mirror row_mask:0xf bank_mask:0xf
	v_mov_b32_e32 v226, v227
	s_nop 0
	v_readlane_b32 s44, v226, 0
	v_readlane_b32 s45, v226, 16
	v_readlane_b32 s46, v226, 32
	v_readlane_b32 s47, v226, 48
	s_nop 1
	v_mov_b32_e32 v226, s44
	v_add_f32_e32 v226, s45, v226
	v_add_f32_e32 v226, s46, v226
	v_add_f32_e32 v226, s47, v226
	v_mov_b32_e32 v228, 0x358637bd
	v_fmamk_f32 v226, v226, 0x3a800000, v228
	v_rsq_f32_e32 v226, v226
	s_nop 0
	v_mul_f32_e32 v64, v226, v64
	v_mul_f32_e32 v64, v96, v64
	v_mul_f32_e32 v65, v226, v65
	v_mul_f32_e32 v65, v97, v65
	v_mul_f32_e32 v66, v226, v66
	v_mul_f32_e32 v66, v98, v66
	v_mul_f32_e32 v67, v226, v67
	v_mul_f32_e32 v67, v99, v67
	v_mul_f32_e32 v68, v226, v68
	v_mul_f32_e32 v68, v100, v68
	v_mul_f32_e32 v69, v226, v69
	v_mul_f32_e32 v69, v101, v69
	v_mul_f32_e32 v70, v226, v70
	v_mul_f32_e32 v70, v102, v70
	v_mul_f32_e32 v71, v226, v71
	v_mul_f32_e32 v71, v103, v71
	v_mul_f32_e32 v72, v226, v72
	v_mul_f32_e32 v72, v104, v72
	v_mul_f32_e32 v73, v226, v73
	v_mul_f32_e32 v73, v105, v73
	v_mul_f32_e32 v74, v226, v74
	v_mul_f32_e32 v74, v106, v74
	v_mul_f32_e32 v75, v226, v75
	v_mul_f32_e32 v75, v107, v75
	v_mul_f32_e32 v76, v226, v76
	v_mul_f32_e32 v76, v108, v76
	v_mul_f32_e32 v77, v226, v77
	v_mul_f32_e32 v77, v109, v77
	v_mul_f32_e32 v78, v226, v78
	v_mul_f32_e32 v78, v110, v78
	v_mul_f32_e32 v79, v226, v79
	v_mul_f32_e32 v79, v111, v79
	v_lshlrev_b32_e32 v80, 16, v152
	v_and_b32_e32 v81, 0xffff0000, v152
	v_lshlrev_b32_e32 v82, 16, v153
	v_and_b32_e32 v83, 0xffff0000, v153
	v_lshlrev_b32_e32 v84, 16, v154
	v_and_b32_e32 v85, 0xffff0000, v154
	v_lshlrev_b32_e32 v86, 16, v155
	v_and_b32_e32 v87, 0xffff0000, v155
	v_lshlrev_b32_e32 v88, 16, v156
	v_and_b32_e32 v89, 0xffff0000, v156
	v_lshlrev_b32_e32 v90, 16, v157
	v_and_b32_e32 v91, 0xffff0000, v157
	v_lshlrev_b32_e32 v92, 16, v158
	v_and_b32_e32 v93, 0xffff0000, v158
	v_lshlrev_b32_e32 v94, 16, v159
	v_and_b32_e32 v95, 0xffff0000, v159
	v_mul_f32_e32 v226, v80, v80
	v_fmac_f32_e32 v226, v81, v81
	v_fmac_f32_e32 v226, v82, v82
	v_fmac_f32_e32 v226, v83, v83
	v_fmac_f32_e32 v226, v84, v84
	v_fmac_f32_e32 v226, v85, v85
	v_fmac_f32_e32 v226, v86, v86
	v_fmac_f32_e32 v226, v87, v87
	v_fmac_f32_e32 v226, v88, v88
	v_fmac_f32_e32 v226, v89, v89
	v_fmac_f32_e32 v226, v90, v90
	v_fmac_f32_e32 v226, v91, v91
	v_fmac_f32_e32 v226, v92, v92
	v_fmac_f32_e32 v226, v93, v93
	v_fmac_f32_e32 v226, v94, v94
	v_fmac_f32_e32 v226, v95, v95
	s_nop 1
	v_add_f32_dpp v227, v226, v226 quad_perm:[1,0,3,2] row_mask:0xf bank_mask:0xf
	v_mov_b32_e32 v226, v227
	s_nop 1
	v_add_f32_dpp v227, v226, v226 quad_perm:[2,3,0,1] row_mask:0xf bank_mask:0xf
	v_mov_b32_e32 v226, v227
	s_nop 1
	v_add_f32_dpp v227, v226, v226 row_half_mirror row_mask:0xf bank_mask:0xf
	v_mov_b32_e32 v226, v227
	s_nop 1
	v_add_f32_dpp v227, v226, v226 row_mirror row_mask:0xf bank_mask:0xf
	v_mov_b32_e32 v226, v227
	s_nop 0
	v_readlane_b32 s44, v226, 0
	v_readlane_b32 s45, v226, 16
	v_readlane_b32 s46, v226, 32
	v_readlane_b32 s47, v226, 48
	s_nop 1
	v_mov_b32_e32 v226, s44
	v_add_f32_e32 v226, s45, v226
	v_add_f32_e32 v226, s46, v226
	v_add_f32_e32 v226, s47, v226
	v_mov_b32_e32 v228, 0x358637bd
	v_fmamk_f32 v226, v226, 0x3a800000, v228
	v_rsq_f32_e32 v226, v226
	s_nop 0
	v_mul_f32_e32 v80, v226, v80
	v_mul_f32_e32 v80, v96, v80
	v_mul_f32_e32 v81, v226, v81
	v_mul_f32_e32 v81, v97, v81
	v_mul_f32_e32 v82, v226, v82
	v_mul_f32_e32 v82, v98, v82
	v_mul_f32_e32 v83, v226, v83
	v_mul_f32_e32 v83, v99, v83
	v_mul_f32_e32 v84, v226, v84
	v_mul_f32_e32 v84, v100, v84
	v_mul_f32_e32 v85, v226, v85
	v_mul_f32_e32 v85, v101, v85
	v_mul_f32_e32 v86, v226, v86
	v_mul_f32_e32 v86, v102, v86
	v_mul_f32_e32 v87, v226, v87
	v_mul_f32_e32 v87, v103, v87
	v_mul_f32_e32 v88, v226, v88
	v_mul_f32_e32 v88, v104, v88
	v_mul_f32_e32 v89, v226, v89
	v_mul_f32_e32 v89, v105, v89
	v_mul_f32_e32 v90, v226, v90
	v_mul_f32_e32 v90, v106, v90
	v_mul_f32_e32 v91, v226, v91
	v_mul_f32_e32 v91, v107, v91
	v_mul_f32_e32 v92, v226, v92
	v_mul_f32_e32 v92, v108, v92
	v_mul_f32_e32 v93, v226, v93
	v_mul_f32_e32 v93, v109, v93
	v_mul_f32_e32 v94, v226, v94
	v_mul_f32_e32 v94, v110, v94
	v_mul_f32_e32 v95, v226, v95
	v_mul_f32_e32 v95, v111, v95
	s_add_u32 s3, s3, s42
	s_add_u32 s41, s41, 1
	s_cmp_lt_u32 s3, 0x8000
	s_cbranch_scc1 .Lp11_group
	s_waitcnt vmcnt(0)

; DEVI int launder(int x) { asm volatile("" : "+v"(x)); return x; }
; template <int PART>
; DEVI void phase_peer_gather(const Params& p, unsigned char* smem) {
;   const int w0_ = threadIdx.x >> 6;
; #pragma unroll 1
;   for (int tok = blockIdx.x * 4 + w0_; tok < NTOK; tok += gridDim.x * 4) {
;     if (NTOK % (gridDim.x * 4) == 0) __syncthreads();
;     const int tid = launder(threadIdx.x), lane = tid & 63;
;     const uint4* hp4 = (const uint4*)(p.hn + (size_t)tok * LDA + lane * 16);
;     float hv[16], xn[16], y[16];
;     {
;       const uint4 a0 = hp4[0], a1 = hp4[1];
;       const unsigned hu[8] = {a0.x, a0.y, a0.z, a0.w, a1.x, a1.y, a1.z, a1.w};
; #pragma unroll
;       for (int i = 0; i < 8; ++i) { hv[2 * i] = __uint_as_float(hu[i] << 16); hv[2 * i + 1] = __uint_as_float(hu[i] & 0xffff0000u); }
;     }
;     float ss = 0.f;
; #pragma unroll
;     for (int i = 0; i < 16; ++i) ss += hv[i] * hv[i];
;     ss = wave_sum(ss);
;     const float rstd = rsqrtf(ss * (1.f / D) + 1e-6f);
;     {
;       const float4* g4 = (const float4*)p.peer_g + lane * 4;
;       const float4 a0 = g4[0], a1 = g4[1], a2 = g4[2], a3 = g4[3];
;       const float gg[16] = {a0.x, a0.y, a0.z, a0.w, a1.x, a1.y, a1.z, a1.w, a2.x, a2.y, a2.z, a2.w, a3.x, a3.y, a3.z, a3.w};
; #pragma unroll
;       for (int i = 0; i < 16; ++i) { xn[i] = hv[i] * rstd * gg[i]; y[i] = 0.f; }
;     }
;     int e0 = p.experts[(size_t)tok * 128 + lane], e1 = p.experts[(size_t)tok * 128 + 64 + lane];
;     float g0 = p.gates[(size_t)tok * 128 + lane], g1 = p.gates[(size_t)tok * 128 + 64 + lane];
;     if (PART == 0) {
;       int* sE = (int*)(smem + (tid >> 6) * 1024);
;       float* sG = (float*)(sE + 128);
;       int pos0 = 0, pos1 = 0, base = 0;
;       const int flip_ = (((tok - (blockIdx.x * 4 + w0_)) / (int)(gridDim.x * 4)) & 1) ? 15 : 0;
.Lp11_compiler_path:
	v_lshl_add_u32 v95, s90, 2, v94
	s_mov_b32 s0, 0x8000
	v_cmp_gt_i32_e32 vcc, s0, v95
	s_and_saveexec_b64 s[0:1], vcc
	s_cbranch_execz .LBB0_1393
	s_load_dword s4, s[68:69], 0x200
	s_waitcnt lgkmcnt(0)
	v_mbcnt_lo_u32_b32 v1, -1, 0
	v_readlane_b32 s8, v248, 0
	v_mbcnt_hi_u32_b32 v97, -1, v1
	v_readlane_b32 s9, v248, 1
	s_lshl_b32 s42, s4, 2
	v_cvt_f32_u32_e32 v0, s42
	s_sub_i32 s4, 0, s42
	v_and_b32_e32 v98, 64, v97
	s_mov_b64 s[2:3], 0
	v_rcp_iflag_f32_e32 v0, v0
	s_movk_i32 s33, 0x880
	v_mov_b64_e32 v[64:65], s[8:9]
	v_mov_b32_e32 v67, 0
	v_mul_f32_e32 v0, 0x4f7ffffe, v0
	v_cvt_u32_f32_e32 v0, v0
	v_mov_b32_e32 v96, 0x358637bd
	s_mov_b32 s43, 0x800000
	s_movk_i32 s44, 0x7fff
	v_readfirstlane_b32 s5, v0
	s_mul_i32 s4, s4, s5
	s_mul_hi_u32 s4, s5, s4
	s_add_i32 s45, s5, s4
	s_lshr_b32 s4, s45, 17
	s_mul_i32 s4, s4, s42
	s_sub_i32 s4, 0x8000, s4
	s_sub_i32 s5, s4, s42
	s_cmp_ge_u32 s4, s42
	s_cselect_b32 s4, s5, s4
	s_sub_i32 s5, s4, s42
	s_cmp_ge_u32 s4, s42
	s_cselect_b32 s4, s5, s4
	s_cmp_eq_u32 s4, 0
	s_cselect_b64 s[4:5], -1, 0
	v_cndmask_b32_e64 v0, 0, 1, s[4:5]
	v_add_u32_e32 v99, 64, v98
	v_cmp_ne_u32_e64 s[4:5], 1, v0
	v_xor_b32_e32 v100, 32, v97
	v_xor_b32_e32 v101, 16, v97
	v_xor_b32_e32 v102, 8, v97
	v_xor_b32_e32 v103, 4, v97
	v_xor_b32_e32 v104, 2, v97
	v_xor_b32_e32 v105, 1, v97
	s_waitcnt vmcnt(18)
	v_mov_b32_e32 v68, v95
	v_readlane_b32 s10, v248, 2
	v_readlane_b32 s11, v248, 3
	s_branch .LBB0_1348

; template <int PART>
; DEVI void phase_peer_gather(const Params& p, unsigned char* smem) {
;     ...
;     int e0 = p.experts[(size_t)tok * 128 + lane], e1 = p.experts[(size_t)tok * 128 + 64 + lane];
;     float g0 = p.gates[(size_t)tok * 128 + lane], g1 = p.gates[(size_t)tok * 128 + 64 + lane];
;     ...
;     cf0 = g0; cf1 = g1;
;     LOADB_(ca, 16)
; #pragma unroll 1
;     for (int bi = 16; bi < 32; bi += 2) {
;       LOADB_(cb, bi + 1)
;       COMPV_(ca, bi)
;       if (bi + 2 < 32) { LOADB_(ca, bi + 2) }
.LBB0_1447:
	s_cmp_gt_i32 s88, 12
	s_cselect_b64 s[0:1], -1, 0
	s_cmp_lt_i32 s89, 12
	s_cselect_b64 s[2:3], -1, 0
	s_or_b64 s[0:1], s[0:1], s[2:3]
	s_and_b64 vcc, exec, s[0:1]
	s_cbranch_vccnz .LBB0_1511
	s_load_dword s2, s[68:69], 0x200
	s_waitcnt lgkmcnt(0)
	s_lshl_b32 s2, s2, 2
	s_add_i32 s3, s2, -1
	s_and_b32 s3, s3, s2
	s_cmp_lg_u32 s3, 0
	s_cbranch_scc1 .Lp12_compiler_path
	s_cmp_gt_u32 s2, 0x2000
	s_cbranch_scc1 .Lp12_compiler_path
	v_and_b32_e32 v238, 63, v210
	v_lshlrev_b32_e32 v208, 4, v238
	v_lshlrev_b32_e32 v209, 2, v238
	v_lshlrev_b32_e32 v211, 5, v238
	v_lshlrev_b32_e32 v212, 6, v238
	s_load_dwordx2 s[16:17], s[68:69], 0xd0
	s_load_dwordx2 s[14:15], s[68:69], 0xd8
	s_load_dwordx2 s[6:7], s[68:69], 0xe0
	s_load_dwordx2 s[8:9], s[68:69], 0x1b0
	s_load_dwordx2 s[10:11], s[68:69], 0x1b8
	s_load_dwordx2 s[12:13], s[68:69], 0x1c8
	s_load_dword s2, s[68:69], 0x200
	v_lshrrev_b32_e32 v239, 6, v210
	s_nop 0
	v_readfirstlane_b32 s3, v239
	s_waitcnt lgkmcnt(0)
	s_lshl_b32 s2, s2, 2
	s_lshl_b32 s18, s90, 2
	s_add_u32 s3, s3, s18
	s_add_i32 s18, s2, -1
	s_and_b32 s19, s18, s2
	s_and_b32 s18, s18, 0x8000
	s_or_b32 s32, s18, s19
	s_mov_b32 s34, 0
	s_cmp_ge_u32 s3, 0x8000
	s_cbranch_scc1 .Lp12_done
	global_load_dwordx4 v[128:131], v212, s[16:17]
	global_load_dwordx4 v[132:135], v212, s[16:17] offset:16
	global_load_dwordx4 v[136:139], v212, s[16:17] offset:32
	global_load_dwordx4 v[140:143], v212, s[16:17] offset:48
	s_mov_b32 s33, s3
	s_cmp_lt_u32 s33, 0x8000
	s_cselect_b32 s33, s33, s3
	s_lshl_b32 s18, s33, 9
	v_add_u32_e32 v236, s18, v209
	global_load_dword v176, v236, s[8:9]
	global_load_dword v177, v236, s[8:9] offset:256
	global_load_dword v178, v236, s[10:11]
	global_load_dword v179, v236, s[10:11] offset:256
	s_mov_b32 s33, s3
	s_add_u32 s33, s33, s2
	s_add_u32 s33, s33, s2
	s_cmp_lt_u32 s33, 0x8000
	s_cselect_b32 s33, s33, s3
	s_lshl_b32 s18, s33, 9
	v_add_u32_e32 v236, s18, v209
	global_load_dword v180, v236, s[8:9]
	global_load_dword v181, v236, s[8:9] offset:256
	global_load_dword v182, v236, s[10:11]
	global_load_dword v183, v236, s[10:11] offset:256
	v_mov_b32_e32 v64, 0
	v_mov_b32_e32 v65, 0
	v_mov_b32_e32 v66, 0
	v_mov_b32_e32 v67, 0
	v_mov_b32_e32 v68, 0
	v_mov_b32_e32 v69, 0
	v_mov_b32_e32 v70, 0
	v_mov_b32_e32 v71, 0
	v_mov_b32_e32 v72, 0
	v_mov_b32_e32 v73, 0
	v_mov_b32_e32 v74, 0
	v_mov_b32_e32 v75, 0
	v_mov_b32_e32 v76, 0
	v_mov_b32_e32 v77, 0
	v_mov_b32_e32 v78, 0
	v_mov_b32_e32 v79, 0
	v_mov_b32_e32 v80, 0
	v_mov_b32_e32 v81, 0
	v_mov_b32_e32 v82, 0
	v_mov_b32_e32 v83, 0
	v_mov_b32_e32 v84, 0
	v_mov_b32_e32 v85, 0
	v_mov_b32_e32 v86, 0
	v_mov_b32_e32 v87, 0
	v_mov_b32_e32 v88, 0
	v_mov_b32_e32 v89, 0
	v_mov_b32_e32 v90, 0
	v_mov_b32_e32 v91, 0
	v_mov_b32_e32 v92, 0
	v_mov_b32_e32 v93, 0
	v_mov_b32_e32 v94, 0
	v_mov_b32_e32 v95, 0
	s_waitcnt vmcnt(0)
	v_readlane_b32 s28, v176, 0
	s_lshl_b32 s28, s28, 10
	v_add_u32_e32 v232, s28, v208
	global_load_dwordx4 v[0:3], v232, s[12:13]
	v_readlane_b32 s29, v180, 0
	s_lshl_b32 s29, s29, 10
	v_add_u32_e32 v233, s29, v208
	global_load_dwordx4 v[4:7], v233, s[12:13]
	v_readlane_b32 s30, v176, 1
	s_lshl_b32 s30, s30, 10
	v_add_u32_e32 v234, s30, v208
	global_load_dwordx4 v[8:11], v234, s[12:13]
	v_readlane_b32 s31, v180, 1
	s_lshl_b32 s31, s31, 10
	v_add_u32_e32 v235, s31, v208
	global_load_dwordx4 v[12:15], v235, s[12:13]
	v_readlane_b32 s28, v176, 2
	s_lshl_b32 s28, s28, 10
	v_add_u32_e32 v232, s28, v208
	global_load_dwordx4 v[16:19], v232, s[12:13]
	v_readlane_b32 s29, v180, 2
	s_lshl_b32 s29, s29, 10
	v_add_u32_e32 v233, s29, v208
	global_load_dwordx4 v[20:23], v233, s[12:13]
	v_readlane_b32 s30, v176, 3
	s_lshl_b32 s30, s30, 10
	v_add_u32_e32 v234, s30, v208
	global_load_dwordx4 v[24:27], v234, s[12:13]
	v_readlane_b32 s31, v180, 3
	s_lshl_b32 s31, s31, 10
	v_add_u32_e32 v235, s31, v208
	global_load_dwordx4 v[28:31], v235, s[12:13]
	v_readlane_b32 s28, v176, 4
	s_lshl_b32 s28, s28, 10
	v_add_u32_e32 v232, s28, v208
	global_load_dwordx4 v[32:35], v232, s[12:13]
	v_readlane_b32 s29, v180, 4
	s_lshl_b32 s29, s29, 10
	v_add_u32_e32 v233, s29, v208
	global_load_dwordx4 v[36:39], v233, s[12:13]
	v_readlane_b32 s30, v176, 5
	s_lshl_b32 s30, s30, 10
	v_add_u32_e32 v234, s30, v208
	global_load_dwordx4 v[40:43], v234, s[12:13]
	v_readlane_b32 s31, v180, 5
	s_lshl_b32 s31, s31, 10
	v_add_u32_e32 v235, s31, v208
	global_load_dwordx4 v[44:47], v235, s[12:13]
	v_readlane_b32 s28, v176, 6
	s_lshl_b32 s28, s28, 10
	v_add_u32_e32 v232, s28, v208
	global_load_dwordx4 v[48:51], v232, s[12:13]
	v_readlane_b32 s29, v180, 6
	s_lshl_b32 s29, s29, 10
	v_add_u32_e32 v233, s29, v208
	global_load_dwordx4 v[52:55], v233, s[12:13]
	v_readlane_b32 s30, v176, 7
	s_lshl_b32 s30, s30, 10
	v_add_u32_e32 v234, s30, v208
	global_load_dwordx4 v[56:59], v234, s[12:13]
	v_readlane_b32 s31, v180, 7
	s_lshl_b32 s31, s31, 10
	v_add_u32_e32 v235, s31, v208
	global_load_dwordx4 v[60:63], v235, s[12:13]
	global_load_dwordx4 v[128:131], v212, s[16:17]
	global_load_dwordx4 v[132:135], v212, s[16:17] offset:16
	global_load_dwordx4 v[136:139], v212, s[16:17] offset:32
	global_load_dwordx4 v[140:143], v212, s[16:17] offset:48
	global_load_dwordx4 v[128:131], v212, s[16:17]
	global_load_dwordx4 v[132:135], v212, s[16:17] offset:16
	global_load_dwordx4 v[136:139], v212, s[16:17] offset:32
	global_load_dwordx4 v[140:143], v212, s[16:17] offset:48

; DEVI int launder(int x) { asm volatile("" : "+v"(x)); return x; }
; template <int PART>
; DEVI void phase_peer_gather(const Params& p, unsigned char* smem) {
;   const int w0_ = threadIdx.x >> 6;
; #pragma unroll 1
;   for (int tok = blockIdx.x * 4 + w0_; tok < NTOK; tok += gridDim.x * 4) {
;     if (NTOK % (gridDim.x * 4) == 0) __syncthreads();
;     const int tid = launder(threadIdx.x), lane = tid & 63;
;     ...
;     cf0 = g0; cf1 = g1;
;     LOADB_(ca, 16)
; #pragma unroll 1
;     for (int bi = 16; bi < 32; bi += 2) {
;       LOADB_(cb, bi + 1)
;       COMPV_(ca, bi)
;       if (bi + 2 < 32) { LOADB_(ca, bi + 2) }
;       COMPV_(cb, bi + 1)
;     }
.Lp12_skip1:
	s_nop 1
	v_mov_b32_e32 v176, v192
	v_mov_b32_e32 v177, v193
	v_mov_b32_e32 v178, v194
	v_mov_b32_e32 v179, v195
	v_mov_b32_e32 v180, v196
	v_mov_b32_e32 v181, v197
	v_mov_b32_e32 v182, v198
	v_mov_b32_e32 v183, v199
	v_mov_b32_e32 v64, 0
	v_mov_b32_e32 v65, 0
	v_mov_b32_e32 v66, 0
	v_mov_b32_e32 v67, 0
	v_mov_b32_e32 v68, 0
	v_mov_b32_e32 v69, 0
	v_mov_b32_e32 v70, 0
	v_mov_b32_e32 v71, 0
	v_mov_b32_e32 v72, 0
	v_mov_b32_e32 v73, 0
	v_mov_b32_e32 v74, 0
	v_mov_b32_e32 v75, 0
	v_mov_b32_e32 v76, 0
	v_mov_b32_e32 v77, 0
	v_mov_b32_e32 v78, 0
	v_mov_b32_e32 v79, 0
	v_mov_b32_e32 v80, 0
	v_mov_b32_e32 v81, 0
	v_mov_b32_e32 v82, 0
	v_mov_b32_e32 v83, 0
	v_mov_b32_e32 v84, 0
	v_mov_b32_e32 v85, 0
	v_mov_b32_e32 v86, 0
	v_mov_b32_e32 v87, 0
	v_mov_b32_e32 v88, 0
	v_mov_b32_e32 v89, 0
	v_mov_b32_e32 v90, 0
	v_mov_b32_e32 v91, 0
	v_mov_b32_e32 v92, 0
	v_mov_b32_e32 v93, 0
	v_mov_b32_e32 v94, 0
	v_mov_b32_e32 v95, 0
	s_add_u32 s3, s3, s35
	s_add_u32 s34, s34, 1
	s_cmp_lt_u32 s3, 0x8000
	s_cbranch_scc1 .Lp12_group
	s_waitcnt vmcnt(0)
.Lp12_done:
	s_branch .LBB0_1457
.Lp12_compiler_path:
	v_lshl_add_u32 v104, s90, 2, v94
	s_mov_b32 s0, 0x8000
	v_cmp_gt_i32_e32 vcc, s0, v104
	s_and_saveexec_b64 s[0:1], vcc
	s_cbranch_execz .LBB0_1457
	s_load_dword s2, s[68:69], 0x200
	v_readlane_b32 s4, v248, 0
	v_readlane_b32 s5, v248, 1
	s_waitcnt lgkmcnt(0)
	v_mbcnt_lo_u32_b32 v1, -1, 0
	s_movk_i32 s11, 0x880
	s_lshl_b32 s9, s2, 2
	v_cvt_f32_u32_e32 v0, s9
	v_mov_b64_e32 v[106:107], s[4:5]
	s_sub_i32 s4, 0, s9
	s_mov_b64 s[2:3], 0
	v_rcp_iflag_f32_e32 v0, v0
	v_mov_b32_e32 v109, 0
	v_mov_b32_e32 v128, 0x358637bd
	s_mov_b32 s13, 0x800000
	v_mul_f32_e32 v0, 0x4f7ffffe, v0
	v_cvt_u32_f32_e32 v0, v0
	v_mbcnt_hi_u32_b32 v129, -1, v1
	s_movk_i32 s15, 0x7fff
	v_readlane_b32 s6, v248, 2
	v_readfirstlane_b32 s5, v0
	s_mul_i32 s4, s4, s5
	s_mul_hi_u32 s4, s5, s4
	s_add_i32 s5, s5, s4
	s_lshr_b32 s4, s5, 17
	s_mul_i32 s4, s4, s9
	s_sub_i32 s4, 0x8000, s4
	s_sub_i32 s5, s4, s9
	s_cmp_ge_u32 s4, s9
	s_cselect_b32 s4, s5, s4
	s_sub_i32 s5, s4, s9
	s_cmp_ge_u32 s4, s9
	s_cselect_b32 s4, s5, s4
	s_cmp_eq_u32 s4, 0
	s_cselect_b64 s[4:5], -1, 0
	v_cndmask_b32_e64 v0, 0, 1, s[4:5]
	v_cmp_ne_u32_e64 s[4:5], 1, v0
	v_readlane_b32 s7, v248, 3
	s_branch .LBB0_1451
